# v67 + even-phase LOAD segments issue their first LDS-DMA before the ds_reads (DMA issue chain starts 8 slots earlier)
# speedup vs baseline: 1.0124x; 1.0009x over previous
.LBB0_297:
	s_add_u32 s47, s38, s46
	s_addc_u32 s66, s39, 0
	s_add_u32 s64, s47, 0x100
	s_addc_u32 s65, s66, 0
	s_and_b64 s[48:49], s[44:45], exec
	s_cselect_b32 s49, s70, s65
	s_cselect_b32 s48, s71, s64
	s_add_u32 s46, s36, s46
	s_addc_u32 s64, s37, 0
	s_add_u32 s46, s46, 0x100
	s_addc_u32 s64, s64, 0
	s_and_b64 s[44:45], s[44:45], exec
	s_cselect_b32 s65, s72, s64
	s_cselect_b32 s64, s73, s46
	s_add_u32 s68, s47, 0x10080
	ds_read_b128 v[150:153], v146
	ds_read_b128 v[154:157], v146 offset:1024
	ds_read_b128 v[158:161], v146 offset:2048
	ds_read_b128 v[162:165], v146 offset:3072
	ds_read_b128 v[166:169], v147
	ds_read_b128 v[170:173], v147 offset:1024
	ds_read_b128 v[174:177], v147 offset:2048
	ds_read_b128 v[178:181], v147 offset:3072
	s_addc_u32 s69, s66, 0
	s_add_i32 s83, s30, s2
	s_add_i32 m0, s16, 0xc000
	s_add_i32 s84, s16, 0xe000
	s_add_i32 s80, s83, 0x2000
	s_add_u32 s66, s64, 0x40000
	s_addc_u32 s67, s65, 0
	s_add_i32 s82, s31, s2
	s_add_i32 s81, s82, 0x2000
	s_add_i32 s79, 0, 0x18000
	s_add_i32 s78, 0, 0x1c000
	s_add_u32 s46, s48, 0x10000
	s_addc_u32 s47, s49, 0
	s_add_i32 s77, s79, s2
	s_add_i32 s75, s77, 0x2000
	s_add_u32 s44, s64, 0x40080
	s_addc_u32 s45, s65, 0
	s_add_i32 s76, s78, s2
	s_add_i32 s74, s76, 0x2000
	v_lshl_add_u64 v[202:203], s[68:69], 0, v[130:131]
	ds_read_b128 v[182:185], v148
	ds_read_b128 v[186:189], v148 offset:1024
	ds_read_b128 v[190:193], v148 offset:2048
	ds_read_b128 v[194:197], v148 offset:3072
	ds_read_b128 v[198:201], v148 offset:4096
	ds_read_b128 v[206:209], v148 offset:5120
	ds_read_b128 v[210:213], v148 offset:6144
	ds_read_b128 v[214:217], v148 offset:7168
	global_load_lds_dwordx4 v[202:203], off
	s_mov_b32 m0, s84
	v_lshl_add_u64 v[202:203], s[68:69], 0, v[132:133]
	global_load_lds_dwordx4 v[202:203], off
	s_waitcnt vmcnt(8) lgkmcnt(0)
	s_setprio 1
	s_barrier
	v_mfma_f32_16x16x32_bf16 v[126:129], v[150:153], v[182:185], v[126:129]
	v_mfma_f32_16x16x32_bf16 v[122:125], v[158:161], v[182:185], v[122:125]
	v_mfma_f32_16x16x32_bf16 v[118:121], v[150:153], v[190:193], v[118:121]
	v_mfma_f32_16x16x32_bf16 v[114:117], v[158:161], v[190:193], v[114:117]
	v_mfma_f32_16x16x32_bf16 v[102:105], v[150:153], v[198:201], v[102:105]
	v_mfma_f32_16x16x32_bf16 v[98:101], v[158:161], v[198:201], v[98:101]
	v_mfma_f32_16x16x32_bf16 v[86:89], v[150:153], v[210:213], v[86:89]
	v_mfma_f32_16x16x32_bf16 v[82:85], v[158:161], v[210:213], v[82:85]
	v_mfma_f32_16x16x32_bf16 v[126:129], v[154:157], v[186:189], v[126:129]
	v_mfma_f32_16x16x32_bf16 v[122:125], v[162:165], v[186:189], v[122:125]
	v_mfma_f32_16x16x32_bf16 v[118:121], v[154:157], v[194:197], v[118:121]
	v_mfma_f32_16x16x32_bf16 v[114:117], v[162:165], v[194:197], v[114:117]
	v_mfma_f32_16x16x32_bf16 v[102:105], v[154:157], v[206:209], v[102:105]
	v_mfma_f32_16x16x32_bf16 v[98:101], v[162:165], v[206:209], v[98:101]
	v_mfma_f32_16x16x32_bf16 v[86:89], v[154:157], v[214:217], v[86:89]
	v_mfma_f32_16x16x32_bf16 v[82:85], v[162:165], v[214:217], v[82:85]
	v_mfma_f32_16x16x32_bf16 v[110:113], v[166:169], v[182:185], v[110:113]
	v_mfma_f32_16x16x32_bf16 v[106:109], v[174:177], v[182:185], v[106:109]
	v_mfma_f32_16x16x32_bf16 v[94:97], v[166:169], v[190:193], v[94:97]
	v_mfma_f32_16x16x32_bf16 v[90:93], v[174:177], v[190:193], v[90:93]
	v_mfma_f32_16x16x32_bf16 v[78:81], v[166:169], v[198:201], v[78:81]
	v_mfma_f32_16x16x32_bf16 v[74:77], v[174:177], v[198:201], v[74:77]
	v_mfma_f32_16x16x32_bf16 v[70:73], v[166:169], v[210:213], v[70:73]
	v_mfma_f32_16x16x32_bf16 v[66:69], v[174:177], v[210:213], v[66:69]
	v_mfma_f32_16x16x32_bf16 v[110:113], v[170:173], v[186:189], v[110:113]
	v_mfma_f32_16x16x32_bf16 v[106:109], v[178:181], v[186:189], v[106:109]
	v_mfma_f32_16x16x32_bf16 v[94:97], v[170:173], v[194:197], v[94:97]
	v_mfma_f32_16x16x32_bf16 v[90:93], v[178:181], v[194:197], v[90:93]
	v_mfma_f32_16x16x32_bf16 v[78:81], v[170:173], v[206:209], v[78:81]
	v_mfma_f32_16x16x32_bf16 v[74:77], v[178:181], v[206:209], v[74:77]
	v_mfma_f32_16x16x32_bf16 v[70:73], v[170:173], v[214:217], v[70:73]
	v_mfma_f32_16x16x32_bf16 v[66:69], v[178:181], v[214:217], v[66:69]
	s_setprio 0
	s_barrier
	s_mov_b32 m0, s83
	v_lshl_add_u64 v[202:203], s[64:65], 0, v[136:137]
	global_load_lds_dwordx4 v[202:203], off
	ds_read_b128 v[182:185], v148 offset:16384
	ds_read_b128 v[186:189], v148 offset:17408
	ds_read_b128 v[190:193], v148 offset:18432
	ds_read_b128 v[194:197], v148 offset:19456
	ds_read_b128 v[198:201], v148 offset:20480
	ds_read_b128 v[206:209], v148 offset:21504
	ds_read_b128 v[210:213], v148 offset:22528
	ds_read_b128 v[214:217], v148 offset:23552
	v_lshl_add_u64 v[218:219], s[64:65], 0, v[134:135]
	s_mov_b32 m0, s80
	v_lshl_add_u64 v[220:221], s[66:67], 0, v[136:137]
	global_load_lds_dwordx4 v[218:219], off
	s_mov_b32 m0, s82
	v_lshl_add_u64 v[222:223], s[48:49], 0, v[132:133]
	global_load_lds_dwordx4 v[220:221], off
	s_mov_b32 m0, s81
	v_lshl_add_u64 v[220:221], s[66:67], 0, v[134:135]
	global_load_lds_dwordx4 v[220:221], off
	s_mov_b32 m0, s16
	v_lshl_add_u64 v[220:221], s[48:49], 0, v[130:131]
	global_load_lds_dwordx4 v[220:221], off
	s_mov_b32 m0, s17
	s_nop 0
	global_load_lds_dwordx4 v[222:223], off
	s_waitcnt vmcnt(8) lgkmcnt(0)
	s_setprio 1
	s_barrier
	v_mfma_f32_16x16x32_bf16 v[62:65], v[150:153], v[182:185], v[62:65]
	v_mfma_f32_16x16x32_bf16 v[58:61], v[158:161], v[182:185], v[58:61]
	v_mfma_f32_16x16x32_bf16 v[54:57], v[150:153], v[190:193], v[54:57]
	v_mfma_f32_16x16x32_bf16 v[50:53], v[158:161], v[190:193], v[50:53]
	v_mfma_f32_16x16x32_bf16 v[38:41], v[150:153], v[198:201], v[38:41]
	v_mfma_f32_16x16x32_bf16 v[34:37], v[158:161], v[198:201], v[34:37]
	v_mfma_f32_16x16x32_bf16 v[22:25], v[150:153], v[210:213], v[22:25]
	v_mfma_f32_16x16x32_bf16 v[18:21], v[158:161], v[210:213], v[18:21]
	v_mfma_f32_16x16x32_bf16 v[62:65], v[154:157], v[186:189], v[62:65]
	v_mfma_f32_16x16x32_bf16 v[58:61], v[162:165], v[186:189], v[58:61]
	v_mfma_f32_16x16x32_bf16 v[54:57], v[154:157], v[194:197], v[54:57]
	v_mfma_f32_16x16x32_bf16 v[50:53], v[162:165], v[194:197], v[50:53]
	v_mfma_f32_16x16x32_bf16 v[38:41], v[154:157], v[206:209], v[38:41]
	v_mfma_f32_16x16x32_bf16 v[34:37], v[162:165], v[206:209], v[34:37]
	v_mfma_f32_16x16x32_bf16 v[22:25], v[154:157], v[214:217], v[22:25]
	v_mfma_f32_16x16x32_bf16 v[18:21], v[162:165], v[214:217], v[18:21]
	v_mfma_f32_16x16x32_bf16 v[46:49], v[166:169], v[182:185], v[46:49]
	v_mfma_f32_16x16x32_bf16 v[42:45], v[174:177], v[182:185], v[42:45]
	v_mfma_f32_16x16x32_bf16 v[30:33], v[166:169], v[190:193], v[30:33]
	v_mfma_f32_16x16x32_bf16 v[26:29], v[174:177], v[190:193], v[26:29]
	v_mfma_f32_16x16x32_bf16 v[14:17], v[166:169], v[198:201], v[14:17]
	v_mfma_f32_16x16x32_bf16 v[10:13], v[174:177], v[198:201], v[10:13]
	v_mfma_f32_16x16x32_bf16 v[6:9], v[166:169], v[210:213], v[6:9]
	v_mfma_f32_16x16x32_bf16 v[2:5], v[174:177], v[210:213], v[2:5]
	v_mfma_f32_16x16x32_bf16 v[46:49], v[170:173], v[186:189], v[46:49]
	v_mfma_f32_16x16x32_bf16 v[42:45], v[178:181], v[186:189], v[42:45]
	v_mfma_f32_16x16x32_bf16 v[30:33], v[170:173], v[194:197], v[30:33]
	v_mfma_f32_16x16x32_bf16 v[26:29], v[178:181], v[194:197], v[26:29]
	v_mfma_f32_16x16x32_bf16 v[14:17], v[170:173], v[206:209], v[14:17]
	v_mfma_f32_16x16x32_bf16 v[10:13], v[178:181], v[206:209], v[10:13]
	v_mfma_f32_16x16x32_bf16 v[6:9], v[170:173], v[214:217], v[6:9]
	v_mfma_f32_16x16x32_bf16 v[2:5], v[178:181], v[214:217], v[2:5]
	s_setprio 0
	s_barrier
	v_add_u32_e32 v149, s79, v145
	ds_read_b128 v[150:153], v149
	ds_read_b128 v[154:157], v149 offset:1024
	ds_read_b128 v[158:161], v149 offset:2048
	ds_read_b128 v[162:165], v149 offset:3072
	v_add_u32_e32 v149, s78, v145
	ds_read_b128 v[166:169], v149
	ds_read_b128 v[170:173], v149 offset:1024
	ds_read_b128 v[174:177], v149 offset:2048
	ds_read_b128 v[178:181], v149 offset:3072
	s_mov_b32 m0, s18
	v_lshl_add_u64 v[224:225], s[46:47], 0, v[130:131]
	ds_read_b128 v[182:185], v148 offset:32768
	ds_read_b128 v[186:189], v148 offset:33792
	ds_read_b128 v[190:193], v148 offset:34816
	ds_read_b128 v[194:197], v148 offset:35840
	ds_read_b128 v[198:201], v148 offset:36864
	ds_read_b128 v[206:209], v148 offset:37888
	ds_read_b128 v[210:213], v148 offset:38912
	ds_read_b128 v[214:217], v148 offset:39936
	global_load_lds_dwordx4 v[224:225], off
	s_mov_b32 m0, s19
	v_lshl_add_u64 v[224:225], s[46:47], 0, v[132:133]
	global_load_lds_dwordx4 v[224:225], off
	s_waitcnt vmcnt(8) lgkmcnt(0)
	s_setprio 1
	s_barrier
	v_mfma_f32_16x16x32_bf16 v[126:129], v[150:153], v[182:185], v[126:129]
	v_mfma_f32_16x16x32_bf16 v[122:125], v[158:161], v[182:185], v[122:125]
	v_mfma_f32_16x16x32_bf16 v[118:121], v[150:153], v[190:193], v[118:121]
	v_mfma_f32_16x16x32_bf16 v[114:117], v[158:161], v[190:193], v[114:117]
	v_mfma_f32_16x16x32_bf16 v[102:105], v[150:153], v[198:201], v[102:105]
	v_mfma_f32_16x16x32_bf16 v[98:101], v[158:161], v[198:201], v[98:101]
	v_mfma_f32_16x16x32_bf16 v[86:89], v[150:153], v[210:213], v[86:89]
	v_mfma_f32_16x16x32_bf16 v[82:85], v[158:161], v[210:213], v[82:85]
	v_mfma_f32_16x16x32_bf16 v[126:129], v[154:157], v[186:189], v[126:129]
	v_mfma_f32_16x16x32_bf16 v[122:125], v[162:165], v[186:189], v[122:125]
	v_mfma_f32_16x16x32_bf16 v[118:121], v[154:157], v[194:197], v[118:121]
	v_mfma_f32_16x16x32_bf16 v[114:117], v[162:165], v[194:197], v[114:117]
	v_mfma_f32_16x16x32_bf16 v[102:105], v[154:157], v[206:209], v[102:105]
	v_mfma_f32_16x16x32_bf16 v[98:101], v[162:165], v[206:209], v[98:101]
	v_mfma_f32_16x16x32_bf16 v[86:89], v[154:157], v[214:217], v[86:89]
	v_mfma_f32_16x16x32_bf16 v[82:85], v[162:165], v[214:217], v[82:85]
	v_mfma_f32_16x16x32_bf16 v[110:113], v[166:169], v[182:185], v[110:113]
	v_mfma_f32_16x16x32_bf16 v[106:109], v[174:177], v[182:185], v[106:109]
	v_mfma_f32_16x16x32_bf16 v[94:97], v[166:169], v[190:193], v[94:97]
	v_mfma_f32_16x16x32_bf16 v[90:93], v[174:177], v[190:193], v[90:93]
	v_mfma_f32_16x16x32_bf16 v[78:81], v[166:169], v[198:201], v[78:81]
	v_mfma_f32_16x16x32_bf16 v[74:77], v[174:177], v[198:201], v[74:77]
	v_mfma_f32_16x16x32_bf16 v[70:73], v[166:169], v[210:213], v[70:73]
	v_mfma_f32_16x16x32_bf16 v[66:69], v[174:177], v[210:213], v[66:69]
	v_mfma_f32_16x16x32_bf16 v[110:113], v[170:173], v[186:189], v[110:113]
	v_mfma_f32_16x16x32_bf16 v[106:109], v[178:181], v[186:189], v[106:109]
	v_mfma_f32_16x16x32_bf16 v[94:97], v[170:173], v[194:197], v[94:97]
	v_mfma_f32_16x16x32_bf16 v[90:93], v[178:181], v[194:197], v[90:93]
	v_mfma_f32_16x16x32_bf16 v[78:81], v[170:173], v[206:209], v[78:81]
	v_mfma_f32_16x16x32_bf16 v[74:77], v[178:181], v[206:209], v[74:77]
	v_mfma_f32_16x16x32_bf16 v[70:73], v[170:173], v[214:217], v[70:73]
	v_mfma_f32_16x16x32_bf16 v[66:69], v[178:181], v[214:217], v[66:69]
	s_setprio 0
	s_barrier
	s_mov_b32 m0, s77
	v_lshl_add_u64 v[202:203], v[202:203], 0, s[8:9]
	global_load_lds_dwordx4 v[202:203], off
	ds_read_b128 v[182:185], v148 offset:49152
	ds_read_b128 v[186:189], v148 offset:50176
	ds_read_b128 v[190:193], v148 offset:51200
	ds_read_b128 v[194:197], v148 offset:52224
	ds_read_b128 v[198:201], v148 offset:53248
	ds_read_b128 v[206:209], v148 offset:54272
	ds_read_b128 v[210:213], v148 offset:55296
	ds_read_b128 v[214:217], v148 offset:56320
	s_mov_b32 m0, s75
	v_lshl_add_u64 v[202:203], v[218:219], 0, s[8:9]
	global_load_lds_dwordx4 v[202:203], off
	s_mov_b32 m0, s76
	v_lshl_add_u64 v[202:203], s[44:45], 0, v[136:137]
	global_load_lds_dwordx4 v[202:203], off
	s_mov_b32 m0, s74
	v_lshl_add_u64 v[202:203], s[44:45], 0, v[134:135]
	global_load_lds_dwordx4 v[202:203], off
	s_mov_b32 m0, s28
	v_lshl_add_u64 v[202:203], v[220:221], 0, s[8:9]
	global_load_lds_dwordx4 v[202:203], off
	s_mov_b32 m0, s29
	v_lshl_add_u64 v[202:203], v[222:223], 0, s[8:9]
	global_load_lds_dwordx4 v[202:203], off
	s_waitcnt vmcnt(8) lgkmcnt(0)
	s_setprio 1
	s_barrier
	v_mfma_f32_16x16x32_bf16 v[62:65], v[150:153], v[182:185], v[62:65]
	v_mfma_f32_16x16x32_bf16 v[58:61], v[158:161], v[182:185], v[58:61]
	v_mfma_f32_16x16x32_bf16 v[54:57], v[150:153], v[190:193], v[54:57]
	v_mfma_f32_16x16x32_bf16 v[50:53], v[158:161], v[190:193], v[50:53]
	v_mfma_f32_16x16x32_bf16 v[38:41], v[150:153], v[198:201], v[38:41]
	v_mfma_f32_16x16x32_bf16 v[34:37], v[158:161], v[198:201], v[34:37]
	v_mfma_f32_16x16x32_bf16 v[22:25], v[150:153], v[210:213], v[22:25]
	v_mfma_f32_16x16x32_bf16 v[18:21], v[158:161], v[210:213], v[18:21]
	v_mfma_f32_16x16x32_bf16 v[62:65], v[154:157], v[186:189], v[62:65]
	v_mfma_f32_16x16x32_bf16 v[58:61], v[162:165], v[186:189], v[58:61]
	v_mfma_f32_16x16x32_bf16 v[54:57], v[154:157], v[194:197], v[54:57]
	v_mfma_f32_16x16x32_bf16 v[50:53], v[162:165], v[194:197], v[50:53]
	v_mfma_f32_16x16x32_bf16 v[38:41], v[154:157], v[206:209], v[38:41]
	v_mfma_f32_16x16x32_bf16 v[34:37], v[162:165], v[206:209], v[34:37]
	v_mfma_f32_16x16x32_bf16 v[22:25], v[154:157], v[214:217], v[22:25]
	v_mfma_f32_16x16x32_bf16 v[18:21], v[162:165], v[214:217], v[18:21]
	v_mfma_f32_16x16x32_bf16 v[46:49], v[166:169], v[182:185], v[46:49]
	v_mfma_f32_16x16x32_bf16 v[42:45], v[174:177], v[182:185], v[42:45]
	v_mfma_f32_16x16x32_bf16 v[30:33], v[166:169], v[190:193], v[30:33]
	v_mfma_f32_16x16x32_bf16 v[26:29], v[174:177], v[190:193], v[26:29]
	v_mfma_f32_16x16x32_bf16 v[14:17], v[166:169], v[198:201], v[14:17]
	v_mfma_f32_16x16x32_bf16 v[10:13], v[174:177], v[198:201], v[10:13]
	v_mfma_f32_16x16x32_bf16 v[6:9], v[166:169], v[210:213], v[6:9]
	v_mfma_f32_16x16x32_bf16 v[2:5], v[174:177], v[210:213], v[2:5]
	v_mfma_f32_16x16x32_bf16 v[46:49], v[170:173], v[186:189], v[46:49]
	v_mfma_f32_16x16x32_bf16 v[42:45], v[178:181], v[186:189], v[42:45]
	v_mfma_f32_16x16x32_bf16 v[30:33], v[170:173], v[194:197], v[30:33]
	v_mfma_f32_16x16x32_bf16 v[26:29], v[178:181], v[194:197], v[26:29]
	v_mfma_f32_16x16x32_bf16 v[14:17], v[170:173], v[206:209], v[14:17]
	v_mfma_f32_16x16x32_bf16 v[10:13], v[178:181], v[206:209], v[10:13]
	v_mfma_f32_16x16x32_bf16 v[6:9], v[170:173], v[214:217], v[6:9]
	v_mfma_f32_16x16x32_bf16 v[2:5], v[178:181], v[214:217], v[2:5]
	s_setprio 0
	s_barrier
	s_movk_i32 s46, 0x100
	s_andn2_b64 vcc, exec, s[42:43]
	s_mov_b64 s[44:45], -1
	s_mov_b64 s[42:43], 0
	s_cbranch_vccz .LBB0_297
	s_and_b64 vcc, exec, s[10:11]
	s_cbranch_vccz .LBB0_300
	s_barrier

.LBB0_313:
	s_add_u32 s49, s38, s48
	s_addc_u32 s68, s39, 0
	s_add_u32 s66, s49, 0x100
	s_addc_u32 s67, s68, 0
	s_and_b64 s[64:65], s[46:47], exec
	s_cselect_b32 s65, s43, s67
	s_cselect_b32 s64, s75, s66
	s_add_u32 s48, s36, s48
	s_addc_u32 s66, s37, 0
	s_add_u32 s48, s48, 0x100
	s_addc_u32 s66, s66, 0
	s_and_b64 s[46:47], s[46:47], exec
	s_cselect_b32 s67, s76, s66
	s_cselect_b32 s66, s77, s48
	s_add_u32 s70, s49, 0x10080
	ds_read_b128 v[144:147], v140
	ds_read_b128 v[148:151], v140 offset:1024
	ds_read_b128 v[152:155], v140 offset:2048
	ds_read_b128 v[156:159], v140 offset:3072
	ds_read_b128 v[160:163], v141
	ds_read_b128 v[164:167], v141 offset:1024
	ds_read_b128 v[168:171], v141 offset:2048
	ds_read_b128 v[172:175], v141 offset:3072
	s_addc_u32 s71, s68, 0
	s_add_i32 s87, s33, s2
	s_add_i32 m0, s16, 0xc000
	s_add_i32 s88, s16, 0xe000
	s_add_i32 s84, s87, 0x2000
	s_add_u32 s68, s66, 0x1000
	s_addc_u32 s69, s67, 0
	s_add_i32 s86, s34, s2
	s_add_i32 s85, s86, 0x2000
	s_add_i32 s83, 0, 0x18000
	s_add_i32 s82, 0, 0x1c000
	s_add_u32 s48, s64, 0x10000
	s_addc_u32 s49, s65, 0
	s_add_i32 s81, s83, s2
	s_add_i32 s79, s81, 0x2000
	s_add_u32 s46, s66, 0x1080
	s_addc_u32 s47, s67, 0
	s_add_i32 s80, s82, s2
	s_add_i32 s78, s80, 0x2000
	v_lshl_add_u64 v[210:211], s[70:71], 0, v[130:131]
	ds_read_b128 v[176:179], v142
	ds_read_b128 v[180:183], v142 offset:1024
	ds_read_b128 v[184:187], v142 offset:2048
	ds_read_b128 v[188:191], v142 offset:3072
	ds_read_b128 v[192:195], v142 offset:4096
	ds_read_b128 v[196:199], v142 offset:5120
	ds_read_b128 v[200:203], v142 offset:6144
	ds_read_b128 v[206:209], v142 offset:7168
	global_load_lds_dwordx4 v[210:211], off
	s_mov_b32 m0, s88
	v_lshl_add_u64 v[210:211], s[70:71], 0, v[132:133]
	global_load_lds_dwordx4 v[210:211], off
	s_waitcnt vmcnt(8) lgkmcnt(0)
	s_setprio 1
	s_barrier
	v_mfma_f32_16x16x32_bf16 v[126:129], v[144:147], v[176:179], v[126:129]
	v_mfma_f32_16x16x32_bf16 v[122:125], v[152:155], v[176:179], v[122:125]
	v_mfma_f32_16x16x32_bf16 v[118:121], v[144:147], v[184:187], v[118:121]
	v_mfma_f32_16x16x32_bf16 v[114:117], v[152:155], v[184:187], v[114:117]
	v_mfma_f32_16x16x32_bf16 v[102:105], v[144:147], v[192:195], v[102:105]
	v_mfma_f32_16x16x32_bf16 v[98:101], v[152:155], v[192:195], v[98:101]
	v_mfma_f32_16x16x32_bf16 v[86:89], v[144:147], v[200:203], v[86:89]
	v_mfma_f32_16x16x32_bf16 v[82:85], v[152:155], v[200:203], v[82:85]
	v_mfma_f32_16x16x32_bf16 v[126:129], v[148:151], v[180:183], v[126:129]
	v_mfma_f32_16x16x32_bf16 v[122:125], v[156:159], v[180:183], v[122:125]
	v_mfma_f32_16x16x32_bf16 v[118:121], v[148:151], v[188:191], v[118:121]
	v_mfma_f32_16x16x32_bf16 v[114:117], v[156:159], v[188:191], v[114:117]
	v_mfma_f32_16x16x32_bf16 v[102:105], v[148:151], v[196:199], v[102:105]
	v_mfma_f32_16x16x32_bf16 v[98:101], v[156:159], v[196:199], v[98:101]
	v_mfma_f32_16x16x32_bf16 v[86:89], v[148:151], v[206:209], v[86:89]
	v_mfma_f32_16x16x32_bf16 v[82:85], v[156:159], v[206:209], v[82:85]
	v_mfma_f32_16x16x32_bf16 v[110:113], v[160:163], v[176:179], v[110:113]
	v_mfma_f32_16x16x32_bf16 v[106:109], v[168:171], v[176:179], v[106:109]
	v_mfma_f32_16x16x32_bf16 v[94:97], v[160:163], v[184:187], v[94:97]
	v_mfma_f32_16x16x32_bf16 v[90:93], v[168:171], v[184:187], v[90:93]
	v_mfma_f32_16x16x32_bf16 v[78:81], v[160:163], v[192:195], v[78:81]
	v_mfma_f32_16x16x32_bf16 v[74:77], v[168:171], v[192:195], v[74:77]
	v_mfma_f32_16x16x32_bf16 v[70:73], v[160:163], v[200:203], v[70:73]
	v_mfma_f32_16x16x32_bf16 v[66:69], v[168:171], v[200:203], v[66:69]
	v_mfma_f32_16x16x32_bf16 v[110:113], v[164:167], v[180:183], v[110:113]
	v_mfma_f32_16x16x32_bf16 v[106:109], v[172:175], v[180:183], v[106:109]
	v_mfma_f32_16x16x32_bf16 v[94:97], v[164:167], v[188:191], v[94:97]
	v_mfma_f32_16x16x32_bf16 v[90:93], v[172:175], v[188:191], v[90:93]
	v_mfma_f32_16x16x32_bf16 v[78:81], v[164:167], v[196:199], v[78:81]
	v_mfma_f32_16x16x32_bf16 v[74:77], v[172:175], v[196:199], v[74:77]
	v_mfma_f32_16x16x32_bf16 v[70:73], v[164:167], v[206:209], v[70:73]
	v_mfma_f32_16x16x32_bf16 v[66:69], v[172:175], v[206:209], v[66:69]
	s_setprio 0
	s_barrier
	s_mov_b32 m0, s87
	v_lshl_add_u64 v[210:211], s[66:67], 0, v[136:137]
	global_load_lds_dwordx4 v[210:211], off
	ds_read_b128 v[176:179], v142 offset:16384
	ds_read_b128 v[180:183], v142 offset:17408
	ds_read_b128 v[184:187], v142 offset:18432
	ds_read_b128 v[188:191], v142 offset:19456
	ds_read_b128 v[192:195], v142 offset:20480
	ds_read_b128 v[196:199], v142 offset:21504
	ds_read_b128 v[200:203], v142 offset:22528
	ds_read_b128 v[206:209], v142 offset:23552
	v_lshl_add_u64 v[212:213], s[66:67], 0, v[134:135]
	s_mov_b32 m0, s84
	v_lshl_add_u64 v[214:215], s[68:69], 0, v[136:137]
	global_load_lds_dwordx4 v[212:213], off
	s_mov_b32 m0, s86
	v_lshl_add_u64 v[216:217], s[64:65], 0, v[132:133]
	global_load_lds_dwordx4 v[214:215], off
	s_mov_b32 m0, s85
	v_lshl_add_u64 v[214:215], s[68:69], 0, v[134:135]
	global_load_lds_dwordx4 v[214:215], off
	s_mov_b32 m0, s16
	v_lshl_add_u64 v[214:215], s[64:65], 0, v[130:131]
	global_load_lds_dwordx4 v[214:215], off
	s_mov_b32 m0, s17
	s_nop 0
	global_load_lds_dwordx4 v[216:217], off
	s_waitcnt vmcnt(8) lgkmcnt(0)
	s_setprio 1
	s_barrier
	v_mfma_f32_16x16x32_bf16 v[62:65], v[144:147], v[176:179], v[62:65]
	v_mfma_f32_16x16x32_bf16 v[58:61], v[152:155], v[176:179], v[58:61]
	v_mfma_f32_16x16x32_bf16 v[54:57], v[144:147], v[184:187], v[54:57]
	v_mfma_f32_16x16x32_bf16 v[50:53], v[152:155], v[184:187], v[50:53]
	v_mfma_f32_16x16x32_bf16 v[38:41], v[144:147], v[192:195], v[38:41]
	v_mfma_f32_16x16x32_bf16 v[34:37], v[152:155], v[192:195], v[34:37]
	v_mfma_f32_16x16x32_bf16 v[22:25], v[144:147], v[200:203], v[22:25]
	v_mfma_f32_16x16x32_bf16 v[18:21], v[152:155], v[200:203], v[18:21]
	v_mfma_f32_16x16x32_bf16 v[62:65], v[148:151], v[180:183], v[62:65]
	v_mfma_f32_16x16x32_bf16 v[58:61], v[156:159], v[180:183], v[58:61]
	v_mfma_f32_16x16x32_bf16 v[54:57], v[148:151], v[188:191], v[54:57]
	v_mfma_f32_16x16x32_bf16 v[50:53], v[156:159], v[188:191], v[50:53]
	v_mfma_f32_16x16x32_bf16 v[38:41], v[148:151], v[196:199], v[38:41]
	v_mfma_f32_16x16x32_bf16 v[34:37], v[156:159], v[196:199], v[34:37]
	v_mfma_f32_16x16x32_bf16 v[22:25], v[148:151], v[206:209], v[22:25]
	v_mfma_f32_16x16x32_bf16 v[18:21], v[156:159], v[206:209], v[18:21]
	v_mfma_f32_16x16x32_bf16 v[46:49], v[160:163], v[176:179], v[46:49]
	v_mfma_f32_16x16x32_bf16 v[42:45], v[168:171], v[176:179], v[42:45]
	v_mfma_f32_16x16x32_bf16 v[30:33], v[160:163], v[184:187], v[30:33]
	v_mfma_f32_16x16x32_bf16 v[26:29], v[168:171], v[184:187], v[26:29]
	v_mfma_f32_16x16x32_bf16 v[14:17], v[160:163], v[192:195], v[14:17]
	v_mfma_f32_16x16x32_bf16 v[10:13], v[168:171], v[192:195], v[10:13]
	v_mfma_f32_16x16x32_bf16 v[6:9], v[160:163], v[200:203], v[6:9]
	v_mfma_f32_16x16x32_bf16 v[2:5], v[168:171], v[200:203], v[2:5]
	v_mfma_f32_16x16x32_bf16 v[46:49], v[164:167], v[180:183], v[46:49]
	v_mfma_f32_16x16x32_bf16 v[42:45], v[172:175], v[180:183], v[42:45]
	v_mfma_f32_16x16x32_bf16 v[30:33], v[164:167], v[188:191], v[30:33]
	v_mfma_f32_16x16x32_bf16 v[26:29], v[172:175], v[188:191], v[26:29]
	v_mfma_f32_16x16x32_bf16 v[14:17], v[164:167], v[196:199], v[14:17]
	v_mfma_f32_16x16x32_bf16 v[10:13], v[172:175], v[196:199], v[10:13]
	v_mfma_f32_16x16x32_bf16 v[6:9], v[164:167], v[206:209], v[6:9]
	v_mfma_f32_16x16x32_bf16 v[2:5], v[172:175], v[206:209], v[2:5]
	s_setprio 0
	s_barrier
	v_add_u32_e32 v143, s83, v139
	ds_read_b128 v[144:147], v143
	ds_read_b128 v[148:151], v143 offset:1024
	ds_read_b128 v[152:155], v143 offset:2048
	ds_read_b128 v[156:159], v143 offset:3072
	v_add_u32_e32 v143, s82, v139
	ds_read_b128 v[160:163], v143
	ds_read_b128 v[164:167], v143 offset:1024
	ds_read_b128 v[168:171], v143 offset:2048
	ds_read_b128 v[172:175], v143 offset:3072
	s_mov_b32 m0, s18
	v_lshl_add_u64 v[218:219], s[48:49], 0, v[130:131]
	ds_read_b128 v[176:179], v142 offset:32768
	ds_read_b128 v[180:183], v142 offset:33792
	ds_read_b128 v[184:187], v142 offset:34816
	ds_read_b128 v[188:191], v142 offset:35840
	ds_read_b128 v[192:195], v142 offset:36864
	ds_read_b128 v[196:199], v142 offset:37888
	ds_read_b128 v[200:203], v142 offset:38912
	ds_read_b128 v[206:209], v142 offset:39936
	global_load_lds_dwordx4 v[218:219], off
	s_mov_b32 m0, s19
	v_lshl_add_u64 v[218:219], s[48:49], 0, v[132:133]
	global_load_lds_dwordx4 v[218:219], off
	s_waitcnt vmcnt(8) lgkmcnt(0)
	s_setprio 1
	s_barrier
	v_mfma_f32_16x16x32_bf16 v[126:129], v[144:147], v[176:179], v[126:129]
	v_mfma_f32_16x16x32_bf16 v[122:125], v[152:155], v[176:179], v[122:125]
	v_mfma_f32_16x16x32_bf16 v[118:121], v[144:147], v[184:187], v[118:121]
	v_mfma_f32_16x16x32_bf16 v[114:117], v[152:155], v[184:187], v[114:117]
	v_mfma_f32_16x16x32_bf16 v[102:105], v[144:147], v[192:195], v[102:105]
	v_mfma_f32_16x16x32_bf16 v[98:101], v[152:155], v[192:195], v[98:101]
	v_mfma_f32_16x16x32_bf16 v[86:89], v[144:147], v[200:203], v[86:89]
	v_mfma_f32_16x16x32_bf16 v[82:85], v[152:155], v[200:203], v[82:85]
	v_mfma_f32_16x16x32_bf16 v[126:129], v[148:151], v[180:183], v[126:129]
	v_mfma_f32_16x16x32_bf16 v[122:125], v[156:159], v[180:183], v[122:125]
	v_mfma_f32_16x16x32_bf16 v[118:121], v[148:151], v[188:191], v[118:121]
	v_mfma_f32_16x16x32_bf16 v[114:117], v[156:159], v[188:191], v[114:117]
	v_mfma_f32_16x16x32_bf16 v[102:105], v[148:151], v[196:199], v[102:105]
	v_mfma_f32_16x16x32_bf16 v[98:101], v[156:159], v[196:199], v[98:101]
	v_mfma_f32_16x16x32_bf16 v[86:89], v[148:151], v[206:209], v[86:89]
	v_mfma_f32_16x16x32_bf16 v[82:85], v[156:159], v[206:209], v[82:85]
	v_mfma_f32_16x16x32_bf16 v[110:113], v[160:163], v[176:179], v[110:113]
	v_mfma_f32_16x16x32_bf16 v[106:109], v[168:171], v[176:179], v[106:109]
	v_mfma_f32_16x16x32_bf16 v[94:97], v[160:163], v[184:187], v[94:97]
	v_mfma_f32_16x16x32_bf16 v[90:93], v[168:171], v[184:187], v[90:93]
	v_mfma_f32_16x16x32_bf16 v[78:81], v[160:163], v[192:195], v[78:81]
	v_mfma_f32_16x16x32_bf16 v[74:77], v[168:171], v[192:195], v[74:77]
	v_mfma_f32_16x16x32_bf16 v[70:73], v[160:163], v[200:203], v[70:73]
	v_mfma_f32_16x16x32_bf16 v[66:69], v[168:171], v[200:203], v[66:69]
	v_mfma_f32_16x16x32_bf16 v[110:113], v[164:167], v[180:183], v[110:113]
	v_mfma_f32_16x16x32_bf16 v[106:109], v[172:175], v[180:183], v[106:109]
	v_mfma_f32_16x16x32_bf16 v[94:97], v[164:167], v[188:191], v[94:97]
	v_mfma_f32_16x16x32_bf16 v[90:93], v[172:175], v[188:191], v[90:93]
	v_mfma_f32_16x16x32_bf16 v[78:81], v[164:167], v[196:199], v[78:81]
	v_mfma_f32_16x16x32_bf16 v[74:77], v[172:175], v[196:199], v[74:77]
	v_mfma_f32_16x16x32_bf16 v[70:73], v[164:167], v[206:209], v[70:73]
	v_mfma_f32_16x16x32_bf16 v[66:69], v[172:175], v[206:209], v[66:69]
	s_setprio 0
	s_barrier
	s_mov_b32 m0, s81
	v_lshl_add_u64 v[210:211], v[210:211], 0, s[8:9]
	global_load_lds_dwordx4 v[210:211], off
	ds_read_b128 v[176:179], v142 offset:49152
	ds_read_b128 v[180:183], v142 offset:50176
	ds_read_b128 v[184:187], v142 offset:51200
	ds_read_b128 v[188:191], v142 offset:52224
	ds_read_b128 v[192:195], v142 offset:53248
	ds_read_b128 v[196:199], v142 offset:54272
	ds_read_b128 v[200:203], v142 offset:55296
	ds_read_b128 v[206:209], v142 offset:56320
	s_mov_b32 m0, s79
	v_lshl_add_u64 v[210:211], v[212:213], 0, s[8:9]
	global_load_lds_dwordx4 v[210:211], off
	s_mov_b32 m0, s80
	v_lshl_add_u64 v[210:211], s[46:47], 0, v[136:137]
	global_load_lds_dwordx4 v[210:211], off
	s_mov_b32 m0, s78
	v_lshl_add_u64 v[210:211], s[46:47], 0, v[134:135]
	global_load_lds_dwordx4 v[210:211], off
	s_mov_b32 m0, s30
	v_lshl_add_u64 v[210:211], v[214:215], 0, s[8:9]
	global_load_lds_dwordx4 v[210:211], off
	s_mov_b32 m0, s31
	v_lshl_add_u64 v[210:211], v[216:217], 0, s[8:9]
	global_load_lds_dwordx4 v[210:211], off
	s_waitcnt vmcnt(8) lgkmcnt(0)
	s_setprio 1
	s_barrier
	v_mfma_f32_16x16x32_bf16 v[62:65], v[144:147], v[176:179], v[62:65]
	v_mfma_f32_16x16x32_bf16 v[58:61], v[152:155], v[176:179], v[58:61]
	v_mfma_f32_16x16x32_bf16 v[54:57], v[144:147], v[184:187], v[54:57]
	v_mfma_f32_16x16x32_bf16 v[50:53], v[152:155], v[184:187], v[50:53]
	v_mfma_f32_16x16x32_bf16 v[38:41], v[144:147], v[192:195], v[38:41]
	v_mfma_f32_16x16x32_bf16 v[34:37], v[152:155], v[192:195], v[34:37]
	v_mfma_f32_16x16x32_bf16 v[22:25], v[144:147], v[200:203], v[22:25]
	v_mfma_f32_16x16x32_bf16 v[18:21], v[152:155], v[200:203], v[18:21]
	v_mfma_f32_16x16x32_bf16 v[62:65], v[148:151], v[180:183], v[62:65]
	v_mfma_f32_16x16x32_bf16 v[58:61], v[156:159], v[180:183], v[58:61]
	v_mfma_f32_16x16x32_bf16 v[54:57], v[148:151], v[188:191], v[54:57]
	v_mfma_f32_16x16x32_bf16 v[50:53], v[156:159], v[188:191], v[50:53]
	v_mfma_f32_16x16x32_bf16 v[38:41], v[148:151], v[196:199], v[38:41]
	v_mfma_f32_16x16x32_bf16 v[34:37], v[156:159], v[196:199], v[34:37]
	v_mfma_f32_16x16x32_bf16 v[22:25], v[148:151], v[206:209], v[22:25]
	v_mfma_f32_16x16x32_bf16 v[18:21], v[156:159], v[206:209], v[18:21]
	v_mfma_f32_16x16x32_bf16 v[46:49], v[160:163], v[176:179], v[46:49]
	v_mfma_f32_16x16x32_bf16 v[42:45], v[168:171], v[176:179], v[42:45]
	v_mfma_f32_16x16x32_bf16 v[30:33], v[160:163], v[184:187], v[30:33]
	v_mfma_f32_16x16x32_bf16 v[26:29], v[168:171], v[184:187], v[26:29]
	v_mfma_f32_16x16x32_bf16 v[14:17], v[160:163], v[192:195], v[14:17]
	v_mfma_f32_16x16x32_bf16 v[10:13], v[168:171], v[192:195], v[10:13]
	v_mfma_f32_16x16x32_bf16 v[6:9], v[160:163], v[200:203], v[6:9]
	v_mfma_f32_16x16x32_bf16 v[2:5], v[168:171], v[200:203], v[2:5]
	v_mfma_f32_16x16x32_bf16 v[46:49], v[164:167], v[180:183], v[46:49]
	v_mfma_f32_16x16x32_bf16 v[42:45], v[172:175], v[180:183], v[42:45]
	v_mfma_f32_16x16x32_bf16 v[30:33], v[164:167], v[188:191], v[30:33]
	v_mfma_f32_16x16x32_bf16 v[26:29], v[172:175], v[188:191], v[26:29]
	v_mfma_f32_16x16x32_bf16 v[14:17], v[164:167], v[196:199], v[14:17]
	v_mfma_f32_16x16x32_bf16 v[10:13], v[172:175], v[196:199], v[10:13]
	v_mfma_f32_16x16x32_bf16 v[6:9], v[164:167], v[206:209], v[6:9]
	v_mfma_f32_16x16x32_bf16 v[2:5], v[172:175], v[206:209], v[2:5]
	s_setprio 0
	s_barrier
	s_movk_i32 s48, 0x100
	s_andn2_b64 vcc, exec, s[44:45]
	s_mov_b64 s[46:47], -1
	s_mov_b64 s[44:45], 0
	s_cbranch_vccz .LBB0_313
	s_and_b64 vcc, exec, s[10:11]
	s_cbranch_vccz .LBB0_316
	s_barrier

.LBB0_383:
	s_add_u32 s26, s0, s22
	s_addc_u32 s27, s1, s23
	s_and_b64 s[44:45], s[36:37], exec
	s_cselect_b32 s15, s27, s43
	s_cselect_b32 s39, s26, s42
	s_add_u32 s66, s42, 0x100
	s_addc_u32 s67, s43, 0
	s_mov_b32 s68, -2
	s_mov_b64 s[42:43], 0
	ds_read_b128 v[152:155], v146
	ds_read_b128 v[156:159], v146 offset:1024
	ds_read_b128 v[160:163], v146 offset:2048
	ds_read_b128 v[164:167], v146 offset:3072
	ds_read_b128 v[168:171], v147
	ds_read_b128 v[172:175], v147 offset:1024
	ds_read_b128 v[176:179], v147 offset:2048
	ds_read_b128 v[180:183], v147 offset:3072
	s_add_u32 s44, s42, 0x100
	s_addc_u32 s45, s43, 0
	s_add_u32 s46, s66, s42
	s_addc_u32 s47, s67, s43
	s_cmp_eq_u32 s68, 4
	s_cselect_b32 s48, 0, s44
	s_cselect_b32 s49, 0, s45
	s_cselect_b32 s46, s39, s46
	s_cselect_b32 s47, s15, s47
	s_add_u32 s48, s6, s48
	s_addc_u32 s49, s7, s49
	s_mov_b32 m0, s29
	v_lshl_add_u64 v[218:219], v[138:139], 0, s[42:43]
	ds_read_b128 v[184:187], v148
	ds_read_b128 v[188:191], v148 offset:1024
	ds_read_b128 v[192:195], v148 offset:2048
	ds_read_b128 v[196:199], v148 offset:3072
	ds_read_b128 v[200:203], v148 offset:4096
	ds_read_b128 v[206:209], v148 offset:5120
	ds_read_b128 v[210:213], v148 offset:6144
	ds_read_b128 v[214:217], v148 offset:7168
	global_load_lds_dwordx4 v[218:219], off
	s_mov_b32 m0, s30
	v_lshl_add_u64 v[218:219], v[140:141], 0, s[42:43]
	global_load_lds_dwordx4 v[218:219], off
	s_waitcnt vmcnt(8) lgkmcnt(0)
	s_setprio 1
	s_barrier
	v_mfma_f32_16x16x32_bf16 v[126:129], v[152:155], v[184:187], 0
	v_mfma_f32_16x16x32_bf16 v[122:125], v[160:163], v[184:187], 0
	v_mfma_f32_16x16x32_bf16 v[118:121], v[152:155], v[192:195], 0
	v_mfma_f32_16x16x32_bf16 v[114:117], v[160:163], v[192:195], 0
	v_mfma_f32_16x16x32_bf16 v[102:105], v[152:155], v[200:203], 0
	v_mfma_f32_16x16x32_bf16 v[98:101], v[160:163], v[200:203], 0
	v_mfma_f32_16x16x32_bf16 v[86:89], v[152:155], v[210:213], 0
	v_mfma_f32_16x16x32_bf16 v[82:85], v[160:163], v[210:213], 0
	v_mfma_f32_16x16x32_bf16 v[126:129], v[156:159], v[188:191], v[126:129]
	v_mfma_f32_16x16x32_bf16 v[122:125], v[164:167], v[188:191], v[122:125]
	v_mfma_f32_16x16x32_bf16 v[118:121], v[156:159], v[196:199], v[118:121]
	v_mfma_f32_16x16x32_bf16 v[114:117], v[164:167], v[196:199], v[114:117]
	v_mfma_f32_16x16x32_bf16 v[102:105], v[156:159], v[206:209], v[102:105]
	v_mfma_f32_16x16x32_bf16 v[98:101], v[164:167], v[206:209], v[98:101]
	v_mfma_f32_16x16x32_bf16 v[86:89], v[156:159], v[214:217], v[86:89]
	v_mfma_f32_16x16x32_bf16 v[82:85], v[164:167], v[214:217], v[82:85]
	v_mfma_f32_16x16x32_bf16 v[110:113], v[168:171], v[184:187], 0
	v_mfma_f32_16x16x32_bf16 v[106:109], v[176:179], v[184:187], 0
	v_mfma_f32_16x16x32_bf16 v[94:97], v[168:171], v[192:195], 0
	v_mfma_f32_16x16x32_bf16 v[90:93], v[176:179], v[192:195], 0
	v_mfma_f32_16x16x32_bf16 v[78:81], v[168:171], v[200:203], 0
	v_mfma_f32_16x16x32_bf16 v[74:77], v[176:179], v[200:203], 0
	v_mfma_f32_16x16x32_bf16 v[70:73], v[168:171], v[210:213], 0
	v_mfma_f32_16x16x32_bf16 v[66:69], v[176:179], v[210:213], 0
	v_mfma_f32_16x16x32_bf16 v[110:113], v[172:175], v[188:191], v[110:113]
	v_mfma_f32_16x16x32_bf16 v[106:109], v[180:183], v[188:191], v[106:109]
	v_mfma_f32_16x16x32_bf16 v[94:97], v[172:175], v[196:199], v[94:97]
	v_mfma_f32_16x16x32_bf16 v[90:93], v[180:183], v[196:199], v[90:93]
	v_mfma_f32_16x16x32_bf16 v[78:81], v[172:175], v[206:209], v[78:81]
	v_mfma_f32_16x16x32_bf16 v[74:77], v[180:183], v[206:209], v[74:77]
	v_mfma_f32_16x16x32_bf16 v[70:73], v[172:175], v[214:217], v[70:73]
	v_mfma_f32_16x16x32_bf16 v[66:69], v[180:183], v[214:217], v[66:69]
	s_setprio 0
	s_barrier
	s_mov_b32 m0, s31
	v_lshl_add_u64 v[218:219], s[46:47], 0, v[134:135]
	s_add_u32 s42, s46, 0x20000
	global_load_lds_dwordx4 v[218:219], off
	ds_read_b128 v[184:187], v148 offset:16384
	ds_read_b128 v[188:191], v148 offset:17408
	ds_read_b128 v[192:195], v148 offset:18432
	ds_read_b128 v[196:199], v148 offset:19456
	ds_read_b128 v[200:203], v148 offset:20480
	ds_read_b128 v[206:209], v148 offset:21504
	ds_read_b128 v[210:213], v148 offset:22528
	ds_read_b128 v[214:217], v148 offset:23552
	v_lshl_add_u64 v[220:221], s[46:47], 0, v[130:131]
	s_mov_b32 m0, s33
	s_addc_u32 s43, s47, 0
	global_load_lds_dwordx4 v[220:221], off
	v_lshl_add_u64 v[222:223], s[42:43], 0, v[134:135]
	s_mov_b32 m0, s34
	v_lshl_add_u64 v[224:225], s[48:49], 0, v[132:133]
	global_load_lds_dwordx4 v[222:223], off
	s_mov_b32 m0, s35
	v_lshl_add_u64 v[222:223], s[42:43], 0, v[130:131]
	global_load_lds_dwordx4 v[222:223], off
	s_mov_b32 m0, s2
	v_lshl_add_u64 v[222:223], s[48:49], 0, v[136:137]
	global_load_lds_dwordx4 v[222:223], off
	s_mov_b32 m0, s3
	s_nop 0
	global_load_lds_dwordx4 v[224:225], off
	s_waitcnt vmcnt(8) lgkmcnt(0)
	s_setprio 1
	s_barrier
	v_mfma_f32_16x16x32_bf16 v[62:65], v[152:155], v[184:187], 0
	v_mfma_f32_16x16x32_bf16 v[58:61], v[160:163], v[184:187], 0
	v_mfma_f32_16x16x32_bf16 v[54:57], v[152:155], v[192:195], 0
	v_mfma_f32_16x16x32_bf16 v[50:53], v[160:163], v[192:195], 0
	v_mfma_f32_16x16x32_bf16 v[38:41], v[152:155], v[200:203], 0
	v_mfma_f32_16x16x32_bf16 v[34:37], v[160:163], v[200:203], 0
	v_mfma_f32_16x16x32_bf16 v[22:25], v[152:155], v[210:213], 0
	v_mfma_f32_16x16x32_bf16 v[18:21], v[160:163], v[210:213], 0
	v_mfma_f32_16x16x32_bf16 v[62:65], v[156:159], v[188:191], v[62:65]
	v_mfma_f32_16x16x32_bf16 v[58:61], v[164:167], v[188:191], v[58:61]
	v_mfma_f32_16x16x32_bf16 v[54:57], v[156:159], v[196:199], v[54:57]
	v_mfma_f32_16x16x32_bf16 v[50:53], v[164:167], v[196:199], v[50:53]
	v_mfma_f32_16x16x32_bf16 v[38:41], v[156:159], v[206:209], v[38:41]
	v_mfma_f32_16x16x32_bf16 v[34:37], v[164:167], v[206:209], v[34:37]
	v_mfma_f32_16x16x32_bf16 v[22:25], v[156:159], v[214:217], v[22:25]
	v_mfma_f32_16x16x32_bf16 v[18:21], v[164:167], v[214:217], v[18:21]
	v_mfma_f32_16x16x32_bf16 v[46:49], v[168:171], v[184:187], 0
	v_mfma_f32_16x16x32_bf16 v[42:45], v[176:179], v[184:187], 0
	v_mfma_f32_16x16x32_bf16 v[30:33], v[168:171], v[192:195], 0
	v_mfma_f32_16x16x32_bf16 v[26:29], v[176:179], v[192:195], 0
	v_mfma_f32_16x16x32_bf16 v[14:17], v[168:171], v[200:203], 0
	v_mfma_f32_16x16x32_bf16 v[10:13], v[176:179], v[200:203], 0
	v_mfma_f32_16x16x32_bf16 v[6:9], v[168:171], v[210:213], 0
	v_mfma_f32_16x16x32_bf16 v[2:5], v[176:179], v[210:213], 0
	v_mfma_f32_16x16x32_bf16 v[46:49], v[172:175], v[188:191], v[46:49]
	v_mfma_f32_16x16x32_bf16 v[42:45], v[180:183], v[188:191], v[42:45]
	v_mfma_f32_16x16x32_bf16 v[30:33], v[172:175], v[196:199], v[30:33]
	v_mfma_f32_16x16x32_bf16 v[26:29], v[180:183], v[196:199], v[26:29]
	v_mfma_f32_16x16x32_bf16 v[14:17], v[172:175], v[206:209], v[14:17]
	v_mfma_f32_16x16x32_bf16 v[10:13], v[180:183], v[206:209], v[10:13]
	v_mfma_f32_16x16x32_bf16 v[6:9], v[172:175], v[214:217], v[6:9]
	v_mfma_f32_16x16x32_bf16 v[2:5], v[180:183], v[214:217], v[2:5]
	s_setprio 0
	s_barrier
	ds_read_b128 v[152:155], v149
	ds_read_b128 v[156:159], v149 offset:1024
	ds_read_b128 v[160:163], v149 offset:2048
	ds_read_b128 v[164:167], v149 offset:3072
	ds_read_b128 v[168:171], v150
	ds_read_b128 v[172:175], v150 offset:1024
	ds_read_b128 v[176:179], v150 offset:2048
	ds_read_b128 v[180:183], v150 offset:3072
	s_add_u32 s42, s48, 0x20000
	s_addc_u32 s43, s49, 0
	s_mov_b32 m0, s16
	v_lshl_add_u64 v[226:227], s[42:43], 0, v[136:137]
	ds_read_b128 v[184:187], v148 offset:32768
	ds_read_b128 v[188:191], v148 offset:33792
	ds_read_b128 v[192:195], v148 offset:34816
	ds_read_b128 v[196:199], v148 offset:35840
	ds_read_b128 v[200:203], v148 offset:36864
	ds_read_b128 v[206:209], v148 offset:37888
	ds_read_b128 v[210:213], v148 offset:38912
	ds_read_b128 v[214:217], v148 offset:39936
	global_load_lds_dwordx4 v[226:227], off
	s_mov_b32 m0, s17
	v_lshl_add_u64 v[226:227], s[42:43], 0, v[132:133]
	global_load_lds_dwordx4 v[226:227], off
	s_waitcnt vmcnt(8) lgkmcnt(0)
	s_setprio 1
	s_barrier
	v_mfma_f32_16x16x32_bf16 v[126:129], v[152:155], v[184:187], v[126:129]
	v_mfma_f32_16x16x32_bf16 v[122:125], v[160:163], v[184:187], v[122:125]
	v_mfma_f32_16x16x32_bf16 v[118:121], v[152:155], v[192:195], v[118:121]
	v_mfma_f32_16x16x32_bf16 v[114:117], v[160:163], v[192:195], v[114:117]
	v_mfma_f32_16x16x32_bf16 v[102:105], v[152:155], v[200:203], v[102:105]
	v_mfma_f32_16x16x32_bf16 v[98:101], v[160:163], v[200:203], v[98:101]
	v_mfma_f32_16x16x32_bf16 v[86:89], v[152:155], v[210:213], v[86:89]
	v_mfma_f32_16x16x32_bf16 v[82:85], v[160:163], v[210:213], v[82:85]
	v_mfma_f32_16x16x32_bf16 v[126:129], v[156:159], v[188:191], v[126:129]
	v_mfma_f32_16x16x32_bf16 v[122:125], v[164:167], v[188:191], v[122:125]
	v_mfma_f32_16x16x32_bf16 v[118:121], v[156:159], v[196:199], v[118:121]
	v_mfma_f32_16x16x32_bf16 v[114:117], v[164:167], v[196:199], v[114:117]
	v_mfma_f32_16x16x32_bf16 v[102:105], v[156:159], v[206:209], v[102:105]
	v_mfma_f32_16x16x32_bf16 v[98:101], v[164:167], v[206:209], v[98:101]
	v_mfma_f32_16x16x32_bf16 v[86:89], v[156:159], v[214:217], v[86:89]
	v_mfma_f32_16x16x32_bf16 v[82:85], v[164:167], v[214:217], v[82:85]
	v_mfma_f32_16x16x32_bf16 v[110:113], v[168:171], v[184:187], v[110:113]
	v_mfma_f32_16x16x32_bf16 v[106:109], v[176:179], v[184:187], v[106:109]
	v_mfma_f32_16x16x32_bf16 v[94:97], v[168:171], v[192:195], v[94:97]
	v_mfma_f32_16x16x32_bf16 v[90:93], v[176:179], v[192:195], v[90:93]
	v_mfma_f32_16x16x32_bf16 v[78:81], v[168:171], v[200:203], v[78:81]
	v_mfma_f32_16x16x32_bf16 v[74:77], v[176:179], v[200:203], v[74:77]
	v_mfma_f32_16x16x32_bf16 v[70:73], v[168:171], v[210:213], v[70:73]
	v_mfma_f32_16x16x32_bf16 v[66:69], v[176:179], v[210:213], v[66:69]
	v_mfma_f32_16x16x32_bf16 v[110:113], v[172:175], v[188:191], v[110:113]
	v_mfma_f32_16x16x32_bf16 v[106:109], v[180:183], v[188:191], v[106:109]
	v_mfma_f32_16x16x32_bf16 v[94:97], v[172:175], v[196:199], v[94:97]
	v_mfma_f32_16x16x32_bf16 v[90:93], v[180:183], v[196:199], v[90:93]
	v_mfma_f32_16x16x32_bf16 v[78:81], v[172:175], v[206:209], v[78:81]
	v_mfma_f32_16x16x32_bf16 v[74:77], v[180:183], v[206:209], v[74:77]
	v_mfma_f32_16x16x32_bf16 v[70:73], v[172:175], v[214:217], v[70:73]
	v_mfma_f32_16x16x32_bf16 v[66:69], v[180:183], v[214:217], v[66:69]
	s_setprio 0
	s_barrier
	s_mov_b32 m0, s62
	v_lshl_add_u64 v[218:219], v[218:219], 0, s[10:11]
	s_add_u32 s42, s46, 0x20080
	global_load_lds_dwordx4 v[218:219], off
	ds_read_b128 v[184:187], v148 offset:49152
	ds_read_b128 v[188:191], v148 offset:50176
	ds_read_b128 v[192:195], v148 offset:51200
	ds_read_b128 v[196:199], v148 offset:52224
	ds_read_b128 v[200:203], v148 offset:53248
	ds_read_b128 v[206:209], v148 offset:54272
	ds_read_b128 v[210:213], v148 offset:55296
	ds_read_b128 v[214:217], v148 offset:56320
	v_lshl_add_u64 v[218:219], v[220:221], 0, s[10:11]
	s_mov_b32 m0, s63
	s_addc_u32 s43, s47, 0
	global_load_lds_dwordx4 v[218:219], off
	s_mov_b32 m0, s64
	v_lshl_add_u64 v[218:219], s[42:43], 0, v[134:135]
	global_load_lds_dwordx4 v[218:219], off
	s_mov_b32 m0, s65
	v_lshl_add_u64 v[218:219], s[42:43], 0, v[130:131]
	global_load_lds_dwordx4 v[218:219], off
	s_mov_b32 m0, s25
	v_lshl_add_u64 v[218:219], v[222:223], 0, s[10:11]
	global_load_lds_dwordx4 v[218:219], off
	s_mov_b32 m0, s28
	v_lshl_add_u64 v[218:219], v[224:225], 0, s[10:11]
	global_load_lds_dwordx4 v[218:219], off
	s_waitcnt vmcnt(8) lgkmcnt(0)
	s_setprio 1
	s_barrier
	v_mfma_f32_16x16x32_bf16 v[62:65], v[152:155], v[184:187], v[62:65]
	v_mfma_f32_16x16x32_bf16 v[58:61], v[160:163], v[184:187], v[58:61]
	v_mfma_f32_16x16x32_bf16 v[54:57], v[152:155], v[192:195], v[54:57]
	v_mfma_f32_16x16x32_bf16 v[50:53], v[160:163], v[192:195], v[50:53]
	v_mfma_f32_16x16x32_bf16 v[38:41], v[152:155], v[200:203], v[38:41]
	v_mfma_f32_16x16x32_bf16 v[34:37], v[160:163], v[200:203], v[34:37]
	v_mfma_f32_16x16x32_bf16 v[22:25], v[152:155], v[210:213], v[22:25]
	v_mfma_f32_16x16x32_bf16 v[18:21], v[160:163], v[210:213], v[18:21]
	v_mfma_f32_16x16x32_bf16 v[62:65], v[156:159], v[188:191], v[62:65]
	v_mfma_f32_16x16x32_bf16 v[58:61], v[164:167], v[188:191], v[58:61]
	v_mfma_f32_16x16x32_bf16 v[54:57], v[156:159], v[196:199], v[54:57]
	v_mfma_f32_16x16x32_bf16 v[50:53], v[164:167], v[196:199], v[50:53]
	v_mfma_f32_16x16x32_bf16 v[38:41], v[156:159], v[206:209], v[38:41]
	v_mfma_f32_16x16x32_bf16 v[34:37], v[164:167], v[206:209], v[34:37]
	v_mfma_f32_16x16x32_bf16 v[22:25], v[156:159], v[214:217], v[22:25]
	v_mfma_f32_16x16x32_bf16 v[18:21], v[164:167], v[214:217], v[18:21]
	v_mfma_f32_16x16x32_bf16 v[46:49], v[168:171], v[184:187], v[46:49]
	v_mfma_f32_16x16x32_bf16 v[42:45], v[176:179], v[184:187], v[42:45]
	v_mfma_f32_16x16x32_bf16 v[30:33], v[168:171], v[192:195], v[30:33]
	v_mfma_f32_16x16x32_bf16 v[26:29], v[176:179], v[192:195], v[26:29]
	v_mfma_f32_16x16x32_bf16 v[14:17], v[168:171], v[200:203], v[14:17]
	v_mfma_f32_16x16x32_bf16 v[10:13], v[176:179], v[200:203], v[10:13]
	v_mfma_f32_16x16x32_bf16 v[6:9], v[168:171], v[210:213], v[6:9]
	v_mfma_f32_16x16x32_bf16 v[2:5], v[176:179], v[210:213], v[2:5]
	v_mfma_f32_16x16x32_bf16 v[46:49], v[172:175], v[188:191], v[46:49]
	v_mfma_f32_16x16x32_bf16 v[42:45], v[180:183], v[188:191], v[42:45]
	v_mfma_f32_16x16x32_bf16 v[30:33], v[172:175], v[196:199], v[30:33]
	v_mfma_f32_16x16x32_bf16 v[26:29], v[180:183], v[196:199], v[26:29]
	v_mfma_f32_16x16x32_bf16 v[14:17], v[172:175], v[206:209], v[14:17]
	v_mfma_f32_16x16x32_bf16 v[10:13], v[180:183], v[206:209], v[10:13]
	v_mfma_f32_16x16x32_bf16 v[6:9], v[172:175], v[214:217], v[6:9]
	v_mfma_f32_16x16x32_bf16 v[2:5], v[180:183], v[214:217], v[2:5]
	s_setprio 0
	s_barrier
	s_add_i32 s68, s68, 2
	s_cmp_gt_u32 s68, 5
	s_mov_b64 s[42:43], s[44:45]
.LBB0_384:
	ds_read_b128 v[152:155], v146
	ds_read_b128 v[156:159], v146 offset:1024
	ds_read_b128 v[160:163], v146 offset:2048
	ds_read_b128 v[164:167], v146 offset:3072
	ds_read_b128 v[168:171], v147
	ds_read_b128 v[172:175], v147 offset:1024
	ds_read_b128 v[176:179], v147 offset:2048
	ds_read_b128 v[180:183], v147 offset:3072
	s_add_u32 s44, s42, 0x100
	s_addc_u32 s45, s43, 0
	s_add_u32 s46, s66, s42
	s_addc_u32 s47, s67, s43
	s_cmp_eq_u32 s68, 4
	s_cselect_b32 s48, 0, s44
	s_cselect_b32 s49, 0, s45
	s_cselect_b32 s46, s39, s46
	s_cselect_b32 s47, s15, s47
	s_add_u32 s48, s6, s48
	s_addc_u32 s49, s7, s49
	s_mov_b32 m0, s29
	v_lshl_add_u64 v[218:219], v[138:139], 0, s[42:43]
	ds_read_b128 v[184:187], v148
	ds_read_b128 v[188:191], v148 offset:1024
	ds_read_b128 v[192:195], v148 offset:2048
	ds_read_b128 v[196:199], v148 offset:3072
	ds_read_b128 v[200:203], v148 offset:4096
	ds_read_b128 v[206:209], v148 offset:5120
	ds_read_b128 v[210:213], v148 offset:6144
	ds_read_b128 v[214:217], v148 offset:7168
	global_load_lds_dwordx4 v[218:219], off
	s_mov_b32 m0, s30
	v_lshl_add_u64 v[218:219], v[140:141], 0, s[42:43]
	global_load_lds_dwordx4 v[218:219], off
	s_waitcnt vmcnt(8) lgkmcnt(0)
	s_setprio 1
	s_barrier
	v_mfma_f32_16x16x32_bf16 v[126:129], v[152:155], v[184:187], v[126:129]
	v_mfma_f32_16x16x32_bf16 v[122:125], v[160:163], v[184:187], v[122:125]
	v_mfma_f32_16x16x32_bf16 v[118:121], v[152:155], v[192:195], v[118:121]
	v_mfma_f32_16x16x32_bf16 v[114:117], v[160:163], v[192:195], v[114:117]
	v_mfma_f32_16x16x32_bf16 v[102:105], v[152:155], v[200:203], v[102:105]
	v_mfma_f32_16x16x32_bf16 v[98:101], v[160:163], v[200:203], v[98:101]
	v_mfma_f32_16x16x32_bf16 v[86:89], v[152:155], v[210:213], v[86:89]
	v_mfma_f32_16x16x32_bf16 v[82:85], v[160:163], v[210:213], v[82:85]
	v_mfma_f32_16x16x32_bf16 v[126:129], v[156:159], v[188:191], v[126:129]
	v_mfma_f32_16x16x32_bf16 v[122:125], v[164:167], v[188:191], v[122:125]
	v_mfma_f32_16x16x32_bf16 v[118:121], v[156:159], v[196:199], v[118:121]
	v_mfma_f32_16x16x32_bf16 v[114:117], v[164:167], v[196:199], v[114:117]
	v_mfma_f32_16x16x32_bf16 v[102:105], v[156:159], v[206:209], v[102:105]
	v_mfma_f32_16x16x32_bf16 v[98:101], v[164:167], v[206:209], v[98:101]
	v_mfma_f32_16x16x32_bf16 v[86:89], v[156:159], v[214:217], v[86:89]
	v_mfma_f32_16x16x32_bf16 v[82:85], v[164:167], v[214:217], v[82:85]
	v_mfma_f32_16x16x32_bf16 v[110:113], v[168:171], v[184:187], v[110:113]
	v_mfma_f32_16x16x32_bf16 v[106:109], v[176:179], v[184:187], v[106:109]
	v_mfma_f32_16x16x32_bf16 v[94:97], v[168:171], v[192:195], v[94:97]
	v_mfma_f32_16x16x32_bf16 v[90:93], v[176:179], v[192:195], v[90:93]
	v_mfma_f32_16x16x32_bf16 v[78:81], v[168:171], v[200:203], v[78:81]
	v_mfma_f32_16x16x32_bf16 v[74:77], v[176:179], v[200:203], v[74:77]
	v_mfma_f32_16x16x32_bf16 v[70:73], v[168:171], v[210:213], v[70:73]
	v_mfma_f32_16x16x32_bf16 v[66:69], v[176:179], v[210:213], v[66:69]
	v_mfma_f32_16x16x32_bf16 v[110:113], v[172:175], v[188:191], v[110:113]
	v_mfma_f32_16x16x32_bf16 v[106:109], v[180:183], v[188:191], v[106:109]
	v_mfma_f32_16x16x32_bf16 v[94:97], v[172:175], v[196:199], v[94:97]
	v_mfma_f32_16x16x32_bf16 v[90:93], v[180:183], v[196:199], v[90:93]
	v_mfma_f32_16x16x32_bf16 v[78:81], v[172:175], v[206:209], v[78:81]
	v_mfma_f32_16x16x32_bf16 v[74:77], v[180:183], v[206:209], v[74:77]
	v_mfma_f32_16x16x32_bf16 v[70:73], v[172:175], v[214:217], v[70:73]
	v_mfma_f32_16x16x32_bf16 v[66:69], v[180:183], v[214:217], v[66:69]
	s_setprio 0
	s_barrier
	s_mov_b32 m0, s31
	v_lshl_add_u64 v[218:219], s[46:47], 0, v[134:135]
	s_add_u32 s42, s46, 0x20000
	global_load_lds_dwordx4 v[218:219], off
	ds_read_b128 v[184:187], v148 offset:16384
	ds_read_b128 v[188:191], v148 offset:17408
	ds_read_b128 v[192:195], v148 offset:18432
	ds_read_b128 v[196:199], v148 offset:19456
	ds_read_b128 v[200:203], v148 offset:20480
	ds_read_b128 v[206:209], v148 offset:21504
	ds_read_b128 v[210:213], v148 offset:22528
	ds_read_b128 v[214:217], v148 offset:23552
	v_lshl_add_u64 v[220:221], s[46:47], 0, v[130:131]
	s_mov_b32 m0, s33
	s_addc_u32 s43, s47, 0
	global_load_lds_dwordx4 v[220:221], off
	v_lshl_add_u64 v[222:223], s[42:43], 0, v[134:135]
	s_mov_b32 m0, s34
	v_lshl_add_u64 v[224:225], s[48:49], 0, v[132:133]
	global_load_lds_dwordx4 v[222:223], off
	s_mov_b32 m0, s35
	v_lshl_add_u64 v[222:223], s[42:43], 0, v[130:131]
	global_load_lds_dwordx4 v[222:223], off
	s_mov_b32 m0, s2
	v_lshl_add_u64 v[222:223], s[48:49], 0, v[136:137]
	global_load_lds_dwordx4 v[222:223], off
	s_mov_b32 m0, s3
	s_nop 0
	global_load_lds_dwordx4 v[224:225], off
	s_waitcnt vmcnt(8) lgkmcnt(0)
	s_setprio 1
	s_barrier
	v_mfma_f32_16x16x32_bf16 v[62:65], v[152:155], v[184:187], v[62:65]
	v_mfma_f32_16x16x32_bf16 v[58:61], v[160:163], v[184:187], v[58:61]
	v_mfma_f32_16x16x32_bf16 v[54:57], v[152:155], v[192:195], v[54:57]
	v_mfma_f32_16x16x32_bf16 v[50:53], v[160:163], v[192:195], v[50:53]
	v_mfma_f32_16x16x32_bf16 v[38:41], v[152:155], v[200:203], v[38:41]
	v_mfma_f32_16x16x32_bf16 v[34:37], v[160:163], v[200:203], v[34:37]
	v_mfma_f32_16x16x32_bf16 v[22:25], v[152:155], v[210:213], v[22:25]
	v_mfma_f32_16x16x32_bf16 v[18:21], v[160:163], v[210:213], v[18:21]
	v_mfma_f32_16x16x32_bf16 v[62:65], v[156:159], v[188:191], v[62:65]
	v_mfma_f32_16x16x32_bf16 v[58:61], v[164:167], v[188:191], v[58:61]
	v_mfma_f32_16x16x32_bf16 v[54:57], v[156:159], v[196:199], v[54:57]
	v_mfma_f32_16x16x32_bf16 v[50:53], v[164:167], v[196:199], v[50:53]
	v_mfma_f32_16x16x32_bf16 v[38:41], v[156:159], v[206:209], v[38:41]
	v_mfma_f32_16x16x32_bf16 v[34:37], v[164:167], v[206:209], v[34:37]
	v_mfma_f32_16x16x32_bf16 v[22:25], v[156:159], v[214:217], v[22:25]
	v_mfma_f32_16x16x32_bf16 v[18:21], v[164:167], v[214:217], v[18:21]
	v_mfma_f32_16x16x32_bf16 v[46:49], v[168:171], v[184:187], v[46:49]
	v_mfma_f32_16x16x32_bf16 v[42:45], v[176:179], v[184:187], v[42:45]
	v_mfma_f32_16x16x32_bf16 v[30:33], v[168:171], v[192:195], v[30:33]
	v_mfma_f32_16x16x32_bf16 v[26:29], v[176:179], v[192:195], v[26:29]
	v_mfma_f32_16x16x32_bf16 v[14:17], v[168:171], v[200:203], v[14:17]
	v_mfma_f32_16x16x32_bf16 v[10:13], v[176:179], v[200:203], v[10:13]
	v_mfma_f32_16x16x32_bf16 v[6:9], v[168:171], v[210:213], v[6:9]
	v_mfma_f32_16x16x32_bf16 v[2:5], v[176:179], v[210:213], v[2:5]
	v_mfma_f32_16x16x32_bf16 v[46:49], v[172:175], v[188:191], v[46:49]
	v_mfma_f32_16x16x32_bf16 v[42:45], v[180:183], v[188:191], v[42:45]
	v_mfma_f32_16x16x32_bf16 v[30:33], v[172:175], v[196:199], v[30:33]
	v_mfma_f32_16x16x32_bf16 v[26:29], v[180:183], v[196:199], v[26:29]
	v_mfma_f32_16x16x32_bf16 v[14:17], v[172:175], v[206:209], v[14:17]
	v_mfma_f32_16x16x32_bf16 v[10:13], v[180:183], v[206:209], v[10:13]
	v_mfma_f32_16x16x32_bf16 v[6:9], v[172:175], v[214:217], v[6:9]
	v_mfma_f32_16x16x32_bf16 v[2:5], v[180:183], v[214:217], v[2:5]
	s_setprio 0
	s_barrier
	ds_read_b128 v[152:155], v149
	ds_read_b128 v[156:159], v149 offset:1024
	ds_read_b128 v[160:163], v149 offset:2048
	ds_read_b128 v[164:167], v149 offset:3072
	ds_read_b128 v[168:171], v150
	ds_read_b128 v[172:175], v150 offset:1024
	ds_read_b128 v[176:179], v150 offset:2048
	ds_read_b128 v[180:183], v150 offset:3072
	s_add_u32 s42, s48, 0x20000
	s_addc_u32 s43, s49, 0
	s_mov_b32 m0, s16
	v_lshl_add_u64 v[226:227], s[42:43], 0, v[136:137]
	ds_read_b128 v[184:187], v148 offset:32768
	ds_read_b128 v[188:191], v148 offset:33792
	ds_read_b128 v[192:195], v148 offset:34816
	ds_read_b128 v[196:199], v148 offset:35840
	ds_read_b128 v[200:203], v148 offset:36864
	ds_read_b128 v[206:209], v148 offset:37888
	ds_read_b128 v[210:213], v148 offset:38912
	ds_read_b128 v[214:217], v148 offset:39936
	global_load_lds_dwordx4 v[226:227], off
	s_mov_b32 m0, s17
	v_lshl_add_u64 v[226:227], s[42:43], 0, v[132:133]
	global_load_lds_dwordx4 v[226:227], off
	s_waitcnt vmcnt(8) lgkmcnt(0)
	s_setprio 1
	s_barrier
	v_mfma_f32_16x16x32_bf16 v[126:129], v[152:155], v[184:187], v[126:129]
	v_mfma_f32_16x16x32_bf16 v[122:125], v[160:163], v[184:187], v[122:125]
	v_mfma_f32_16x16x32_bf16 v[118:121], v[152:155], v[192:195], v[118:121]
	v_mfma_f32_16x16x32_bf16 v[114:117], v[160:163], v[192:195], v[114:117]
	v_mfma_f32_16x16x32_bf16 v[102:105], v[152:155], v[200:203], v[102:105]
	v_mfma_f32_16x16x32_bf16 v[98:101], v[160:163], v[200:203], v[98:101]
	v_mfma_f32_16x16x32_bf16 v[86:89], v[152:155], v[210:213], v[86:89]
	v_mfma_f32_16x16x32_bf16 v[82:85], v[160:163], v[210:213], v[82:85]
	v_mfma_f32_16x16x32_bf16 v[126:129], v[156:159], v[188:191], v[126:129]
	v_mfma_f32_16x16x32_bf16 v[122:125], v[164:167], v[188:191], v[122:125]
	v_mfma_f32_16x16x32_bf16 v[118:121], v[156:159], v[196:199], v[118:121]
	v_mfma_f32_16x16x32_bf16 v[114:117], v[164:167], v[196:199], v[114:117]
	v_mfma_f32_16x16x32_bf16 v[102:105], v[156:159], v[206:209], v[102:105]
	v_mfma_f32_16x16x32_bf16 v[98:101], v[164:167], v[206:209], v[98:101]
	v_mfma_f32_16x16x32_bf16 v[86:89], v[156:159], v[214:217], v[86:89]
	v_mfma_f32_16x16x32_bf16 v[82:85], v[164:167], v[214:217], v[82:85]
	v_mfma_f32_16x16x32_bf16 v[110:113], v[168:171], v[184:187], v[110:113]
	v_mfma_f32_16x16x32_bf16 v[106:109], v[176:179], v[184:187], v[106:109]
	v_mfma_f32_16x16x32_bf16 v[94:97], v[168:171], v[192:195], v[94:97]
	v_mfma_f32_16x16x32_bf16 v[90:93], v[176:179], v[192:195], v[90:93]
	v_mfma_f32_16x16x32_bf16 v[78:81], v[168:171], v[200:203], v[78:81]
	v_mfma_f32_16x16x32_bf16 v[74:77], v[176:179], v[200:203], v[74:77]
	v_mfma_f32_16x16x32_bf16 v[70:73], v[168:171], v[210:213], v[70:73]
	v_mfma_f32_16x16x32_bf16 v[66:69], v[176:179], v[210:213], v[66:69]
	v_mfma_f32_16x16x32_bf16 v[110:113], v[172:175], v[188:191], v[110:113]
	v_mfma_f32_16x16x32_bf16 v[106:109], v[180:183], v[188:191], v[106:109]
	v_mfma_f32_16x16x32_bf16 v[94:97], v[172:175], v[196:199], v[94:97]
	v_mfma_f32_16x16x32_bf16 v[90:93], v[180:183], v[196:199], v[90:93]
	v_mfma_f32_16x16x32_bf16 v[78:81], v[172:175], v[206:209], v[78:81]
	v_mfma_f32_16x16x32_bf16 v[74:77], v[180:183], v[206:209], v[74:77]
	v_mfma_f32_16x16x32_bf16 v[70:73], v[172:175], v[214:217], v[70:73]
	v_mfma_f32_16x16x32_bf16 v[66:69], v[180:183], v[214:217], v[66:69]
	s_setprio 0
	s_barrier
	s_mov_b32 m0, s62
	v_lshl_add_u64 v[218:219], v[218:219], 0, s[10:11]
	s_add_u32 s42, s46, 0x20080
	global_load_lds_dwordx4 v[218:219], off
	ds_read_b128 v[184:187], v148 offset:49152
	ds_read_b128 v[188:191], v148 offset:50176
	ds_read_b128 v[192:195], v148 offset:51200
	ds_read_b128 v[196:199], v148 offset:52224
	ds_read_b128 v[200:203], v148 offset:53248
	ds_read_b128 v[206:209], v148 offset:54272
	ds_read_b128 v[210:213], v148 offset:55296
	ds_read_b128 v[214:217], v148 offset:56320
	v_lshl_add_u64 v[218:219], v[220:221], 0, s[10:11]
	s_mov_b32 m0, s63
	s_addc_u32 s43, s47, 0
	global_load_lds_dwordx4 v[218:219], off
	s_mov_b32 m0, s64
	v_lshl_add_u64 v[218:219], s[42:43], 0, v[134:135]
	global_load_lds_dwordx4 v[218:219], off
	s_mov_b32 m0, s65
	v_lshl_add_u64 v[218:219], s[42:43], 0, v[130:131]
	global_load_lds_dwordx4 v[218:219], off
	s_mov_b32 m0, s25
	v_lshl_add_u64 v[218:219], v[222:223], 0, s[10:11]
	global_load_lds_dwordx4 v[218:219], off
	s_mov_b32 m0, s28
	v_lshl_add_u64 v[218:219], v[224:225], 0, s[10:11]
	global_load_lds_dwordx4 v[218:219], off
	s_waitcnt vmcnt(8) lgkmcnt(0)
	s_setprio 1
	s_barrier
	v_mfma_f32_16x16x32_bf16 v[62:65], v[152:155], v[184:187], v[62:65]
	v_mfma_f32_16x16x32_bf16 v[58:61], v[160:163], v[184:187], v[58:61]
	v_mfma_f32_16x16x32_bf16 v[54:57], v[152:155], v[192:195], v[54:57]
	v_mfma_f32_16x16x32_bf16 v[50:53], v[160:163], v[192:195], v[50:53]
	v_mfma_f32_16x16x32_bf16 v[38:41], v[152:155], v[200:203], v[38:41]
	v_mfma_f32_16x16x32_bf16 v[34:37], v[160:163], v[200:203], v[34:37]
	v_mfma_f32_16x16x32_bf16 v[22:25], v[152:155], v[210:213], v[22:25]
	v_mfma_f32_16x16x32_bf16 v[18:21], v[160:163], v[210:213], v[18:21]
	v_mfma_f32_16x16x32_bf16 v[62:65], v[156:159], v[188:191], v[62:65]
	v_mfma_f32_16x16x32_bf16 v[58:61], v[164:167], v[188:191], v[58:61]
	v_mfma_f32_16x16x32_bf16 v[54:57], v[156:159], v[196:199], v[54:57]
	v_mfma_f32_16x16x32_bf16 v[50:53], v[164:167], v[196:199], v[50:53]
	v_mfma_f32_16x16x32_bf16 v[38:41], v[156:159], v[206:209], v[38:41]
	v_mfma_f32_16x16x32_bf16 v[34:37], v[164:167], v[206:209], v[34:37]
	v_mfma_f32_16x16x32_bf16 v[22:25], v[156:159], v[214:217], v[22:25]
	v_mfma_f32_16x16x32_bf16 v[18:21], v[164:167], v[214:217], v[18:21]
	v_mfma_f32_16x16x32_bf16 v[46:49], v[168:171], v[184:187], v[46:49]
	v_mfma_f32_16x16x32_bf16 v[42:45], v[176:179], v[184:187], v[42:45]
	v_mfma_f32_16x16x32_bf16 v[30:33], v[168:171], v[192:195], v[30:33]
	v_mfma_f32_16x16x32_bf16 v[26:29], v[176:179], v[192:195], v[26:29]
	v_mfma_f32_16x16x32_bf16 v[14:17], v[168:171], v[200:203], v[14:17]
	v_mfma_f32_16x16x32_bf16 v[10:13], v[176:179], v[200:203], v[10:13]
	v_mfma_f32_16x16x32_bf16 v[6:9], v[168:171], v[210:213], v[6:9]
	v_mfma_f32_16x16x32_bf16 v[2:5], v[176:179], v[210:213], v[2:5]
	v_mfma_f32_16x16x32_bf16 v[46:49], v[172:175], v[188:191], v[46:49]
	v_mfma_f32_16x16x32_bf16 v[42:45], v[180:183], v[188:191], v[42:45]
	v_mfma_f32_16x16x32_bf16 v[30:33], v[172:175], v[196:199], v[30:33]
	v_mfma_f32_16x16x32_bf16 v[26:29], v[180:183], v[196:199], v[26:29]
	v_mfma_f32_16x16x32_bf16 v[14:17], v[172:175], v[206:209], v[14:17]
	v_mfma_f32_16x16x32_bf16 v[10:13], v[180:183], v[206:209], v[10:13]
	v_mfma_f32_16x16x32_bf16 v[6:9], v[172:175], v[214:217], v[6:9]
	v_mfma_f32_16x16x32_bf16 v[2:5], v[180:183], v[214:217], v[2:5]
	s_setprio 0
	s_barrier
	s_add_i32 s68, s68, 2
	s_cmp_gt_u32 s68, 5
	s_mov_b64 s[42:43], s[44:45]
	s_cbranch_scc0 .LBB0_384
	s_and_b64 vcc, exec, s[12:13]
	s_cbranch_vccz .LBB0_387
	s_barrier

.LBB0_406:
	s_lshl_b32 s74, s12, 7
	s_add_i32 s12, s12, 2
	v_cndmask_b32_e64 v138, 0, 1, s[66:67]
	s_lshl_b64 s[66:67], s[12:13], 7
	s_and_b64 s[68:69], s[64:65], exec
	s_cselect_b32 s66, 0, s66
	s_cselect_b32 s67, 0, s67
	s_add_u32 s70, s8, s66
	s_addc_u32 s71, s9, s67
	s_lshl_b64 s[66:67], s[12:13], 12
	s_add_u32 s12, s48, s66
	s_addc_u32 s66, s49, s67
	s_and_b64 s[64:65], s[64:65], exec
	s_cselect_b32 s73, s14, s66
	s_cselect_b32 s72, s15, s12
	s_add_u32 s76, s10, s74
	s_addc_u32 s77, s11, 0
	s_add_i32 s91, s62, s16
	s_add_i32 m0, s17, 0xc000
	s_add_i32 s92, s17, 0xe000
	s_add_i32 s88, s91, 0x2000
	s_add_u32 s74, s72, 0x10000
	ds_read_b128 v[146:149], v141
	ds_read_b128 v[150:153], v141 offset:1024
	ds_read_b128 v[154:157], v141 offset:2048
	ds_read_b128 v[158:161], v141 offset:3072
	ds_read_b128 v[162:165], v143
	ds_read_b128 v[166:169], v143 offset:1024
	ds_read_b128 v[170:173], v143 offset:2048
	ds_read_b128 v[174:177], v143 offset:3072
	s_addc_u32 s75, s73, 0
	s_add_i32 s90, s63, s16
	s_add_i32 s89, s90, 0x2000
	s_add_i32 s87, 0, 0x18000
	s_add_i32 s86, 0, 0x1c000
	s_add_u32 s68, s70, 0x10000
	s_addc_u32 s69, s71, 0
	s_add_u32 s64, s72, 0x1000
	s_addc_u32 s65, s73, 0
	s_add_i32 s85, s87, s16
	s_add_i32 s83, s85, 0x2000
	s_add_u32 s66, s72, 0x11000
	s_addc_u32 s67, s73, 0
	s_add_i32 s84, s86, s16
	s_add_i32 s12, s84, 0x2000
	v_cmp_ne_u32_e32 vcc, 1, v138
	v_lshl_add_u64 v[202:203], s[76:77], 0, v[136:137]
	v_lshl_add_u64 v[202:203], v[202:203], 0, s[36:37]
	ds_read_b128 v[178:181], v144
	ds_read_b128 v[182:185], v144 offset:1024
	ds_read_b128 v[186:189], v144 offset:2048
	ds_read_b128 v[190:193], v144 offset:3072
	ds_read_b128 v[194:197], v144 offset:4096
	ds_read_b128 v[198:201], v144 offset:5120
	ds_read_b128 v[206:209], v144 offset:6144
	ds_read_b128 v[210:213], v144 offset:7168
	global_load_lds_dwordx4 v[202:203], off
	v_lshl_add_u64 v[202:203], s[76:77], 0, v[132:133]
	s_mov_b32 m0, s92
	v_lshl_add_u64 v[202:203], v[202:203], 0, s[36:37]
	global_load_lds_dwordx4 v[202:203], off
	s_waitcnt vmcnt(8) lgkmcnt(0)
	s_setprio 1
	s_barrier
	v_mfma_f32_16x16x32_bf16 v[126:129], v[146:149], v[178:181], v[126:129]
	v_mfma_f32_16x16x32_bf16 v[122:125], v[154:157], v[178:181], v[122:125]
	v_mfma_f32_16x16x32_bf16 v[118:121], v[146:149], v[186:189], v[118:121]
	v_mfma_f32_16x16x32_bf16 v[110:113], v[154:157], v[186:189], v[110:113]
	v_mfma_f32_16x16x32_bf16 v[102:105], v[146:149], v[194:197], v[102:105]
	v_mfma_f32_16x16x32_bf16 v[98:101], v[154:157], v[194:197], v[98:101]
	v_mfma_f32_16x16x32_bf16 v[86:89], v[146:149], v[206:209], v[86:89]
	v_mfma_f32_16x16x32_bf16 v[82:85], v[154:157], v[206:209], v[82:85]
	v_mfma_f32_16x16x32_bf16 v[126:129], v[150:153], v[182:185], v[126:129]
	v_mfma_f32_16x16x32_bf16 v[122:125], v[158:161], v[182:185], v[122:125]
	v_mfma_f32_16x16x32_bf16 v[118:121], v[150:153], v[190:193], v[118:121]
	v_mfma_f32_16x16x32_bf16 v[110:113], v[158:161], v[190:193], v[110:113]
	v_mfma_f32_16x16x32_bf16 v[102:105], v[150:153], v[198:201], v[102:105]
	v_mfma_f32_16x16x32_bf16 v[98:101], v[158:161], v[198:201], v[98:101]
	v_mfma_f32_16x16x32_bf16 v[86:89], v[150:153], v[210:213], v[86:89]
	v_mfma_f32_16x16x32_bf16 v[82:85], v[158:161], v[210:213], v[82:85]
	v_mfma_f32_16x16x32_bf16 v[114:117], v[162:165], v[178:181], v[114:117]
	v_mfma_f32_16x16x32_bf16 v[106:109], v[170:173], v[178:181], v[106:109]
	v_mfma_f32_16x16x32_bf16 v[94:97], v[162:165], v[186:189], v[94:97]
	v_mfma_f32_16x16x32_bf16 v[90:93], v[170:173], v[186:189], v[90:93]
	v_mfma_f32_16x16x32_bf16 v[78:81], v[162:165], v[194:197], v[78:81]
	v_mfma_f32_16x16x32_bf16 v[74:77], v[170:173], v[194:197], v[74:77]
	v_mfma_f32_16x16x32_bf16 v[70:73], v[162:165], v[206:209], v[70:73]
	v_mfma_f32_16x16x32_bf16 v[66:69], v[170:173], v[206:209], v[66:69]
	v_mfma_f32_16x16x32_bf16 v[114:117], v[166:169], v[182:185], v[114:117]
	v_mfma_f32_16x16x32_bf16 v[106:109], v[174:177], v[182:185], v[106:109]
	v_mfma_f32_16x16x32_bf16 v[94:97], v[166:169], v[190:193], v[94:97]
	v_mfma_f32_16x16x32_bf16 v[90:93], v[174:177], v[190:193], v[90:93]
	v_mfma_f32_16x16x32_bf16 v[78:81], v[166:169], v[198:201], v[78:81]
	v_mfma_f32_16x16x32_bf16 v[74:77], v[174:177], v[198:201], v[74:77]
	v_mfma_f32_16x16x32_bf16 v[70:73], v[166:169], v[210:213], v[70:73]
	v_mfma_f32_16x16x32_bf16 v[66:69], v[174:177], v[210:213], v[66:69]
	s_setprio 0
	s_barrier
	s_mov_b32 m0, s91
	v_lshl_add_u64 v[202:203], s[72:73], 0, v[134:135]
	global_load_lds_dwordx4 v[202:203], off
	ds_read_b128 v[178:181], v144 offset:16384
	ds_read_b128 v[182:185], v144 offset:17408
	ds_read_b128 v[186:189], v144 offset:18432
	ds_read_b128 v[190:193], v144 offset:19456
	ds_read_b128 v[194:197], v144 offset:20480
	ds_read_b128 v[198:201], v144 offset:21504
	ds_read_b128 v[206:209], v144 offset:22528
	ds_read_b128 v[210:213], v144 offset:23552
	v_lshl_add_u64 v[202:203], s[72:73], 0, v[130:131]
	s_mov_b32 m0, s88
	v_lshl_add_u64 v[214:215], s[70:71], 0, v[132:133]
	global_load_lds_dwordx4 v[202:203], off
	s_mov_b32 m0, s90
	v_lshl_add_u64 v[202:203], s[74:75], 0, v[134:135]
	global_load_lds_dwordx4 v[202:203], off
	s_mov_b32 m0, s89
	v_lshl_add_u64 v[202:203], s[74:75], 0, v[130:131]
	global_load_lds_dwordx4 v[202:203], off
	s_mov_b32 m0, s17
	v_lshl_add_u64 v[202:203], s[70:71], 0, v[136:137]
	global_load_lds_dwordx4 v[202:203], off
	s_mov_b32 m0, s18
	s_nop 0
	global_load_lds_dwordx4 v[214:215], off
	s_waitcnt vmcnt(8) lgkmcnt(0)
	s_setprio 1
	s_barrier
	v_mfma_f32_16x16x32_bf16 v[62:65], v[146:149], v[178:181], v[62:65]
	v_mfma_f32_16x16x32_bf16 v[58:61], v[154:157], v[178:181], v[58:61]
	v_mfma_f32_16x16x32_bf16 v[54:57], v[146:149], v[186:189], v[54:57]
	v_mfma_f32_16x16x32_bf16 v[50:53], v[154:157], v[186:189], v[50:53]
	v_mfma_f32_16x16x32_bf16 v[38:41], v[146:149], v[194:197], v[38:41]
	v_mfma_f32_16x16x32_bf16 v[34:37], v[154:157], v[194:197], v[34:37]
	v_mfma_f32_16x16x32_bf16 v[22:25], v[146:149], v[206:209], v[22:25]
	v_mfma_f32_16x16x32_bf16 v[18:21], v[154:157], v[206:209], v[18:21]
	v_mfma_f32_16x16x32_bf16 v[62:65], v[150:153], v[182:185], v[62:65]
	v_mfma_f32_16x16x32_bf16 v[58:61], v[158:161], v[182:185], v[58:61]
	v_mfma_f32_16x16x32_bf16 v[54:57], v[150:153], v[190:193], v[54:57]
	v_mfma_f32_16x16x32_bf16 v[50:53], v[158:161], v[190:193], v[50:53]
	v_mfma_f32_16x16x32_bf16 v[38:41], v[150:153], v[198:201], v[38:41]
	v_mfma_f32_16x16x32_bf16 v[34:37], v[158:161], v[198:201], v[34:37]
	v_mfma_f32_16x16x32_bf16 v[22:25], v[150:153], v[210:213], v[22:25]
	v_mfma_f32_16x16x32_bf16 v[18:21], v[158:161], v[210:213], v[18:21]
	v_mfma_f32_16x16x32_bf16 v[46:49], v[162:165], v[178:181], v[46:49]
	v_mfma_f32_16x16x32_bf16 v[42:45], v[170:173], v[178:181], v[42:45]
	v_mfma_f32_16x16x32_bf16 v[30:33], v[162:165], v[186:189], v[30:33]
	v_mfma_f32_16x16x32_bf16 v[26:29], v[170:173], v[186:189], v[26:29]
	v_mfma_f32_16x16x32_bf16 v[14:17], v[162:165], v[194:197], v[14:17]
	v_mfma_f32_16x16x32_bf16 v[10:13], v[170:173], v[194:197], v[10:13]
	v_mfma_f32_16x16x32_bf16 v[6:9], v[162:165], v[206:209], v[6:9]
	v_mfma_f32_16x16x32_bf16 v[2:5], v[170:173], v[206:209], v[2:5]
	v_mfma_f32_16x16x32_bf16 v[46:49], v[166:169], v[182:185], v[46:49]
	v_mfma_f32_16x16x32_bf16 v[42:45], v[174:177], v[182:185], v[42:45]
	v_mfma_f32_16x16x32_bf16 v[30:33], v[166:169], v[190:193], v[30:33]
	v_mfma_f32_16x16x32_bf16 v[26:29], v[174:177], v[190:193], v[26:29]
	v_mfma_f32_16x16x32_bf16 v[14:17], v[166:169], v[198:201], v[14:17]
	v_mfma_f32_16x16x32_bf16 v[10:13], v[174:177], v[198:201], v[10:13]
	v_mfma_f32_16x16x32_bf16 v[6:9], v[166:169], v[210:213], v[6:9]
	v_mfma_f32_16x16x32_bf16 v[2:5], v[174:177], v[210:213], v[2:5]
	s_setprio 0
	s_barrier
	v_add_u32_e32 v138, s87, v140
	ds_read_b128 v[146:149], v138
	ds_read_b128 v[150:153], v138 offset:1024
	ds_read_b128 v[154:157], v138 offset:2048
	ds_read_b128 v[158:161], v138 offset:3072
	v_add_u32_e32 v138, s86, v140
	ds_read_b128 v[162:165], v138
	ds_read_b128 v[166:169], v138 offset:1024
	ds_read_b128 v[170:173], v138 offset:2048
	ds_read_b128 v[174:177], v138 offset:3072
	s_mov_b32 m0, s19
	v_lshl_add_u64 v[216:217], s[68:69], 0, v[136:137]
	ds_read_b128 v[178:181], v144 offset:32768
	ds_read_b128 v[182:185], v144 offset:33792
	ds_read_b128 v[186:189], v144 offset:34816
	ds_read_b128 v[190:193], v144 offset:35840
	ds_read_b128 v[194:197], v144 offset:36864
	ds_read_b128 v[198:201], v144 offset:37888
	ds_read_b128 v[206:209], v144 offset:38912
	ds_read_b128 v[210:213], v144 offset:39936
	global_load_lds_dwordx4 v[216:217], off
	s_mov_b32 m0, s24
	v_lshl_add_u64 v[216:217], s[68:69], 0, v[132:133]
	global_load_lds_dwordx4 v[216:217], off
	s_waitcnt vmcnt(8) lgkmcnt(0)
	s_setprio 1
	s_barrier
	v_mfma_f32_16x16x32_bf16 v[126:129], v[146:149], v[178:181], v[126:129]
	v_mfma_f32_16x16x32_bf16 v[122:125], v[154:157], v[178:181], v[122:125]
	v_mfma_f32_16x16x32_bf16 v[118:121], v[146:149], v[186:189], v[118:121]
	v_mfma_f32_16x16x32_bf16 v[110:113], v[154:157], v[186:189], v[110:113]
	v_mfma_f32_16x16x32_bf16 v[102:105], v[146:149], v[194:197], v[102:105]
	v_mfma_f32_16x16x32_bf16 v[98:101], v[154:157], v[194:197], v[98:101]
	v_mfma_f32_16x16x32_bf16 v[86:89], v[146:149], v[206:209], v[86:89]
	v_mfma_f32_16x16x32_bf16 v[82:85], v[154:157], v[206:209], v[82:85]
	v_mfma_f32_16x16x32_bf16 v[126:129], v[150:153], v[182:185], v[126:129]
	v_mfma_f32_16x16x32_bf16 v[122:125], v[158:161], v[182:185], v[122:125]
	v_mfma_f32_16x16x32_bf16 v[118:121], v[150:153], v[190:193], v[118:121]
	v_mfma_f32_16x16x32_bf16 v[110:113], v[158:161], v[190:193], v[110:113]
	v_mfma_f32_16x16x32_bf16 v[102:105], v[150:153], v[198:201], v[102:105]
	v_mfma_f32_16x16x32_bf16 v[98:101], v[158:161], v[198:201], v[98:101]
	v_mfma_f32_16x16x32_bf16 v[86:89], v[150:153], v[210:213], v[86:89]
	v_mfma_f32_16x16x32_bf16 v[82:85], v[158:161], v[210:213], v[82:85]
	v_mfma_f32_16x16x32_bf16 v[114:117], v[162:165], v[178:181], v[114:117]
	v_mfma_f32_16x16x32_bf16 v[106:109], v[170:173], v[178:181], v[106:109]
	v_mfma_f32_16x16x32_bf16 v[94:97], v[162:165], v[186:189], v[94:97]
	v_mfma_f32_16x16x32_bf16 v[90:93], v[170:173], v[186:189], v[90:93]
	v_mfma_f32_16x16x32_bf16 v[78:81], v[162:165], v[194:197], v[78:81]
	v_mfma_f32_16x16x32_bf16 v[74:77], v[170:173], v[194:197], v[74:77]
	v_mfma_f32_16x16x32_bf16 v[70:73], v[162:165], v[206:209], v[70:73]
	v_mfma_f32_16x16x32_bf16 v[66:69], v[170:173], v[206:209], v[66:69]
	v_mfma_f32_16x16x32_bf16 v[114:117], v[166:169], v[182:185], v[114:117]
	v_mfma_f32_16x16x32_bf16 v[106:109], v[174:177], v[182:185], v[106:109]
	v_mfma_f32_16x16x32_bf16 v[94:97], v[166:169], v[190:193], v[94:97]
	v_mfma_f32_16x16x32_bf16 v[90:93], v[174:177], v[190:193], v[90:93]
	v_mfma_f32_16x16x32_bf16 v[78:81], v[166:169], v[198:201], v[78:81]
	v_mfma_f32_16x16x32_bf16 v[74:77], v[174:177], v[198:201], v[74:77]
	v_mfma_f32_16x16x32_bf16 v[70:73], v[166:169], v[210:213], v[70:73]
	v_mfma_f32_16x16x32_bf16 v[66:69], v[174:177], v[210:213], v[66:69]
	s_setprio 0
	s_barrier
	s_mov_b32 m0, s85
	v_lshl_add_u64 v[216:217], s[64:65], 0, v[134:135]
	global_load_lds_dwordx4 v[216:217], off
	ds_read_b128 v[178:181], v144 offset:49152
	ds_read_b128 v[182:185], v144 offset:50176
	ds_read_b128 v[186:189], v144 offset:51200
	ds_read_b128 v[190:193], v144 offset:52224
	ds_read_b128 v[194:197], v144 offset:53248
	ds_read_b128 v[198:201], v144 offset:54272
	ds_read_b128 v[206:209], v144 offset:55296
	ds_read_b128 v[210:213], v144 offset:56320
	v_lshl_add_u64 v[216:217], s[64:65], 0, v[130:131]
	s_mov_b32 m0, s83
	v_lshl_add_u64 v[202:203], v[202:203], 0, s[36:37]
	global_load_lds_dwordx4 v[216:217], off
	s_mov_b32 m0, s84
	v_lshl_add_u64 v[216:217], s[66:67], 0, v[134:135]
	global_load_lds_dwordx4 v[216:217], off
	s_mov_b32 m0, s12
	v_lshl_add_u64 v[216:217], s[66:67], 0, v[130:131]
	global_load_lds_dwordx4 v[216:217], off
	s_mov_b32 m0, s31
	s_nop 0
	global_load_lds_dwordx4 v[202:203], off
	s_mov_b32 m0, s33
	v_lshl_add_u64 v[202:203], v[214:215], 0, s[36:37]
	global_load_lds_dwordx4 v[202:203], off
	s_waitcnt vmcnt(8) lgkmcnt(0)
	s_setprio 1
	s_barrier
	v_mfma_f32_16x16x32_bf16 v[62:65], v[146:149], v[178:181], v[62:65]
	v_mfma_f32_16x16x32_bf16 v[58:61], v[154:157], v[178:181], v[58:61]
	v_mfma_f32_16x16x32_bf16 v[54:57], v[146:149], v[186:189], v[54:57]
	v_mfma_f32_16x16x32_bf16 v[50:53], v[154:157], v[186:189], v[50:53]
	v_mfma_f32_16x16x32_bf16 v[38:41], v[146:149], v[194:197], v[38:41]
	v_mfma_f32_16x16x32_bf16 v[34:37], v[154:157], v[194:197], v[34:37]
	v_mfma_f32_16x16x32_bf16 v[22:25], v[146:149], v[206:209], v[22:25]
	v_mfma_f32_16x16x32_bf16 v[18:21], v[154:157], v[206:209], v[18:21]
	v_mfma_f32_16x16x32_bf16 v[62:65], v[150:153], v[182:185], v[62:65]
	v_mfma_f32_16x16x32_bf16 v[58:61], v[158:161], v[182:185], v[58:61]
	v_mfma_f32_16x16x32_bf16 v[54:57], v[150:153], v[190:193], v[54:57]
	v_mfma_f32_16x16x32_bf16 v[50:53], v[158:161], v[190:193], v[50:53]
	v_mfma_f32_16x16x32_bf16 v[38:41], v[150:153], v[198:201], v[38:41]
	v_mfma_f32_16x16x32_bf16 v[34:37], v[158:161], v[198:201], v[34:37]
	v_mfma_f32_16x16x32_bf16 v[22:25], v[150:153], v[210:213], v[22:25]
	v_mfma_f32_16x16x32_bf16 v[18:21], v[158:161], v[210:213], v[18:21]
	v_mfma_f32_16x16x32_bf16 v[46:49], v[162:165], v[178:181], v[46:49]
	v_mfma_f32_16x16x32_bf16 v[42:45], v[170:173], v[178:181], v[42:45]
	v_mfma_f32_16x16x32_bf16 v[30:33], v[162:165], v[186:189], v[30:33]
	v_mfma_f32_16x16x32_bf16 v[26:29], v[170:173], v[186:189], v[26:29]
	v_mfma_f32_16x16x32_bf16 v[14:17], v[162:165], v[194:197], v[14:17]
	v_mfma_f32_16x16x32_bf16 v[10:13], v[170:173], v[194:197], v[10:13]
	v_mfma_f32_16x16x32_bf16 v[6:9], v[162:165], v[206:209], v[6:9]
	v_mfma_f32_16x16x32_bf16 v[2:5], v[170:173], v[206:209], v[2:5]
	v_mfma_f32_16x16x32_bf16 v[46:49], v[166:169], v[182:185], v[46:49]
	v_mfma_f32_16x16x32_bf16 v[42:45], v[174:177], v[182:185], v[42:45]
	v_mfma_f32_16x16x32_bf16 v[30:33], v[166:169], v[190:193], v[30:33]
	v_mfma_f32_16x16x32_bf16 v[26:29], v[174:177], v[190:193], v[26:29]
	v_mfma_f32_16x16x32_bf16 v[14:17], v[166:169], v[198:201], v[14:17]
	v_mfma_f32_16x16x32_bf16 v[10:13], v[174:177], v[198:201], v[10:13]
	v_mfma_f32_16x16x32_bf16 v[6:9], v[166:169], v[210:213], v[6:9]
	v_mfma_f32_16x16x32_bf16 v[2:5], v[174:177], v[210:213], v[2:5]
	s_setprio 0
	s_barrier
	s_mov_b64 s[66:67], 0
	s_mov_b64 s[64:65], -1
	s_mov_b32 s12, 2
	s_cbranch_vccz .LBB0_406
	s_and_b64 vcc, exec, s[22:23]
	s_cbranch_vccz .LBB0_409
	s_barrier

.LBB0_476:
	s_add_u32 s22, s2, s49
	s_addc_u32 s23, s3, s29
	s_and_b64 s[26:27], s[20:21], exec
	s_cselect_b32 s63, s23, s37
	s_cselect_b32 s64, s22, s36
	s_add_u32 s26, s16, s12
	s_addc_u32 s27, s17, s13
	s_and_b64 s[42:43], s[20:21], exec
	s_cselect_b32 s65, s27, s39
	s_cselect_b32 s66, s26, s38
	s_add_u32 s36, s36, 0x20080
	s_addc_u32 s37, s37, 0
	s_add_u32 s67, s38, 0x100
	s_addc_u32 s68, s39, 0
	s_mov_b32 s69, -2
	ds_read_b128 v[148:151], v144
	ds_read_b128 v[152:155], v144 offset:1024
	ds_read_b128 v[156:159], v144 offset:2048
	ds_read_b128 v[160:163], v144 offset:3072
	ds_read_b128 v[164:167], v145
	ds_read_b128 v[168:171], v145 offset:1024
	ds_read_b128 v[172:175], v145 offset:2048
	ds_read_b128 v[176:179], v145 offset:3072
	s_add_u32 s38, s36, 0xfffe0080
	s_addc_u32 s39, s37, -1
	s_cmp_eq_u32 s69, 4
	s_cselect_b32 s43, s63, s39
	s_cselect_b32 s42, s64, s38
	s_cselect_b32 s39, s65, s68
	s_cselect_b32 s38, s66, s67
	v_lshl_add_u64 v[214:215], s[36:37], 0, v[138:139]
	s_add_i32 m0, s19, 0xc000
	ds_read_b128 v[180:183], v146
	ds_read_b128 v[184:187], v146 offset:1024
	ds_read_b128 v[188:191], v146 offset:2048
	ds_read_b128 v[192:195], v146 offset:3072
	ds_read_b128 v[196:199], v146 offset:4096
	ds_read_b128 v[200:203], v146 offset:5120
	ds_read_b128 v[206:209], v146 offset:6144
	ds_read_b128 v[210:213], v146 offset:7168
	global_load_lds_dwordx4 v[214:215], off
	s_add_i32 m0, s19, 0xe000
	v_lshl_add_u64 v[214:215], s[36:37], 0, v[140:141]
	global_load_lds_dwordx4 v[214:215], off
	s_waitcnt vmcnt(8) lgkmcnt(0)
	s_setprio 1
	s_barrier
	v_mfma_f32_16x16x32_bf16 v[126:129], v[148:151], v[180:183], 0
	v_mfma_f32_16x16x32_bf16 v[122:125], v[156:159], v[180:183], 0
	v_mfma_f32_16x16x32_bf16 v[118:121], v[148:151], v[188:191], 0
	v_mfma_f32_16x16x32_bf16 v[114:117], v[156:159], v[188:191], 0
	v_mfma_f32_16x16x32_bf16 v[102:105], v[148:151], v[196:199], 0
	v_mfma_f32_16x16x32_bf16 v[98:101], v[156:159], v[196:199], 0
	v_mfma_f32_16x16x32_bf16 v[86:89], v[148:151], v[206:209], 0
	v_mfma_f32_16x16x32_bf16 v[82:85], v[156:159], v[206:209], 0
	v_mfma_f32_16x16x32_bf16 v[126:129], v[152:155], v[184:187], v[126:129]
	v_mfma_f32_16x16x32_bf16 v[122:125], v[160:163], v[184:187], v[122:125]
	v_mfma_f32_16x16x32_bf16 v[118:121], v[152:155], v[192:195], v[118:121]
	v_mfma_f32_16x16x32_bf16 v[114:117], v[160:163], v[192:195], v[114:117]
	v_mfma_f32_16x16x32_bf16 v[102:105], v[152:155], v[200:203], v[102:105]
	v_mfma_f32_16x16x32_bf16 v[98:101], v[160:163], v[200:203], v[98:101]
	v_mfma_f32_16x16x32_bf16 v[86:89], v[152:155], v[210:213], v[86:89]
	v_mfma_f32_16x16x32_bf16 v[82:85], v[160:163], v[210:213], v[82:85]
	v_mfma_f32_16x16x32_bf16 v[110:113], v[164:167], v[180:183], 0
	v_mfma_f32_16x16x32_bf16 v[106:109], v[172:175], v[180:183], 0
	v_mfma_f32_16x16x32_bf16 v[94:97], v[164:167], v[188:191], 0
	v_mfma_f32_16x16x32_bf16 v[90:93], v[172:175], v[188:191], 0
	v_mfma_f32_16x16x32_bf16 v[78:81], v[164:167], v[196:199], 0
	v_mfma_f32_16x16x32_bf16 v[74:77], v[172:175], v[196:199], 0
	v_mfma_f32_16x16x32_bf16 v[70:73], v[164:167], v[206:209], 0
	v_mfma_f32_16x16x32_bf16 v[66:69], v[172:175], v[206:209], 0
	v_mfma_f32_16x16x32_bf16 v[110:113], v[168:171], v[184:187], v[110:113]
	v_mfma_f32_16x16x32_bf16 v[106:109], v[176:179], v[184:187], v[106:109]
	v_mfma_f32_16x16x32_bf16 v[94:97], v[168:171], v[192:195], v[94:97]
	v_mfma_f32_16x16x32_bf16 v[90:93], v[176:179], v[192:195], v[90:93]
	v_mfma_f32_16x16x32_bf16 v[78:81], v[168:171], v[200:203], v[78:81]
	v_mfma_f32_16x16x32_bf16 v[74:77], v[176:179], v[200:203], v[74:77]
	v_mfma_f32_16x16x32_bf16 v[70:73], v[168:171], v[210:213], v[70:73]
	v_mfma_f32_16x16x32_bf16 v[66:69], v[176:179], v[210:213], v[66:69]
	s_setprio 0
	s_barrier
	s_add_i32 s70, s35, s18
	s_mov_b32 m0, s70
	v_lshl_add_u64 v[214:215], s[38:39], 0, v[134:135]
	global_load_lds_dwordx4 v[214:215], off
	ds_read_b128 v[180:183], v146 offset:16384
	ds_read_b128 v[184:187], v146 offset:17408
	ds_read_b128 v[188:191], v146 offset:18432
	ds_read_b128 v[192:195], v146 offset:19456
	ds_read_b128 v[196:199], v146 offset:20480
	ds_read_b128 v[200:203], v146 offset:21504
	ds_read_b128 v[206:209], v146 offset:22528
	ds_read_b128 v[210:213], v146 offset:23552
	s_add_i32 m0, s70, 0x2000
	s_add_u32 s70, s38, 0x200000
	v_lshl_add_u64 v[216:217], s[38:39], 0, v[130:131]
	s_addc_u32 s71, s39, 0
	s_add_i32 s72, s44, s18
	global_load_lds_dwordx4 v[216:217], off
	v_lshl_add_u64 v[218:219], s[70:71], 0, v[134:135]
	s_mov_b32 m0, s72
	v_lshl_add_u64 v[220:221], s[42:43], 0, v[132:133]
	global_load_lds_dwordx4 v[218:219], off
	s_add_i32 m0, s72, 0x2000
	v_lshl_add_u64 v[218:219], s[70:71], 0, v[130:131]
	global_load_lds_dwordx4 v[218:219], off
	s_mov_b32 m0, s19
	v_lshl_add_u64 v[218:219], s[42:43], 0, v[136:137]
	global_load_lds_dwordx4 v[218:219], off
	s_mov_b32 m0, s24
	s_nop 0
	global_load_lds_dwordx4 v[220:221], off
	s_waitcnt vmcnt(8) lgkmcnt(0)
	s_setprio 1
	s_barrier
	v_mfma_f32_16x16x32_bf16 v[62:65], v[148:151], v[180:183], 0
	v_mfma_f32_16x16x32_bf16 v[58:61], v[156:159], v[180:183], 0
	v_mfma_f32_16x16x32_bf16 v[54:57], v[148:151], v[188:191], 0
	v_mfma_f32_16x16x32_bf16 v[50:53], v[156:159], v[188:191], 0
	v_mfma_f32_16x16x32_bf16 v[38:41], v[148:151], v[196:199], 0
	v_mfma_f32_16x16x32_bf16 v[34:37], v[156:159], v[196:199], 0
	v_mfma_f32_16x16x32_bf16 v[22:25], v[148:151], v[206:209], 0
	v_mfma_f32_16x16x32_bf16 v[18:21], v[156:159], v[206:209], 0
	v_mfma_f32_16x16x32_bf16 v[62:65], v[152:155], v[184:187], v[62:65]
	v_mfma_f32_16x16x32_bf16 v[58:61], v[160:163], v[184:187], v[58:61]
	v_mfma_f32_16x16x32_bf16 v[54:57], v[152:155], v[192:195], v[54:57]
	v_mfma_f32_16x16x32_bf16 v[50:53], v[160:163], v[192:195], v[50:53]
	v_mfma_f32_16x16x32_bf16 v[38:41], v[152:155], v[200:203], v[38:41]
	v_mfma_f32_16x16x32_bf16 v[34:37], v[160:163], v[200:203], v[34:37]
	v_mfma_f32_16x16x32_bf16 v[22:25], v[152:155], v[210:213], v[22:25]
	v_mfma_f32_16x16x32_bf16 v[18:21], v[160:163], v[210:213], v[18:21]
	v_mfma_f32_16x16x32_bf16 v[46:49], v[164:167], v[180:183], 0
	v_mfma_f32_16x16x32_bf16 v[42:45], v[172:175], v[180:183], 0
	v_mfma_f32_16x16x32_bf16 v[30:33], v[164:167], v[188:191], 0
	v_mfma_f32_16x16x32_bf16 v[26:29], v[172:175], v[188:191], 0
	v_mfma_f32_16x16x32_bf16 v[14:17], v[164:167], v[196:199], 0
	v_mfma_f32_16x16x32_bf16 v[10:13], v[172:175], v[196:199], 0
	v_mfma_f32_16x16x32_bf16 v[6:9], v[164:167], v[206:209], 0
	v_mfma_f32_16x16x32_bf16 v[2:5], v[172:175], v[206:209], 0
	v_mfma_f32_16x16x32_bf16 v[46:49], v[168:171], v[184:187], v[46:49]
	v_mfma_f32_16x16x32_bf16 v[42:45], v[176:179], v[184:187], v[42:45]
	v_mfma_f32_16x16x32_bf16 v[30:33], v[168:171], v[192:195], v[30:33]
	v_mfma_f32_16x16x32_bf16 v[26:29], v[176:179], v[192:195], v[26:29]
	v_mfma_f32_16x16x32_bf16 v[14:17], v[168:171], v[200:203], v[14:17]
	v_mfma_f32_16x16x32_bf16 v[10:13], v[176:179], v[200:203], v[10:13]
	v_mfma_f32_16x16x32_bf16 v[6:9], v[168:171], v[210:213], v[6:9]
	v_mfma_f32_16x16x32_bf16 v[2:5], v[176:179], v[210:213], v[2:5]
	s_setprio 0
	s_barrier
	s_add_i32 s70, 0, 0x18000
	v_add_u32_e32 v147, s70, v143
	s_add_i32 s71, 0, 0x1c000
	ds_read_b128 v[148:151], v147
	ds_read_b128 v[152:155], v147 offset:1024
	ds_read_b128 v[156:159], v147 offset:2048
	ds_read_b128 v[160:163], v147 offset:3072
	v_add_u32_e32 v147, s71, v143
	ds_read_b128 v[164:167], v147
	ds_read_b128 v[168:171], v147 offset:1024
	ds_read_b128 v[172:175], v147 offset:2048
	ds_read_b128 v[176:179], v147 offset:3072
	s_add_u32 s42, s42, 0x20000
	s_addc_u32 s43, s43, 0
	s_mov_b32 m0, s25
	v_lshl_add_u64 v[222:223], s[42:43], 0, v[136:137]
	ds_read_b128 v[180:183], v146 offset:32768
	ds_read_b128 v[184:187], v146 offset:33792
	ds_read_b128 v[188:191], v146 offset:34816
	ds_read_b128 v[192:195], v146 offset:35840
	ds_read_b128 v[196:199], v146 offset:36864
	ds_read_b128 v[200:203], v146 offset:37888
	ds_read_b128 v[206:209], v146 offset:38912
	ds_read_b128 v[210:213], v146 offset:39936
	global_load_lds_dwordx4 v[222:223], off
	s_mov_b32 m0, s28
	v_lshl_add_u64 v[222:223], s[42:43], 0, v[132:133]
	global_load_lds_dwordx4 v[222:223], off
	s_waitcnt vmcnt(8) lgkmcnt(0)
	s_setprio 1
	s_barrier
	v_mfma_f32_16x16x32_bf16 v[126:129], v[148:151], v[180:183], v[126:129]
	v_mfma_f32_16x16x32_bf16 v[122:125], v[156:159], v[180:183], v[122:125]
	v_mfma_f32_16x16x32_bf16 v[118:121], v[148:151], v[188:191], v[118:121]
	v_mfma_f32_16x16x32_bf16 v[114:117], v[156:159], v[188:191], v[114:117]
	v_mfma_f32_16x16x32_bf16 v[102:105], v[148:151], v[196:199], v[102:105]
	v_mfma_f32_16x16x32_bf16 v[98:101], v[156:159], v[196:199], v[98:101]
	v_mfma_f32_16x16x32_bf16 v[86:89], v[148:151], v[206:209], v[86:89]
	v_mfma_f32_16x16x32_bf16 v[82:85], v[156:159], v[206:209], v[82:85]
	v_mfma_f32_16x16x32_bf16 v[126:129], v[152:155], v[184:187], v[126:129]
	v_mfma_f32_16x16x32_bf16 v[122:125], v[160:163], v[184:187], v[122:125]
	v_mfma_f32_16x16x32_bf16 v[118:121], v[152:155], v[192:195], v[118:121]
	v_mfma_f32_16x16x32_bf16 v[114:117], v[160:163], v[192:195], v[114:117]
	v_mfma_f32_16x16x32_bf16 v[102:105], v[152:155], v[200:203], v[102:105]
	v_mfma_f32_16x16x32_bf16 v[98:101], v[160:163], v[200:203], v[98:101]
	v_mfma_f32_16x16x32_bf16 v[86:89], v[152:155], v[210:213], v[86:89]
	v_mfma_f32_16x16x32_bf16 v[82:85], v[160:163], v[210:213], v[82:85]
	v_mfma_f32_16x16x32_bf16 v[110:113], v[164:167], v[180:183], v[110:113]
	v_mfma_f32_16x16x32_bf16 v[106:109], v[172:175], v[180:183], v[106:109]
	v_mfma_f32_16x16x32_bf16 v[94:97], v[164:167], v[188:191], v[94:97]
	v_mfma_f32_16x16x32_bf16 v[90:93], v[172:175], v[188:191], v[90:93]
	v_mfma_f32_16x16x32_bf16 v[78:81], v[164:167], v[196:199], v[78:81]
	v_mfma_f32_16x16x32_bf16 v[74:77], v[172:175], v[196:199], v[74:77]
	v_mfma_f32_16x16x32_bf16 v[70:73], v[164:167], v[206:209], v[70:73]
	v_mfma_f32_16x16x32_bf16 v[66:69], v[172:175], v[206:209], v[66:69]
	v_mfma_f32_16x16x32_bf16 v[110:113], v[168:171], v[184:187], v[110:113]
	v_mfma_f32_16x16x32_bf16 v[106:109], v[176:179], v[184:187], v[106:109]
	v_mfma_f32_16x16x32_bf16 v[94:97], v[168:171], v[192:195], v[94:97]
	v_mfma_f32_16x16x32_bf16 v[90:93], v[176:179], v[192:195], v[90:93]
	v_mfma_f32_16x16x32_bf16 v[78:81], v[168:171], v[200:203], v[78:81]
	v_mfma_f32_16x16x32_bf16 v[74:77], v[176:179], v[200:203], v[74:77]
	v_mfma_f32_16x16x32_bf16 v[70:73], v[168:171], v[210:213], v[70:73]
	v_mfma_f32_16x16x32_bf16 v[66:69], v[176:179], v[210:213], v[66:69]
	s_setprio 0
	s_barrier
	s_add_i32 s42, s70, s18
	s_mov_b32 m0, s42
	v_lshl_add_u64 v[214:215], v[214:215], 0, s[8:9]
	global_load_lds_dwordx4 v[214:215], off
	ds_read_b128 v[180:183], v146 offset:49152
	ds_read_b128 v[184:187], v146 offset:50176
	ds_read_b128 v[188:191], v146 offset:51200
	ds_read_b128 v[192:195], v146 offset:52224
	ds_read_b128 v[196:199], v146 offset:53248
	ds_read_b128 v[200:203], v146 offset:54272
	ds_read_b128 v[206:209], v146 offset:55296
	ds_read_b128 v[210:213], v146 offset:56320
	s_add_i32 m0, s42, 0x2000
	s_add_u32 s38, s38, 0x200080
	v_lshl_add_u64 v[214:215], v[216:217], 0, s[8:9]
	s_addc_u32 s39, s39, 0
	s_add_i32 s42, s71, s18
	global_load_lds_dwordx4 v[214:215], off
	s_mov_b32 m0, s42
	v_lshl_add_u64 v[214:215], s[38:39], 0, v[134:135]
	global_load_lds_dwordx4 v[214:215], off
	s_add_i32 m0, s42, 0x2000
	v_lshl_add_u64 v[214:215], s[38:39], 0, v[130:131]
	global_load_lds_dwordx4 v[214:215], off
	s_mov_b32 m0, s33
	v_lshl_add_u64 v[214:215], v[218:219], 0, s[8:9]
	global_load_lds_dwordx4 v[214:215], off
	s_mov_b32 m0, s34
	v_lshl_add_u64 v[214:215], v[220:221], 0, s[8:9]
	global_load_lds_dwordx4 v[214:215], off
	s_waitcnt vmcnt(8) lgkmcnt(0)
	s_setprio 1
	s_barrier
	v_mfma_f32_16x16x32_bf16 v[62:65], v[148:151], v[180:183], v[62:65]
	v_mfma_f32_16x16x32_bf16 v[58:61], v[156:159], v[180:183], v[58:61]
	v_mfma_f32_16x16x32_bf16 v[54:57], v[148:151], v[188:191], v[54:57]
	v_mfma_f32_16x16x32_bf16 v[50:53], v[156:159], v[188:191], v[50:53]
	v_mfma_f32_16x16x32_bf16 v[38:41], v[148:151], v[196:199], v[38:41]
	v_mfma_f32_16x16x32_bf16 v[34:37], v[156:159], v[196:199], v[34:37]
	v_mfma_f32_16x16x32_bf16 v[22:25], v[148:151], v[206:209], v[22:25]
	v_mfma_f32_16x16x32_bf16 v[18:21], v[156:159], v[206:209], v[18:21]
	v_mfma_f32_16x16x32_bf16 v[62:65], v[152:155], v[184:187], v[62:65]
	v_mfma_f32_16x16x32_bf16 v[58:61], v[160:163], v[184:187], v[58:61]
	v_mfma_f32_16x16x32_bf16 v[54:57], v[152:155], v[192:195], v[54:57]
	v_mfma_f32_16x16x32_bf16 v[50:53], v[160:163], v[192:195], v[50:53]
	v_mfma_f32_16x16x32_bf16 v[38:41], v[152:155], v[200:203], v[38:41]
	v_mfma_f32_16x16x32_bf16 v[34:37], v[160:163], v[200:203], v[34:37]
	v_mfma_f32_16x16x32_bf16 v[22:25], v[152:155], v[210:213], v[22:25]
	v_mfma_f32_16x16x32_bf16 v[18:21], v[160:163], v[210:213], v[18:21]
	v_mfma_f32_16x16x32_bf16 v[46:49], v[164:167], v[180:183], v[46:49]
	v_mfma_f32_16x16x32_bf16 v[42:45], v[172:175], v[180:183], v[42:45]
	v_mfma_f32_16x16x32_bf16 v[30:33], v[164:167], v[188:191], v[30:33]
	v_mfma_f32_16x16x32_bf16 v[26:29], v[172:175], v[188:191], v[26:29]
	v_mfma_f32_16x16x32_bf16 v[14:17], v[164:167], v[196:199], v[14:17]
	v_mfma_f32_16x16x32_bf16 v[10:13], v[172:175], v[196:199], v[10:13]
	v_mfma_f32_16x16x32_bf16 v[6:9], v[164:167], v[206:209], v[6:9]
	v_mfma_f32_16x16x32_bf16 v[2:5], v[172:175], v[206:209], v[2:5]
	v_mfma_f32_16x16x32_bf16 v[46:49], v[168:171], v[184:187], v[46:49]
	v_mfma_f32_16x16x32_bf16 v[42:45], v[176:179], v[184:187], v[42:45]
	v_mfma_f32_16x16x32_bf16 v[30:33], v[168:171], v[192:195], v[30:33]
	v_mfma_f32_16x16x32_bf16 v[26:29], v[176:179], v[192:195], v[26:29]
	v_mfma_f32_16x16x32_bf16 v[14:17], v[168:171], v[200:203], v[14:17]
	v_mfma_f32_16x16x32_bf16 v[10:13], v[176:179], v[200:203], v[10:13]
	v_mfma_f32_16x16x32_bf16 v[6:9], v[168:171], v[210:213], v[6:9]
	v_mfma_f32_16x16x32_bf16 v[2:5], v[176:179], v[210:213], v[2:5]
	s_setprio 0
	s_barrier
	s_add_i32 s69, s69, 2
	s_add_u32 s36, s36, 0x100
	s_addc_u32 s37, s37, 0
	s_add_u32 s67, s67, 0x100
	s_addc_u32 s68, s68, 0
	s_cmp_gt_u32 s69, 5
.LBB0_477:
	ds_read_b128 v[148:151], v144
	ds_read_b128 v[152:155], v144 offset:1024
	ds_read_b128 v[156:159], v144 offset:2048
	ds_read_b128 v[160:163], v144 offset:3072
	ds_read_b128 v[164:167], v145
	ds_read_b128 v[168:171], v145 offset:1024
	ds_read_b128 v[172:175], v145 offset:2048
	ds_read_b128 v[176:179], v145 offset:3072
	s_add_u32 s38, s36, 0xfffe0080
	s_addc_u32 s39, s37, -1
	s_cmp_eq_u32 s69, 4
	s_cselect_b32 s43, s63, s39
	s_cselect_b32 s42, s64, s38
	s_cselect_b32 s39, s65, s68
	s_cselect_b32 s38, s66, s67
	v_lshl_add_u64 v[214:215], s[36:37], 0, v[138:139]
	s_add_i32 m0, s19, 0xc000
	ds_read_b128 v[180:183], v146
	ds_read_b128 v[184:187], v146 offset:1024
	ds_read_b128 v[188:191], v146 offset:2048
	ds_read_b128 v[192:195], v146 offset:3072
	ds_read_b128 v[196:199], v146 offset:4096
	ds_read_b128 v[200:203], v146 offset:5120
	ds_read_b128 v[206:209], v146 offset:6144
	ds_read_b128 v[210:213], v146 offset:7168
	global_load_lds_dwordx4 v[214:215], off
	s_add_i32 m0, s19, 0xe000
	v_lshl_add_u64 v[214:215], s[36:37], 0, v[140:141]
	global_load_lds_dwordx4 v[214:215], off
	s_waitcnt vmcnt(8) lgkmcnt(0)
	s_setprio 1
	s_barrier
	v_mfma_f32_16x16x32_bf16 v[126:129], v[148:151], v[180:183], v[126:129]
	v_mfma_f32_16x16x32_bf16 v[122:125], v[156:159], v[180:183], v[122:125]
	v_mfma_f32_16x16x32_bf16 v[118:121], v[148:151], v[188:191], v[118:121]
	v_mfma_f32_16x16x32_bf16 v[114:117], v[156:159], v[188:191], v[114:117]
	v_mfma_f32_16x16x32_bf16 v[102:105], v[148:151], v[196:199], v[102:105]
	v_mfma_f32_16x16x32_bf16 v[98:101], v[156:159], v[196:199], v[98:101]
	v_mfma_f32_16x16x32_bf16 v[86:89], v[148:151], v[206:209], v[86:89]
	v_mfma_f32_16x16x32_bf16 v[82:85], v[156:159], v[206:209], v[82:85]
	v_mfma_f32_16x16x32_bf16 v[126:129], v[152:155], v[184:187], v[126:129]
	v_mfma_f32_16x16x32_bf16 v[122:125], v[160:163], v[184:187], v[122:125]
	v_mfma_f32_16x16x32_bf16 v[118:121], v[152:155], v[192:195], v[118:121]
	v_mfma_f32_16x16x32_bf16 v[114:117], v[160:163], v[192:195], v[114:117]
	v_mfma_f32_16x16x32_bf16 v[102:105], v[152:155], v[200:203], v[102:105]
	v_mfma_f32_16x16x32_bf16 v[98:101], v[160:163], v[200:203], v[98:101]
	v_mfma_f32_16x16x32_bf16 v[86:89], v[152:155], v[210:213], v[86:89]
	v_mfma_f32_16x16x32_bf16 v[82:85], v[160:163], v[210:213], v[82:85]
	v_mfma_f32_16x16x32_bf16 v[110:113], v[164:167], v[180:183], v[110:113]
	v_mfma_f32_16x16x32_bf16 v[106:109], v[172:175], v[180:183], v[106:109]
	v_mfma_f32_16x16x32_bf16 v[94:97], v[164:167], v[188:191], v[94:97]
	v_mfma_f32_16x16x32_bf16 v[90:93], v[172:175], v[188:191], v[90:93]
	v_mfma_f32_16x16x32_bf16 v[78:81], v[164:167], v[196:199], v[78:81]
	v_mfma_f32_16x16x32_bf16 v[74:77], v[172:175], v[196:199], v[74:77]
	v_mfma_f32_16x16x32_bf16 v[70:73], v[164:167], v[206:209], v[70:73]
	v_mfma_f32_16x16x32_bf16 v[66:69], v[172:175], v[206:209], v[66:69]
	v_mfma_f32_16x16x32_bf16 v[110:113], v[168:171], v[184:187], v[110:113]
	v_mfma_f32_16x16x32_bf16 v[106:109], v[176:179], v[184:187], v[106:109]
	v_mfma_f32_16x16x32_bf16 v[94:97], v[168:171], v[192:195], v[94:97]
	v_mfma_f32_16x16x32_bf16 v[90:93], v[176:179], v[192:195], v[90:93]
	v_mfma_f32_16x16x32_bf16 v[78:81], v[168:171], v[200:203], v[78:81]
	v_mfma_f32_16x16x32_bf16 v[74:77], v[176:179], v[200:203], v[74:77]
	v_mfma_f32_16x16x32_bf16 v[70:73], v[168:171], v[210:213], v[70:73]
	v_mfma_f32_16x16x32_bf16 v[66:69], v[176:179], v[210:213], v[66:69]
	s_setprio 0
	s_barrier
	s_add_i32 s70, s35, s18
	s_mov_b32 m0, s70
	v_lshl_add_u64 v[214:215], s[38:39], 0, v[134:135]
	global_load_lds_dwordx4 v[214:215], off
	ds_read_b128 v[180:183], v146 offset:16384
	ds_read_b128 v[184:187], v146 offset:17408
	ds_read_b128 v[188:191], v146 offset:18432
	ds_read_b128 v[192:195], v146 offset:19456
	ds_read_b128 v[196:199], v146 offset:20480
	ds_read_b128 v[200:203], v146 offset:21504
	ds_read_b128 v[206:209], v146 offset:22528
	ds_read_b128 v[210:213], v146 offset:23552
	s_add_i32 m0, s70, 0x2000
	s_add_u32 s70, s38, 0x200000
	v_lshl_add_u64 v[216:217], s[38:39], 0, v[130:131]
	s_addc_u32 s71, s39, 0
	s_add_i32 s72, s44, s18
	global_load_lds_dwordx4 v[216:217], off
	v_lshl_add_u64 v[218:219], s[70:71], 0, v[134:135]
	s_mov_b32 m0, s72
	v_lshl_add_u64 v[220:221], s[42:43], 0, v[132:133]
	global_load_lds_dwordx4 v[218:219], off
	s_add_i32 m0, s72, 0x2000
	v_lshl_add_u64 v[218:219], s[70:71], 0, v[130:131]
	global_load_lds_dwordx4 v[218:219], off
	s_mov_b32 m0, s19
	v_lshl_add_u64 v[218:219], s[42:43], 0, v[136:137]
	global_load_lds_dwordx4 v[218:219], off
	s_mov_b32 m0, s24
	s_nop 0
	global_load_lds_dwordx4 v[220:221], off
	s_waitcnt vmcnt(8) lgkmcnt(0)
	s_setprio 1
	s_barrier
	v_mfma_f32_16x16x32_bf16 v[62:65], v[148:151], v[180:183], v[62:65]
	v_mfma_f32_16x16x32_bf16 v[58:61], v[156:159], v[180:183], v[58:61]
	v_mfma_f32_16x16x32_bf16 v[54:57], v[148:151], v[188:191], v[54:57]
	v_mfma_f32_16x16x32_bf16 v[50:53], v[156:159], v[188:191], v[50:53]
	v_mfma_f32_16x16x32_bf16 v[38:41], v[148:151], v[196:199], v[38:41]
	v_mfma_f32_16x16x32_bf16 v[34:37], v[156:159], v[196:199], v[34:37]
	v_mfma_f32_16x16x32_bf16 v[22:25], v[148:151], v[206:209], v[22:25]
	v_mfma_f32_16x16x32_bf16 v[18:21], v[156:159], v[206:209], v[18:21]
	v_mfma_f32_16x16x32_bf16 v[62:65], v[152:155], v[184:187], v[62:65]
	v_mfma_f32_16x16x32_bf16 v[58:61], v[160:163], v[184:187], v[58:61]
	v_mfma_f32_16x16x32_bf16 v[54:57], v[152:155], v[192:195], v[54:57]
	v_mfma_f32_16x16x32_bf16 v[50:53], v[160:163], v[192:195], v[50:53]
	v_mfma_f32_16x16x32_bf16 v[38:41], v[152:155], v[200:203], v[38:41]
	v_mfma_f32_16x16x32_bf16 v[34:37], v[160:163], v[200:203], v[34:37]
	v_mfma_f32_16x16x32_bf16 v[22:25], v[152:155], v[210:213], v[22:25]
	v_mfma_f32_16x16x32_bf16 v[18:21], v[160:163], v[210:213], v[18:21]
	v_mfma_f32_16x16x32_bf16 v[46:49], v[164:167], v[180:183], v[46:49]
	v_mfma_f32_16x16x32_bf16 v[42:45], v[172:175], v[180:183], v[42:45]
	v_mfma_f32_16x16x32_bf16 v[30:33], v[164:167], v[188:191], v[30:33]
	v_mfma_f32_16x16x32_bf16 v[26:29], v[172:175], v[188:191], v[26:29]
	v_mfma_f32_16x16x32_bf16 v[14:17], v[164:167], v[196:199], v[14:17]
	v_mfma_f32_16x16x32_bf16 v[10:13], v[172:175], v[196:199], v[10:13]
	v_mfma_f32_16x16x32_bf16 v[6:9], v[164:167], v[206:209], v[6:9]
	v_mfma_f32_16x16x32_bf16 v[2:5], v[172:175], v[206:209], v[2:5]
	v_mfma_f32_16x16x32_bf16 v[46:49], v[168:171], v[184:187], v[46:49]
	v_mfma_f32_16x16x32_bf16 v[42:45], v[176:179], v[184:187], v[42:45]
	v_mfma_f32_16x16x32_bf16 v[30:33], v[168:171], v[192:195], v[30:33]
	v_mfma_f32_16x16x32_bf16 v[26:29], v[176:179], v[192:195], v[26:29]
	v_mfma_f32_16x16x32_bf16 v[14:17], v[168:171], v[200:203], v[14:17]
	v_mfma_f32_16x16x32_bf16 v[10:13], v[176:179], v[200:203], v[10:13]
	v_mfma_f32_16x16x32_bf16 v[6:9], v[168:171], v[210:213], v[6:9]
	v_mfma_f32_16x16x32_bf16 v[2:5], v[176:179], v[210:213], v[2:5]
	s_setprio 0
	s_barrier
	s_add_i32 s70, 0, 0x18000
	v_add_u32_e32 v147, s70, v143
	s_add_i32 s71, 0, 0x1c000
	ds_read_b128 v[148:151], v147
	ds_read_b128 v[152:155], v147 offset:1024
	ds_read_b128 v[156:159], v147 offset:2048
	ds_read_b128 v[160:163], v147 offset:3072
	v_add_u32_e32 v147, s71, v143
	ds_read_b128 v[164:167], v147
	ds_read_b128 v[168:171], v147 offset:1024
	ds_read_b128 v[172:175], v147 offset:2048
	ds_read_b128 v[176:179], v147 offset:3072
	s_add_u32 s42, s42, 0x20000
	s_addc_u32 s43, s43, 0
	s_mov_b32 m0, s25
	v_lshl_add_u64 v[222:223], s[42:43], 0, v[136:137]
	ds_read_b128 v[180:183], v146 offset:32768
	ds_read_b128 v[184:187], v146 offset:33792
	ds_read_b128 v[188:191], v146 offset:34816
	ds_read_b128 v[192:195], v146 offset:35840
	ds_read_b128 v[196:199], v146 offset:36864
	ds_read_b128 v[200:203], v146 offset:37888
	ds_read_b128 v[206:209], v146 offset:38912
	ds_read_b128 v[210:213], v146 offset:39936
	global_load_lds_dwordx4 v[222:223], off
	s_mov_b32 m0, s28
	v_lshl_add_u64 v[222:223], s[42:43], 0, v[132:133]
	global_load_lds_dwordx4 v[222:223], off
	s_waitcnt vmcnt(8) lgkmcnt(0)
	s_setprio 1
	s_barrier
	v_mfma_f32_16x16x32_bf16 v[126:129], v[148:151], v[180:183], v[126:129]
	v_mfma_f32_16x16x32_bf16 v[122:125], v[156:159], v[180:183], v[122:125]
	v_mfma_f32_16x16x32_bf16 v[118:121], v[148:151], v[188:191], v[118:121]
	v_mfma_f32_16x16x32_bf16 v[114:117], v[156:159], v[188:191], v[114:117]
	v_mfma_f32_16x16x32_bf16 v[102:105], v[148:151], v[196:199], v[102:105]
	v_mfma_f32_16x16x32_bf16 v[98:101], v[156:159], v[196:199], v[98:101]
	v_mfma_f32_16x16x32_bf16 v[86:89], v[148:151], v[206:209], v[86:89]
	v_mfma_f32_16x16x32_bf16 v[82:85], v[156:159], v[206:209], v[82:85]
	v_mfma_f32_16x16x32_bf16 v[126:129], v[152:155], v[184:187], v[126:129]
	v_mfma_f32_16x16x32_bf16 v[122:125], v[160:163], v[184:187], v[122:125]
	v_mfma_f32_16x16x32_bf16 v[118:121], v[152:155], v[192:195], v[118:121]
	v_mfma_f32_16x16x32_bf16 v[114:117], v[160:163], v[192:195], v[114:117]
	v_mfma_f32_16x16x32_bf16 v[102:105], v[152:155], v[200:203], v[102:105]
	v_mfma_f32_16x16x32_bf16 v[98:101], v[160:163], v[200:203], v[98:101]
	v_mfma_f32_16x16x32_bf16 v[86:89], v[152:155], v[210:213], v[86:89]
	v_mfma_f32_16x16x32_bf16 v[82:85], v[160:163], v[210:213], v[82:85]
	v_mfma_f32_16x16x32_bf16 v[110:113], v[164:167], v[180:183], v[110:113]
	v_mfma_f32_16x16x32_bf16 v[106:109], v[172:175], v[180:183], v[106:109]
	v_mfma_f32_16x16x32_bf16 v[94:97], v[164:167], v[188:191], v[94:97]
	v_mfma_f32_16x16x32_bf16 v[90:93], v[172:175], v[188:191], v[90:93]
	v_mfma_f32_16x16x32_bf16 v[78:81], v[164:167], v[196:199], v[78:81]
	v_mfma_f32_16x16x32_bf16 v[74:77], v[172:175], v[196:199], v[74:77]
	v_mfma_f32_16x16x32_bf16 v[70:73], v[164:167], v[206:209], v[70:73]
	v_mfma_f32_16x16x32_bf16 v[66:69], v[172:175], v[206:209], v[66:69]
	v_mfma_f32_16x16x32_bf16 v[110:113], v[168:171], v[184:187], v[110:113]
	v_mfma_f32_16x16x32_bf16 v[106:109], v[176:179], v[184:187], v[106:109]
	v_mfma_f32_16x16x32_bf16 v[94:97], v[168:171], v[192:195], v[94:97]
	v_mfma_f32_16x16x32_bf16 v[90:93], v[176:179], v[192:195], v[90:93]
	v_mfma_f32_16x16x32_bf16 v[78:81], v[168:171], v[200:203], v[78:81]
	v_mfma_f32_16x16x32_bf16 v[74:77], v[176:179], v[200:203], v[74:77]
	v_mfma_f32_16x16x32_bf16 v[70:73], v[168:171], v[210:213], v[70:73]
	v_mfma_f32_16x16x32_bf16 v[66:69], v[176:179], v[210:213], v[66:69]
	s_setprio 0
	s_barrier
	s_add_i32 s42, s70, s18
	s_mov_b32 m0, s42
	v_lshl_add_u64 v[214:215], v[214:215], 0, s[8:9]
	global_load_lds_dwordx4 v[214:215], off
	ds_read_b128 v[180:183], v146 offset:49152
	ds_read_b128 v[184:187], v146 offset:50176
	ds_read_b128 v[188:191], v146 offset:51200
	ds_read_b128 v[192:195], v146 offset:52224
	ds_read_b128 v[196:199], v146 offset:53248
	ds_read_b128 v[200:203], v146 offset:54272
	ds_read_b128 v[206:209], v146 offset:55296
	ds_read_b128 v[210:213], v146 offset:56320
	s_add_i32 m0, s42, 0x2000
	s_add_u32 s38, s38, 0x200080
	v_lshl_add_u64 v[214:215], v[216:217], 0, s[8:9]
	s_addc_u32 s39, s39, 0
	s_add_i32 s42, s71, s18
	global_load_lds_dwordx4 v[214:215], off
	s_mov_b32 m0, s42
	v_lshl_add_u64 v[214:215], s[38:39], 0, v[134:135]
	global_load_lds_dwordx4 v[214:215], off
	s_add_i32 m0, s42, 0x2000
	v_lshl_add_u64 v[214:215], s[38:39], 0, v[130:131]
	global_load_lds_dwordx4 v[214:215], off
	s_mov_b32 m0, s33
	v_lshl_add_u64 v[214:215], v[218:219], 0, s[8:9]
	global_load_lds_dwordx4 v[214:215], off
	s_mov_b32 m0, s34
	v_lshl_add_u64 v[214:215], v[220:221], 0, s[8:9]
	global_load_lds_dwordx4 v[214:215], off
	s_waitcnt vmcnt(8) lgkmcnt(0)
	s_setprio 1
	s_barrier
	v_mfma_f32_16x16x32_bf16 v[62:65], v[148:151], v[180:183], v[62:65]
	v_mfma_f32_16x16x32_bf16 v[58:61], v[156:159], v[180:183], v[58:61]
	v_mfma_f32_16x16x32_bf16 v[54:57], v[148:151], v[188:191], v[54:57]
	v_mfma_f32_16x16x32_bf16 v[50:53], v[156:159], v[188:191], v[50:53]
	v_mfma_f32_16x16x32_bf16 v[38:41], v[148:151], v[196:199], v[38:41]
	v_mfma_f32_16x16x32_bf16 v[34:37], v[156:159], v[196:199], v[34:37]
	v_mfma_f32_16x16x32_bf16 v[22:25], v[148:151], v[206:209], v[22:25]
	v_mfma_f32_16x16x32_bf16 v[18:21], v[156:159], v[206:209], v[18:21]
	v_mfma_f32_16x16x32_bf16 v[62:65], v[152:155], v[184:187], v[62:65]
	v_mfma_f32_16x16x32_bf16 v[58:61], v[160:163], v[184:187], v[58:61]
	v_mfma_f32_16x16x32_bf16 v[54:57], v[152:155], v[192:195], v[54:57]
	v_mfma_f32_16x16x32_bf16 v[50:53], v[160:163], v[192:195], v[50:53]
	v_mfma_f32_16x16x32_bf16 v[38:41], v[152:155], v[200:203], v[38:41]
	v_mfma_f32_16x16x32_bf16 v[34:37], v[160:163], v[200:203], v[34:37]
	v_mfma_f32_16x16x32_bf16 v[22:25], v[152:155], v[210:213], v[22:25]
	v_mfma_f32_16x16x32_bf16 v[18:21], v[160:163], v[210:213], v[18:21]
	v_mfma_f32_16x16x32_bf16 v[46:49], v[164:167], v[180:183], v[46:49]
	v_mfma_f32_16x16x32_bf16 v[42:45], v[172:175], v[180:183], v[42:45]
	v_mfma_f32_16x16x32_bf16 v[30:33], v[164:167], v[188:191], v[30:33]
	v_mfma_f32_16x16x32_bf16 v[26:29], v[172:175], v[188:191], v[26:29]
	v_mfma_f32_16x16x32_bf16 v[14:17], v[164:167], v[196:199], v[14:17]
	v_mfma_f32_16x16x32_bf16 v[10:13], v[172:175], v[196:199], v[10:13]
	v_mfma_f32_16x16x32_bf16 v[6:9], v[164:167], v[206:209], v[6:9]
	v_mfma_f32_16x16x32_bf16 v[2:5], v[172:175], v[206:209], v[2:5]
	v_mfma_f32_16x16x32_bf16 v[46:49], v[168:171], v[184:187], v[46:49]
	v_mfma_f32_16x16x32_bf16 v[42:45], v[176:179], v[184:187], v[42:45]
	v_mfma_f32_16x16x32_bf16 v[30:33], v[168:171], v[192:195], v[30:33]
	v_mfma_f32_16x16x32_bf16 v[26:29], v[176:179], v[192:195], v[26:29]
	v_mfma_f32_16x16x32_bf16 v[14:17], v[168:171], v[200:203], v[14:17]
	v_mfma_f32_16x16x32_bf16 v[10:13], v[176:179], v[200:203], v[10:13]
	v_mfma_f32_16x16x32_bf16 v[6:9], v[168:171], v[210:213], v[6:9]
	v_mfma_f32_16x16x32_bf16 v[2:5], v[176:179], v[210:213], v[2:5]
	s_setprio 0
	s_barrier
	s_add_i32 s69, s69, 2
	s_add_u32 s36, s36, 0x100
	s_addc_u32 s37, s37, 0
	s_add_u32 s67, s67, 0x100
	s_addc_u32 s68, s68, 0
	s_cmp_gt_u32 s69, 5
	s_cbranch_scc0 .LBB0_477
	s_and_b64 vcc, exec, s[10:11]
	s_cbranch_vccz .LBB0_480
	s_barrier

.LBB0_565:
	v_readlane_b32 s62, v249, 27
	v_readlane_b32 s63, v249, 28
	s_add_u32 s72, s62, s68
	s_addc_u32 s73, s63, s69
	s_and_b64 s[62:63], s[70:71], exec
	s_cselect_b32 s31, s73, s77
	s_cselect_b32 s33, s72, s76
	s_add_u32 s74, s35, s66
	s_addc_u32 s75, s85, s67
	s_and_b64 s[62:63], s[70:71], exec
	s_cselect_b32 s34, s75, s79
	s_cselect_b32 s39, s74, s78
	s_add_i32 s45, s7, -2
	s_add_u32 s76, s76, 0x40080
	s_addc_u32 s77, s77, 0
	s_add_u32 s47, s78, 0x100
	s_addc_u32 s62, s79, 0
	s_mov_b32 s63, 0
	s_waitcnt vmcnt(0)
	ds_read_b128 v[114:117], v190
	ds_read_b128 v[118:121], v190 offset:1024
	ds_read_b128 v[122:125], v190 offset:2048
	ds_read_b128 v[126:129], v190 offset:3072
	ds_read_b128 v[146:149], v191
	ds_read_b128 v[150:153], v191 offset:1024
	ds_read_b128 v[154:157], v191 offset:2048
	ds_read_b128 v[158:161], v191 offset:3072
	s_add_i32 s82, s63, 2
	s_add_u32 s78, s76, 0xfffc0080
	s_addc_u32 s79, s77, -1
	s_cmp_eq_u32 s45, s63
	s_cselect_b32 s81, s31, s79
	s_cselect_b32 s80, s33, s78
	s_cselect_b32 s79, s34, s62
	s_cselect_b32 s78, s39, s47
	v_lshl_add_u64 v[186:187], s[76:77], 0, v[180:181]
	s_add_i32 m0, s87, 0xc000
	ds_read_b128 v[162:165], v192
	ds_read_b128 v[166:169], v192 offset:1024
	ds_read_b128 v[194:197], v192 offset:2048
	ds_read_b128 v[198:201], v192 offset:3072
	ds_read_b128 v[206:209], v192 offset:4096
	ds_read_b128 v[210:213], v192 offset:5120
	ds_read_b128 v[214:217], v192 offset:6144
	ds_read_b128 v[218:221], v192 offset:7168
	global_load_lds_dwordx4 v[186:187], off
	s_add_i32 m0, s87, 0xe000
	v_lshl_add_u64 v[186:187], s[76:77], 0, v[182:183]
	global_load_lds_dwordx4 v[186:187], off
	s_waitcnt vmcnt(8)
	s_waitcnt lgkmcnt(0)
	s_setprio 1
	s_barrier
	v_mfma_f32_16x16x32_bf16 v[142:145], v[114:117], v[162:165], 0
	v_mfma_f32_16x16x32_bf16 v[138:141], v[122:125], v[162:165], 0
	v_mfma_f32_16x16x32_bf16 v[110:113], v[114:117], v[194:197], 0
	v_mfma_f32_16x16x32_bf16 v[106:109], v[122:125], v[194:197], 0
	v_mfma_f32_16x16x32_bf16 v[98:101], v[114:117], v[206:209], 0
	v_mfma_f32_16x16x32_bf16 v[90:93], v[122:125], v[206:209], 0
	v_mfma_f32_16x16x32_bf16 v[82:85], v[114:117], v[214:217], 0
	v_mfma_f32_16x16x32_bf16 v[74:77], v[122:125], v[214:217], 0
	v_mfma_f32_16x16x32_bf16 v[142:145], v[118:121], v[166:169], v[142:145]
	v_mfma_f32_16x16x32_bf16 v[138:141], v[126:129], v[166:169], v[138:141]
	v_mfma_f32_16x16x32_bf16 v[110:113], v[118:121], v[198:201], v[110:113]
	v_mfma_f32_16x16x32_bf16 v[106:109], v[126:129], v[198:201], v[106:109]
	v_mfma_f32_16x16x32_bf16 v[98:101], v[118:121], v[210:213], v[98:101]
	v_mfma_f32_16x16x32_bf16 v[90:93], v[126:129], v[210:213], v[90:93]
	v_mfma_f32_16x16x32_bf16 v[82:85], v[118:121], v[218:221], v[82:85]
	v_mfma_f32_16x16x32_bf16 v[74:77], v[126:129], v[218:221], v[74:77]
	v_mfma_f32_16x16x32_bf16 v[134:137], v[146:149], v[162:165], 0
	v_mfma_f32_16x16x32_bf16 v[130:133], v[154:157], v[162:165], 0
	v_mfma_f32_16x16x32_bf16 v[102:105], v[146:149], v[194:197], 0
	v_mfma_f32_16x16x32_bf16 v[94:97], v[154:157], v[194:197], 0
	v_mfma_f32_16x16x32_bf16 v[86:89], v[146:149], v[206:209], 0
	v_mfma_f32_16x16x32_bf16 v[78:81], v[154:157], v[206:209], 0
	v_mfma_f32_16x16x32_bf16 v[70:73], v[146:149], v[214:217], 0
	v_mfma_f32_16x16x32_bf16 v[66:69], v[154:157], v[214:217], 0
	v_mfma_f32_16x16x32_bf16 v[134:137], v[150:153], v[166:169], v[134:137]
	v_mfma_f32_16x16x32_bf16 v[130:133], v[158:161], v[166:169], v[130:133]
	v_mfma_f32_16x16x32_bf16 v[102:105], v[150:153], v[198:201], v[102:105]
	v_mfma_f32_16x16x32_bf16 v[94:97], v[158:161], v[198:201], v[94:97]
	v_mfma_f32_16x16x32_bf16 v[86:89], v[150:153], v[210:213], v[86:89]
	v_mfma_f32_16x16x32_bf16 v[78:81], v[158:161], v[210:213], v[78:81]
	v_mfma_f32_16x16x32_bf16 v[70:73], v[150:153], v[218:221], v[70:73]
	v_mfma_f32_16x16x32_bf16 v[66:69], v[158:161], v[218:221], v[66:69]
	s_setprio 0
	s_barrier
	s_add_i32 s63, s24, s86
	s_mov_b32 m0, s63
	v_lshl_add_u64 v[186:187], s[78:79], 0, v[172:173]
	global_load_lds_dwordx4 v[186:187], off
	ds_read_b128 v[162:165], v192 offset:16384
	ds_read_b128 v[166:169], v192 offset:17408
	ds_read_b128 v[194:197], v192 offset:18432
	ds_read_b128 v[198:201], v192 offset:19456
	ds_read_b128 v[206:209], v192 offset:20480
	ds_read_b128 v[210:213], v192 offset:21504
	ds_read_b128 v[214:217], v192 offset:22528
	ds_read_b128 v[218:221], v192 offset:23552
	s_add_i32 m0, s63, 0x2000
	s_add_u32 vcc_lo, s78, 0x40000
	v_lshl_add_u64 v[202:203], s[78:79], 0, v[176:177]
	s_addc_u32 vcc_hi, s79, 0
	s_add_i32 s63, s25, s86
	global_load_lds_dwordx4 v[202:203], off
	v_lshl_add_u64 v[222:223], vcc, 0, v[172:173]
	s_mov_b32 m0, s63
	v_lshl_add_u64 v[224:225], s[80:81], 0, v[174:175]
	global_load_lds_dwordx4 v[222:223], off
	s_add_i32 m0, s63, 0x2000
	v_lshl_add_u64 v[222:223], vcc, 0, v[176:177]
	global_load_lds_dwordx4 v[222:223], off
	s_mov_b32 m0, s87
	v_lshl_add_u64 v[222:223], s[80:81], 0, v[170:171]
	global_load_lds_dwordx4 v[222:223], off
	s_mov_b32 m0, s88
	s_nop 0
	global_load_lds_dwordx4 v[224:225], off
	s_waitcnt vmcnt(8) lgkmcnt(0)
	s_setprio 1
	s_barrier
	v_mfma_f32_16x16x32_bf16 v[62:65], v[114:117], v[162:165], 0
	v_mfma_f32_16x16x32_bf16 v[58:61], v[122:125], v[162:165], 0
	v_mfma_f32_16x16x32_bf16 v[50:53], v[114:117], v[194:197], 0
	v_mfma_f32_16x16x32_bf16 v[42:45], v[122:125], v[194:197], 0
	v_mfma_f32_16x16x32_bf16 v[34:37], v[114:117], v[206:209], 0
	v_mfma_f32_16x16x32_bf16 v[26:29], v[122:125], v[206:209], 0
	v_mfma_f32_16x16x32_bf16 v[18:21], v[114:117], v[214:217], 0
	v_mfma_f32_16x16x32_bf16 v[10:13], v[122:125], v[214:217], 0
	v_mfma_f32_16x16x32_bf16 v[62:65], v[118:121], v[166:169], v[62:65]
	v_mfma_f32_16x16x32_bf16 v[58:61], v[126:129], v[166:169], v[58:61]
	v_mfma_f32_16x16x32_bf16 v[50:53], v[118:121], v[198:201], v[50:53]
	v_mfma_f32_16x16x32_bf16 v[42:45], v[126:129], v[198:201], v[42:45]
	v_mfma_f32_16x16x32_bf16 v[34:37], v[118:121], v[210:213], v[34:37]
	v_mfma_f32_16x16x32_bf16 v[26:29], v[126:129], v[210:213], v[26:29]
	v_mfma_f32_16x16x32_bf16 v[18:21], v[118:121], v[218:221], v[18:21]
	v_mfma_f32_16x16x32_bf16 v[10:13], v[126:129], v[218:221], v[10:13]
	v_mfma_f32_16x16x32_bf16 v[54:57], v[146:149], v[162:165], 0
	v_mfma_f32_16x16x32_bf16 v[46:49], v[154:157], v[162:165], 0
	v_mfma_f32_16x16x32_bf16 v[38:41], v[146:149], v[194:197], 0
	v_mfma_f32_16x16x32_bf16 v[30:33], v[154:157], v[194:197], 0
	v_mfma_f32_16x16x32_bf16 v[22:25], v[146:149], v[206:209], 0
	v_mfma_f32_16x16x32_bf16 v[14:17], v[154:157], v[206:209], 0
	v_mfma_f32_16x16x32_bf16 v[6:9], v[146:149], v[214:217], 0
	v_mfma_f32_16x16x32_bf16 v[2:5], v[154:157], v[214:217], 0
	v_mfma_f32_16x16x32_bf16 v[54:57], v[150:153], v[166:169], v[54:57]
	v_mfma_f32_16x16x32_bf16 v[46:49], v[158:161], v[166:169], v[46:49]
	v_mfma_f32_16x16x32_bf16 v[38:41], v[150:153], v[198:201], v[38:41]
	v_mfma_f32_16x16x32_bf16 v[30:33], v[158:161], v[198:201], v[30:33]
	v_mfma_f32_16x16x32_bf16 v[22:25], v[150:153], v[210:213], v[22:25]
	v_mfma_f32_16x16x32_bf16 v[14:17], v[158:161], v[210:213], v[14:17]
	v_mfma_f32_16x16x32_bf16 v[6:9], v[150:153], v[218:221], v[6:9]
	v_mfma_f32_16x16x32_bf16 v[2:5], v[158:161], v[218:221], v[2:5]
	s_setprio 0
	s_barrier
	s_add_i32 s63, 0, 0x18000
	s_add_i32 s83, 0, 0x1c000
	v_add_u32_e32 v126, s63, v189
	v_add_u32_e32 v158, s83, v189
	ds_read_b128 v[114:117], v126
	ds_read_b128 v[118:121], v126 offset:1024
	ds_read_b128 v[122:125], v126 offset:2048
	ds_read_b128 v[126:129], v126 offset:3072
	ds_read_b128 v[146:149], v158
	ds_read_b128 v[150:153], v158 offset:1024
	ds_read_b128 v[154:157], v158 offset:2048
	ds_read_b128 v[158:161], v158 offset:3072
	s_add_u32 s80, s80, 0x40000
	s_addc_u32 s81, s81, 0
	s_mov_b32 m0, s89
	v_lshl_add_u64 v[226:227], s[80:81], 0, v[170:171]
	ds_read_b128 v[162:165], v192 offset:32768
	ds_read_b128 v[166:169], v192 offset:33792
	ds_read_b128 v[194:197], v192 offset:34816
	ds_read_b128 v[198:201], v192 offset:35840
	ds_read_b128 v[206:209], v192 offset:36864
	ds_read_b128 v[210:213], v192 offset:37888
	ds_read_b128 v[214:217], v192 offset:38912
	ds_read_b128 v[218:221], v192 offset:39936
	global_load_lds_dwordx4 v[226:227], off
	s_mov_b32 m0, s90
	v_lshl_add_u64 v[226:227], s[80:81], 0, v[174:175]
	global_load_lds_dwordx4 v[226:227], off
	s_waitcnt vmcnt(8) lgkmcnt(0)
	s_setprio 1
	s_barrier
	v_mfma_f32_16x16x32_bf16 v[142:145], v[114:117], v[162:165], v[142:145]
	v_mfma_f32_16x16x32_bf16 v[138:141], v[122:125], v[162:165], v[138:141]
	v_mfma_f32_16x16x32_bf16 v[110:113], v[114:117], v[194:197], v[110:113]
	v_mfma_f32_16x16x32_bf16 v[106:109], v[122:125], v[194:197], v[106:109]
	v_mfma_f32_16x16x32_bf16 v[98:101], v[114:117], v[206:209], v[98:101]
	v_mfma_f32_16x16x32_bf16 v[90:93], v[122:125], v[206:209], v[90:93]
	v_mfma_f32_16x16x32_bf16 v[82:85], v[114:117], v[214:217], v[82:85]
	v_mfma_f32_16x16x32_bf16 v[74:77], v[122:125], v[214:217], v[74:77]
	v_mfma_f32_16x16x32_bf16 v[142:145], v[118:121], v[166:169], v[142:145]
	v_mfma_f32_16x16x32_bf16 v[138:141], v[126:129], v[166:169], v[138:141]
	v_mfma_f32_16x16x32_bf16 v[110:113], v[118:121], v[198:201], v[110:113]
	v_mfma_f32_16x16x32_bf16 v[106:109], v[126:129], v[198:201], v[106:109]
	v_mfma_f32_16x16x32_bf16 v[98:101], v[118:121], v[210:213], v[98:101]
	v_mfma_f32_16x16x32_bf16 v[90:93], v[126:129], v[210:213], v[90:93]
	v_mfma_f32_16x16x32_bf16 v[82:85], v[118:121], v[218:221], v[82:85]
	v_mfma_f32_16x16x32_bf16 v[74:77], v[126:129], v[218:221], v[74:77]
	v_mfma_f32_16x16x32_bf16 v[134:137], v[146:149], v[162:165], v[134:137]
	v_mfma_f32_16x16x32_bf16 v[130:133], v[154:157], v[162:165], v[130:133]
	v_mfma_f32_16x16x32_bf16 v[102:105], v[146:149], v[194:197], v[102:105]
	v_mfma_f32_16x16x32_bf16 v[94:97], v[154:157], v[194:197], v[94:97]
	v_mfma_f32_16x16x32_bf16 v[86:89], v[146:149], v[206:209], v[86:89]
	v_mfma_f32_16x16x32_bf16 v[78:81], v[154:157], v[206:209], v[78:81]
	v_mfma_f32_16x16x32_bf16 v[70:73], v[146:149], v[214:217], v[70:73]
	v_mfma_f32_16x16x32_bf16 v[66:69], v[154:157], v[214:217], v[66:69]
	v_mfma_f32_16x16x32_bf16 v[134:137], v[150:153], v[166:169], v[134:137]
	v_mfma_f32_16x16x32_bf16 v[130:133], v[158:161], v[166:169], v[130:133]
	v_mfma_f32_16x16x32_bf16 v[102:105], v[150:153], v[198:201], v[102:105]
	v_mfma_f32_16x16x32_bf16 v[94:97], v[158:161], v[198:201], v[94:97]
	v_mfma_f32_16x16x32_bf16 v[86:89], v[150:153], v[210:213], v[86:89]
	v_mfma_f32_16x16x32_bf16 v[78:81], v[158:161], v[210:213], v[78:81]
	v_mfma_f32_16x16x32_bf16 v[70:73], v[150:153], v[218:221], v[70:73]
	v_mfma_f32_16x16x32_bf16 v[66:69], v[158:161], v[218:221], v[66:69]
	s_setprio 0
	s_barrier
	s_add_i32 s63, s63, s86
	s_mov_b32 m0, s63
	v_lshl_add_u64 v[186:187], v[186:187], 0, s[22:23]
	global_load_lds_dwordx4 v[186:187], off
	ds_read_b128 v[162:165], v192 offset:49152
	ds_read_b128 v[166:169], v192 offset:50176
	ds_read_b128 v[194:197], v192 offset:51200
	ds_read_b128 v[198:201], v192 offset:52224
	ds_read_b128 v[206:209], v192 offset:53248
	ds_read_b128 v[210:213], v192 offset:54272
	ds_read_b128 v[214:217], v192 offset:55296
	ds_read_b128 v[218:221], v192 offset:56320
	s_add_i32 m0, s63, 0x2000
	s_add_u32 s78, s78, 0x40080
	v_lshl_add_u64 v[186:187], v[202:203], 0, s[22:23]
	s_addc_u32 s79, s79, 0
	s_add_i32 s63, s83, s86
	global_load_lds_dwordx4 v[186:187], off
	s_mov_b32 m0, s63
	v_lshl_add_u64 v[186:187], s[78:79], 0, v[172:173]
	global_load_lds_dwordx4 v[186:187], off
	s_add_i32 m0, s63, 0x2000
	v_lshl_add_u64 v[186:187], s[78:79], 0, v[176:177]
	global_load_lds_dwordx4 v[186:187], off
	s_mov_b32 m0, s95
	v_lshl_add_u64 v[186:187], v[222:223], 0, s[22:23]
	global_load_lds_dwordx4 v[186:187], off
	s_mov_b32 m0, s96
	v_lshl_add_u64 v[186:187], v[224:225], 0, s[22:23]
	global_load_lds_dwordx4 v[186:187], off
	s_waitcnt vmcnt(8) lgkmcnt(0)
	s_setprio 1
	s_barrier
	v_mfma_f32_16x16x32_bf16 v[62:65], v[114:117], v[162:165], v[62:65]
	v_mfma_f32_16x16x32_bf16 v[58:61], v[122:125], v[162:165], v[58:61]
	v_mfma_f32_16x16x32_bf16 v[50:53], v[114:117], v[194:197], v[50:53]
	v_mfma_f32_16x16x32_bf16 v[42:45], v[122:125], v[194:197], v[42:45]
	v_mfma_f32_16x16x32_bf16 v[34:37], v[114:117], v[206:209], v[34:37]
	v_mfma_f32_16x16x32_bf16 v[26:29], v[122:125], v[206:209], v[26:29]
	v_mfma_f32_16x16x32_bf16 v[18:21], v[114:117], v[214:217], v[18:21]
	v_mfma_f32_16x16x32_bf16 v[10:13], v[122:125], v[214:217], v[10:13]
	v_mfma_f32_16x16x32_bf16 v[62:65], v[118:121], v[166:169], v[62:65]
	v_mfma_f32_16x16x32_bf16 v[58:61], v[126:129], v[166:169], v[58:61]
	v_mfma_f32_16x16x32_bf16 v[50:53], v[118:121], v[198:201], v[50:53]
	v_mfma_f32_16x16x32_bf16 v[42:45], v[126:129], v[198:201], v[42:45]
	v_mfma_f32_16x16x32_bf16 v[34:37], v[118:121], v[210:213], v[34:37]
	v_mfma_f32_16x16x32_bf16 v[26:29], v[126:129], v[210:213], v[26:29]
	v_mfma_f32_16x16x32_bf16 v[18:21], v[118:121], v[218:221], v[18:21]
	v_mfma_f32_16x16x32_bf16 v[10:13], v[126:129], v[218:221], v[10:13]
	v_mfma_f32_16x16x32_bf16 v[54:57], v[146:149], v[162:165], v[54:57]
	v_mfma_f32_16x16x32_bf16 v[46:49], v[154:157], v[162:165], v[46:49]
	v_mfma_f32_16x16x32_bf16 v[38:41], v[146:149], v[194:197], v[38:41]
	v_mfma_f32_16x16x32_bf16 v[30:33], v[154:157], v[194:197], v[30:33]
	v_mfma_f32_16x16x32_bf16 v[22:25], v[146:149], v[206:209], v[22:25]
	v_mfma_f32_16x16x32_bf16 v[14:17], v[154:157], v[206:209], v[14:17]
	v_mfma_f32_16x16x32_bf16 v[6:9], v[146:149], v[214:217], v[6:9]
	v_mfma_f32_16x16x32_bf16 v[2:5], v[154:157], v[214:217], v[2:5]
	v_mfma_f32_16x16x32_bf16 v[54:57], v[150:153], v[166:169], v[54:57]
	v_mfma_f32_16x16x32_bf16 v[46:49], v[158:161], v[166:169], v[46:49]
	v_mfma_f32_16x16x32_bf16 v[38:41], v[150:153], v[198:201], v[38:41]
	v_mfma_f32_16x16x32_bf16 v[30:33], v[158:161], v[198:201], v[30:33]
	v_mfma_f32_16x16x32_bf16 v[22:25], v[150:153], v[210:213], v[22:25]
	v_mfma_f32_16x16x32_bf16 v[14:17], v[158:161], v[210:213], v[14:17]
	v_mfma_f32_16x16x32_bf16 v[6:9], v[150:153], v[218:221], v[6:9]
	v_mfma_f32_16x16x32_bf16 v[2:5], v[158:161], v[218:221], v[2:5]
	s_setprio 0
	s_barrier
	s_add_u32 s76, s76, 0x100
	s_addc_u32 s77, s77, 0
	s_add_u32 s47, s47, 0x100
	s_addc_u32 s62, s62, 0
	s_cmp_ge_i32 s82, s7
	s_mov_b32 s63, s82
.LBB0_566:
	s_waitcnt vmcnt(0)
	ds_read_b128 v[114:117], v190
	ds_read_b128 v[118:121], v190 offset:1024
	ds_read_b128 v[122:125], v190 offset:2048
	ds_read_b128 v[126:129], v190 offset:3072
	ds_read_b128 v[146:149], v191
	ds_read_b128 v[150:153], v191 offset:1024
	ds_read_b128 v[154:157], v191 offset:2048
	ds_read_b128 v[158:161], v191 offset:3072
	s_add_i32 s82, s63, 2
	s_add_u32 s78, s76, 0xfffc0080
	s_addc_u32 s79, s77, -1
	s_cmp_eq_u32 s45, s63
	s_cselect_b32 s81, s31, s79
	s_cselect_b32 s80, s33, s78
	s_cselect_b32 s79, s34, s62
	s_cselect_b32 s78, s39, s47
	v_lshl_add_u64 v[186:187], s[76:77], 0, v[180:181]
	s_add_i32 m0, s87, 0xc000
	ds_read_b128 v[162:165], v192
	ds_read_b128 v[166:169], v192 offset:1024
	ds_read_b128 v[194:197], v192 offset:2048
	ds_read_b128 v[198:201], v192 offset:3072
	ds_read_b128 v[206:209], v192 offset:4096
	ds_read_b128 v[210:213], v192 offset:5120
	ds_read_b128 v[214:217], v192 offset:6144
	ds_read_b128 v[218:221], v192 offset:7168
	global_load_lds_dwordx4 v[186:187], off
	s_add_i32 m0, s87, 0xe000
	v_lshl_add_u64 v[186:187], s[76:77], 0, v[182:183]
	global_load_lds_dwordx4 v[186:187], off
	s_waitcnt vmcnt(8)
	s_waitcnt lgkmcnt(0)
	s_setprio 1
	s_barrier
	v_mfma_f32_16x16x32_bf16 v[142:145], v[114:117], v[162:165], v[142:145]
	v_mfma_f32_16x16x32_bf16 v[138:141], v[122:125], v[162:165], v[138:141]
	v_mfma_f32_16x16x32_bf16 v[110:113], v[114:117], v[194:197], v[110:113]
	v_mfma_f32_16x16x32_bf16 v[106:109], v[122:125], v[194:197], v[106:109]
	v_mfma_f32_16x16x32_bf16 v[98:101], v[114:117], v[206:209], v[98:101]
	v_mfma_f32_16x16x32_bf16 v[90:93], v[122:125], v[206:209], v[90:93]
	v_mfma_f32_16x16x32_bf16 v[82:85], v[114:117], v[214:217], v[82:85]
	v_mfma_f32_16x16x32_bf16 v[74:77], v[122:125], v[214:217], v[74:77]
	v_mfma_f32_16x16x32_bf16 v[142:145], v[118:121], v[166:169], v[142:145]
	v_mfma_f32_16x16x32_bf16 v[138:141], v[126:129], v[166:169], v[138:141]
	v_mfma_f32_16x16x32_bf16 v[110:113], v[118:121], v[198:201], v[110:113]
	v_mfma_f32_16x16x32_bf16 v[106:109], v[126:129], v[198:201], v[106:109]
	v_mfma_f32_16x16x32_bf16 v[98:101], v[118:121], v[210:213], v[98:101]
	v_mfma_f32_16x16x32_bf16 v[90:93], v[126:129], v[210:213], v[90:93]
	v_mfma_f32_16x16x32_bf16 v[82:85], v[118:121], v[218:221], v[82:85]
	v_mfma_f32_16x16x32_bf16 v[74:77], v[126:129], v[218:221], v[74:77]
	v_mfma_f32_16x16x32_bf16 v[134:137], v[146:149], v[162:165], v[134:137]
	v_mfma_f32_16x16x32_bf16 v[130:133], v[154:157], v[162:165], v[130:133]
	v_mfma_f32_16x16x32_bf16 v[102:105], v[146:149], v[194:197], v[102:105]
	v_mfma_f32_16x16x32_bf16 v[94:97], v[154:157], v[194:197], v[94:97]
	v_mfma_f32_16x16x32_bf16 v[86:89], v[146:149], v[206:209], v[86:89]
	v_mfma_f32_16x16x32_bf16 v[78:81], v[154:157], v[206:209], v[78:81]
	v_mfma_f32_16x16x32_bf16 v[70:73], v[146:149], v[214:217], v[70:73]
	v_mfma_f32_16x16x32_bf16 v[66:69], v[154:157], v[214:217], v[66:69]
	v_mfma_f32_16x16x32_bf16 v[134:137], v[150:153], v[166:169], v[134:137]
	v_mfma_f32_16x16x32_bf16 v[130:133], v[158:161], v[166:169], v[130:133]
	v_mfma_f32_16x16x32_bf16 v[102:105], v[150:153], v[198:201], v[102:105]
	v_mfma_f32_16x16x32_bf16 v[94:97], v[158:161], v[198:201], v[94:97]
	v_mfma_f32_16x16x32_bf16 v[86:89], v[150:153], v[210:213], v[86:89]
	v_mfma_f32_16x16x32_bf16 v[78:81], v[158:161], v[210:213], v[78:81]
	v_mfma_f32_16x16x32_bf16 v[70:73], v[150:153], v[218:221], v[70:73]
	v_mfma_f32_16x16x32_bf16 v[66:69], v[158:161], v[218:221], v[66:69]
	s_setprio 0
	s_barrier
	s_add_i32 s63, s24, s86
	s_mov_b32 m0, s63
	v_lshl_add_u64 v[186:187], s[78:79], 0, v[172:173]
	global_load_lds_dwordx4 v[186:187], off
	ds_read_b128 v[162:165], v192 offset:16384
	ds_read_b128 v[166:169], v192 offset:17408
	ds_read_b128 v[194:197], v192 offset:18432
	ds_read_b128 v[198:201], v192 offset:19456
	ds_read_b128 v[206:209], v192 offset:20480
	ds_read_b128 v[210:213], v192 offset:21504
	ds_read_b128 v[214:217], v192 offset:22528
	ds_read_b128 v[218:221], v192 offset:23552
	s_add_i32 m0, s63, 0x2000
	s_add_u32 vcc_lo, s78, 0x40000
	v_lshl_add_u64 v[202:203], s[78:79], 0, v[176:177]
	s_addc_u32 vcc_hi, s79, 0
	s_add_i32 s63, s25, s86
	global_load_lds_dwordx4 v[202:203], off
	v_lshl_add_u64 v[222:223], vcc, 0, v[172:173]
	s_mov_b32 m0, s63
	v_lshl_add_u64 v[224:225], s[80:81], 0, v[174:175]
	global_load_lds_dwordx4 v[222:223], off
	s_add_i32 m0, s63, 0x2000
	v_lshl_add_u64 v[222:223], vcc, 0, v[176:177]
	global_load_lds_dwordx4 v[222:223], off
	s_mov_b32 m0, s87
	v_lshl_add_u64 v[222:223], s[80:81], 0, v[170:171]
	global_load_lds_dwordx4 v[222:223], off
	s_mov_b32 m0, s88
	s_nop 0
	global_load_lds_dwordx4 v[224:225], off
	s_waitcnt vmcnt(8) lgkmcnt(0)
	s_setprio 1
	s_barrier
	v_mfma_f32_16x16x32_bf16 v[62:65], v[114:117], v[162:165], v[62:65]
	v_mfma_f32_16x16x32_bf16 v[58:61], v[122:125], v[162:165], v[58:61]
	v_mfma_f32_16x16x32_bf16 v[50:53], v[114:117], v[194:197], v[50:53]
	v_mfma_f32_16x16x32_bf16 v[42:45], v[122:125], v[194:197], v[42:45]
	v_mfma_f32_16x16x32_bf16 v[34:37], v[114:117], v[206:209], v[34:37]
	v_mfma_f32_16x16x32_bf16 v[26:29], v[122:125], v[206:209], v[26:29]
	v_mfma_f32_16x16x32_bf16 v[18:21], v[114:117], v[214:217], v[18:21]
	v_mfma_f32_16x16x32_bf16 v[10:13], v[122:125], v[214:217], v[10:13]
	v_mfma_f32_16x16x32_bf16 v[62:65], v[118:121], v[166:169], v[62:65]
	v_mfma_f32_16x16x32_bf16 v[58:61], v[126:129], v[166:169], v[58:61]
	v_mfma_f32_16x16x32_bf16 v[50:53], v[118:121], v[198:201], v[50:53]
	v_mfma_f32_16x16x32_bf16 v[42:45], v[126:129], v[198:201], v[42:45]
	v_mfma_f32_16x16x32_bf16 v[34:37], v[118:121], v[210:213], v[34:37]
	v_mfma_f32_16x16x32_bf16 v[26:29], v[126:129], v[210:213], v[26:29]
	v_mfma_f32_16x16x32_bf16 v[18:21], v[118:121], v[218:221], v[18:21]
	v_mfma_f32_16x16x32_bf16 v[10:13], v[126:129], v[218:221], v[10:13]
	v_mfma_f32_16x16x32_bf16 v[54:57], v[146:149], v[162:165], v[54:57]
	v_mfma_f32_16x16x32_bf16 v[46:49], v[154:157], v[162:165], v[46:49]
	v_mfma_f32_16x16x32_bf16 v[38:41], v[146:149], v[194:197], v[38:41]
	v_mfma_f32_16x16x32_bf16 v[30:33], v[154:157], v[194:197], v[30:33]
	v_mfma_f32_16x16x32_bf16 v[22:25], v[146:149], v[206:209], v[22:25]
	v_mfma_f32_16x16x32_bf16 v[14:17], v[154:157], v[206:209], v[14:17]
	v_mfma_f32_16x16x32_bf16 v[6:9], v[146:149], v[214:217], v[6:9]
	v_mfma_f32_16x16x32_bf16 v[2:5], v[154:157], v[214:217], v[2:5]
	v_mfma_f32_16x16x32_bf16 v[54:57], v[150:153], v[166:169], v[54:57]
	v_mfma_f32_16x16x32_bf16 v[46:49], v[158:161], v[166:169], v[46:49]
	v_mfma_f32_16x16x32_bf16 v[38:41], v[150:153], v[198:201], v[38:41]
	v_mfma_f32_16x16x32_bf16 v[30:33], v[158:161], v[198:201], v[30:33]
	v_mfma_f32_16x16x32_bf16 v[22:25], v[150:153], v[210:213], v[22:25]
	v_mfma_f32_16x16x32_bf16 v[14:17], v[158:161], v[210:213], v[14:17]
	v_mfma_f32_16x16x32_bf16 v[6:9], v[150:153], v[218:221], v[6:9]
	v_mfma_f32_16x16x32_bf16 v[2:5], v[158:161], v[218:221], v[2:5]
	s_setprio 0
	s_barrier
	s_add_i32 s63, 0, 0x18000
	s_add_i32 s83, 0, 0x1c000
	v_add_u32_e32 v126, s63, v189
	v_add_u32_e32 v158, s83, v189
	ds_read_b128 v[114:117], v126
	ds_read_b128 v[118:121], v126 offset:1024
	ds_read_b128 v[122:125], v126 offset:2048
	ds_read_b128 v[126:129], v126 offset:3072
	ds_read_b128 v[146:149], v158
	ds_read_b128 v[150:153], v158 offset:1024
	ds_read_b128 v[154:157], v158 offset:2048
	ds_read_b128 v[158:161], v158 offset:3072
	s_add_u32 s80, s80, 0x40000
	s_addc_u32 s81, s81, 0
	s_mov_b32 m0, s89
	v_lshl_add_u64 v[226:227], s[80:81], 0, v[170:171]
	ds_read_b128 v[162:165], v192 offset:32768
	ds_read_b128 v[166:169], v192 offset:33792
	ds_read_b128 v[194:197], v192 offset:34816
	ds_read_b128 v[198:201], v192 offset:35840
	ds_read_b128 v[206:209], v192 offset:36864
	ds_read_b128 v[210:213], v192 offset:37888
	ds_read_b128 v[214:217], v192 offset:38912
	ds_read_b128 v[218:221], v192 offset:39936
	global_load_lds_dwordx4 v[226:227], off
	s_mov_b32 m0, s90
	v_lshl_add_u64 v[226:227], s[80:81], 0, v[174:175]
	global_load_lds_dwordx4 v[226:227], off
	s_waitcnt vmcnt(8) lgkmcnt(0)
	s_setprio 1
	s_barrier
	v_mfma_f32_16x16x32_bf16 v[142:145], v[114:117], v[162:165], v[142:145]
	v_mfma_f32_16x16x32_bf16 v[138:141], v[122:125], v[162:165], v[138:141]
	v_mfma_f32_16x16x32_bf16 v[110:113], v[114:117], v[194:197], v[110:113]
	v_mfma_f32_16x16x32_bf16 v[106:109], v[122:125], v[194:197], v[106:109]
	v_mfma_f32_16x16x32_bf16 v[98:101], v[114:117], v[206:209], v[98:101]
	v_mfma_f32_16x16x32_bf16 v[90:93], v[122:125], v[206:209], v[90:93]
	v_mfma_f32_16x16x32_bf16 v[82:85], v[114:117], v[214:217], v[82:85]
	v_mfma_f32_16x16x32_bf16 v[74:77], v[122:125], v[214:217], v[74:77]
	v_mfma_f32_16x16x32_bf16 v[142:145], v[118:121], v[166:169], v[142:145]
	v_mfma_f32_16x16x32_bf16 v[138:141], v[126:129], v[166:169], v[138:141]
	v_mfma_f32_16x16x32_bf16 v[110:113], v[118:121], v[198:201], v[110:113]
	v_mfma_f32_16x16x32_bf16 v[106:109], v[126:129], v[198:201], v[106:109]
	v_mfma_f32_16x16x32_bf16 v[98:101], v[118:121], v[210:213], v[98:101]
	v_mfma_f32_16x16x32_bf16 v[90:93], v[126:129], v[210:213], v[90:93]
	v_mfma_f32_16x16x32_bf16 v[82:85], v[118:121], v[218:221], v[82:85]
	v_mfma_f32_16x16x32_bf16 v[74:77], v[126:129], v[218:221], v[74:77]
	v_mfma_f32_16x16x32_bf16 v[134:137], v[146:149], v[162:165], v[134:137]
	v_mfma_f32_16x16x32_bf16 v[130:133], v[154:157], v[162:165], v[130:133]
	v_mfma_f32_16x16x32_bf16 v[102:105], v[146:149], v[194:197], v[102:105]
	v_mfma_f32_16x16x32_bf16 v[94:97], v[154:157], v[194:197], v[94:97]
	v_mfma_f32_16x16x32_bf16 v[86:89], v[146:149], v[206:209], v[86:89]
	v_mfma_f32_16x16x32_bf16 v[78:81], v[154:157], v[206:209], v[78:81]
	v_mfma_f32_16x16x32_bf16 v[70:73], v[146:149], v[214:217], v[70:73]
	v_mfma_f32_16x16x32_bf16 v[66:69], v[154:157], v[214:217], v[66:69]
	v_mfma_f32_16x16x32_bf16 v[134:137], v[150:153], v[166:169], v[134:137]
	v_mfma_f32_16x16x32_bf16 v[130:133], v[158:161], v[166:169], v[130:133]
	v_mfma_f32_16x16x32_bf16 v[102:105], v[150:153], v[198:201], v[102:105]
	v_mfma_f32_16x16x32_bf16 v[94:97], v[158:161], v[198:201], v[94:97]
	v_mfma_f32_16x16x32_bf16 v[86:89], v[150:153], v[210:213], v[86:89]
	v_mfma_f32_16x16x32_bf16 v[78:81], v[158:161], v[210:213], v[78:81]
	v_mfma_f32_16x16x32_bf16 v[70:73], v[150:153], v[218:221], v[70:73]
	v_mfma_f32_16x16x32_bf16 v[66:69], v[158:161], v[218:221], v[66:69]
	s_setprio 0
	s_barrier
	s_add_i32 s63, s63, s86
	s_mov_b32 m0, s63
	v_lshl_add_u64 v[186:187], v[186:187], 0, s[22:23]
	global_load_lds_dwordx4 v[186:187], off
	ds_read_b128 v[162:165], v192 offset:49152
	ds_read_b128 v[166:169], v192 offset:50176
	ds_read_b128 v[194:197], v192 offset:51200
	ds_read_b128 v[198:201], v192 offset:52224
	ds_read_b128 v[206:209], v192 offset:53248
	ds_read_b128 v[210:213], v192 offset:54272
	ds_read_b128 v[214:217], v192 offset:55296
	ds_read_b128 v[218:221], v192 offset:56320
	s_add_i32 m0, s63, 0x2000
	s_add_u32 s78, s78, 0x40080
	v_lshl_add_u64 v[186:187], v[202:203], 0, s[22:23]
	s_addc_u32 s79, s79, 0
	s_add_i32 s63, s83, s86
	global_load_lds_dwordx4 v[186:187], off
	s_mov_b32 m0, s63
	v_lshl_add_u64 v[186:187], s[78:79], 0, v[172:173]
	global_load_lds_dwordx4 v[186:187], off
	s_add_i32 m0, s63, 0x2000
	v_lshl_add_u64 v[186:187], s[78:79], 0, v[176:177]
	global_load_lds_dwordx4 v[186:187], off
	s_mov_b32 m0, s95
	v_lshl_add_u64 v[186:187], v[222:223], 0, s[22:23]
	global_load_lds_dwordx4 v[186:187], off
	s_mov_b32 m0, s96
	v_lshl_add_u64 v[186:187], v[224:225], 0, s[22:23]
	global_load_lds_dwordx4 v[186:187], off
	s_waitcnt vmcnt(8) lgkmcnt(0)
	s_setprio 1
	s_barrier
	v_mfma_f32_16x16x32_bf16 v[62:65], v[114:117], v[162:165], v[62:65]
	v_mfma_f32_16x16x32_bf16 v[58:61], v[122:125], v[162:165], v[58:61]
	v_mfma_f32_16x16x32_bf16 v[50:53], v[114:117], v[194:197], v[50:53]
	v_mfma_f32_16x16x32_bf16 v[42:45], v[122:125], v[194:197], v[42:45]
	v_mfma_f32_16x16x32_bf16 v[34:37], v[114:117], v[206:209], v[34:37]
	v_mfma_f32_16x16x32_bf16 v[26:29], v[122:125], v[206:209], v[26:29]
	v_mfma_f32_16x16x32_bf16 v[18:21], v[114:117], v[214:217], v[18:21]
	v_mfma_f32_16x16x32_bf16 v[10:13], v[122:125], v[214:217], v[10:13]
	v_mfma_f32_16x16x32_bf16 v[62:65], v[118:121], v[166:169], v[62:65]
	v_mfma_f32_16x16x32_bf16 v[58:61], v[126:129], v[166:169], v[58:61]
	v_mfma_f32_16x16x32_bf16 v[50:53], v[118:121], v[198:201], v[50:53]
	v_mfma_f32_16x16x32_bf16 v[42:45], v[126:129], v[198:201], v[42:45]
	v_mfma_f32_16x16x32_bf16 v[34:37], v[118:121], v[210:213], v[34:37]
	v_mfma_f32_16x16x32_bf16 v[26:29], v[126:129], v[210:213], v[26:29]
	v_mfma_f32_16x16x32_bf16 v[18:21], v[118:121], v[218:221], v[18:21]
	v_mfma_f32_16x16x32_bf16 v[10:13], v[126:129], v[218:221], v[10:13]
	v_mfma_f32_16x16x32_bf16 v[54:57], v[146:149], v[162:165], v[54:57]
	v_mfma_f32_16x16x32_bf16 v[46:49], v[154:157], v[162:165], v[46:49]
	v_mfma_f32_16x16x32_bf16 v[38:41], v[146:149], v[194:197], v[38:41]
	v_mfma_f32_16x16x32_bf16 v[30:33], v[154:157], v[194:197], v[30:33]
	v_mfma_f32_16x16x32_bf16 v[22:25], v[146:149], v[206:209], v[22:25]
	v_mfma_f32_16x16x32_bf16 v[14:17], v[154:157], v[206:209], v[14:17]
	v_mfma_f32_16x16x32_bf16 v[6:9], v[146:149], v[214:217], v[6:9]
	v_mfma_f32_16x16x32_bf16 v[2:5], v[154:157], v[214:217], v[2:5]
	v_mfma_f32_16x16x32_bf16 v[54:57], v[150:153], v[166:169], v[54:57]
	v_mfma_f32_16x16x32_bf16 v[46:49], v[158:161], v[166:169], v[46:49]
	v_mfma_f32_16x16x32_bf16 v[38:41], v[150:153], v[198:201], v[38:41]
	v_mfma_f32_16x16x32_bf16 v[30:33], v[158:161], v[198:201], v[30:33]
	v_mfma_f32_16x16x32_bf16 v[22:25], v[150:153], v[210:213], v[22:25]
	v_mfma_f32_16x16x32_bf16 v[14:17], v[158:161], v[210:213], v[14:17]
	v_mfma_f32_16x16x32_bf16 v[6:9], v[150:153], v[218:221], v[6:9]
	v_mfma_f32_16x16x32_bf16 v[2:5], v[158:161], v[218:221], v[2:5]
	s_setprio 0
	s_barrier
	s_add_u32 s76, s76, 0x100
	s_addc_u32 s77, s77, 0
	s_add_u32 s47, s47, 0x100
	s_addc_u32 s62, s62, 0
	s_cmp_ge_i32 s82, s7
	s_mov_b32 s63, s82
	s_cbranch_scc0 .LBB0_566
	s_and_b64 vcc, exec, s[26:27]
	s_cbranch_vccz .LBB0_569
	s_barrier

.LBB0_744:
	s_add_u32 s36, s96, s22
	s_addc_u32 s37, s97, s23
	s_and_b64 s[14:15], s[4:5], exec
	s_cselect_b32 s14, s37, s43
	s_cselect_b32 s15, s36, s42
	s_add_u32 s38, s2, s26
	s_addc_u32 s39, s3, s27
	s_and_b64 s[46:47], s[4:5], exec
	s_cselect_b32 s21, s39, s45
	s_cselect_b32 s65, s38, s44
	s_add_u32 s42, s42, 0x40080
	s_addc_u32 s43, s43, 0
	s_add_u32 s66, s44, 0x100
	s_addc_u32 s67, s45, 0
	s_mov_b32 s68, -2
	ds_read_b128 v[154:157], v150
	ds_read_b128 v[158:161], v150 offset:1024
	ds_read_b128 v[162:165], v150 offset:2048
	ds_read_b128 v[166:169], v150 offset:3072
	ds_read_b128 v[170:173], v151
	ds_read_b128 v[174:177], v151 offset:1024
	ds_read_b128 v[178:181], v151 offset:2048
	ds_read_b128 v[182:185], v151 offset:3072
	s_add_u32 s44, s42, 0xfffc0080
	s_addc_u32 s45, s43, -1
	s_cmp_eq_u32 s68, 12
	s_cselect_b32 s47, s14, s45
	s_cselect_b32 s46, s15, s44
	s_cselect_b32 s45, s21, s67
	s_cselect_b32 s44, s65, s66
	v_lshl_add_u64 v[146:147], s[42:43], 0, v[138:139]
	s_add_i32 m0, s19, 0xc000
	ds_read_b128 v[186:189], v152
	ds_read_b128 v[190:193], v152 offset:1024
	ds_read_b128 v[194:197], v152 offset:2048
	ds_read_b128 v[198:201], v152 offset:3072
	ds_read_b128 v[206:209], v152 offset:4096
	ds_read_b128 v[210:213], v152 offset:5120
	ds_read_b128 v[214:217], v152 offset:6144
	ds_read_b128 v[218:221], v152 offset:7168
	global_load_lds_dwordx4 v[146:147], off
	s_add_i32 m0, s19, 0xe000
	v_lshl_add_u64 v[146:147], s[42:43], 0, v[140:141]
	global_load_lds_dwordx4 v[146:147], off
	s_waitcnt vmcnt(8) lgkmcnt(0)
	s_setprio 1
	s_barrier
	v_mfma_f32_16x16x32_bf16 v[126:129], v[154:157], v[186:189], 0
	v_mfma_f32_16x16x32_bf16 v[122:125], v[162:165], v[186:189], 0
	v_mfma_f32_16x16x32_bf16 v[110:113], v[154:157], v[194:197], 0
	v_mfma_f32_16x16x32_bf16 v[106:109], v[162:165], v[194:197], 0
	v_mfma_f32_16x16x32_bf16 v[94:97], v[154:157], v[206:209], 0
	v_mfma_f32_16x16x32_bf16 v[90:93], v[162:165], v[206:209], 0
	v_mfma_f32_16x16x32_bf16 v[78:81], v[154:157], v[214:217], 0
	v_mfma_f32_16x16x32_bf16 v[74:77], v[162:165], v[214:217], 0
	v_mfma_f32_16x16x32_bf16 v[126:129], v[158:161], v[190:193], v[126:129]
	v_mfma_f32_16x16x32_bf16 v[122:125], v[166:169], v[190:193], v[122:125]
	v_mfma_f32_16x16x32_bf16 v[110:113], v[158:161], v[198:201], v[110:113]
	v_mfma_f32_16x16x32_bf16 v[106:109], v[166:169], v[198:201], v[106:109]
	v_mfma_f32_16x16x32_bf16 v[94:97], v[158:161], v[210:213], v[94:97]
	v_mfma_f32_16x16x32_bf16 v[90:93], v[166:169], v[210:213], v[90:93]
	v_mfma_f32_16x16x32_bf16 v[78:81], v[158:161], v[218:221], v[78:81]
	v_mfma_f32_16x16x32_bf16 v[74:77], v[166:169], v[218:221], v[74:77]
	v_mfma_f32_16x16x32_bf16 v[118:121], v[170:173], v[186:189], 0
	v_mfma_f32_16x16x32_bf16 v[114:117], v[178:181], v[186:189], 0
	v_mfma_f32_16x16x32_bf16 v[102:105], v[170:173], v[194:197], 0
	v_mfma_f32_16x16x32_bf16 v[98:101], v[178:181], v[194:197], 0
	v_mfma_f32_16x16x32_bf16 v[86:89], v[170:173], v[206:209], 0
	v_mfma_f32_16x16x32_bf16 v[82:85], v[178:181], v[206:209], 0
	v_mfma_f32_16x16x32_bf16 v[70:73], v[170:173], v[214:217], 0
	v_mfma_f32_16x16x32_bf16 v[66:69], v[178:181], v[214:217], 0
	v_mfma_f32_16x16x32_bf16 v[118:121], v[174:177], v[190:193], v[118:121]
	v_mfma_f32_16x16x32_bf16 v[114:117], v[182:185], v[190:193], v[114:117]
	v_mfma_f32_16x16x32_bf16 v[102:105], v[174:177], v[198:201], v[102:105]
	v_mfma_f32_16x16x32_bf16 v[98:101], v[182:185], v[198:201], v[98:101]
	v_mfma_f32_16x16x32_bf16 v[86:89], v[174:177], v[210:213], v[86:89]
	v_mfma_f32_16x16x32_bf16 v[82:85], v[182:185], v[210:213], v[82:85]
	v_mfma_f32_16x16x32_bf16 v[70:73], v[174:177], v[218:221], v[70:73]
	v_mfma_f32_16x16x32_bf16 v[66:69], v[182:185], v[218:221], v[66:69]
	s_setprio 0
	s_barrier
	s_add_i32 s69, s49, s16
	s_mov_b32 m0, s69
	v_lshl_add_u64 v[146:147], s[44:45], 0, v[134:135]
	global_load_lds_dwordx4 v[146:147], off
	ds_read_b128 v[186:189], v152 offset:16384
	ds_read_b128 v[190:193], v152 offset:17408
	ds_read_b128 v[194:197], v152 offset:18432
	ds_read_b128 v[198:201], v152 offset:19456
	ds_read_b128 v[206:209], v152 offset:20480
	ds_read_b128 v[210:213], v152 offset:21504
	ds_read_b128 v[214:217], v152 offset:22528
	ds_read_b128 v[218:221], v152 offset:23552
	s_add_i32 m0, s69, 0x2000
	s_add_u32 s70, s44, 0x40000
	v_lshl_add_u64 v[202:203], s[44:45], 0, v[130:131]
	s_addc_u32 s71, s45, 0
	s_add_i32 s69, s62, s16
	global_load_lds_dwordx4 v[202:203], off
	v_lshl_add_u64 v[222:223], s[70:71], 0, v[134:135]
	s_mov_b32 m0, s69
	v_lshl_add_u64 v[224:225], s[46:47], 0, v[132:133]
	global_load_lds_dwordx4 v[222:223], off
	s_add_i32 m0, s69, 0x2000
	v_lshl_add_u64 v[222:223], s[70:71], 0, v[130:131]
	global_load_lds_dwordx4 v[222:223], off
	s_mov_b32 m0, s19
	v_lshl_add_u64 v[222:223], s[46:47], 0, v[136:137]
	global_load_lds_dwordx4 v[222:223], off
	s_mov_b32 m0, s24
	s_nop 0
	global_load_lds_dwordx4 v[224:225], off
	s_waitcnt vmcnt(8) lgkmcnt(0)
	s_setprio 1
	s_barrier
	v_mfma_f32_16x16x32_bf16 v[62:65], v[154:157], v[186:189], 0
	v_mfma_f32_16x16x32_bf16 v[58:61], v[162:165], v[186:189], 0
	v_mfma_f32_16x16x32_bf16 v[46:49], v[154:157], v[194:197], 0
	v_mfma_f32_16x16x32_bf16 v[42:45], v[162:165], v[194:197], 0
	v_mfma_f32_16x16x32_bf16 v[30:33], v[154:157], v[206:209], 0
	v_mfma_f32_16x16x32_bf16 v[26:29], v[162:165], v[206:209], 0
	v_mfma_f32_16x16x32_bf16 v[14:17], v[154:157], v[214:217], 0
	v_mfma_f32_16x16x32_bf16 v[10:13], v[162:165], v[214:217], 0
	v_mfma_f32_16x16x32_bf16 v[62:65], v[158:161], v[190:193], v[62:65]
	v_mfma_f32_16x16x32_bf16 v[58:61], v[166:169], v[190:193], v[58:61]
	v_mfma_f32_16x16x32_bf16 v[46:49], v[158:161], v[198:201], v[46:49]
	v_mfma_f32_16x16x32_bf16 v[42:45], v[166:169], v[198:201], v[42:45]
	v_mfma_f32_16x16x32_bf16 v[30:33], v[158:161], v[210:213], v[30:33]
	v_mfma_f32_16x16x32_bf16 v[26:29], v[166:169], v[210:213], v[26:29]
	v_mfma_f32_16x16x32_bf16 v[14:17], v[158:161], v[218:221], v[14:17]
	v_mfma_f32_16x16x32_bf16 v[10:13], v[166:169], v[218:221], v[10:13]
	v_mfma_f32_16x16x32_bf16 v[54:57], v[170:173], v[186:189], 0
	v_mfma_f32_16x16x32_bf16 v[50:53], v[178:181], v[186:189], 0
	v_mfma_f32_16x16x32_bf16 v[38:41], v[170:173], v[194:197], 0
	v_mfma_f32_16x16x32_bf16 v[34:37], v[178:181], v[194:197], 0
	v_mfma_f32_16x16x32_bf16 v[22:25], v[170:173], v[206:209], 0
	v_mfma_f32_16x16x32_bf16 v[18:21], v[178:181], v[206:209], 0
	v_mfma_f32_16x16x32_bf16 v[6:9], v[170:173], v[214:217], 0
	v_mfma_f32_16x16x32_bf16 v[2:5], v[178:181], v[214:217], 0
	v_mfma_f32_16x16x32_bf16 v[54:57], v[174:177], v[190:193], v[54:57]
	v_mfma_f32_16x16x32_bf16 v[50:53], v[182:185], v[190:193], v[50:53]
	v_mfma_f32_16x16x32_bf16 v[38:41], v[174:177], v[198:201], v[38:41]
	v_mfma_f32_16x16x32_bf16 v[34:37], v[182:185], v[198:201], v[34:37]
	v_mfma_f32_16x16x32_bf16 v[22:25], v[174:177], v[210:213], v[22:25]
	v_mfma_f32_16x16x32_bf16 v[18:21], v[182:185], v[210:213], v[18:21]
	v_mfma_f32_16x16x32_bf16 v[6:9], v[174:177], v[218:221], v[6:9]
	v_mfma_f32_16x16x32_bf16 v[2:5], v[182:185], v[218:221], v[2:5]
	s_setprio 0
	s_barrier
	s_add_i32 s69, 0, 0x18000
	v_add_u32_e32 v153, s69, v149
	s_add_i32 s70, 0, 0x1c000
	ds_read_b128 v[154:157], v153
	ds_read_b128 v[158:161], v153 offset:1024
	ds_read_b128 v[162:165], v153 offset:2048
	ds_read_b128 v[166:169], v153 offset:3072
	v_add_u32_e32 v153, s70, v149
	ds_read_b128 v[170:173], v153
	ds_read_b128 v[174:177], v153 offset:1024
	ds_read_b128 v[178:181], v153 offset:2048
	ds_read_b128 v[182:185], v153 offset:3072
	s_add_u32 s46, s46, 0x40000
	s_addc_u32 s47, s47, 0
	s_mov_b32 m0, s25
	v_lshl_add_u64 v[226:227], s[46:47], 0, v[136:137]
	ds_read_b128 v[186:189], v152 offset:32768
	ds_read_b128 v[190:193], v152 offset:33792
	ds_read_b128 v[194:197], v152 offset:34816
	ds_read_b128 v[198:201], v152 offset:35840
	ds_read_b128 v[206:209], v152 offset:36864
	ds_read_b128 v[210:213], v152 offset:37888
	ds_read_b128 v[214:217], v152 offset:38912
	ds_read_b128 v[218:221], v152 offset:39936
	global_load_lds_dwordx4 v[226:227], off
	s_mov_b32 m0, s28
	v_lshl_add_u64 v[226:227], s[46:47], 0, v[132:133]
	global_load_lds_dwordx4 v[226:227], off
	s_waitcnt vmcnt(8) lgkmcnt(0)
	s_setprio 1
	s_barrier
	v_mfma_f32_16x16x32_bf16 v[126:129], v[154:157], v[186:189], v[126:129]
	v_mfma_f32_16x16x32_bf16 v[122:125], v[162:165], v[186:189], v[122:125]
	v_mfma_f32_16x16x32_bf16 v[110:113], v[154:157], v[194:197], v[110:113]
	v_mfma_f32_16x16x32_bf16 v[106:109], v[162:165], v[194:197], v[106:109]
	v_mfma_f32_16x16x32_bf16 v[94:97], v[154:157], v[206:209], v[94:97]
	v_mfma_f32_16x16x32_bf16 v[90:93], v[162:165], v[206:209], v[90:93]
	v_mfma_f32_16x16x32_bf16 v[78:81], v[154:157], v[214:217], v[78:81]
	v_mfma_f32_16x16x32_bf16 v[74:77], v[162:165], v[214:217], v[74:77]
	v_mfma_f32_16x16x32_bf16 v[126:129], v[158:161], v[190:193], v[126:129]
	v_mfma_f32_16x16x32_bf16 v[122:125], v[166:169], v[190:193], v[122:125]
	v_mfma_f32_16x16x32_bf16 v[110:113], v[158:161], v[198:201], v[110:113]
	v_mfma_f32_16x16x32_bf16 v[106:109], v[166:169], v[198:201], v[106:109]
	v_mfma_f32_16x16x32_bf16 v[94:97], v[158:161], v[210:213], v[94:97]
	v_mfma_f32_16x16x32_bf16 v[90:93], v[166:169], v[210:213], v[90:93]
	v_mfma_f32_16x16x32_bf16 v[78:81], v[158:161], v[218:221], v[78:81]
	v_mfma_f32_16x16x32_bf16 v[74:77], v[166:169], v[218:221], v[74:77]
	v_mfma_f32_16x16x32_bf16 v[118:121], v[170:173], v[186:189], v[118:121]
	v_mfma_f32_16x16x32_bf16 v[114:117], v[178:181], v[186:189], v[114:117]
	v_mfma_f32_16x16x32_bf16 v[102:105], v[170:173], v[194:197], v[102:105]
	v_mfma_f32_16x16x32_bf16 v[98:101], v[178:181], v[194:197], v[98:101]
	v_mfma_f32_16x16x32_bf16 v[86:89], v[170:173], v[206:209], v[86:89]
	v_mfma_f32_16x16x32_bf16 v[82:85], v[178:181], v[206:209], v[82:85]
	v_mfma_f32_16x16x32_bf16 v[70:73], v[170:173], v[214:217], v[70:73]
	v_mfma_f32_16x16x32_bf16 v[66:69], v[178:181], v[214:217], v[66:69]
	v_mfma_f32_16x16x32_bf16 v[118:121], v[174:177], v[190:193], v[118:121]
	v_mfma_f32_16x16x32_bf16 v[114:117], v[182:185], v[190:193], v[114:117]
	v_mfma_f32_16x16x32_bf16 v[102:105], v[174:177], v[198:201], v[102:105]
	v_mfma_f32_16x16x32_bf16 v[98:101], v[182:185], v[198:201], v[98:101]
	v_mfma_f32_16x16x32_bf16 v[86:89], v[174:177], v[210:213], v[86:89]
	v_mfma_f32_16x16x32_bf16 v[82:85], v[182:185], v[210:213], v[82:85]
	v_mfma_f32_16x16x32_bf16 v[70:73], v[174:177], v[218:221], v[70:73]
	v_mfma_f32_16x16x32_bf16 v[66:69], v[182:185], v[218:221], v[66:69]
	s_setprio 0
	s_barrier
	s_add_i32 s46, s69, s16
	s_mov_b32 m0, s46
	v_lshl_add_u64 v[146:147], v[146:147], 0, s[10:11]
	global_load_lds_dwordx4 v[146:147], off
	ds_read_b128 v[186:189], v152 offset:49152
	ds_read_b128 v[190:193], v152 offset:50176
	ds_read_b128 v[194:197], v152 offset:51200
	ds_read_b128 v[198:201], v152 offset:52224
	ds_read_b128 v[206:209], v152 offset:53248
	ds_read_b128 v[210:213], v152 offset:54272
	ds_read_b128 v[214:217], v152 offset:55296
	ds_read_b128 v[218:221], v152 offset:56320
	s_add_i32 m0, s46, 0x2000
	s_add_u32 s44, s44, 0x40080
	v_lshl_add_u64 v[146:147], v[202:203], 0, s[10:11]
	s_addc_u32 s45, s45, 0
	s_add_i32 s46, s70, s16
	global_load_lds_dwordx4 v[146:147], off
	s_mov_b32 m0, s46
	v_lshl_add_u64 v[146:147], s[44:45], 0, v[134:135]
	global_load_lds_dwordx4 v[146:147], off
	s_add_i32 m0, s46, 0x2000
	v_lshl_add_u64 v[146:147], s[44:45], 0, v[130:131]
	global_load_lds_dwordx4 v[146:147], off
	s_mov_b32 m0, s33
	v_lshl_add_u64 v[146:147], v[222:223], 0, s[10:11]
	global_load_lds_dwordx4 v[146:147], off
	s_mov_b32 m0, s35
	v_lshl_add_u64 v[146:147], v[224:225], 0, s[10:11]
	global_load_lds_dwordx4 v[146:147], off
	s_waitcnt vmcnt(8) lgkmcnt(0)
	s_setprio 1
	s_barrier
	v_mfma_f32_16x16x32_bf16 v[62:65], v[154:157], v[186:189], v[62:65]
	v_mfma_f32_16x16x32_bf16 v[58:61], v[162:165], v[186:189], v[58:61]
	v_mfma_f32_16x16x32_bf16 v[46:49], v[154:157], v[194:197], v[46:49]
	v_mfma_f32_16x16x32_bf16 v[42:45], v[162:165], v[194:197], v[42:45]
	v_mfma_f32_16x16x32_bf16 v[30:33], v[154:157], v[206:209], v[30:33]
	v_mfma_f32_16x16x32_bf16 v[26:29], v[162:165], v[206:209], v[26:29]
	v_mfma_f32_16x16x32_bf16 v[14:17], v[154:157], v[214:217], v[14:17]
	v_mfma_f32_16x16x32_bf16 v[10:13], v[162:165], v[214:217], v[10:13]
	v_mfma_f32_16x16x32_bf16 v[62:65], v[158:161], v[190:193], v[62:65]
	v_mfma_f32_16x16x32_bf16 v[58:61], v[166:169], v[190:193], v[58:61]
	v_mfma_f32_16x16x32_bf16 v[46:49], v[158:161], v[198:201], v[46:49]
	v_mfma_f32_16x16x32_bf16 v[42:45], v[166:169], v[198:201], v[42:45]
	v_mfma_f32_16x16x32_bf16 v[30:33], v[158:161], v[210:213], v[30:33]
	v_mfma_f32_16x16x32_bf16 v[26:29], v[166:169], v[210:213], v[26:29]
	v_mfma_f32_16x16x32_bf16 v[14:17], v[158:161], v[218:221], v[14:17]
	v_mfma_f32_16x16x32_bf16 v[10:13], v[166:169], v[218:221], v[10:13]
	v_mfma_f32_16x16x32_bf16 v[54:57], v[170:173], v[186:189], v[54:57]
	v_mfma_f32_16x16x32_bf16 v[50:53], v[178:181], v[186:189], v[50:53]
	v_mfma_f32_16x16x32_bf16 v[38:41], v[170:173], v[194:197], v[38:41]
	v_mfma_f32_16x16x32_bf16 v[34:37], v[178:181], v[194:197], v[34:37]
	v_mfma_f32_16x16x32_bf16 v[22:25], v[170:173], v[206:209], v[22:25]
	v_mfma_f32_16x16x32_bf16 v[18:21], v[178:181], v[206:209], v[18:21]
	v_mfma_f32_16x16x32_bf16 v[6:9], v[170:173], v[214:217], v[6:9]
	v_mfma_f32_16x16x32_bf16 v[2:5], v[178:181], v[214:217], v[2:5]
	v_mfma_f32_16x16x32_bf16 v[54:57], v[174:177], v[190:193], v[54:57]
	v_mfma_f32_16x16x32_bf16 v[50:53], v[182:185], v[190:193], v[50:53]
	v_mfma_f32_16x16x32_bf16 v[38:41], v[174:177], v[198:201], v[38:41]
	v_mfma_f32_16x16x32_bf16 v[34:37], v[182:185], v[198:201], v[34:37]
	v_mfma_f32_16x16x32_bf16 v[22:25], v[174:177], v[210:213], v[22:25]
	v_mfma_f32_16x16x32_bf16 v[18:21], v[182:185], v[210:213], v[18:21]
	v_mfma_f32_16x16x32_bf16 v[6:9], v[174:177], v[218:221], v[6:9]
	v_mfma_f32_16x16x32_bf16 v[2:5], v[182:185], v[218:221], v[2:5]
	s_setprio 0
	s_barrier
	s_add_i32 s68, s68, 2
	s_add_u32 s42, s42, 0x100
	s_addc_u32 s43, s43, 0
	s_add_u32 s66, s66, 0x100
	s_addc_u32 s67, s67, 0
	s_cmp_gt_u32 s68, 13
.LBB0_745:
	ds_read_b128 v[154:157], v150
	ds_read_b128 v[158:161], v150 offset:1024
	ds_read_b128 v[162:165], v150 offset:2048
	ds_read_b128 v[166:169], v150 offset:3072
	ds_read_b128 v[170:173], v151
	ds_read_b128 v[174:177], v151 offset:1024
	ds_read_b128 v[178:181], v151 offset:2048
	ds_read_b128 v[182:185], v151 offset:3072
	s_add_u32 s44, s42, 0xfffc0080
	s_addc_u32 s45, s43, -1
	s_cmp_eq_u32 s68, 12
	s_cselect_b32 s47, s14, s45
	s_cselect_b32 s46, s15, s44
	s_cselect_b32 s45, s21, s67
	s_cselect_b32 s44, s65, s66
	v_lshl_add_u64 v[146:147], s[42:43], 0, v[138:139]
	s_add_i32 m0, s19, 0xc000
	ds_read_b128 v[186:189], v152
	ds_read_b128 v[190:193], v152 offset:1024
	ds_read_b128 v[194:197], v152 offset:2048
	ds_read_b128 v[198:201], v152 offset:3072
	ds_read_b128 v[206:209], v152 offset:4096
	ds_read_b128 v[210:213], v152 offset:5120
	ds_read_b128 v[214:217], v152 offset:6144
	ds_read_b128 v[218:221], v152 offset:7168
	global_load_lds_dwordx4 v[146:147], off
	s_add_i32 m0, s19, 0xe000
	v_lshl_add_u64 v[146:147], s[42:43], 0, v[140:141]
	global_load_lds_dwordx4 v[146:147], off
	s_waitcnt vmcnt(8) lgkmcnt(0)
	s_setprio 1
	s_barrier
	v_mfma_f32_16x16x32_bf16 v[126:129], v[154:157], v[186:189], v[126:129]
	v_mfma_f32_16x16x32_bf16 v[122:125], v[162:165], v[186:189], v[122:125]
	v_mfma_f32_16x16x32_bf16 v[110:113], v[154:157], v[194:197], v[110:113]
	v_mfma_f32_16x16x32_bf16 v[106:109], v[162:165], v[194:197], v[106:109]
	v_mfma_f32_16x16x32_bf16 v[94:97], v[154:157], v[206:209], v[94:97]
	v_mfma_f32_16x16x32_bf16 v[90:93], v[162:165], v[206:209], v[90:93]
	v_mfma_f32_16x16x32_bf16 v[78:81], v[154:157], v[214:217], v[78:81]
	v_mfma_f32_16x16x32_bf16 v[74:77], v[162:165], v[214:217], v[74:77]
	v_mfma_f32_16x16x32_bf16 v[126:129], v[158:161], v[190:193], v[126:129]
	v_mfma_f32_16x16x32_bf16 v[122:125], v[166:169], v[190:193], v[122:125]
	v_mfma_f32_16x16x32_bf16 v[110:113], v[158:161], v[198:201], v[110:113]
	v_mfma_f32_16x16x32_bf16 v[106:109], v[166:169], v[198:201], v[106:109]
	v_mfma_f32_16x16x32_bf16 v[94:97], v[158:161], v[210:213], v[94:97]
	v_mfma_f32_16x16x32_bf16 v[90:93], v[166:169], v[210:213], v[90:93]
	v_mfma_f32_16x16x32_bf16 v[78:81], v[158:161], v[218:221], v[78:81]
	v_mfma_f32_16x16x32_bf16 v[74:77], v[166:169], v[218:221], v[74:77]
	v_mfma_f32_16x16x32_bf16 v[118:121], v[170:173], v[186:189], v[118:121]
	v_mfma_f32_16x16x32_bf16 v[114:117], v[178:181], v[186:189], v[114:117]
	v_mfma_f32_16x16x32_bf16 v[102:105], v[170:173], v[194:197], v[102:105]
	v_mfma_f32_16x16x32_bf16 v[98:101], v[178:181], v[194:197], v[98:101]
	v_mfma_f32_16x16x32_bf16 v[86:89], v[170:173], v[206:209], v[86:89]
	v_mfma_f32_16x16x32_bf16 v[82:85], v[178:181], v[206:209], v[82:85]
	v_mfma_f32_16x16x32_bf16 v[70:73], v[170:173], v[214:217], v[70:73]
	v_mfma_f32_16x16x32_bf16 v[66:69], v[178:181], v[214:217], v[66:69]
	v_mfma_f32_16x16x32_bf16 v[118:121], v[174:177], v[190:193], v[118:121]
	v_mfma_f32_16x16x32_bf16 v[114:117], v[182:185], v[190:193], v[114:117]
	v_mfma_f32_16x16x32_bf16 v[102:105], v[174:177], v[198:201], v[102:105]
	v_mfma_f32_16x16x32_bf16 v[98:101], v[182:185], v[198:201], v[98:101]
	v_mfma_f32_16x16x32_bf16 v[86:89], v[174:177], v[210:213], v[86:89]
	v_mfma_f32_16x16x32_bf16 v[82:85], v[182:185], v[210:213], v[82:85]
	v_mfma_f32_16x16x32_bf16 v[70:73], v[174:177], v[218:221], v[70:73]
	v_mfma_f32_16x16x32_bf16 v[66:69], v[182:185], v[218:221], v[66:69]
	s_setprio 0
	s_barrier
	s_add_i32 s69, s49, s16
	s_mov_b32 m0, s69
	v_lshl_add_u64 v[146:147], s[44:45], 0, v[134:135]
	global_load_lds_dwordx4 v[146:147], off
	ds_read_b128 v[186:189], v152 offset:16384
	ds_read_b128 v[190:193], v152 offset:17408
	ds_read_b128 v[194:197], v152 offset:18432
	ds_read_b128 v[198:201], v152 offset:19456
	ds_read_b128 v[206:209], v152 offset:20480
	ds_read_b128 v[210:213], v152 offset:21504
	ds_read_b128 v[214:217], v152 offset:22528
	ds_read_b128 v[218:221], v152 offset:23552
	s_add_i32 m0, s69, 0x2000
	s_add_u32 s70, s44, 0x40000
	v_lshl_add_u64 v[202:203], s[44:45], 0, v[130:131]
	s_addc_u32 s71, s45, 0
	s_add_i32 s69, s62, s16
	global_load_lds_dwordx4 v[202:203], off
	v_lshl_add_u64 v[222:223], s[70:71], 0, v[134:135]
	s_mov_b32 m0, s69
	v_lshl_add_u64 v[224:225], s[46:47], 0, v[132:133]
	global_load_lds_dwordx4 v[222:223], off
	s_add_i32 m0, s69, 0x2000
	v_lshl_add_u64 v[222:223], s[70:71], 0, v[130:131]
	global_load_lds_dwordx4 v[222:223], off
	s_mov_b32 m0, s19
	v_lshl_add_u64 v[222:223], s[46:47], 0, v[136:137]
	global_load_lds_dwordx4 v[222:223], off
	s_mov_b32 m0, s24
	s_nop 0
	global_load_lds_dwordx4 v[224:225], off
	s_waitcnt vmcnt(8) lgkmcnt(0)
	s_setprio 1
	s_barrier
	v_mfma_f32_16x16x32_bf16 v[62:65], v[154:157], v[186:189], v[62:65]
	v_mfma_f32_16x16x32_bf16 v[58:61], v[162:165], v[186:189], v[58:61]
	v_mfma_f32_16x16x32_bf16 v[46:49], v[154:157], v[194:197], v[46:49]
	v_mfma_f32_16x16x32_bf16 v[42:45], v[162:165], v[194:197], v[42:45]
	v_mfma_f32_16x16x32_bf16 v[30:33], v[154:157], v[206:209], v[30:33]
	v_mfma_f32_16x16x32_bf16 v[26:29], v[162:165], v[206:209], v[26:29]
	v_mfma_f32_16x16x32_bf16 v[14:17], v[154:157], v[214:217], v[14:17]
	v_mfma_f32_16x16x32_bf16 v[10:13], v[162:165], v[214:217], v[10:13]
	v_mfma_f32_16x16x32_bf16 v[62:65], v[158:161], v[190:193], v[62:65]
	v_mfma_f32_16x16x32_bf16 v[58:61], v[166:169], v[190:193], v[58:61]
	v_mfma_f32_16x16x32_bf16 v[46:49], v[158:161], v[198:201], v[46:49]
	v_mfma_f32_16x16x32_bf16 v[42:45], v[166:169], v[198:201], v[42:45]
	v_mfma_f32_16x16x32_bf16 v[30:33], v[158:161], v[210:213], v[30:33]
	v_mfma_f32_16x16x32_bf16 v[26:29], v[166:169], v[210:213], v[26:29]
	v_mfma_f32_16x16x32_bf16 v[14:17], v[158:161], v[218:221], v[14:17]
	v_mfma_f32_16x16x32_bf16 v[10:13], v[166:169], v[218:221], v[10:13]
	v_mfma_f32_16x16x32_bf16 v[54:57], v[170:173], v[186:189], v[54:57]
	v_mfma_f32_16x16x32_bf16 v[50:53], v[178:181], v[186:189], v[50:53]
	v_mfma_f32_16x16x32_bf16 v[38:41], v[170:173], v[194:197], v[38:41]
	v_mfma_f32_16x16x32_bf16 v[34:37], v[178:181], v[194:197], v[34:37]
	v_mfma_f32_16x16x32_bf16 v[22:25], v[170:173], v[206:209], v[22:25]
	v_mfma_f32_16x16x32_bf16 v[18:21], v[178:181], v[206:209], v[18:21]
	v_mfma_f32_16x16x32_bf16 v[6:9], v[170:173], v[214:217], v[6:9]
	v_mfma_f32_16x16x32_bf16 v[2:5], v[178:181], v[214:217], v[2:5]
	v_mfma_f32_16x16x32_bf16 v[54:57], v[174:177], v[190:193], v[54:57]
	v_mfma_f32_16x16x32_bf16 v[50:53], v[182:185], v[190:193], v[50:53]
	v_mfma_f32_16x16x32_bf16 v[38:41], v[174:177], v[198:201], v[38:41]
	v_mfma_f32_16x16x32_bf16 v[34:37], v[182:185], v[198:201], v[34:37]
	v_mfma_f32_16x16x32_bf16 v[22:25], v[174:177], v[210:213], v[22:25]
	v_mfma_f32_16x16x32_bf16 v[18:21], v[182:185], v[210:213], v[18:21]
	v_mfma_f32_16x16x32_bf16 v[6:9], v[174:177], v[218:221], v[6:9]
	v_mfma_f32_16x16x32_bf16 v[2:5], v[182:185], v[218:221], v[2:5]
	s_setprio 0
	s_barrier
	s_add_i32 s69, 0, 0x18000
	v_add_u32_e32 v153, s69, v149
	s_add_i32 s70, 0, 0x1c000
	ds_read_b128 v[154:157], v153
	ds_read_b128 v[158:161], v153 offset:1024
	ds_read_b128 v[162:165], v153 offset:2048
	ds_read_b128 v[166:169], v153 offset:3072
	v_add_u32_e32 v153, s70, v149
	ds_read_b128 v[170:173], v153
	ds_read_b128 v[174:177], v153 offset:1024
	ds_read_b128 v[178:181], v153 offset:2048
	ds_read_b128 v[182:185], v153 offset:3072
	s_add_u32 s46, s46, 0x40000
	s_addc_u32 s47, s47, 0
	s_mov_b32 m0, s25
	v_lshl_add_u64 v[226:227], s[46:47], 0, v[136:137]
	ds_read_b128 v[186:189], v152 offset:32768
	ds_read_b128 v[190:193], v152 offset:33792
	ds_read_b128 v[194:197], v152 offset:34816
	ds_read_b128 v[198:201], v152 offset:35840
	ds_read_b128 v[206:209], v152 offset:36864
	ds_read_b128 v[210:213], v152 offset:37888
	ds_read_b128 v[214:217], v152 offset:38912
	ds_read_b128 v[218:221], v152 offset:39936
	global_load_lds_dwordx4 v[226:227], off
	s_mov_b32 m0, s28
	v_lshl_add_u64 v[226:227], s[46:47], 0, v[132:133]
	global_load_lds_dwordx4 v[226:227], off
	s_waitcnt vmcnt(8) lgkmcnt(0)
	s_setprio 1
	s_barrier
	v_mfma_f32_16x16x32_bf16 v[126:129], v[154:157], v[186:189], v[126:129]
	v_mfma_f32_16x16x32_bf16 v[122:125], v[162:165], v[186:189], v[122:125]
	v_mfma_f32_16x16x32_bf16 v[110:113], v[154:157], v[194:197], v[110:113]
	v_mfma_f32_16x16x32_bf16 v[106:109], v[162:165], v[194:197], v[106:109]
	v_mfma_f32_16x16x32_bf16 v[94:97], v[154:157], v[206:209], v[94:97]
	v_mfma_f32_16x16x32_bf16 v[90:93], v[162:165], v[206:209], v[90:93]
	v_mfma_f32_16x16x32_bf16 v[78:81], v[154:157], v[214:217], v[78:81]
	v_mfma_f32_16x16x32_bf16 v[74:77], v[162:165], v[214:217], v[74:77]
	v_mfma_f32_16x16x32_bf16 v[126:129], v[158:161], v[190:193], v[126:129]
	v_mfma_f32_16x16x32_bf16 v[122:125], v[166:169], v[190:193], v[122:125]
	v_mfma_f32_16x16x32_bf16 v[110:113], v[158:161], v[198:201], v[110:113]
	v_mfma_f32_16x16x32_bf16 v[106:109], v[166:169], v[198:201], v[106:109]
	v_mfma_f32_16x16x32_bf16 v[94:97], v[158:161], v[210:213], v[94:97]
	v_mfma_f32_16x16x32_bf16 v[90:93], v[166:169], v[210:213], v[90:93]
	v_mfma_f32_16x16x32_bf16 v[78:81], v[158:161], v[218:221], v[78:81]
	v_mfma_f32_16x16x32_bf16 v[74:77], v[166:169], v[218:221], v[74:77]
	v_mfma_f32_16x16x32_bf16 v[118:121], v[170:173], v[186:189], v[118:121]
	v_mfma_f32_16x16x32_bf16 v[114:117], v[178:181], v[186:189], v[114:117]
	v_mfma_f32_16x16x32_bf16 v[102:105], v[170:173], v[194:197], v[102:105]
	v_mfma_f32_16x16x32_bf16 v[98:101], v[178:181], v[194:197], v[98:101]
	v_mfma_f32_16x16x32_bf16 v[86:89], v[170:173], v[206:209], v[86:89]
	v_mfma_f32_16x16x32_bf16 v[82:85], v[178:181], v[206:209], v[82:85]
	v_mfma_f32_16x16x32_bf16 v[70:73], v[170:173], v[214:217], v[70:73]
	v_mfma_f32_16x16x32_bf16 v[66:69], v[178:181], v[214:217], v[66:69]
	v_mfma_f32_16x16x32_bf16 v[118:121], v[174:177], v[190:193], v[118:121]
	v_mfma_f32_16x16x32_bf16 v[114:117], v[182:185], v[190:193], v[114:117]
	v_mfma_f32_16x16x32_bf16 v[102:105], v[174:177], v[198:201], v[102:105]
	v_mfma_f32_16x16x32_bf16 v[98:101], v[182:185], v[198:201], v[98:101]
	v_mfma_f32_16x16x32_bf16 v[86:89], v[174:177], v[210:213], v[86:89]
	v_mfma_f32_16x16x32_bf16 v[82:85], v[182:185], v[210:213], v[82:85]
	v_mfma_f32_16x16x32_bf16 v[70:73], v[174:177], v[218:221], v[70:73]
	v_mfma_f32_16x16x32_bf16 v[66:69], v[182:185], v[218:221], v[66:69]
	s_setprio 0
	s_barrier
	s_add_i32 s46, s69, s16
	s_mov_b32 m0, s46
	v_lshl_add_u64 v[146:147], v[146:147], 0, s[10:11]
	global_load_lds_dwordx4 v[146:147], off
	ds_read_b128 v[186:189], v152 offset:49152
	ds_read_b128 v[190:193], v152 offset:50176
	ds_read_b128 v[194:197], v152 offset:51200
	ds_read_b128 v[198:201], v152 offset:52224
	ds_read_b128 v[206:209], v152 offset:53248
	ds_read_b128 v[210:213], v152 offset:54272
	ds_read_b128 v[214:217], v152 offset:55296
	ds_read_b128 v[218:221], v152 offset:56320
	s_add_i32 m0, s46, 0x2000
	s_add_u32 s44, s44, 0x40080
	v_lshl_add_u64 v[146:147], v[202:203], 0, s[10:11]
	s_addc_u32 s45, s45, 0
	s_add_i32 s46, s70, s16
	global_load_lds_dwordx4 v[146:147], off
	s_mov_b32 m0, s46
	v_lshl_add_u64 v[146:147], s[44:45], 0, v[134:135]
	global_load_lds_dwordx4 v[146:147], off
	s_add_i32 m0, s46, 0x2000
	v_lshl_add_u64 v[146:147], s[44:45], 0, v[130:131]
	global_load_lds_dwordx4 v[146:147], off
	s_mov_b32 m0, s33
	v_lshl_add_u64 v[146:147], v[222:223], 0, s[10:11]
	global_load_lds_dwordx4 v[146:147], off
	s_mov_b32 m0, s35
	v_lshl_add_u64 v[146:147], v[224:225], 0, s[10:11]
	global_load_lds_dwordx4 v[146:147], off
	s_waitcnt vmcnt(8) lgkmcnt(0)
	s_setprio 1
	s_barrier
	v_mfma_f32_16x16x32_bf16 v[62:65], v[154:157], v[186:189], v[62:65]
	v_mfma_f32_16x16x32_bf16 v[58:61], v[162:165], v[186:189], v[58:61]
	v_mfma_f32_16x16x32_bf16 v[46:49], v[154:157], v[194:197], v[46:49]
	v_mfma_f32_16x16x32_bf16 v[42:45], v[162:165], v[194:197], v[42:45]
	v_mfma_f32_16x16x32_bf16 v[30:33], v[154:157], v[206:209], v[30:33]
	v_mfma_f32_16x16x32_bf16 v[26:29], v[162:165], v[206:209], v[26:29]
	v_mfma_f32_16x16x32_bf16 v[14:17], v[154:157], v[214:217], v[14:17]
	v_mfma_f32_16x16x32_bf16 v[10:13], v[162:165], v[214:217], v[10:13]
	v_mfma_f32_16x16x32_bf16 v[62:65], v[158:161], v[190:193], v[62:65]
	v_mfma_f32_16x16x32_bf16 v[58:61], v[166:169], v[190:193], v[58:61]
	v_mfma_f32_16x16x32_bf16 v[46:49], v[158:161], v[198:201], v[46:49]
	v_mfma_f32_16x16x32_bf16 v[42:45], v[166:169], v[198:201], v[42:45]
	v_mfma_f32_16x16x32_bf16 v[30:33], v[158:161], v[210:213], v[30:33]
	v_mfma_f32_16x16x32_bf16 v[26:29], v[166:169], v[210:213], v[26:29]
	v_mfma_f32_16x16x32_bf16 v[14:17], v[158:161], v[218:221], v[14:17]
	v_mfma_f32_16x16x32_bf16 v[10:13], v[166:169], v[218:221], v[10:13]
	v_mfma_f32_16x16x32_bf16 v[54:57], v[170:173], v[186:189], v[54:57]
	v_mfma_f32_16x16x32_bf16 v[50:53], v[178:181], v[186:189], v[50:53]
	v_mfma_f32_16x16x32_bf16 v[38:41], v[170:173], v[194:197], v[38:41]
	v_mfma_f32_16x16x32_bf16 v[34:37], v[178:181], v[194:197], v[34:37]
	v_mfma_f32_16x16x32_bf16 v[22:25], v[170:173], v[206:209], v[22:25]
	v_mfma_f32_16x16x32_bf16 v[18:21], v[178:181], v[206:209], v[18:21]
	v_mfma_f32_16x16x32_bf16 v[6:9], v[170:173], v[214:217], v[6:9]
	v_mfma_f32_16x16x32_bf16 v[2:5], v[178:181], v[214:217], v[2:5]
	v_mfma_f32_16x16x32_bf16 v[54:57], v[174:177], v[190:193], v[54:57]
	v_mfma_f32_16x16x32_bf16 v[50:53], v[182:185], v[190:193], v[50:53]
	v_mfma_f32_16x16x32_bf16 v[38:41], v[174:177], v[198:201], v[38:41]
	v_mfma_f32_16x16x32_bf16 v[34:37], v[182:185], v[198:201], v[34:37]
	v_mfma_f32_16x16x32_bf16 v[22:25], v[174:177], v[210:213], v[22:25]
	v_mfma_f32_16x16x32_bf16 v[18:21], v[182:185], v[210:213], v[18:21]
	v_mfma_f32_16x16x32_bf16 v[6:9], v[174:177], v[218:221], v[6:9]
	v_mfma_f32_16x16x32_bf16 v[2:5], v[182:185], v[218:221], v[2:5]
	s_setprio 0
	s_barrier
	s_add_i32 s68, s68, 2
	s_add_u32 s42, s42, 0x100
	s_addc_u32 s43, s43, 0
	s_add_u32 s66, s66, 0x100
	s_addc_u32 s67, s67, 0
	s_cmp_gt_u32 s68, 13
	s_cbranch_scc0 .LBB0_745
	s_and_b64 vcc, exec, s[12:13]
	s_cbranch_vccz .LBB0_748
	s_barrier

.LBB0_833:
	s_add_u32 s72, s0, s68
	s_addc_u32 s73, s1, s69
	s_and_b64 s[62:63], s[70:71], exec
	s_cselect_b32 s15, s73, s77
	s_cselect_b32 s33, s72, s76
	s_add_u32 s74, s35, s66
	s_addc_u32 s75, s85, s67
	s_and_b64 s[62:63], s[70:71], exec
	s_cselect_b32 s34, s75, s79
	s_cselect_b32 s39, s74, s78
	s_add_i32 s45, s7, -2
	s_add_u32 s76, s76, 0x100080
	s_addc_u32 s77, s77, 0
	s_add_u32 s47, s78, 0x100
	s_addc_u32 s62, s79, 0
	s_mov_b32 s63, 0
	s_waitcnt vmcnt(0)
	ds_read_b128 v[114:117], v190
	ds_read_b128 v[118:121], v190 offset:1024
	ds_read_b128 v[122:125], v190 offset:2048
	ds_read_b128 v[126:129], v190 offset:3072
	ds_read_b128 v[146:149], v191
	ds_read_b128 v[150:153], v191 offset:1024
	ds_read_b128 v[154:157], v191 offset:2048
	ds_read_b128 v[158:161], v191 offset:3072
	s_add_i32 s82, s63, 2
	s_add_u32 s78, s76, 0xfff00080
	s_addc_u32 s79, s77, -1
	s_cmp_eq_u32 s45, s63
	s_cselect_b32 s81, s15, s79
	s_cselect_b32 s80, s33, s78
	s_cselect_b32 s79, s34, s62
	s_cselect_b32 s78, s39, s47
	v_lshl_add_u64 v[186:187], s[76:77], 0, v[180:181]
	s_add_i32 m0, s87, 0xc000
	ds_read_b128 v[162:165], v192
	ds_read_b128 v[166:169], v192 offset:1024
	ds_read_b128 v[194:197], v192 offset:2048
	ds_read_b128 v[198:201], v192 offset:3072
	ds_read_b128 v[206:209], v192 offset:4096
	ds_read_b128 v[210:213], v192 offset:5120
	ds_read_b128 v[214:217], v192 offset:6144
	ds_read_b128 v[218:221], v192 offset:7168
	global_load_lds_dwordx4 v[186:187], off
	s_add_i32 m0, s87, 0xe000
	v_lshl_add_u64 v[186:187], s[76:77], 0, v[182:183]
	global_load_lds_dwordx4 v[186:187], off
	s_waitcnt vmcnt(8) lgkmcnt(0)
	s_setprio 1
	s_barrier
	v_mfma_f32_16x16x32_bf16 v[142:145], v[114:117], v[162:165], 0
	v_mfma_f32_16x16x32_bf16 v[138:141], v[122:125], v[162:165], 0
	v_mfma_f32_16x16x32_bf16 v[110:113], v[114:117], v[194:197], 0
	v_mfma_f32_16x16x32_bf16 v[106:109], v[122:125], v[194:197], 0
	v_mfma_f32_16x16x32_bf16 v[98:101], v[114:117], v[206:209], 0
	v_mfma_f32_16x16x32_bf16 v[90:93], v[122:125], v[206:209], 0
	v_mfma_f32_16x16x32_bf16 v[82:85], v[114:117], v[214:217], 0
	v_mfma_f32_16x16x32_bf16 v[74:77], v[122:125], v[214:217], 0
	v_mfma_f32_16x16x32_bf16 v[142:145], v[118:121], v[166:169], v[142:145]
	v_mfma_f32_16x16x32_bf16 v[138:141], v[126:129], v[166:169], v[138:141]
	v_mfma_f32_16x16x32_bf16 v[110:113], v[118:121], v[198:201], v[110:113]
	v_mfma_f32_16x16x32_bf16 v[106:109], v[126:129], v[198:201], v[106:109]
	v_mfma_f32_16x16x32_bf16 v[98:101], v[118:121], v[210:213], v[98:101]
	v_mfma_f32_16x16x32_bf16 v[90:93], v[126:129], v[210:213], v[90:93]
	v_mfma_f32_16x16x32_bf16 v[82:85], v[118:121], v[218:221], v[82:85]
	v_mfma_f32_16x16x32_bf16 v[74:77], v[126:129], v[218:221], v[74:77]
	v_mfma_f32_16x16x32_bf16 v[134:137], v[146:149], v[162:165], 0
	v_mfma_f32_16x16x32_bf16 v[130:133], v[154:157], v[162:165], 0
	v_mfma_f32_16x16x32_bf16 v[102:105], v[146:149], v[194:197], 0
	v_mfma_f32_16x16x32_bf16 v[94:97], v[154:157], v[194:197], 0
	v_mfma_f32_16x16x32_bf16 v[86:89], v[146:149], v[206:209], 0
	v_mfma_f32_16x16x32_bf16 v[78:81], v[154:157], v[206:209], 0
	v_mfma_f32_16x16x32_bf16 v[70:73], v[146:149], v[214:217], 0
	v_mfma_f32_16x16x32_bf16 v[66:69], v[154:157], v[214:217], 0
	v_mfma_f32_16x16x32_bf16 v[134:137], v[150:153], v[166:169], v[134:137]
	v_mfma_f32_16x16x32_bf16 v[130:133], v[158:161], v[166:169], v[130:133]
	v_mfma_f32_16x16x32_bf16 v[102:105], v[150:153], v[198:201], v[102:105]
	v_mfma_f32_16x16x32_bf16 v[94:97], v[158:161], v[198:201], v[94:97]
	v_mfma_f32_16x16x32_bf16 v[86:89], v[150:153], v[210:213], v[86:89]
	v_mfma_f32_16x16x32_bf16 v[78:81], v[158:161], v[210:213], v[78:81]
	v_mfma_f32_16x16x32_bf16 v[70:73], v[150:153], v[218:221], v[70:73]
	v_mfma_f32_16x16x32_bf16 v[66:69], v[158:161], v[218:221], v[66:69]
	s_setprio 0
	s_barrier
	s_add_i32 s63, s24, s86
	s_mov_b32 m0, s63
	v_lshl_add_u64 v[186:187], s[78:79], 0, v[172:173]
	global_load_lds_dwordx4 v[186:187], off
	ds_read_b128 v[162:165], v192 offset:16384
	ds_read_b128 v[166:169], v192 offset:17408
	ds_read_b128 v[194:197], v192 offset:18432
	ds_read_b128 v[198:201], v192 offset:19456
	ds_read_b128 v[206:209], v192 offset:20480
	ds_read_b128 v[210:213], v192 offset:21504
	ds_read_b128 v[214:217], v192 offset:22528
	ds_read_b128 v[218:221], v192 offset:23552
	s_add_i32 m0, s63, 0x2000
	s_add_u32 vcc_lo, s78, 0x100000
	v_lshl_add_u64 v[202:203], s[78:79], 0, v[176:177]
	s_addc_u32 vcc_hi, s79, 0
	s_add_i32 s63, s25, s86
	global_load_lds_dwordx4 v[202:203], off
	v_lshl_add_u64 v[222:223], vcc, 0, v[172:173]
	s_mov_b32 m0, s63
	v_lshl_add_u64 v[224:225], s[80:81], 0, v[174:175]
	global_load_lds_dwordx4 v[222:223], off
	s_add_i32 m0, s63, 0x2000
	v_lshl_add_u64 v[222:223], vcc, 0, v[176:177]
	global_load_lds_dwordx4 v[222:223], off
	s_mov_b32 m0, s87
	v_lshl_add_u64 v[222:223], s[80:81], 0, v[170:171]
	global_load_lds_dwordx4 v[222:223], off
	s_mov_b32 m0, s88
	s_nop 0
	global_load_lds_dwordx4 v[224:225], off
	s_waitcnt vmcnt(8) lgkmcnt(0)
	s_setprio 1
	s_barrier
	v_mfma_f32_16x16x32_bf16 v[62:65], v[114:117], v[162:165], 0
	v_mfma_f32_16x16x32_bf16 v[58:61], v[122:125], v[162:165], 0
	v_mfma_f32_16x16x32_bf16 v[50:53], v[114:117], v[194:197], 0
	v_mfma_f32_16x16x32_bf16 v[42:45], v[122:125], v[194:197], 0
	v_mfma_f32_16x16x32_bf16 v[34:37], v[114:117], v[206:209], 0
	v_mfma_f32_16x16x32_bf16 v[26:29], v[122:125], v[206:209], 0
	v_mfma_f32_16x16x32_bf16 v[18:21], v[114:117], v[214:217], 0
	v_mfma_f32_16x16x32_bf16 v[10:13], v[122:125], v[214:217], 0
	v_mfma_f32_16x16x32_bf16 v[62:65], v[118:121], v[166:169], v[62:65]
	v_mfma_f32_16x16x32_bf16 v[58:61], v[126:129], v[166:169], v[58:61]
	v_mfma_f32_16x16x32_bf16 v[50:53], v[118:121], v[198:201], v[50:53]
	v_mfma_f32_16x16x32_bf16 v[42:45], v[126:129], v[198:201], v[42:45]
	v_mfma_f32_16x16x32_bf16 v[34:37], v[118:121], v[210:213], v[34:37]
	v_mfma_f32_16x16x32_bf16 v[26:29], v[126:129], v[210:213], v[26:29]
	v_mfma_f32_16x16x32_bf16 v[18:21], v[118:121], v[218:221], v[18:21]
	v_mfma_f32_16x16x32_bf16 v[10:13], v[126:129], v[218:221], v[10:13]
	v_mfma_f32_16x16x32_bf16 v[54:57], v[146:149], v[162:165], 0
	v_mfma_f32_16x16x32_bf16 v[46:49], v[154:157], v[162:165], 0
	v_mfma_f32_16x16x32_bf16 v[38:41], v[146:149], v[194:197], 0
	v_mfma_f32_16x16x32_bf16 v[30:33], v[154:157], v[194:197], 0
	v_mfma_f32_16x16x32_bf16 v[22:25], v[146:149], v[206:209], 0
	v_mfma_f32_16x16x32_bf16 v[14:17], v[154:157], v[206:209], 0
	v_mfma_f32_16x16x32_bf16 v[6:9], v[146:149], v[214:217], 0
	v_mfma_f32_16x16x32_bf16 v[2:5], v[154:157], v[214:217], 0
	v_mfma_f32_16x16x32_bf16 v[54:57], v[150:153], v[166:169], v[54:57]
	v_mfma_f32_16x16x32_bf16 v[46:49], v[158:161], v[166:169], v[46:49]
	v_mfma_f32_16x16x32_bf16 v[38:41], v[150:153], v[198:201], v[38:41]
	v_mfma_f32_16x16x32_bf16 v[30:33], v[158:161], v[198:201], v[30:33]
	v_mfma_f32_16x16x32_bf16 v[22:25], v[150:153], v[210:213], v[22:25]
	v_mfma_f32_16x16x32_bf16 v[14:17], v[158:161], v[210:213], v[14:17]
	v_mfma_f32_16x16x32_bf16 v[6:9], v[150:153], v[218:221], v[6:9]
	v_mfma_f32_16x16x32_bf16 v[2:5], v[158:161], v[218:221], v[2:5]
	s_setprio 0
	s_barrier
	s_add_i32 s63, 0, 0x18000
	s_add_i32 s83, 0, 0x1c000
	v_add_u32_e32 v126, s63, v189
	v_add_u32_e32 v158, s83, v189
	ds_read_b128 v[114:117], v126
	ds_read_b128 v[118:121], v126 offset:1024
	ds_read_b128 v[122:125], v126 offset:2048
	ds_read_b128 v[126:129], v126 offset:3072
	ds_read_b128 v[146:149], v158
	ds_read_b128 v[150:153], v158 offset:1024
	ds_read_b128 v[154:157], v158 offset:2048
	ds_read_b128 v[158:161], v158 offset:3072
	s_add_u32 s80, s80, 0x100000
	s_addc_u32 s81, s81, 0
	s_mov_b32 m0, s89
	v_lshl_add_u64 v[226:227], s[80:81], 0, v[170:171]
	ds_read_b128 v[162:165], v192 offset:32768
	ds_read_b128 v[166:169], v192 offset:33792
	ds_read_b128 v[194:197], v192 offset:34816
	ds_read_b128 v[198:201], v192 offset:35840
	ds_read_b128 v[206:209], v192 offset:36864
	ds_read_b128 v[210:213], v192 offset:37888
	ds_read_b128 v[214:217], v192 offset:38912
	ds_read_b128 v[218:221], v192 offset:39936
	global_load_lds_dwordx4 v[226:227], off
	s_mov_b32 m0, s90
	v_lshl_add_u64 v[226:227], s[80:81], 0, v[174:175]
	global_load_lds_dwordx4 v[226:227], off
	s_waitcnt vmcnt(8) lgkmcnt(0)
	s_setprio 1
	s_barrier
	v_mfma_f32_16x16x32_bf16 v[142:145], v[114:117], v[162:165], v[142:145]
	v_mfma_f32_16x16x32_bf16 v[138:141], v[122:125], v[162:165], v[138:141]
	v_mfma_f32_16x16x32_bf16 v[110:113], v[114:117], v[194:197], v[110:113]
	v_mfma_f32_16x16x32_bf16 v[106:109], v[122:125], v[194:197], v[106:109]
	v_mfma_f32_16x16x32_bf16 v[98:101], v[114:117], v[206:209], v[98:101]
	v_mfma_f32_16x16x32_bf16 v[90:93], v[122:125], v[206:209], v[90:93]
	v_mfma_f32_16x16x32_bf16 v[82:85], v[114:117], v[214:217], v[82:85]
	v_mfma_f32_16x16x32_bf16 v[74:77], v[122:125], v[214:217], v[74:77]
	v_mfma_f32_16x16x32_bf16 v[142:145], v[118:121], v[166:169], v[142:145]
	v_mfma_f32_16x16x32_bf16 v[138:141], v[126:129], v[166:169], v[138:141]
	v_mfma_f32_16x16x32_bf16 v[110:113], v[118:121], v[198:201], v[110:113]
	v_mfma_f32_16x16x32_bf16 v[106:109], v[126:129], v[198:201], v[106:109]
	v_mfma_f32_16x16x32_bf16 v[98:101], v[118:121], v[210:213], v[98:101]
	v_mfma_f32_16x16x32_bf16 v[90:93], v[126:129], v[210:213], v[90:93]
	v_mfma_f32_16x16x32_bf16 v[82:85], v[118:121], v[218:221], v[82:85]
	v_mfma_f32_16x16x32_bf16 v[74:77], v[126:129], v[218:221], v[74:77]
	v_mfma_f32_16x16x32_bf16 v[134:137], v[146:149], v[162:165], v[134:137]
	v_mfma_f32_16x16x32_bf16 v[130:133], v[154:157], v[162:165], v[130:133]
	v_mfma_f32_16x16x32_bf16 v[102:105], v[146:149], v[194:197], v[102:105]
	v_mfma_f32_16x16x32_bf16 v[94:97], v[154:157], v[194:197], v[94:97]
	v_mfma_f32_16x16x32_bf16 v[86:89], v[146:149], v[206:209], v[86:89]
	v_mfma_f32_16x16x32_bf16 v[78:81], v[154:157], v[206:209], v[78:81]
	v_mfma_f32_16x16x32_bf16 v[70:73], v[146:149], v[214:217], v[70:73]
	v_mfma_f32_16x16x32_bf16 v[66:69], v[154:157], v[214:217], v[66:69]
	v_mfma_f32_16x16x32_bf16 v[134:137], v[150:153], v[166:169], v[134:137]
	v_mfma_f32_16x16x32_bf16 v[130:133], v[158:161], v[166:169], v[130:133]
	v_mfma_f32_16x16x32_bf16 v[102:105], v[150:153], v[198:201], v[102:105]
	v_mfma_f32_16x16x32_bf16 v[94:97], v[158:161], v[198:201], v[94:97]
	v_mfma_f32_16x16x32_bf16 v[86:89], v[150:153], v[210:213], v[86:89]
	v_mfma_f32_16x16x32_bf16 v[78:81], v[158:161], v[210:213], v[78:81]
	v_mfma_f32_16x16x32_bf16 v[70:73], v[150:153], v[218:221], v[70:73]
	v_mfma_f32_16x16x32_bf16 v[66:69], v[158:161], v[218:221], v[66:69]
	s_setprio 0
	s_barrier
	s_add_i32 s63, s63, s86
	s_mov_b32 m0, s63
	v_lshl_add_u64 v[186:187], v[186:187], 0, s[22:23]
	global_load_lds_dwordx4 v[186:187], off
	ds_read_b128 v[162:165], v192 offset:49152
	ds_read_b128 v[166:169], v192 offset:50176
	ds_read_b128 v[194:197], v192 offset:51200
	ds_read_b128 v[198:201], v192 offset:52224
	ds_read_b128 v[206:209], v192 offset:53248
	ds_read_b128 v[210:213], v192 offset:54272
	ds_read_b128 v[214:217], v192 offset:55296
	ds_read_b128 v[218:221], v192 offset:56320
	s_add_i32 m0, s63, 0x2000
	s_add_u32 s78, s78, 0x100080
	v_lshl_add_u64 v[186:187], v[202:203], 0, s[22:23]
	s_addc_u32 s79, s79, 0
	s_add_i32 s63, s83, s86
	global_load_lds_dwordx4 v[186:187], off
	s_mov_b32 m0, s63
	v_lshl_add_u64 v[186:187], s[78:79], 0, v[172:173]
	global_load_lds_dwordx4 v[186:187], off
	s_add_i32 m0, s63, 0x2000
	v_lshl_add_u64 v[186:187], s[78:79], 0, v[176:177]
	global_load_lds_dwordx4 v[186:187], off
	s_mov_b32 m0, s95
	v_lshl_add_u64 v[186:187], v[222:223], 0, s[22:23]
	global_load_lds_dwordx4 v[186:187], off
	s_mov_b32 m0, s96
	v_lshl_add_u64 v[186:187], v[224:225], 0, s[22:23]
	global_load_lds_dwordx4 v[186:187], off
	s_waitcnt vmcnt(8) lgkmcnt(0)
	s_setprio 1
	s_barrier
	v_mfma_f32_16x16x32_bf16 v[62:65], v[114:117], v[162:165], v[62:65]
	v_mfma_f32_16x16x32_bf16 v[58:61], v[122:125], v[162:165], v[58:61]
	v_mfma_f32_16x16x32_bf16 v[50:53], v[114:117], v[194:197], v[50:53]
	v_mfma_f32_16x16x32_bf16 v[42:45], v[122:125], v[194:197], v[42:45]
	v_mfma_f32_16x16x32_bf16 v[34:37], v[114:117], v[206:209], v[34:37]
	v_mfma_f32_16x16x32_bf16 v[26:29], v[122:125], v[206:209], v[26:29]
	v_mfma_f32_16x16x32_bf16 v[18:21], v[114:117], v[214:217], v[18:21]
	v_mfma_f32_16x16x32_bf16 v[10:13], v[122:125], v[214:217], v[10:13]
	v_mfma_f32_16x16x32_bf16 v[62:65], v[118:121], v[166:169], v[62:65]
	v_mfma_f32_16x16x32_bf16 v[58:61], v[126:129], v[166:169], v[58:61]
	v_mfma_f32_16x16x32_bf16 v[50:53], v[118:121], v[198:201], v[50:53]
	v_mfma_f32_16x16x32_bf16 v[42:45], v[126:129], v[198:201], v[42:45]
	v_mfma_f32_16x16x32_bf16 v[34:37], v[118:121], v[210:213], v[34:37]
	v_mfma_f32_16x16x32_bf16 v[26:29], v[126:129], v[210:213], v[26:29]
	v_mfma_f32_16x16x32_bf16 v[18:21], v[118:121], v[218:221], v[18:21]
	v_mfma_f32_16x16x32_bf16 v[10:13], v[126:129], v[218:221], v[10:13]
	v_mfma_f32_16x16x32_bf16 v[54:57], v[146:149], v[162:165], v[54:57]
	v_mfma_f32_16x16x32_bf16 v[46:49], v[154:157], v[162:165], v[46:49]
	v_mfma_f32_16x16x32_bf16 v[38:41], v[146:149], v[194:197], v[38:41]
	v_mfma_f32_16x16x32_bf16 v[30:33], v[154:157], v[194:197], v[30:33]
	v_mfma_f32_16x16x32_bf16 v[22:25], v[146:149], v[206:209], v[22:25]
	v_mfma_f32_16x16x32_bf16 v[14:17], v[154:157], v[206:209], v[14:17]
	v_mfma_f32_16x16x32_bf16 v[6:9], v[146:149], v[214:217], v[6:9]
	v_mfma_f32_16x16x32_bf16 v[2:5], v[154:157], v[214:217], v[2:5]
	v_mfma_f32_16x16x32_bf16 v[54:57], v[150:153], v[166:169], v[54:57]
	v_mfma_f32_16x16x32_bf16 v[46:49], v[158:161], v[166:169], v[46:49]
	v_mfma_f32_16x16x32_bf16 v[38:41], v[150:153], v[198:201], v[38:41]
	v_mfma_f32_16x16x32_bf16 v[30:33], v[158:161], v[198:201], v[30:33]
	v_mfma_f32_16x16x32_bf16 v[22:25], v[150:153], v[210:213], v[22:25]
	v_mfma_f32_16x16x32_bf16 v[14:17], v[158:161], v[210:213], v[14:17]
	v_mfma_f32_16x16x32_bf16 v[6:9], v[150:153], v[218:221], v[6:9]
	v_mfma_f32_16x16x32_bf16 v[2:5], v[158:161], v[218:221], v[2:5]
	s_setprio 0
	s_barrier
	s_add_u32 s76, s76, 0x100
	s_addc_u32 s77, s77, 0
	s_add_u32 s47, s47, 0x100
	s_addc_u32 s62, s62, 0
	s_cmp_ge_i32 s82, s7
	s_mov_b32 s63, s82
.LBB0_834:
	ds_read_b128 v[114:117], v190
	ds_read_b128 v[118:121], v190 offset:1024
	ds_read_b128 v[122:125], v190 offset:2048
	ds_read_b128 v[126:129], v190 offset:3072
	ds_read_b128 v[146:149], v191
	ds_read_b128 v[150:153], v191 offset:1024
	ds_read_b128 v[154:157], v191 offset:2048
	ds_read_b128 v[158:161], v191 offset:3072
	s_add_i32 s82, s63, 2
	s_add_u32 s78, s76, 0xfff00080
	s_addc_u32 s79, s77, -1
	s_cmp_eq_u32 s45, s63
	s_cselect_b32 s81, s15, s79
	s_cselect_b32 s80, s33, s78
	s_cselect_b32 s79, s34, s62
	s_cselect_b32 s78, s39, s47
	v_lshl_add_u64 v[186:187], s[76:77], 0, v[180:181]
	s_add_i32 m0, s87, 0xc000
	ds_read_b128 v[162:165], v192
	ds_read_b128 v[166:169], v192 offset:1024
	ds_read_b128 v[194:197], v192 offset:2048
	ds_read_b128 v[198:201], v192 offset:3072
	ds_read_b128 v[206:209], v192 offset:4096
	ds_read_b128 v[210:213], v192 offset:5120
	ds_read_b128 v[214:217], v192 offset:6144
	ds_read_b128 v[218:221], v192 offset:7168
	global_load_lds_dwordx4 v[186:187], off
	s_add_i32 m0, s87, 0xe000
	v_lshl_add_u64 v[186:187], s[76:77], 0, v[182:183]
	global_load_lds_dwordx4 v[186:187], off
	s_waitcnt vmcnt(8) lgkmcnt(0)
	s_setprio 1
	s_barrier
	v_mfma_f32_16x16x32_bf16 v[142:145], v[114:117], v[162:165], v[142:145]
	v_mfma_f32_16x16x32_bf16 v[138:141], v[122:125], v[162:165], v[138:141]
	v_mfma_f32_16x16x32_bf16 v[110:113], v[114:117], v[194:197], v[110:113]
	v_mfma_f32_16x16x32_bf16 v[106:109], v[122:125], v[194:197], v[106:109]
	v_mfma_f32_16x16x32_bf16 v[98:101], v[114:117], v[206:209], v[98:101]
	v_mfma_f32_16x16x32_bf16 v[90:93], v[122:125], v[206:209], v[90:93]
	v_mfma_f32_16x16x32_bf16 v[82:85], v[114:117], v[214:217], v[82:85]
	v_mfma_f32_16x16x32_bf16 v[74:77], v[122:125], v[214:217], v[74:77]
	v_mfma_f32_16x16x32_bf16 v[142:145], v[118:121], v[166:169], v[142:145]
	v_mfma_f32_16x16x32_bf16 v[138:141], v[126:129], v[166:169], v[138:141]
	v_mfma_f32_16x16x32_bf16 v[110:113], v[118:121], v[198:201], v[110:113]
	v_mfma_f32_16x16x32_bf16 v[106:109], v[126:129], v[198:201], v[106:109]
	v_mfma_f32_16x16x32_bf16 v[98:101], v[118:121], v[210:213], v[98:101]
	v_mfma_f32_16x16x32_bf16 v[90:93], v[126:129], v[210:213], v[90:93]
	v_mfma_f32_16x16x32_bf16 v[82:85], v[118:121], v[218:221], v[82:85]
	v_mfma_f32_16x16x32_bf16 v[74:77], v[126:129], v[218:221], v[74:77]
	v_mfma_f32_16x16x32_bf16 v[134:137], v[146:149], v[162:165], v[134:137]
	v_mfma_f32_16x16x32_bf16 v[130:133], v[154:157], v[162:165], v[130:133]
	v_mfma_f32_16x16x32_bf16 v[102:105], v[146:149], v[194:197], v[102:105]
	v_mfma_f32_16x16x32_bf16 v[94:97], v[154:157], v[194:197], v[94:97]
	v_mfma_f32_16x16x32_bf16 v[86:89], v[146:149], v[206:209], v[86:89]
	v_mfma_f32_16x16x32_bf16 v[78:81], v[154:157], v[206:209], v[78:81]
	v_mfma_f32_16x16x32_bf16 v[70:73], v[146:149], v[214:217], v[70:73]
	v_mfma_f32_16x16x32_bf16 v[66:69], v[154:157], v[214:217], v[66:69]
	v_mfma_f32_16x16x32_bf16 v[134:137], v[150:153], v[166:169], v[134:137]
	v_mfma_f32_16x16x32_bf16 v[130:133], v[158:161], v[166:169], v[130:133]
	v_mfma_f32_16x16x32_bf16 v[102:105], v[150:153], v[198:201], v[102:105]
	v_mfma_f32_16x16x32_bf16 v[94:97], v[158:161], v[198:201], v[94:97]
	v_mfma_f32_16x16x32_bf16 v[86:89], v[150:153], v[210:213], v[86:89]
	v_mfma_f32_16x16x32_bf16 v[78:81], v[158:161], v[210:213], v[78:81]
	v_mfma_f32_16x16x32_bf16 v[70:73], v[150:153], v[218:221], v[70:73]
	v_mfma_f32_16x16x32_bf16 v[66:69], v[158:161], v[218:221], v[66:69]
	s_setprio 0
	s_barrier
	s_add_i32 s63, s24, s86
	s_mov_b32 m0, s63
	v_lshl_add_u64 v[186:187], s[78:79], 0, v[172:173]
	global_load_lds_dwordx4 v[186:187], off
	ds_read_b128 v[162:165], v192 offset:16384
	ds_read_b128 v[166:169], v192 offset:17408
	ds_read_b128 v[194:197], v192 offset:18432
	ds_read_b128 v[198:201], v192 offset:19456
	ds_read_b128 v[206:209], v192 offset:20480
	ds_read_b128 v[210:213], v192 offset:21504
	ds_read_b128 v[214:217], v192 offset:22528
	ds_read_b128 v[218:221], v192 offset:23552
	s_add_i32 m0, s63, 0x2000
	s_add_u32 vcc_lo, s78, 0x100000
	v_lshl_add_u64 v[202:203], s[78:79], 0, v[176:177]
	s_addc_u32 vcc_hi, s79, 0
	s_add_i32 s63, s25, s86
	global_load_lds_dwordx4 v[202:203], off
	v_lshl_add_u64 v[222:223], vcc, 0, v[172:173]
	s_mov_b32 m0, s63
	v_lshl_add_u64 v[224:225], s[80:81], 0, v[174:175]
	global_load_lds_dwordx4 v[222:223], off
	s_add_i32 m0, s63, 0x2000
	v_lshl_add_u64 v[222:223], vcc, 0, v[176:177]
	global_load_lds_dwordx4 v[222:223], off
	s_mov_b32 m0, s87
	v_lshl_add_u64 v[222:223], s[80:81], 0, v[170:171]
	global_load_lds_dwordx4 v[222:223], off
	s_mov_b32 m0, s88
	s_nop 0
	global_load_lds_dwordx4 v[224:225], off
	s_waitcnt vmcnt(8) lgkmcnt(0)
	s_setprio 1
	s_barrier
	v_mfma_f32_16x16x32_bf16 v[62:65], v[114:117], v[162:165], v[62:65]
	v_mfma_f32_16x16x32_bf16 v[58:61], v[122:125], v[162:165], v[58:61]
	v_mfma_f32_16x16x32_bf16 v[50:53], v[114:117], v[194:197], v[50:53]
	v_mfma_f32_16x16x32_bf16 v[42:45], v[122:125], v[194:197], v[42:45]
	v_mfma_f32_16x16x32_bf16 v[34:37], v[114:117], v[206:209], v[34:37]
	v_mfma_f32_16x16x32_bf16 v[26:29], v[122:125], v[206:209], v[26:29]
	v_mfma_f32_16x16x32_bf16 v[18:21], v[114:117], v[214:217], v[18:21]
	v_mfma_f32_16x16x32_bf16 v[10:13], v[122:125], v[214:217], v[10:13]
	v_mfma_f32_16x16x32_bf16 v[62:65], v[118:121], v[166:169], v[62:65]
	v_mfma_f32_16x16x32_bf16 v[58:61], v[126:129], v[166:169], v[58:61]
	v_mfma_f32_16x16x32_bf16 v[50:53], v[118:121], v[198:201], v[50:53]
	v_mfma_f32_16x16x32_bf16 v[42:45], v[126:129], v[198:201], v[42:45]
	v_mfma_f32_16x16x32_bf16 v[34:37], v[118:121], v[210:213], v[34:37]
	v_mfma_f32_16x16x32_bf16 v[26:29], v[126:129], v[210:213], v[26:29]
	v_mfma_f32_16x16x32_bf16 v[18:21], v[118:121], v[218:221], v[18:21]
	v_mfma_f32_16x16x32_bf16 v[10:13], v[126:129], v[218:221], v[10:13]
	v_mfma_f32_16x16x32_bf16 v[54:57], v[146:149], v[162:165], v[54:57]
	v_mfma_f32_16x16x32_bf16 v[46:49], v[154:157], v[162:165], v[46:49]
	v_mfma_f32_16x16x32_bf16 v[38:41], v[146:149], v[194:197], v[38:41]
	v_mfma_f32_16x16x32_bf16 v[30:33], v[154:157], v[194:197], v[30:33]
	v_mfma_f32_16x16x32_bf16 v[22:25], v[146:149], v[206:209], v[22:25]
	v_mfma_f32_16x16x32_bf16 v[14:17], v[154:157], v[206:209], v[14:17]
	v_mfma_f32_16x16x32_bf16 v[6:9], v[146:149], v[214:217], v[6:9]
	v_mfma_f32_16x16x32_bf16 v[2:5], v[154:157], v[214:217], v[2:5]
	v_mfma_f32_16x16x32_bf16 v[54:57], v[150:153], v[166:169], v[54:57]
	v_mfma_f32_16x16x32_bf16 v[46:49], v[158:161], v[166:169], v[46:49]
	v_mfma_f32_16x16x32_bf16 v[38:41], v[150:153], v[198:201], v[38:41]
	v_mfma_f32_16x16x32_bf16 v[30:33], v[158:161], v[198:201], v[30:33]
	v_mfma_f32_16x16x32_bf16 v[22:25], v[150:153], v[210:213], v[22:25]
	v_mfma_f32_16x16x32_bf16 v[14:17], v[158:161], v[210:213], v[14:17]
	v_mfma_f32_16x16x32_bf16 v[6:9], v[150:153], v[218:221], v[6:9]
	v_mfma_f32_16x16x32_bf16 v[2:5], v[158:161], v[218:221], v[2:5]
	s_setprio 0
	s_barrier
	s_add_i32 s63, 0, 0x18000
	s_add_i32 s83, 0, 0x1c000
	v_add_u32_e32 v126, s63, v189
	v_add_u32_e32 v158, s83, v189
	ds_read_b128 v[114:117], v126
	ds_read_b128 v[118:121], v126 offset:1024
	ds_read_b128 v[122:125], v126 offset:2048
	ds_read_b128 v[126:129], v126 offset:3072
	ds_read_b128 v[146:149], v158
	ds_read_b128 v[150:153], v158 offset:1024
	ds_read_b128 v[154:157], v158 offset:2048
	ds_read_b128 v[158:161], v158 offset:3072
	s_add_u32 s80, s80, 0x100000
	s_addc_u32 s81, s81, 0
	s_mov_b32 m0, s89
	v_lshl_add_u64 v[226:227], s[80:81], 0, v[170:171]
	ds_read_b128 v[162:165], v192 offset:32768
	ds_read_b128 v[166:169], v192 offset:33792
	ds_read_b128 v[194:197], v192 offset:34816
	ds_read_b128 v[198:201], v192 offset:35840
	ds_read_b128 v[206:209], v192 offset:36864
	ds_read_b128 v[210:213], v192 offset:37888
	ds_read_b128 v[214:217], v192 offset:38912
	ds_read_b128 v[218:221], v192 offset:39936
	global_load_lds_dwordx4 v[226:227], off
	s_mov_b32 m0, s90
	v_lshl_add_u64 v[226:227], s[80:81], 0, v[174:175]
	global_load_lds_dwordx4 v[226:227], off
	s_waitcnt vmcnt(8) lgkmcnt(0)
	s_setprio 1
	s_barrier
	v_mfma_f32_16x16x32_bf16 v[142:145], v[114:117], v[162:165], v[142:145]
	v_mfma_f32_16x16x32_bf16 v[138:141], v[122:125], v[162:165], v[138:141]
	v_mfma_f32_16x16x32_bf16 v[110:113], v[114:117], v[194:197], v[110:113]
	v_mfma_f32_16x16x32_bf16 v[106:109], v[122:125], v[194:197], v[106:109]
	v_mfma_f32_16x16x32_bf16 v[98:101], v[114:117], v[206:209], v[98:101]
	v_mfma_f32_16x16x32_bf16 v[90:93], v[122:125], v[206:209], v[90:93]
	v_mfma_f32_16x16x32_bf16 v[82:85], v[114:117], v[214:217], v[82:85]
	v_mfma_f32_16x16x32_bf16 v[74:77], v[122:125], v[214:217], v[74:77]
	v_mfma_f32_16x16x32_bf16 v[142:145], v[118:121], v[166:169], v[142:145]
	v_mfma_f32_16x16x32_bf16 v[138:141], v[126:129], v[166:169], v[138:141]
	v_mfma_f32_16x16x32_bf16 v[110:113], v[118:121], v[198:201], v[110:113]
	v_mfma_f32_16x16x32_bf16 v[106:109], v[126:129], v[198:201], v[106:109]
	v_mfma_f32_16x16x32_bf16 v[98:101], v[118:121], v[210:213], v[98:101]
	v_mfma_f32_16x16x32_bf16 v[90:93], v[126:129], v[210:213], v[90:93]
	v_mfma_f32_16x16x32_bf16 v[82:85], v[118:121], v[218:221], v[82:85]
	v_mfma_f32_16x16x32_bf16 v[74:77], v[126:129], v[218:221], v[74:77]
	v_mfma_f32_16x16x32_bf16 v[134:137], v[146:149], v[162:165], v[134:137]
	v_mfma_f32_16x16x32_bf16 v[130:133], v[154:157], v[162:165], v[130:133]
	v_mfma_f32_16x16x32_bf16 v[102:105], v[146:149], v[194:197], v[102:105]
	v_mfma_f32_16x16x32_bf16 v[94:97], v[154:157], v[194:197], v[94:97]
	v_mfma_f32_16x16x32_bf16 v[86:89], v[146:149], v[206:209], v[86:89]
	v_mfma_f32_16x16x32_bf16 v[78:81], v[154:157], v[206:209], v[78:81]
	v_mfma_f32_16x16x32_bf16 v[70:73], v[146:149], v[214:217], v[70:73]
	v_mfma_f32_16x16x32_bf16 v[66:69], v[154:157], v[214:217], v[66:69]
	v_mfma_f32_16x16x32_bf16 v[134:137], v[150:153], v[166:169], v[134:137]
	v_mfma_f32_16x16x32_bf16 v[130:133], v[158:161], v[166:169], v[130:133]
	v_mfma_f32_16x16x32_bf16 v[102:105], v[150:153], v[198:201], v[102:105]
	v_mfma_f32_16x16x32_bf16 v[94:97], v[158:161], v[198:201], v[94:97]
	v_mfma_f32_16x16x32_bf16 v[86:89], v[150:153], v[210:213], v[86:89]
	v_mfma_f32_16x16x32_bf16 v[78:81], v[158:161], v[210:213], v[78:81]
	v_mfma_f32_16x16x32_bf16 v[70:73], v[150:153], v[218:221], v[70:73]
	v_mfma_f32_16x16x32_bf16 v[66:69], v[158:161], v[218:221], v[66:69]
	s_setprio 0
	s_barrier
	s_add_i32 s63, s63, s86
	s_mov_b32 m0, s63
	v_lshl_add_u64 v[186:187], v[186:187], 0, s[22:23]
	global_load_lds_dwordx4 v[186:187], off
	ds_read_b128 v[162:165], v192 offset:49152
	ds_read_b128 v[166:169], v192 offset:50176
	ds_read_b128 v[194:197], v192 offset:51200
	ds_read_b128 v[198:201], v192 offset:52224
	ds_read_b128 v[206:209], v192 offset:53248
	ds_read_b128 v[210:213], v192 offset:54272
	ds_read_b128 v[214:217], v192 offset:55296
	ds_read_b128 v[218:221], v192 offset:56320
	s_add_i32 m0, s63, 0x2000
	s_add_u32 s78, s78, 0x100080
	v_lshl_add_u64 v[186:187], v[202:203], 0, s[22:23]
	s_addc_u32 s79, s79, 0
	s_add_i32 s63, s83, s86
	global_load_lds_dwordx4 v[186:187], off
	s_mov_b32 m0, s63
	v_lshl_add_u64 v[186:187], s[78:79], 0, v[172:173]
	global_load_lds_dwordx4 v[186:187], off
	s_add_i32 m0, s63, 0x2000
	v_lshl_add_u64 v[186:187], s[78:79], 0, v[176:177]
	global_load_lds_dwordx4 v[186:187], off
	s_mov_b32 m0, s95
	v_lshl_add_u64 v[186:187], v[222:223], 0, s[22:23]
	global_load_lds_dwordx4 v[186:187], off
	s_mov_b32 m0, s96
	v_lshl_add_u64 v[186:187], v[224:225], 0, s[22:23]
	global_load_lds_dwordx4 v[186:187], off
	s_waitcnt vmcnt(8) lgkmcnt(0)
	s_setprio 1
	s_barrier
	v_mfma_f32_16x16x32_bf16 v[62:65], v[114:117], v[162:165], v[62:65]
	v_mfma_f32_16x16x32_bf16 v[58:61], v[122:125], v[162:165], v[58:61]
	v_mfma_f32_16x16x32_bf16 v[50:53], v[114:117], v[194:197], v[50:53]
	v_mfma_f32_16x16x32_bf16 v[42:45], v[122:125], v[194:197], v[42:45]
	v_mfma_f32_16x16x32_bf16 v[34:37], v[114:117], v[206:209], v[34:37]
	v_mfma_f32_16x16x32_bf16 v[26:29], v[122:125], v[206:209], v[26:29]
	v_mfma_f32_16x16x32_bf16 v[18:21], v[114:117], v[214:217], v[18:21]
	v_mfma_f32_16x16x32_bf16 v[10:13], v[122:125], v[214:217], v[10:13]
	v_mfma_f32_16x16x32_bf16 v[62:65], v[118:121], v[166:169], v[62:65]
	v_mfma_f32_16x16x32_bf16 v[58:61], v[126:129], v[166:169], v[58:61]
	v_mfma_f32_16x16x32_bf16 v[50:53], v[118:121], v[198:201], v[50:53]
	v_mfma_f32_16x16x32_bf16 v[42:45], v[126:129], v[198:201], v[42:45]
	v_mfma_f32_16x16x32_bf16 v[34:37], v[118:121], v[210:213], v[34:37]
	v_mfma_f32_16x16x32_bf16 v[26:29], v[126:129], v[210:213], v[26:29]
	v_mfma_f32_16x16x32_bf16 v[18:21], v[118:121], v[218:221], v[18:21]
	v_mfma_f32_16x16x32_bf16 v[10:13], v[126:129], v[218:221], v[10:13]
	v_mfma_f32_16x16x32_bf16 v[54:57], v[146:149], v[162:165], v[54:57]
	v_mfma_f32_16x16x32_bf16 v[46:49], v[154:157], v[162:165], v[46:49]
	v_mfma_f32_16x16x32_bf16 v[38:41], v[146:149], v[194:197], v[38:41]
	v_mfma_f32_16x16x32_bf16 v[30:33], v[154:157], v[194:197], v[30:33]
	v_mfma_f32_16x16x32_bf16 v[22:25], v[146:149], v[206:209], v[22:25]
	v_mfma_f32_16x16x32_bf16 v[14:17], v[154:157], v[206:209], v[14:17]
	v_mfma_f32_16x16x32_bf16 v[6:9], v[146:149], v[214:217], v[6:9]
	v_mfma_f32_16x16x32_bf16 v[2:5], v[154:157], v[214:217], v[2:5]
	v_mfma_f32_16x16x32_bf16 v[54:57], v[150:153], v[166:169], v[54:57]
	v_mfma_f32_16x16x32_bf16 v[46:49], v[158:161], v[166:169], v[46:49]
	v_mfma_f32_16x16x32_bf16 v[38:41], v[150:153], v[198:201], v[38:41]
	v_mfma_f32_16x16x32_bf16 v[30:33], v[158:161], v[198:201], v[30:33]
	v_mfma_f32_16x16x32_bf16 v[22:25], v[150:153], v[210:213], v[22:25]
	v_mfma_f32_16x16x32_bf16 v[14:17], v[158:161], v[210:213], v[14:17]
	v_mfma_f32_16x16x32_bf16 v[6:9], v[150:153], v[218:221], v[6:9]
	v_mfma_f32_16x16x32_bf16 v[2:5], v[158:161], v[218:221], v[2:5]
	s_setprio 0
	s_barrier
	s_add_u32 s76, s76, 0x100
	s_addc_u32 s77, s77, 0
	s_add_u32 s47, s47, 0x100
	s_addc_u32 s62, s62, 0
	s_cmp_ge_i32 s82, s7
	s_mov_b32 s63, s82
	s_cbranch_scc0 .LBB0_834
	s_and_b64 vcc, exec, s[26:27]
	s_cbranch_vccz .LBB0_837
	s_barrier

.LBB0_1012:
	s_add_u32 s48, s96, s44
	s_addc_u32 s49, s97, s45
	s_and_b64 s[14:15], s[4:5], exec
	s_cselect_b32 s6, s49, s65
	s_cselect_b32 s14, s48, s64
	s_add_u32 s50, s3, s46
	s_addc_u32 s51, s35, s47
	s_and_b64 s[18:19], s[4:5], exec
	s_cselect_b32 s15, s51, s67
	s_cselect_b32 s17, s50, s66
	s_add_u32 s64, s64, 0x40080
	s_addc_u32 s65, s65, 0
	s_add_u32 s18, s66, 0x100
	s_addc_u32 s19, s67, 0
	s_mov_b32 s24, -2
	s_waitcnt vmcnt(0)
	ds_read_b128 v[130:133], v172
	ds_read_b128 v[134:137], v172 offset:1024
	ds_read_b128 v[138:141], v172 offset:2048
	ds_read_b128 v[142:145], v172 offset:3072
	ds_read_b128 v[164:167], v173
	ds_read_b128 v[176:179], v173 offset:1024
	ds_read_b128 v[180:183], v173 offset:2048
	ds_read_b128 v[184:187], v173 offset:3072
	s_add_u32 s25, s64, 0xfffc0080
	s_addc_u32 s28, s65, -1
	s_cmp_eq_u32 s24, 12
	s_cselect_b32 s69, s6, s28
	s_cselect_b32 s68, s14, s25
	s_cselect_b32 s67, s15, s19
	s_cselect_b32 s66, s17, s18
	v_lshl_add_u64 v[168:169], s[64:65], 0, v[156:157]
	s_add_i32 m0, s73, 0xc000
	ds_read_b128 v[188:191], v174
	ds_read_b128 v[192:195], v174 offset:1024
	ds_read_b128 v[196:199], v174 offset:2048
	ds_read_b128 v[200:203], v174 offset:3072
	ds_read_b128 v[206:209], v174 offset:4096
	ds_read_b128 v[210:213], v174 offset:5120
	ds_read_b128 v[214:217], v174 offset:6144
	ds_read_b128 v[218:221], v174 offset:7168
	global_load_lds_dwordx4 v[168:169], off
	s_add_i32 m0, s73, 0xe000
	v_lshl_add_u64 v[168:169], s[64:65], 0, v[158:159]
	global_load_lds_dwordx4 v[168:169], off
	s_waitcnt vmcnt(8) lgkmcnt(0)
	s_setprio 1
	s_barrier
	v_mfma_f32_16x16x32_bf16 v[126:129], v[130:133], v[188:191], 0
	v_mfma_f32_16x16x32_bf16 v[122:125], v[138:141], v[188:191], 0
	v_mfma_f32_16x16x32_bf16 v[110:113], v[130:133], v[196:199], 0
	v_mfma_f32_16x16x32_bf16 v[106:109], v[138:141], v[196:199], 0
	v_mfma_f32_16x16x32_bf16 v[94:97], v[130:133], v[206:209], 0
	v_mfma_f32_16x16x32_bf16 v[90:93], v[138:141], v[206:209], 0
	v_mfma_f32_16x16x32_bf16 v[78:81], v[130:133], v[214:217], 0
	v_mfma_f32_16x16x32_bf16 v[74:77], v[138:141], v[214:217], 0
	v_mfma_f32_16x16x32_bf16 v[126:129], v[134:137], v[192:195], v[126:129]
	v_mfma_f32_16x16x32_bf16 v[122:125], v[142:145], v[192:195], v[122:125]
	v_mfma_f32_16x16x32_bf16 v[110:113], v[134:137], v[200:203], v[110:113]
	v_mfma_f32_16x16x32_bf16 v[106:109], v[142:145], v[200:203], v[106:109]
	v_mfma_f32_16x16x32_bf16 v[94:97], v[134:137], v[210:213], v[94:97]
	v_mfma_f32_16x16x32_bf16 v[90:93], v[142:145], v[210:213], v[90:93]
	v_mfma_f32_16x16x32_bf16 v[78:81], v[134:137], v[218:221], v[78:81]
	v_mfma_f32_16x16x32_bf16 v[74:77], v[142:145], v[218:221], v[74:77]
	v_mfma_f32_16x16x32_bf16 v[118:121], v[164:167], v[188:191], 0
	v_mfma_f32_16x16x32_bf16 v[114:117], v[180:183], v[188:191], 0
	v_mfma_f32_16x16x32_bf16 v[102:105], v[164:167], v[196:199], 0
	v_mfma_f32_16x16x32_bf16 v[98:101], v[180:183], v[196:199], 0
	v_mfma_f32_16x16x32_bf16 v[86:89], v[164:167], v[206:209], 0
	v_mfma_f32_16x16x32_bf16 v[82:85], v[180:183], v[206:209], 0
	v_mfma_f32_16x16x32_bf16 v[70:73], v[164:167], v[214:217], 0
	v_mfma_f32_16x16x32_bf16 v[66:69], v[180:183], v[214:217], 0
	v_mfma_f32_16x16x32_bf16 v[118:121], v[176:179], v[192:195], v[118:121]
	v_mfma_f32_16x16x32_bf16 v[114:117], v[184:187], v[192:195], v[114:117]
	v_mfma_f32_16x16x32_bf16 v[102:105], v[176:179], v[200:203], v[102:105]
	v_mfma_f32_16x16x32_bf16 v[98:101], v[184:187], v[200:203], v[98:101]
	v_mfma_f32_16x16x32_bf16 v[86:89], v[176:179], v[210:213], v[86:89]
	v_mfma_f32_16x16x32_bf16 v[82:85], v[184:187], v[210:213], v[82:85]
	v_mfma_f32_16x16x32_bf16 v[70:73], v[176:179], v[218:221], v[70:73]
	v_mfma_f32_16x16x32_bf16 v[66:69], v[184:187], v[218:221], v[66:69]
	s_setprio 0
	s_barrier
	s_add_i32 s25, s82, s70
	s_mov_b32 m0, s25
	v_lshl_add_u64 v[168:169], s[66:67], 0, v[150:151]
	global_load_lds_dwordx4 v[168:169], off
	ds_read_b128 v[188:191], v174 offset:16384
	ds_read_b128 v[192:195], v174 offset:17408
	ds_read_b128 v[196:199], v174 offset:18432
	ds_read_b128 v[200:203], v174 offset:19456
	ds_read_b128 v[206:209], v174 offset:20480
	ds_read_b128 v[210:213], v174 offset:21504
	ds_read_b128 v[214:217], v174 offset:22528
	ds_read_b128 v[218:221], v174 offset:23552
	s_add_i32 m0, s25, 0x2000
	s_add_u32 s28, s66, 0x40000
	v_lshl_add_u64 v[222:223], s[66:67], 0, v[146:147]
	s_addc_u32 s29, s67, 0
	s_add_i32 s25, s83, s70
	global_load_lds_dwordx4 v[222:223], off
	v_lshl_add_u64 v[224:225], s[28:29], 0, v[150:151]
	s_mov_b32 m0, s25
	v_lshl_add_u64 v[226:227], s[68:69], 0, v[148:149]
	global_load_lds_dwordx4 v[224:225], off
	s_add_i32 m0, s25, 0x2000
	v_lshl_add_u64 v[224:225], s[28:29], 0, v[146:147]
	global_load_lds_dwordx4 v[224:225], off
	s_mov_b32 m0, s73
	v_lshl_add_u64 v[224:225], s[68:69], 0, v[152:153]
	global_load_lds_dwordx4 v[224:225], off
	s_mov_b32 m0, s74
	s_nop 0
	global_load_lds_dwordx4 v[226:227], off
	s_waitcnt vmcnt(8) lgkmcnt(0)
	s_setprio 1
	s_barrier
	v_mfma_f32_16x16x32_bf16 v[62:65], v[130:133], v[188:191], 0
	v_mfma_f32_16x16x32_bf16 v[58:61], v[138:141], v[188:191], 0
	v_mfma_f32_16x16x32_bf16 v[46:49], v[130:133], v[196:199], 0
	v_mfma_f32_16x16x32_bf16 v[42:45], v[138:141], v[196:199], 0
	v_mfma_f32_16x16x32_bf16 v[30:33], v[130:133], v[206:209], 0
	v_mfma_f32_16x16x32_bf16 v[26:29], v[138:141], v[206:209], 0
	v_mfma_f32_16x16x32_bf16 v[14:17], v[130:133], v[214:217], 0
	v_mfma_f32_16x16x32_bf16 v[10:13], v[138:141], v[214:217], 0
	v_mfma_f32_16x16x32_bf16 v[62:65], v[134:137], v[192:195], v[62:65]
	v_mfma_f32_16x16x32_bf16 v[58:61], v[142:145], v[192:195], v[58:61]
	v_mfma_f32_16x16x32_bf16 v[46:49], v[134:137], v[200:203], v[46:49]
	v_mfma_f32_16x16x32_bf16 v[42:45], v[142:145], v[200:203], v[42:45]
	v_mfma_f32_16x16x32_bf16 v[30:33], v[134:137], v[210:213], v[30:33]
	v_mfma_f32_16x16x32_bf16 v[26:29], v[142:145], v[210:213], v[26:29]
	v_mfma_f32_16x16x32_bf16 v[14:17], v[134:137], v[218:221], v[14:17]
	v_mfma_f32_16x16x32_bf16 v[10:13], v[142:145], v[218:221], v[10:13]
	v_mfma_f32_16x16x32_bf16 v[54:57], v[164:167], v[188:191], 0
	v_mfma_f32_16x16x32_bf16 v[50:53], v[180:183], v[188:191], 0
	v_mfma_f32_16x16x32_bf16 v[38:41], v[164:167], v[196:199], 0
	v_mfma_f32_16x16x32_bf16 v[34:37], v[180:183], v[196:199], 0
	v_mfma_f32_16x16x32_bf16 v[22:25], v[164:167], v[206:209], 0
	v_mfma_f32_16x16x32_bf16 v[18:21], v[180:183], v[206:209], 0
	v_mfma_f32_16x16x32_bf16 v[6:9], v[164:167], v[214:217], 0
	v_mfma_f32_16x16x32_bf16 v[2:5], v[180:183], v[214:217], 0
	v_mfma_f32_16x16x32_bf16 v[54:57], v[176:179], v[192:195], v[54:57]
	v_mfma_f32_16x16x32_bf16 v[50:53], v[184:187], v[192:195], v[50:53]
	v_mfma_f32_16x16x32_bf16 v[38:41], v[176:179], v[200:203], v[38:41]
	v_mfma_f32_16x16x32_bf16 v[34:37], v[184:187], v[200:203], v[34:37]
	v_mfma_f32_16x16x32_bf16 v[22:25], v[176:179], v[210:213], v[22:25]
	v_mfma_f32_16x16x32_bf16 v[18:21], v[184:187], v[210:213], v[18:21]
	v_mfma_f32_16x16x32_bf16 v[6:9], v[176:179], v[218:221], v[6:9]
	v_mfma_f32_16x16x32_bf16 v[2:5], v[184:187], v[218:221], v[2:5]
	s_setprio 0
	s_barrier
	s_add_i32 s25, 0, 0x18000
	s_add_i32 s30, 0, 0x1c000
	v_add_u32_e32 v142, s25, v171
	v_add_u32_e32 v175, s30, v171
	ds_read_b128 v[130:133], v142
	ds_read_b128 v[134:137], v142 offset:1024
	ds_read_b128 v[138:141], v142 offset:2048
	ds_read_b128 v[142:145], v142 offset:3072
	ds_read_b128 v[164:167], v175
	ds_read_b128 v[176:179], v175 offset:1024
	ds_read_b128 v[180:183], v175 offset:2048
	ds_read_b128 v[184:187], v175 offset:3072
	s_add_u32 s28, s68, 0x40000
	s_addc_u32 s29, s69, 0
	s_mov_b32 m0, s75
	v_lshl_add_u64 v[228:229], s[28:29], 0, v[152:153]
	ds_read_b128 v[188:191], v174 offset:32768
	ds_read_b128 v[192:195], v174 offset:33792
	ds_read_b128 v[196:199], v174 offset:34816
	ds_read_b128 v[200:203], v174 offset:35840
	ds_read_b128 v[206:209], v174 offset:36864
	ds_read_b128 v[210:213], v174 offset:37888
	ds_read_b128 v[214:217], v174 offset:38912
	ds_read_b128 v[218:221], v174 offset:39936
	global_load_lds_dwordx4 v[228:229], off
	s_mov_b32 m0, s76
	v_lshl_add_u64 v[228:229], s[28:29], 0, v[148:149]
	global_load_lds_dwordx4 v[228:229], off
	s_waitcnt vmcnt(8) lgkmcnt(0)
	s_setprio 1
	s_barrier
	v_mfma_f32_16x16x32_bf16 v[126:129], v[130:133], v[188:191], v[126:129]
	v_mfma_f32_16x16x32_bf16 v[122:125], v[138:141], v[188:191], v[122:125]
	v_mfma_f32_16x16x32_bf16 v[110:113], v[130:133], v[196:199], v[110:113]
	v_mfma_f32_16x16x32_bf16 v[106:109], v[138:141], v[196:199], v[106:109]
	v_mfma_f32_16x16x32_bf16 v[94:97], v[130:133], v[206:209], v[94:97]
	v_mfma_f32_16x16x32_bf16 v[90:93], v[138:141], v[206:209], v[90:93]
	v_mfma_f32_16x16x32_bf16 v[78:81], v[130:133], v[214:217], v[78:81]
	v_mfma_f32_16x16x32_bf16 v[74:77], v[138:141], v[214:217], v[74:77]
	v_mfma_f32_16x16x32_bf16 v[126:129], v[134:137], v[192:195], v[126:129]
	v_mfma_f32_16x16x32_bf16 v[122:125], v[142:145], v[192:195], v[122:125]
	v_mfma_f32_16x16x32_bf16 v[110:113], v[134:137], v[200:203], v[110:113]
	v_mfma_f32_16x16x32_bf16 v[106:109], v[142:145], v[200:203], v[106:109]
	v_mfma_f32_16x16x32_bf16 v[94:97], v[134:137], v[210:213], v[94:97]
	v_mfma_f32_16x16x32_bf16 v[90:93], v[142:145], v[210:213], v[90:93]
	v_mfma_f32_16x16x32_bf16 v[78:81], v[134:137], v[218:221], v[78:81]
	v_mfma_f32_16x16x32_bf16 v[74:77], v[142:145], v[218:221], v[74:77]
	v_mfma_f32_16x16x32_bf16 v[118:121], v[164:167], v[188:191], v[118:121]
	v_mfma_f32_16x16x32_bf16 v[114:117], v[180:183], v[188:191], v[114:117]
	v_mfma_f32_16x16x32_bf16 v[102:105], v[164:167], v[196:199], v[102:105]
	v_mfma_f32_16x16x32_bf16 v[98:101], v[180:183], v[196:199], v[98:101]
	v_mfma_f32_16x16x32_bf16 v[86:89], v[164:167], v[206:209], v[86:89]
	v_mfma_f32_16x16x32_bf16 v[82:85], v[180:183], v[206:209], v[82:85]
	v_mfma_f32_16x16x32_bf16 v[70:73], v[164:167], v[214:217], v[70:73]
	v_mfma_f32_16x16x32_bf16 v[66:69], v[180:183], v[214:217], v[66:69]
	v_mfma_f32_16x16x32_bf16 v[118:121], v[176:179], v[192:195], v[118:121]
	v_mfma_f32_16x16x32_bf16 v[114:117], v[184:187], v[192:195], v[114:117]
	v_mfma_f32_16x16x32_bf16 v[102:105], v[176:179], v[200:203], v[102:105]
	v_mfma_f32_16x16x32_bf16 v[98:101], v[184:187], v[200:203], v[98:101]
	v_mfma_f32_16x16x32_bf16 v[86:89], v[176:179], v[210:213], v[86:89]
	v_mfma_f32_16x16x32_bf16 v[82:85], v[184:187], v[210:213], v[82:85]
	v_mfma_f32_16x16x32_bf16 v[70:73], v[176:179], v[218:221], v[70:73]
	v_mfma_f32_16x16x32_bf16 v[66:69], v[184:187], v[218:221], v[66:69]
	s_setprio 0
	s_barrier
	s_add_i32 s25, s25, s70
	s_mov_b32 m0, s25
	v_lshl_add_u64 v[168:169], v[168:169], 0, s[36:37]
	global_load_lds_dwordx4 v[168:169], off
	ds_read_b128 v[188:191], v174 offset:49152
	ds_read_b128 v[192:195], v174 offset:50176
	ds_read_b128 v[196:199], v174 offset:51200
	ds_read_b128 v[200:203], v174 offset:52224
	ds_read_b128 v[206:209], v174 offset:53248
	ds_read_b128 v[210:213], v174 offset:54272
	ds_read_b128 v[214:217], v174 offset:55296
	ds_read_b128 v[218:221], v174 offset:56320
	s_add_i32 m0, s25, 0x2000
	s_add_u32 s28, s66, 0x40080
	v_lshl_add_u64 v[168:169], v[222:223], 0, s[36:37]
	s_addc_u32 s29, s67, 0
	s_add_i32 s25, s30, s70
	global_load_lds_dwordx4 v[168:169], off
	s_mov_b32 m0, s25
	v_lshl_add_u64 v[168:169], s[28:29], 0, v[150:151]
	global_load_lds_dwordx4 v[168:169], off
	s_add_i32 m0, s25, 0x2000
	v_lshl_add_u64 v[168:169], s[28:29], 0, v[146:147]
	global_load_lds_dwordx4 v[168:169], off
	s_mov_b32 m0, s79
	v_lshl_add_u64 v[168:169], v[224:225], 0, s[36:37]
	global_load_lds_dwordx4 v[168:169], off
	s_mov_b32 m0, s80
	v_lshl_add_u64 v[168:169], v[226:227], 0, s[36:37]
	global_load_lds_dwordx4 v[168:169], off
	s_waitcnt vmcnt(8) lgkmcnt(0)
	s_setprio 1
	s_barrier
	v_mfma_f32_16x16x32_bf16 v[62:65], v[130:133], v[188:191], v[62:65]
	v_mfma_f32_16x16x32_bf16 v[58:61], v[138:141], v[188:191], v[58:61]
	v_mfma_f32_16x16x32_bf16 v[46:49], v[130:133], v[196:199], v[46:49]
	v_mfma_f32_16x16x32_bf16 v[42:45], v[138:141], v[196:199], v[42:45]
	v_mfma_f32_16x16x32_bf16 v[30:33], v[130:133], v[206:209], v[30:33]
	v_mfma_f32_16x16x32_bf16 v[26:29], v[138:141], v[206:209], v[26:29]
	v_mfma_f32_16x16x32_bf16 v[14:17], v[130:133], v[214:217], v[14:17]
	v_mfma_f32_16x16x32_bf16 v[10:13], v[138:141], v[214:217], v[10:13]
	v_mfma_f32_16x16x32_bf16 v[62:65], v[134:137], v[192:195], v[62:65]
	v_mfma_f32_16x16x32_bf16 v[58:61], v[142:145], v[192:195], v[58:61]
	v_mfma_f32_16x16x32_bf16 v[46:49], v[134:137], v[200:203], v[46:49]
	v_mfma_f32_16x16x32_bf16 v[42:45], v[142:145], v[200:203], v[42:45]
	v_mfma_f32_16x16x32_bf16 v[30:33], v[134:137], v[210:213], v[30:33]
	v_mfma_f32_16x16x32_bf16 v[26:29], v[142:145], v[210:213], v[26:29]
	v_mfma_f32_16x16x32_bf16 v[14:17], v[134:137], v[218:221], v[14:17]
	v_mfma_f32_16x16x32_bf16 v[10:13], v[142:145], v[218:221], v[10:13]
	v_mfma_f32_16x16x32_bf16 v[54:57], v[164:167], v[188:191], v[54:57]
	v_mfma_f32_16x16x32_bf16 v[50:53], v[180:183], v[188:191], v[50:53]
	v_mfma_f32_16x16x32_bf16 v[38:41], v[164:167], v[196:199], v[38:41]
	v_mfma_f32_16x16x32_bf16 v[34:37], v[180:183], v[196:199], v[34:37]
	v_mfma_f32_16x16x32_bf16 v[22:25], v[164:167], v[206:209], v[22:25]
	v_mfma_f32_16x16x32_bf16 v[18:21], v[180:183], v[206:209], v[18:21]
	v_mfma_f32_16x16x32_bf16 v[6:9], v[164:167], v[214:217], v[6:9]
	v_mfma_f32_16x16x32_bf16 v[2:5], v[180:183], v[214:217], v[2:5]
	v_mfma_f32_16x16x32_bf16 v[54:57], v[176:179], v[192:195], v[54:57]
	v_mfma_f32_16x16x32_bf16 v[50:53], v[184:187], v[192:195], v[50:53]
	v_mfma_f32_16x16x32_bf16 v[38:41], v[176:179], v[200:203], v[38:41]
	v_mfma_f32_16x16x32_bf16 v[34:37], v[184:187], v[200:203], v[34:37]
	v_mfma_f32_16x16x32_bf16 v[22:25], v[176:179], v[210:213], v[22:25]
	v_mfma_f32_16x16x32_bf16 v[18:21], v[184:187], v[210:213], v[18:21]
	v_mfma_f32_16x16x32_bf16 v[6:9], v[176:179], v[218:221], v[6:9]
	v_mfma_f32_16x16x32_bf16 v[2:5], v[184:187], v[218:221], v[2:5]
	s_setprio 0
	s_barrier
	s_add_i32 s24, s24, 2
	s_add_u32 s64, s64, 0x100
	s_addc_u32 s65, s65, 0
	s_add_u32 s18, s18, 0x100
	s_addc_u32 s19, s19, 0
	s_cmp_gt_u32 s24, 13
.LBB0_1013:
	ds_read_b128 v[130:133], v172
	ds_read_b128 v[134:137], v172 offset:1024
	ds_read_b128 v[138:141], v172 offset:2048
	ds_read_b128 v[142:145], v172 offset:3072
	ds_read_b128 v[164:167], v173
	ds_read_b128 v[176:179], v173 offset:1024
	ds_read_b128 v[180:183], v173 offset:2048
	ds_read_b128 v[184:187], v173 offset:3072
	s_add_u32 s25, s64, 0xfffc0080
	s_addc_u32 s28, s65, -1
	s_cmp_eq_u32 s24, 12
	s_cselect_b32 s69, s6, s28
	s_cselect_b32 s68, s14, s25
	s_cselect_b32 s67, s15, s19
	s_cselect_b32 s66, s17, s18
	v_lshl_add_u64 v[168:169], s[64:65], 0, v[156:157]
	s_add_i32 m0, s73, 0xc000
	ds_read_b128 v[188:191], v174
	ds_read_b128 v[192:195], v174 offset:1024
	ds_read_b128 v[196:199], v174 offset:2048
	ds_read_b128 v[200:203], v174 offset:3072
	ds_read_b128 v[206:209], v174 offset:4096
	ds_read_b128 v[210:213], v174 offset:5120
	ds_read_b128 v[214:217], v174 offset:6144
	ds_read_b128 v[218:221], v174 offset:7168
	global_load_lds_dwordx4 v[168:169], off
	s_add_i32 m0, s73, 0xe000
	v_lshl_add_u64 v[168:169], s[64:65], 0, v[158:159]
	global_load_lds_dwordx4 v[168:169], off
	s_waitcnt vmcnt(8) lgkmcnt(0)
	s_setprio 1
	s_barrier
	v_mfma_f32_16x16x32_bf16 v[126:129], v[130:133], v[188:191], v[126:129]
	v_mfma_f32_16x16x32_bf16 v[122:125], v[138:141], v[188:191], v[122:125]
	v_mfma_f32_16x16x32_bf16 v[110:113], v[130:133], v[196:199], v[110:113]
	v_mfma_f32_16x16x32_bf16 v[106:109], v[138:141], v[196:199], v[106:109]
	v_mfma_f32_16x16x32_bf16 v[94:97], v[130:133], v[206:209], v[94:97]
	v_mfma_f32_16x16x32_bf16 v[90:93], v[138:141], v[206:209], v[90:93]
	v_mfma_f32_16x16x32_bf16 v[78:81], v[130:133], v[214:217], v[78:81]
	v_mfma_f32_16x16x32_bf16 v[74:77], v[138:141], v[214:217], v[74:77]
	v_mfma_f32_16x16x32_bf16 v[126:129], v[134:137], v[192:195], v[126:129]
	v_mfma_f32_16x16x32_bf16 v[122:125], v[142:145], v[192:195], v[122:125]
	v_mfma_f32_16x16x32_bf16 v[110:113], v[134:137], v[200:203], v[110:113]
	v_mfma_f32_16x16x32_bf16 v[106:109], v[142:145], v[200:203], v[106:109]
	v_mfma_f32_16x16x32_bf16 v[94:97], v[134:137], v[210:213], v[94:97]
	v_mfma_f32_16x16x32_bf16 v[90:93], v[142:145], v[210:213], v[90:93]
	v_mfma_f32_16x16x32_bf16 v[78:81], v[134:137], v[218:221], v[78:81]
	v_mfma_f32_16x16x32_bf16 v[74:77], v[142:145], v[218:221], v[74:77]
	v_mfma_f32_16x16x32_bf16 v[118:121], v[164:167], v[188:191], v[118:121]
	v_mfma_f32_16x16x32_bf16 v[114:117], v[180:183], v[188:191], v[114:117]
	v_mfma_f32_16x16x32_bf16 v[102:105], v[164:167], v[196:199], v[102:105]
	v_mfma_f32_16x16x32_bf16 v[98:101], v[180:183], v[196:199], v[98:101]
	v_mfma_f32_16x16x32_bf16 v[86:89], v[164:167], v[206:209], v[86:89]
	v_mfma_f32_16x16x32_bf16 v[82:85], v[180:183], v[206:209], v[82:85]
	v_mfma_f32_16x16x32_bf16 v[70:73], v[164:167], v[214:217], v[70:73]
	v_mfma_f32_16x16x32_bf16 v[66:69], v[180:183], v[214:217], v[66:69]
	v_mfma_f32_16x16x32_bf16 v[118:121], v[176:179], v[192:195], v[118:121]
	v_mfma_f32_16x16x32_bf16 v[114:117], v[184:187], v[192:195], v[114:117]
	v_mfma_f32_16x16x32_bf16 v[102:105], v[176:179], v[200:203], v[102:105]
	v_mfma_f32_16x16x32_bf16 v[98:101], v[184:187], v[200:203], v[98:101]
	v_mfma_f32_16x16x32_bf16 v[86:89], v[176:179], v[210:213], v[86:89]
	v_mfma_f32_16x16x32_bf16 v[82:85], v[184:187], v[210:213], v[82:85]
	v_mfma_f32_16x16x32_bf16 v[70:73], v[176:179], v[218:221], v[70:73]
	v_mfma_f32_16x16x32_bf16 v[66:69], v[184:187], v[218:221], v[66:69]
	s_setprio 0
	s_barrier
	s_add_i32 s25, s82, s70
	s_mov_b32 m0, s25
	v_lshl_add_u64 v[168:169], s[66:67], 0, v[150:151]
	global_load_lds_dwordx4 v[168:169], off
	ds_read_b128 v[188:191], v174 offset:16384
	ds_read_b128 v[192:195], v174 offset:17408
	ds_read_b128 v[196:199], v174 offset:18432
	ds_read_b128 v[200:203], v174 offset:19456
	ds_read_b128 v[206:209], v174 offset:20480
	ds_read_b128 v[210:213], v174 offset:21504
	ds_read_b128 v[214:217], v174 offset:22528
	ds_read_b128 v[218:221], v174 offset:23552
	s_add_i32 m0, s25, 0x2000
	s_add_u32 s28, s66, 0x40000
	v_lshl_add_u64 v[222:223], s[66:67], 0, v[146:147]
	s_addc_u32 s29, s67, 0
	s_add_i32 s25, s83, s70
	global_load_lds_dwordx4 v[222:223], off
	v_lshl_add_u64 v[224:225], s[28:29], 0, v[150:151]
	s_mov_b32 m0, s25
	v_lshl_add_u64 v[226:227], s[68:69], 0, v[148:149]
	global_load_lds_dwordx4 v[224:225], off
	s_add_i32 m0, s25, 0x2000
	v_lshl_add_u64 v[224:225], s[28:29], 0, v[146:147]
	global_load_lds_dwordx4 v[224:225], off
	s_mov_b32 m0, s73
	v_lshl_add_u64 v[224:225], s[68:69], 0, v[152:153]
	global_load_lds_dwordx4 v[224:225], off
	s_mov_b32 m0, s74
	s_nop 0
	global_load_lds_dwordx4 v[226:227], off
	s_waitcnt vmcnt(8) lgkmcnt(0)
	s_setprio 1
	s_barrier
	v_mfma_f32_16x16x32_bf16 v[62:65], v[130:133], v[188:191], v[62:65]
	v_mfma_f32_16x16x32_bf16 v[58:61], v[138:141], v[188:191], v[58:61]
	v_mfma_f32_16x16x32_bf16 v[46:49], v[130:133], v[196:199], v[46:49]
	v_mfma_f32_16x16x32_bf16 v[42:45], v[138:141], v[196:199], v[42:45]
	v_mfma_f32_16x16x32_bf16 v[30:33], v[130:133], v[206:209], v[30:33]
	v_mfma_f32_16x16x32_bf16 v[26:29], v[138:141], v[206:209], v[26:29]
	v_mfma_f32_16x16x32_bf16 v[14:17], v[130:133], v[214:217], v[14:17]
	v_mfma_f32_16x16x32_bf16 v[10:13], v[138:141], v[214:217], v[10:13]
	v_mfma_f32_16x16x32_bf16 v[62:65], v[134:137], v[192:195], v[62:65]
	v_mfma_f32_16x16x32_bf16 v[58:61], v[142:145], v[192:195], v[58:61]
	v_mfma_f32_16x16x32_bf16 v[46:49], v[134:137], v[200:203], v[46:49]
	v_mfma_f32_16x16x32_bf16 v[42:45], v[142:145], v[200:203], v[42:45]
	v_mfma_f32_16x16x32_bf16 v[30:33], v[134:137], v[210:213], v[30:33]
	v_mfma_f32_16x16x32_bf16 v[26:29], v[142:145], v[210:213], v[26:29]
	v_mfma_f32_16x16x32_bf16 v[14:17], v[134:137], v[218:221], v[14:17]
	v_mfma_f32_16x16x32_bf16 v[10:13], v[142:145], v[218:221], v[10:13]
	v_mfma_f32_16x16x32_bf16 v[54:57], v[164:167], v[188:191], v[54:57]
	v_mfma_f32_16x16x32_bf16 v[50:53], v[180:183], v[188:191], v[50:53]
	v_mfma_f32_16x16x32_bf16 v[38:41], v[164:167], v[196:199], v[38:41]
	v_mfma_f32_16x16x32_bf16 v[34:37], v[180:183], v[196:199], v[34:37]
	v_mfma_f32_16x16x32_bf16 v[22:25], v[164:167], v[206:209], v[22:25]
	v_mfma_f32_16x16x32_bf16 v[18:21], v[180:183], v[206:209], v[18:21]
	v_mfma_f32_16x16x32_bf16 v[6:9], v[164:167], v[214:217], v[6:9]
	v_mfma_f32_16x16x32_bf16 v[2:5], v[180:183], v[214:217], v[2:5]
	v_mfma_f32_16x16x32_bf16 v[54:57], v[176:179], v[192:195], v[54:57]
	v_mfma_f32_16x16x32_bf16 v[50:53], v[184:187], v[192:195], v[50:53]
	v_mfma_f32_16x16x32_bf16 v[38:41], v[176:179], v[200:203], v[38:41]
	v_mfma_f32_16x16x32_bf16 v[34:37], v[184:187], v[200:203], v[34:37]
	v_mfma_f32_16x16x32_bf16 v[22:25], v[176:179], v[210:213], v[22:25]
	v_mfma_f32_16x16x32_bf16 v[18:21], v[184:187], v[210:213], v[18:21]
	v_mfma_f32_16x16x32_bf16 v[6:9], v[176:179], v[218:221], v[6:9]
	v_mfma_f32_16x16x32_bf16 v[2:5], v[184:187], v[218:221], v[2:5]
	s_setprio 0
	s_barrier
	s_add_i32 s25, 0, 0x18000
	s_add_i32 s30, 0, 0x1c000
	v_add_u32_e32 v142, s25, v171
	v_add_u32_e32 v175, s30, v171
	ds_read_b128 v[130:133], v142
	ds_read_b128 v[134:137], v142 offset:1024
	ds_read_b128 v[138:141], v142 offset:2048
	ds_read_b128 v[142:145], v142 offset:3072
	ds_read_b128 v[164:167], v175
	ds_read_b128 v[176:179], v175 offset:1024
	ds_read_b128 v[180:183], v175 offset:2048
	ds_read_b128 v[184:187], v175 offset:3072
	s_add_u32 s28, s68, 0x40000
	s_addc_u32 s29, s69, 0
	s_mov_b32 m0, s75
	v_lshl_add_u64 v[228:229], s[28:29], 0, v[152:153]
	ds_read_b128 v[188:191], v174 offset:32768
	ds_read_b128 v[192:195], v174 offset:33792
	ds_read_b128 v[196:199], v174 offset:34816
	ds_read_b128 v[200:203], v174 offset:35840
	ds_read_b128 v[206:209], v174 offset:36864
	ds_read_b128 v[210:213], v174 offset:37888
	ds_read_b128 v[214:217], v174 offset:38912
	ds_read_b128 v[218:221], v174 offset:39936
	global_load_lds_dwordx4 v[228:229], off
	s_mov_b32 m0, s76
	v_lshl_add_u64 v[228:229], s[28:29], 0, v[148:149]
	global_load_lds_dwordx4 v[228:229], off
	s_waitcnt vmcnt(8) lgkmcnt(0)
	s_setprio 1
	s_barrier
	v_mfma_f32_16x16x32_bf16 v[126:129], v[130:133], v[188:191], v[126:129]
	v_mfma_f32_16x16x32_bf16 v[122:125], v[138:141], v[188:191], v[122:125]
	v_mfma_f32_16x16x32_bf16 v[110:113], v[130:133], v[196:199], v[110:113]
	v_mfma_f32_16x16x32_bf16 v[106:109], v[138:141], v[196:199], v[106:109]
	v_mfma_f32_16x16x32_bf16 v[94:97], v[130:133], v[206:209], v[94:97]
	v_mfma_f32_16x16x32_bf16 v[90:93], v[138:141], v[206:209], v[90:93]
	v_mfma_f32_16x16x32_bf16 v[78:81], v[130:133], v[214:217], v[78:81]
	v_mfma_f32_16x16x32_bf16 v[74:77], v[138:141], v[214:217], v[74:77]
	v_mfma_f32_16x16x32_bf16 v[126:129], v[134:137], v[192:195], v[126:129]
	v_mfma_f32_16x16x32_bf16 v[122:125], v[142:145], v[192:195], v[122:125]
	v_mfma_f32_16x16x32_bf16 v[110:113], v[134:137], v[200:203], v[110:113]
	v_mfma_f32_16x16x32_bf16 v[106:109], v[142:145], v[200:203], v[106:109]
	v_mfma_f32_16x16x32_bf16 v[94:97], v[134:137], v[210:213], v[94:97]
	v_mfma_f32_16x16x32_bf16 v[90:93], v[142:145], v[210:213], v[90:93]
	v_mfma_f32_16x16x32_bf16 v[78:81], v[134:137], v[218:221], v[78:81]
	v_mfma_f32_16x16x32_bf16 v[74:77], v[142:145], v[218:221], v[74:77]
	v_mfma_f32_16x16x32_bf16 v[118:121], v[164:167], v[188:191], v[118:121]
	v_mfma_f32_16x16x32_bf16 v[114:117], v[180:183], v[188:191], v[114:117]
	v_mfma_f32_16x16x32_bf16 v[102:105], v[164:167], v[196:199], v[102:105]
	v_mfma_f32_16x16x32_bf16 v[98:101], v[180:183], v[196:199], v[98:101]
	v_mfma_f32_16x16x32_bf16 v[86:89], v[164:167], v[206:209], v[86:89]
	v_mfma_f32_16x16x32_bf16 v[82:85], v[180:183], v[206:209], v[82:85]
	v_mfma_f32_16x16x32_bf16 v[70:73], v[164:167], v[214:217], v[70:73]
	v_mfma_f32_16x16x32_bf16 v[66:69], v[180:183], v[214:217], v[66:69]
	v_mfma_f32_16x16x32_bf16 v[118:121], v[176:179], v[192:195], v[118:121]
	v_mfma_f32_16x16x32_bf16 v[114:117], v[184:187], v[192:195], v[114:117]
	v_mfma_f32_16x16x32_bf16 v[102:105], v[176:179], v[200:203], v[102:105]
	v_mfma_f32_16x16x32_bf16 v[98:101], v[184:187], v[200:203], v[98:101]
	v_mfma_f32_16x16x32_bf16 v[86:89], v[176:179], v[210:213], v[86:89]
	v_mfma_f32_16x16x32_bf16 v[82:85], v[184:187], v[210:213], v[82:85]
	v_mfma_f32_16x16x32_bf16 v[70:73], v[176:179], v[218:221], v[70:73]
	v_mfma_f32_16x16x32_bf16 v[66:69], v[184:187], v[218:221], v[66:69]
	s_setprio 0
	s_barrier
	s_add_i32 s25, s25, s70
	s_mov_b32 m0, s25
	v_lshl_add_u64 v[168:169], v[168:169], 0, s[36:37]
	global_load_lds_dwordx4 v[168:169], off
	ds_read_b128 v[188:191], v174 offset:49152
	ds_read_b128 v[192:195], v174 offset:50176
	ds_read_b128 v[196:199], v174 offset:51200
	ds_read_b128 v[200:203], v174 offset:52224
	ds_read_b128 v[206:209], v174 offset:53248
	ds_read_b128 v[210:213], v174 offset:54272
	ds_read_b128 v[214:217], v174 offset:55296
	ds_read_b128 v[218:221], v174 offset:56320
	s_add_i32 m0, s25, 0x2000
	s_add_u32 s28, s66, 0x40080
	v_lshl_add_u64 v[168:169], v[222:223], 0, s[36:37]
	s_addc_u32 s29, s67, 0
	s_add_i32 s25, s30, s70
	global_load_lds_dwordx4 v[168:169], off
	s_mov_b32 m0, s25
	v_lshl_add_u64 v[168:169], s[28:29], 0, v[150:151]
	global_load_lds_dwordx4 v[168:169], off
	s_add_i32 m0, s25, 0x2000
	v_lshl_add_u64 v[168:169], s[28:29], 0, v[146:147]
	global_load_lds_dwordx4 v[168:169], off
	s_mov_b32 m0, s79
	v_lshl_add_u64 v[168:169], v[224:225], 0, s[36:37]
	global_load_lds_dwordx4 v[168:169], off
	s_mov_b32 m0, s80
	v_lshl_add_u64 v[168:169], v[226:227], 0, s[36:37]
	global_load_lds_dwordx4 v[168:169], off
	s_waitcnt vmcnt(8) lgkmcnt(0)
	s_setprio 1
	s_barrier
	v_mfma_f32_16x16x32_bf16 v[62:65], v[130:133], v[188:191], v[62:65]
	v_mfma_f32_16x16x32_bf16 v[58:61], v[138:141], v[188:191], v[58:61]
	v_mfma_f32_16x16x32_bf16 v[46:49], v[130:133], v[196:199], v[46:49]
	v_mfma_f32_16x16x32_bf16 v[42:45], v[138:141], v[196:199], v[42:45]
	v_mfma_f32_16x16x32_bf16 v[30:33], v[130:133], v[206:209], v[30:33]
	v_mfma_f32_16x16x32_bf16 v[26:29], v[138:141], v[206:209], v[26:29]
	v_mfma_f32_16x16x32_bf16 v[14:17], v[130:133], v[214:217], v[14:17]
	v_mfma_f32_16x16x32_bf16 v[10:13], v[138:141], v[214:217], v[10:13]
	v_mfma_f32_16x16x32_bf16 v[62:65], v[134:137], v[192:195], v[62:65]
	v_mfma_f32_16x16x32_bf16 v[58:61], v[142:145], v[192:195], v[58:61]
	v_mfma_f32_16x16x32_bf16 v[46:49], v[134:137], v[200:203], v[46:49]
	v_mfma_f32_16x16x32_bf16 v[42:45], v[142:145], v[200:203], v[42:45]
	v_mfma_f32_16x16x32_bf16 v[30:33], v[134:137], v[210:213], v[30:33]
	v_mfma_f32_16x16x32_bf16 v[26:29], v[142:145], v[210:213], v[26:29]
	v_mfma_f32_16x16x32_bf16 v[14:17], v[134:137], v[218:221], v[14:17]
	v_mfma_f32_16x16x32_bf16 v[10:13], v[142:145], v[218:221], v[10:13]
	v_mfma_f32_16x16x32_bf16 v[54:57], v[164:167], v[188:191], v[54:57]
	v_mfma_f32_16x16x32_bf16 v[50:53], v[180:183], v[188:191], v[50:53]
	v_mfma_f32_16x16x32_bf16 v[38:41], v[164:167], v[196:199], v[38:41]
	v_mfma_f32_16x16x32_bf16 v[34:37], v[180:183], v[196:199], v[34:37]
	v_mfma_f32_16x16x32_bf16 v[22:25], v[164:167], v[206:209], v[22:25]
	v_mfma_f32_16x16x32_bf16 v[18:21], v[180:183], v[206:209], v[18:21]
	v_mfma_f32_16x16x32_bf16 v[6:9], v[164:167], v[214:217], v[6:9]
	v_mfma_f32_16x16x32_bf16 v[2:5], v[180:183], v[214:217], v[2:5]
	v_mfma_f32_16x16x32_bf16 v[54:57], v[176:179], v[192:195], v[54:57]
	v_mfma_f32_16x16x32_bf16 v[50:53], v[184:187], v[192:195], v[50:53]
	v_mfma_f32_16x16x32_bf16 v[38:41], v[176:179], v[200:203], v[38:41]
	v_mfma_f32_16x16x32_bf16 v[34:37], v[184:187], v[200:203], v[34:37]
	v_mfma_f32_16x16x32_bf16 v[22:25], v[176:179], v[210:213], v[22:25]
	v_mfma_f32_16x16x32_bf16 v[18:21], v[184:187], v[210:213], v[18:21]
	v_mfma_f32_16x16x32_bf16 v[6:9], v[176:179], v[218:221], v[6:9]
	v_mfma_f32_16x16x32_bf16 v[2:5], v[184:187], v[218:221], v[2:5]
	s_setprio 0
	s_barrier
	s_add_i32 s24, s24, 2
	s_add_u32 s64, s64, 0x100
	s_addc_u32 s65, s65, 0
	s_add_u32 s18, s18, 0x100
	s_addc_u32 s19, s19, 0
	s_cmp_gt_u32 s24, 13
	s_cbranch_scc0 .LBB0_1013
	s_and_b64 vcc, exec, s[38:39]
	s_cbranch_vccz .LBB0_1016
	s_barrier

.LBB0_1427:
	s_add_u32 s90, s35, s86
	s_addc_u32 s91, s64, s87
	s_and_b64 s[14:15], s[88:89], exec
	s_cselect_b32 s14, s91, s11
	s_cselect_b32 s15, s90, s10
	s_add_u32 s92, s65, s74
	s_addc_u32 s93, s68, s75
	s_and_b64 s[66:67], s[88:89], exec
	s_cselect_b32 s51, s93, s95
	s_cselect_b32 s84, s92, s94
	s_add_i32 s85, s18, -2
	s_add_u32 s10, s10, 0x40080
	s_addc_u32 s11, s11, 0
	s_add_u32 vcc_lo, s94, 0x100
	s_addc_u32 vcc_hi, s95, 0
	s_mov_b32 s94, 0
	s_waitcnt vmcnt(0)
	s_add_i32 s66, s94, 2
	s_add_u32 s67, s10, 0xfffc0080
	s_addc_u32 s72, s11, -1
	s_cmp_eq_u32 s85, s94
	s_cselect_b32 s97, s14, s72
	s_cselect_b32 s96, s15, s67
	s_cselect_b32 s95, s51, vcc_hi
	s_cselect_b32 s94, s84, vcc_lo
	s_add_i32 s67, 0, 0x10000
	s_add_i32 s62, 0, 0x14000
	v_add_u32_e32 v126, s67, v199
	v_add_u32_e32 v158, s62, v199
	ds_read_b128 v[114:117], v126
	ds_read_b128 v[118:121], v126 offset:1024
	ds_read_b128 v[122:125], v126 offset:2048
	ds_read_b128 v[126:129], v126 offset:3072
	ds_read_b128 v[146:149], v158
	ds_read_b128 v[150:153], v158 offset:1024
	ds_read_b128 v[154:157], v158 offset:2048
	ds_read_b128 v[158:161], v158 offset:3072
	v_lshl_add_u64 v[202:203], s[10:11], 0, v[196:197]
	s_add_i32 m0, s28, 0xc000
	ds_read_b128 v[162:165], v214
	ds_read_b128 v[166:169], v214 offset:1024
	ds_read_b128 v[216:219], v214 offset:2048
	ds_read_b128 v[220:223], v214 offset:3072
	ds_read_b128 v[224:227], v214 offset:4096
	ds_read_b128 v[228:231], v214 offset:5120
	ds_read_b128 v[232:235], v214 offset:6144
	ds_read_b128 v[236:239], v214 offset:7168
	global_load_lds_dwordx4 v[202:203], off
	s_add_i32 m0, s28, 0xe000
	v_lshl_add_u64 v[202:203], s[10:11], 0, v[176:177]
	global_load_lds_dwordx4 v[202:203], off
	s_waitcnt vmcnt(8) lgkmcnt(0)
	s_setprio 1
	s_barrier
	v_mfma_f32_16x16x32_bf16 v[142:145], v[114:117], v[162:165], 0
	v_mfma_f32_16x16x32_bf16 v[138:141], v[122:125], v[162:165], 0
	v_mfma_f32_16x16x32_bf16 v[110:113], v[114:117], v[216:219], 0
	v_mfma_f32_16x16x32_bf16 v[106:109], v[122:125], v[216:219], 0
	v_mfma_f32_16x16x32_bf16 v[98:101], v[114:117], v[224:227], 0
	v_mfma_f32_16x16x32_bf16 v[90:93], v[122:125], v[224:227], 0
	v_mfma_f32_16x16x32_bf16 v[82:85], v[114:117], v[232:235], 0
	v_mfma_f32_16x16x32_bf16 v[74:77], v[122:125], v[232:235], 0
	v_mfma_f32_16x16x32_bf16 v[142:145], v[118:121], v[166:169], v[142:145]
	v_mfma_f32_16x16x32_bf16 v[138:141], v[126:129], v[166:169], v[138:141]
	v_mfma_f32_16x16x32_bf16 v[110:113], v[118:121], v[220:223], v[110:113]
	v_mfma_f32_16x16x32_bf16 v[106:109], v[126:129], v[220:223], v[106:109]
	v_mfma_f32_16x16x32_bf16 v[98:101], v[118:121], v[228:231], v[98:101]
	v_mfma_f32_16x16x32_bf16 v[90:93], v[126:129], v[228:231], v[90:93]
	v_mfma_f32_16x16x32_bf16 v[82:85], v[118:121], v[236:239], v[82:85]
	v_mfma_f32_16x16x32_bf16 v[74:77], v[126:129], v[236:239], v[74:77]
	v_mfma_f32_16x16x32_bf16 v[134:137], v[146:149], v[162:165], 0
	v_mfma_f32_16x16x32_bf16 v[130:133], v[154:157], v[162:165], 0
	v_mfma_f32_16x16x32_bf16 v[102:105], v[146:149], v[216:219], 0
	v_mfma_f32_16x16x32_bf16 v[94:97], v[154:157], v[216:219], 0
	v_mfma_f32_16x16x32_bf16 v[86:89], v[146:149], v[224:227], 0
	v_mfma_f32_16x16x32_bf16 v[78:81], v[154:157], v[224:227], 0
	v_mfma_f32_16x16x32_bf16 v[70:73], v[146:149], v[232:235], 0
	v_mfma_f32_16x16x32_bf16 v[66:69], v[154:157], v[232:235], 0
	v_mfma_f32_16x16x32_bf16 v[134:137], v[150:153], v[166:169], v[134:137]
	v_mfma_f32_16x16x32_bf16 v[130:133], v[158:161], v[166:169], v[130:133]
	v_mfma_f32_16x16x32_bf16 v[102:105], v[150:153], v[220:223], v[102:105]
	v_mfma_f32_16x16x32_bf16 v[94:97], v[158:161], v[220:223], v[94:97]
	v_mfma_f32_16x16x32_bf16 v[86:89], v[150:153], v[228:231], v[86:89]
	v_mfma_f32_16x16x32_bf16 v[78:81], v[158:161], v[228:231], v[78:81]
	v_mfma_f32_16x16x32_bf16 v[70:73], v[150:153], v[236:239], v[70:73]
	v_mfma_f32_16x16x32_bf16 v[66:69], v[158:161], v[236:239], v[66:69]
	s_setprio 0
	s_barrier
	s_add_i32 s63, s67, s17
	s_mov_b32 m0, s63
	v_lshl_add_u64 v[202:203], s[94:95], 0, v[174:175]
	global_load_lds_dwordx4 v[202:203], off
	ds_read_b128 v[162:165], v214 offset:16384
	ds_read_b128 v[166:169], v214 offset:17408
	ds_read_b128 v[216:219], v214 offset:18432
	ds_read_b128 v[220:223], v214 offset:19456
	ds_read_b128 v[224:227], v214 offset:20480
	ds_read_b128 v[228:231], v214 offset:21504
	ds_read_b128 v[232:235], v214 offset:22528
	ds_read_b128 v[236:239], v214 offset:23552
	s_add_i32 m0, s63, 0x2000
	s_add_u32 s72, s94, 0x40000
	v_lshl_add_u64 v[240:241], s[94:95], 0, v[178:179]
	s_addc_u32 s73, s95, 0
	s_add_i32 s62, s62, s17
	global_load_lds_dwordx4 v[240:241], off
	v_lshl_add_u64 v[242:243], s[72:73], 0, v[174:175]
	s_mov_b32 m0, s62
	v_lshl_add_u64 v[244:245], s[96:97], 0, v[176:177]
	global_load_lds_dwordx4 v[242:243], off
	s_add_i32 m0, s62, 0x2000
	v_lshl_add_u64 v[242:243], s[72:73], 0, v[178:179]
	global_load_lds_dwordx4 v[242:243], off
	s_mov_b32 m0, s28
	v_lshl_add_u64 v[242:243], s[96:97], 0, v[172:173]
	global_load_lds_dwordx4 v[242:243], off
	s_mov_b32 m0, s29
	s_nop 0
	global_load_lds_dwordx4 v[244:245], off
	s_waitcnt vmcnt(8) lgkmcnt(0)
	s_setprio 1
	s_barrier
	v_mfma_f32_16x16x32_bf16 v[62:65], v[114:117], v[162:165], 0
	v_mfma_f32_16x16x32_bf16 v[58:61], v[122:125], v[162:165], 0
	v_mfma_f32_16x16x32_bf16 v[50:53], v[114:117], v[216:219], 0
	v_mfma_f32_16x16x32_bf16 v[42:45], v[122:125], v[216:219], 0
	v_mfma_f32_16x16x32_bf16 v[34:37], v[114:117], v[224:227], 0
	v_mfma_f32_16x16x32_bf16 v[26:29], v[122:125], v[224:227], 0
	v_mfma_f32_16x16x32_bf16 v[18:21], v[114:117], v[232:235], 0
	v_mfma_f32_16x16x32_bf16 v[10:13], v[122:125], v[232:235], 0
	v_mfma_f32_16x16x32_bf16 v[62:65], v[118:121], v[166:169], v[62:65]
	v_mfma_f32_16x16x32_bf16 v[58:61], v[126:129], v[166:169], v[58:61]
	v_mfma_f32_16x16x32_bf16 v[50:53], v[118:121], v[220:223], v[50:53]
	v_mfma_f32_16x16x32_bf16 v[42:45], v[126:129], v[220:223], v[42:45]
	v_mfma_f32_16x16x32_bf16 v[34:37], v[118:121], v[228:231], v[34:37]
	v_mfma_f32_16x16x32_bf16 v[26:29], v[126:129], v[228:231], v[26:29]
	v_mfma_f32_16x16x32_bf16 v[18:21], v[118:121], v[236:239], v[18:21]
	v_mfma_f32_16x16x32_bf16 v[10:13], v[126:129], v[236:239], v[10:13]
	v_mfma_f32_16x16x32_bf16 v[54:57], v[146:149], v[162:165], 0
	v_mfma_f32_16x16x32_bf16 v[46:49], v[154:157], v[162:165], 0
	v_mfma_f32_16x16x32_bf16 v[38:41], v[146:149], v[216:219], 0
	v_mfma_f32_16x16x32_bf16 v[30:33], v[154:157], v[216:219], 0
	v_mfma_f32_16x16x32_bf16 v[22:25], v[146:149], v[224:227], 0
	v_mfma_f32_16x16x32_bf16 v[14:17], v[154:157], v[224:227], 0
	v_mfma_f32_16x16x32_bf16 v[6:9], v[146:149], v[232:235], 0
	v_mfma_f32_16x16x32_bf16 v[2:5], v[154:157], v[232:235], 0
	v_mfma_f32_16x16x32_bf16 v[54:57], v[150:153], v[166:169], v[54:57]
	v_mfma_f32_16x16x32_bf16 v[46:49], v[158:161], v[166:169], v[46:49]
	v_mfma_f32_16x16x32_bf16 v[38:41], v[150:153], v[220:223], v[38:41]
	v_mfma_f32_16x16x32_bf16 v[30:33], v[158:161], v[220:223], v[30:33]
	v_mfma_f32_16x16x32_bf16 v[22:25], v[150:153], v[228:231], v[22:25]
	v_mfma_f32_16x16x32_bf16 v[14:17], v[158:161], v[228:231], v[14:17]
	v_mfma_f32_16x16x32_bf16 v[6:9], v[150:153], v[236:239], v[6:9]
	v_mfma_f32_16x16x32_bf16 v[2:5], v[158:161], v[236:239], v[2:5]
	s_setprio 0
	s_barrier
	s_add_i32 s62, 0, 0x18000
	s_add_i32 s63, 0, 0x1c000
	v_add_u32_e32 v126, s62, v199
	v_add_u32_e32 v158, s63, v199
	ds_read_b128 v[114:117], v126
	ds_read_b128 v[118:121], v126 offset:1024
	ds_read_b128 v[122:125], v126 offset:2048
	ds_read_b128 v[126:129], v126 offset:3072
	ds_read_b128 v[146:149], v158
	ds_read_b128 v[150:153], v158 offset:1024
	ds_read_b128 v[154:157], v158 offset:2048
	ds_read_b128 v[158:161], v158 offset:3072
	s_add_u32 s72, s96, 0x40000
	s_addc_u32 s73, s97, 0
	s_mov_b32 m0, s30
	v_lshl_add_u64 v[246:247], s[72:73], 0, v[172:173]
	ds_read_b128 v[162:165], v214 offset:32768
	ds_read_b128 v[166:169], v214 offset:33792
	ds_read_b128 v[216:219], v214 offset:34816
	ds_read_b128 v[220:223], v214 offset:35840
	ds_read_b128 v[224:227], v214 offset:36864
	ds_read_b128 v[228:231], v214 offset:37888
	ds_read_b128 v[232:235], v214 offset:38912
	ds_read_b128 v[236:239], v214 offset:39936
	global_load_lds_dwordx4 v[246:247], off
	s_mov_b32 m0, s31
	v_lshl_add_u64 v[246:247], s[72:73], 0, v[176:177]
	global_load_lds_dwordx4 v[246:247], off
	s_waitcnt vmcnt(8) lgkmcnt(0)
	s_setprio 1
	s_barrier
	v_mfma_f32_16x16x32_bf16 v[142:145], v[114:117], v[162:165], v[142:145]
	v_mfma_f32_16x16x32_bf16 v[138:141], v[122:125], v[162:165], v[138:141]
	v_mfma_f32_16x16x32_bf16 v[110:113], v[114:117], v[216:219], v[110:113]
	v_mfma_f32_16x16x32_bf16 v[106:109], v[122:125], v[216:219], v[106:109]
	v_mfma_f32_16x16x32_bf16 v[98:101], v[114:117], v[224:227], v[98:101]
	v_mfma_f32_16x16x32_bf16 v[90:93], v[122:125], v[224:227], v[90:93]
	v_mfma_f32_16x16x32_bf16 v[82:85], v[114:117], v[232:235], v[82:85]
	v_mfma_f32_16x16x32_bf16 v[74:77], v[122:125], v[232:235], v[74:77]
	v_mfma_f32_16x16x32_bf16 v[142:145], v[118:121], v[166:169], v[142:145]
	v_mfma_f32_16x16x32_bf16 v[138:141], v[126:129], v[166:169], v[138:141]
	v_mfma_f32_16x16x32_bf16 v[110:113], v[118:121], v[220:223], v[110:113]
	v_mfma_f32_16x16x32_bf16 v[106:109], v[126:129], v[220:223], v[106:109]
	v_mfma_f32_16x16x32_bf16 v[98:101], v[118:121], v[228:231], v[98:101]
	v_mfma_f32_16x16x32_bf16 v[90:93], v[126:129], v[228:231], v[90:93]
	v_mfma_f32_16x16x32_bf16 v[82:85], v[118:121], v[236:239], v[82:85]
	v_mfma_f32_16x16x32_bf16 v[74:77], v[126:129], v[236:239], v[74:77]
	v_mfma_f32_16x16x32_bf16 v[134:137], v[146:149], v[162:165], v[134:137]
	v_mfma_f32_16x16x32_bf16 v[130:133], v[154:157], v[162:165], v[130:133]
	v_mfma_f32_16x16x32_bf16 v[102:105], v[146:149], v[216:219], v[102:105]
	v_mfma_f32_16x16x32_bf16 v[94:97], v[154:157], v[216:219], v[94:97]
	v_mfma_f32_16x16x32_bf16 v[86:89], v[146:149], v[224:227], v[86:89]
	v_mfma_f32_16x16x32_bf16 v[78:81], v[154:157], v[224:227], v[78:81]
	v_mfma_f32_16x16x32_bf16 v[70:73], v[146:149], v[232:235], v[70:73]
	v_mfma_f32_16x16x32_bf16 v[66:69], v[154:157], v[232:235], v[66:69]
	v_mfma_f32_16x16x32_bf16 v[134:137], v[150:153], v[166:169], v[134:137]
	v_mfma_f32_16x16x32_bf16 v[130:133], v[158:161], v[166:169], v[130:133]
	v_mfma_f32_16x16x32_bf16 v[102:105], v[150:153], v[220:223], v[102:105]
	v_mfma_f32_16x16x32_bf16 v[94:97], v[158:161], v[220:223], v[94:97]
	v_mfma_f32_16x16x32_bf16 v[86:89], v[150:153], v[228:231], v[86:89]
	v_mfma_f32_16x16x32_bf16 v[78:81], v[158:161], v[228:231], v[78:81]
	v_mfma_f32_16x16x32_bf16 v[70:73], v[150:153], v[236:239], v[70:73]
	v_mfma_f32_16x16x32_bf16 v[66:69], v[158:161], v[236:239], v[66:69]
	s_setprio 0
	s_barrier
	s_add_i32 s62, s62, s17
	s_mov_b32 m0, s62
	v_lshl_add_u64 v[202:203], v[202:203], 0, s[76:77]
	global_load_lds_dwordx4 v[202:203], off
	ds_read_b128 v[162:165], v214 offset:49152
	ds_read_b128 v[166:169], v214 offset:50176
	ds_read_b128 v[216:219], v214 offset:51200
	ds_read_b128 v[220:223], v214 offset:52224
	ds_read_b128 v[224:227], v214 offset:53248
	ds_read_b128 v[228:231], v214 offset:54272
	ds_read_b128 v[232:235], v214 offset:55296
	ds_read_b128 v[236:239], v214 offset:56320
	s_add_i32 m0, s62, 0x2000
	s_add_u32 s72, s94, 0x40080
	v_lshl_add_u64 v[202:203], v[240:241], 0, s[76:77]
	s_addc_u32 s73, s95, 0
	s_add_i32 s62, s63, s17
	global_load_lds_dwordx4 v[202:203], off
	s_mov_b32 m0, s62
	v_lshl_add_u64 v[202:203], s[72:73], 0, v[174:175]
	global_load_lds_dwordx4 v[202:203], off
	s_add_i32 m0, s62, 0x2000
	v_lshl_add_u64 v[202:203], s[72:73], 0, v[178:179]
	global_load_lds_dwordx4 v[202:203], off
	s_mov_b32 m0, s44
	v_lshl_add_u64 v[202:203], v[242:243], 0, s[76:77]
	global_load_lds_dwordx4 v[202:203], off
	s_mov_b32 m0, s36
	v_lshl_add_u64 v[202:203], v[244:245], 0, s[76:77]
	global_load_lds_dwordx4 v[202:203], off
	s_waitcnt vmcnt(8) lgkmcnt(0)
	s_setprio 1
	s_barrier
	v_mfma_f32_16x16x32_bf16 v[62:65], v[114:117], v[162:165], v[62:65]
	v_mfma_f32_16x16x32_bf16 v[58:61], v[122:125], v[162:165], v[58:61]
	v_mfma_f32_16x16x32_bf16 v[50:53], v[114:117], v[216:219], v[50:53]
	v_mfma_f32_16x16x32_bf16 v[42:45], v[122:125], v[216:219], v[42:45]
	v_mfma_f32_16x16x32_bf16 v[34:37], v[114:117], v[224:227], v[34:37]
	v_mfma_f32_16x16x32_bf16 v[26:29], v[122:125], v[224:227], v[26:29]
	v_mfma_f32_16x16x32_bf16 v[18:21], v[114:117], v[232:235], v[18:21]
	v_mfma_f32_16x16x32_bf16 v[10:13], v[122:125], v[232:235], v[10:13]
	v_mfma_f32_16x16x32_bf16 v[62:65], v[118:121], v[166:169], v[62:65]
	v_mfma_f32_16x16x32_bf16 v[58:61], v[126:129], v[166:169], v[58:61]
	v_mfma_f32_16x16x32_bf16 v[50:53], v[118:121], v[220:223], v[50:53]
	v_mfma_f32_16x16x32_bf16 v[42:45], v[126:129], v[220:223], v[42:45]
	v_mfma_f32_16x16x32_bf16 v[34:37], v[118:121], v[228:231], v[34:37]
	v_mfma_f32_16x16x32_bf16 v[26:29], v[126:129], v[228:231], v[26:29]
	v_mfma_f32_16x16x32_bf16 v[18:21], v[118:121], v[236:239], v[18:21]
	v_mfma_f32_16x16x32_bf16 v[10:13], v[126:129], v[236:239], v[10:13]
	v_mfma_f32_16x16x32_bf16 v[54:57], v[146:149], v[162:165], v[54:57]
	v_mfma_f32_16x16x32_bf16 v[46:49], v[154:157], v[162:165], v[46:49]
	v_mfma_f32_16x16x32_bf16 v[38:41], v[146:149], v[216:219], v[38:41]
	v_mfma_f32_16x16x32_bf16 v[30:33], v[154:157], v[216:219], v[30:33]
	v_mfma_f32_16x16x32_bf16 v[22:25], v[146:149], v[224:227], v[22:25]
	v_mfma_f32_16x16x32_bf16 v[14:17], v[154:157], v[224:227], v[14:17]
	v_mfma_f32_16x16x32_bf16 v[6:9], v[146:149], v[232:235], v[6:9]
	v_mfma_f32_16x16x32_bf16 v[2:5], v[154:157], v[232:235], v[2:5]
	v_mfma_f32_16x16x32_bf16 v[54:57], v[150:153], v[166:169], v[54:57]
	v_mfma_f32_16x16x32_bf16 v[46:49], v[158:161], v[166:169], v[46:49]
	v_mfma_f32_16x16x32_bf16 v[38:41], v[150:153], v[220:223], v[38:41]
	v_mfma_f32_16x16x32_bf16 v[30:33], v[158:161], v[220:223], v[30:33]
	v_mfma_f32_16x16x32_bf16 v[22:25], v[150:153], v[228:231], v[22:25]
	v_mfma_f32_16x16x32_bf16 v[14:17], v[158:161], v[228:231], v[14:17]
	v_mfma_f32_16x16x32_bf16 v[6:9], v[150:153], v[236:239], v[6:9]
	v_mfma_f32_16x16x32_bf16 v[2:5], v[158:161], v[236:239], v[2:5]
	s_setprio 0
	s_barrier
	s_add_u32 s10, s10, 0x100
	s_addc_u32 s11, s11, 0
	s_add_u32 vcc_lo, vcc_lo, 0x100
	s_addc_u32 vcc_hi, vcc_hi, 0
	s_cmp_ge_i32 s66, s18
	s_mov_b32 s94, s66
.LBB0_1428:
	s_add_i32 s66, s94, 2
	s_add_u32 s67, s10, 0xfffc0080
	s_addc_u32 s72, s11, -1
	s_cmp_eq_u32 s85, s94
	s_cselect_b32 s97, s14, s72
	s_cselect_b32 s96, s15, s67
	s_cselect_b32 s95, s51, vcc_hi
	s_cselect_b32 s94, s84, vcc_lo
	s_add_i32 s67, 0, 0x10000
	s_add_i32 s62, 0, 0x14000
	v_add_u32_e32 v126, s67, v199
	v_add_u32_e32 v158, s62, v199
	ds_read_b128 v[114:117], v126
	ds_read_b128 v[118:121], v126 offset:1024
	ds_read_b128 v[122:125], v126 offset:2048
	ds_read_b128 v[126:129], v126 offset:3072
	ds_read_b128 v[146:149], v158
	ds_read_b128 v[150:153], v158 offset:1024
	ds_read_b128 v[154:157], v158 offset:2048
	ds_read_b128 v[158:161], v158 offset:3072
	v_lshl_add_u64 v[202:203], s[10:11], 0, v[196:197]
	s_add_i32 m0, s28, 0xc000
	ds_read_b128 v[162:165], v214
	ds_read_b128 v[166:169], v214 offset:1024
	ds_read_b128 v[216:219], v214 offset:2048
	ds_read_b128 v[220:223], v214 offset:3072
	ds_read_b128 v[224:227], v214 offset:4096
	ds_read_b128 v[228:231], v214 offset:5120
	ds_read_b128 v[232:235], v214 offset:6144
	ds_read_b128 v[236:239], v214 offset:7168
	global_load_lds_dwordx4 v[202:203], off
	s_add_i32 m0, s28, 0xe000
	v_lshl_add_u64 v[202:203], s[10:11], 0, v[176:177]
	global_load_lds_dwordx4 v[202:203], off
	s_waitcnt vmcnt(8) lgkmcnt(0)
	s_setprio 1
	s_barrier
	v_mfma_f32_16x16x32_bf16 v[142:145], v[114:117], v[162:165], v[142:145]
	v_mfma_f32_16x16x32_bf16 v[138:141], v[122:125], v[162:165], v[138:141]
	v_mfma_f32_16x16x32_bf16 v[110:113], v[114:117], v[216:219], v[110:113]
	v_mfma_f32_16x16x32_bf16 v[106:109], v[122:125], v[216:219], v[106:109]
	v_mfma_f32_16x16x32_bf16 v[98:101], v[114:117], v[224:227], v[98:101]
	v_mfma_f32_16x16x32_bf16 v[90:93], v[122:125], v[224:227], v[90:93]
	v_mfma_f32_16x16x32_bf16 v[82:85], v[114:117], v[232:235], v[82:85]
	v_mfma_f32_16x16x32_bf16 v[74:77], v[122:125], v[232:235], v[74:77]
	v_mfma_f32_16x16x32_bf16 v[142:145], v[118:121], v[166:169], v[142:145]
	v_mfma_f32_16x16x32_bf16 v[138:141], v[126:129], v[166:169], v[138:141]
	v_mfma_f32_16x16x32_bf16 v[110:113], v[118:121], v[220:223], v[110:113]
	v_mfma_f32_16x16x32_bf16 v[106:109], v[126:129], v[220:223], v[106:109]
	v_mfma_f32_16x16x32_bf16 v[98:101], v[118:121], v[228:231], v[98:101]
	v_mfma_f32_16x16x32_bf16 v[90:93], v[126:129], v[228:231], v[90:93]
	v_mfma_f32_16x16x32_bf16 v[82:85], v[118:121], v[236:239], v[82:85]
	v_mfma_f32_16x16x32_bf16 v[74:77], v[126:129], v[236:239], v[74:77]
	v_mfma_f32_16x16x32_bf16 v[134:137], v[146:149], v[162:165], v[134:137]
	v_mfma_f32_16x16x32_bf16 v[130:133], v[154:157], v[162:165], v[130:133]
	v_mfma_f32_16x16x32_bf16 v[102:105], v[146:149], v[216:219], v[102:105]
	v_mfma_f32_16x16x32_bf16 v[94:97], v[154:157], v[216:219], v[94:97]
	v_mfma_f32_16x16x32_bf16 v[86:89], v[146:149], v[224:227], v[86:89]
	v_mfma_f32_16x16x32_bf16 v[78:81], v[154:157], v[224:227], v[78:81]
	v_mfma_f32_16x16x32_bf16 v[70:73], v[146:149], v[232:235], v[70:73]
	v_mfma_f32_16x16x32_bf16 v[66:69], v[154:157], v[232:235], v[66:69]
	v_mfma_f32_16x16x32_bf16 v[134:137], v[150:153], v[166:169], v[134:137]
	v_mfma_f32_16x16x32_bf16 v[130:133], v[158:161], v[166:169], v[130:133]
	v_mfma_f32_16x16x32_bf16 v[102:105], v[150:153], v[220:223], v[102:105]
	v_mfma_f32_16x16x32_bf16 v[94:97], v[158:161], v[220:223], v[94:97]
	v_mfma_f32_16x16x32_bf16 v[86:89], v[150:153], v[228:231], v[86:89]
	v_mfma_f32_16x16x32_bf16 v[78:81], v[158:161], v[228:231], v[78:81]
	v_mfma_f32_16x16x32_bf16 v[70:73], v[150:153], v[236:239], v[70:73]
	v_mfma_f32_16x16x32_bf16 v[66:69], v[158:161], v[236:239], v[66:69]
	s_setprio 0
	s_barrier
	s_add_i32 s63, s67, s17
	s_mov_b32 m0, s63
	v_lshl_add_u64 v[202:203], s[94:95], 0, v[174:175]
	global_load_lds_dwordx4 v[202:203], off
	ds_read_b128 v[162:165], v214 offset:16384
	ds_read_b128 v[166:169], v214 offset:17408
	ds_read_b128 v[216:219], v214 offset:18432
	ds_read_b128 v[220:223], v214 offset:19456
	ds_read_b128 v[224:227], v214 offset:20480
	ds_read_b128 v[228:231], v214 offset:21504
	ds_read_b128 v[232:235], v214 offset:22528
	ds_read_b128 v[236:239], v214 offset:23552
	s_add_i32 m0, s63, 0x2000
	s_add_u32 s72, s94, 0x40000
	v_lshl_add_u64 v[240:241], s[94:95], 0, v[178:179]
	s_addc_u32 s73, s95, 0
	s_add_i32 s62, s62, s17
	global_load_lds_dwordx4 v[240:241], off
	v_lshl_add_u64 v[242:243], s[72:73], 0, v[174:175]
	s_mov_b32 m0, s62
	v_lshl_add_u64 v[244:245], s[96:97], 0, v[176:177]
	global_load_lds_dwordx4 v[242:243], off
	s_add_i32 m0, s62, 0x2000
	v_lshl_add_u64 v[242:243], s[72:73], 0, v[178:179]
	global_load_lds_dwordx4 v[242:243], off
	s_mov_b32 m0, s28
	v_lshl_add_u64 v[242:243], s[96:97], 0, v[172:173]
	global_load_lds_dwordx4 v[242:243], off
	s_mov_b32 m0, s29
	s_nop 0
	global_load_lds_dwordx4 v[244:245], off
	s_waitcnt vmcnt(8) lgkmcnt(0)
	s_setprio 1
	s_barrier
	v_mfma_f32_16x16x32_bf16 v[62:65], v[114:117], v[162:165], v[62:65]
	v_mfma_f32_16x16x32_bf16 v[58:61], v[122:125], v[162:165], v[58:61]
	v_mfma_f32_16x16x32_bf16 v[50:53], v[114:117], v[216:219], v[50:53]
	v_mfma_f32_16x16x32_bf16 v[42:45], v[122:125], v[216:219], v[42:45]
	v_mfma_f32_16x16x32_bf16 v[34:37], v[114:117], v[224:227], v[34:37]
	v_mfma_f32_16x16x32_bf16 v[26:29], v[122:125], v[224:227], v[26:29]
	v_mfma_f32_16x16x32_bf16 v[18:21], v[114:117], v[232:235], v[18:21]
	v_mfma_f32_16x16x32_bf16 v[10:13], v[122:125], v[232:235], v[10:13]
	v_mfma_f32_16x16x32_bf16 v[62:65], v[118:121], v[166:169], v[62:65]
	v_mfma_f32_16x16x32_bf16 v[58:61], v[126:129], v[166:169], v[58:61]
	v_mfma_f32_16x16x32_bf16 v[50:53], v[118:121], v[220:223], v[50:53]
	v_mfma_f32_16x16x32_bf16 v[42:45], v[126:129], v[220:223], v[42:45]
	v_mfma_f32_16x16x32_bf16 v[34:37], v[118:121], v[228:231], v[34:37]
	v_mfma_f32_16x16x32_bf16 v[26:29], v[126:129], v[228:231], v[26:29]
	v_mfma_f32_16x16x32_bf16 v[18:21], v[118:121], v[236:239], v[18:21]
	v_mfma_f32_16x16x32_bf16 v[10:13], v[126:129], v[236:239], v[10:13]
	v_mfma_f32_16x16x32_bf16 v[54:57], v[146:149], v[162:165], v[54:57]
	v_mfma_f32_16x16x32_bf16 v[46:49], v[154:157], v[162:165], v[46:49]
	v_mfma_f32_16x16x32_bf16 v[38:41], v[146:149], v[216:219], v[38:41]
	v_mfma_f32_16x16x32_bf16 v[30:33], v[154:157], v[216:219], v[30:33]
	v_mfma_f32_16x16x32_bf16 v[22:25], v[146:149], v[224:227], v[22:25]
	v_mfma_f32_16x16x32_bf16 v[14:17], v[154:157], v[224:227], v[14:17]
	v_mfma_f32_16x16x32_bf16 v[6:9], v[146:149], v[232:235], v[6:9]
	v_mfma_f32_16x16x32_bf16 v[2:5], v[154:157], v[232:235], v[2:5]
	v_mfma_f32_16x16x32_bf16 v[54:57], v[150:153], v[166:169], v[54:57]
	v_mfma_f32_16x16x32_bf16 v[46:49], v[158:161], v[166:169], v[46:49]
	v_mfma_f32_16x16x32_bf16 v[38:41], v[150:153], v[220:223], v[38:41]
	v_mfma_f32_16x16x32_bf16 v[30:33], v[158:161], v[220:223], v[30:33]
	v_mfma_f32_16x16x32_bf16 v[22:25], v[150:153], v[228:231], v[22:25]
	v_mfma_f32_16x16x32_bf16 v[14:17], v[158:161], v[228:231], v[14:17]
	v_mfma_f32_16x16x32_bf16 v[6:9], v[150:153], v[236:239], v[6:9]
	v_mfma_f32_16x16x32_bf16 v[2:5], v[158:161], v[236:239], v[2:5]
	s_setprio 0
	s_barrier
	s_add_i32 s62, 0, 0x18000
	s_add_i32 s63, 0, 0x1c000
	v_add_u32_e32 v126, s62, v199
	v_add_u32_e32 v158, s63, v199
	ds_read_b128 v[114:117], v126
	ds_read_b128 v[118:121], v126 offset:1024
	ds_read_b128 v[122:125], v126 offset:2048
	ds_read_b128 v[126:129], v126 offset:3072
	ds_read_b128 v[146:149], v158
	ds_read_b128 v[150:153], v158 offset:1024
	ds_read_b128 v[154:157], v158 offset:2048
	ds_read_b128 v[158:161], v158 offset:3072
	s_add_u32 s72, s96, 0x40000
	s_addc_u32 s73, s97, 0
	s_mov_b32 m0, s30
	v_lshl_add_u64 v[246:247], s[72:73], 0, v[172:173]
	ds_read_b128 v[162:165], v214 offset:32768
	ds_read_b128 v[166:169], v214 offset:33792
	ds_read_b128 v[216:219], v214 offset:34816
	ds_read_b128 v[220:223], v214 offset:35840
	ds_read_b128 v[224:227], v214 offset:36864
	ds_read_b128 v[228:231], v214 offset:37888
	ds_read_b128 v[232:235], v214 offset:38912
	ds_read_b128 v[236:239], v214 offset:39936
	global_load_lds_dwordx4 v[246:247], off
	s_mov_b32 m0, s31
	v_lshl_add_u64 v[246:247], s[72:73], 0, v[176:177]
	global_load_lds_dwordx4 v[246:247], off
	s_waitcnt vmcnt(8) lgkmcnt(0)
	s_setprio 1
	s_barrier
	v_mfma_f32_16x16x32_bf16 v[142:145], v[114:117], v[162:165], v[142:145]
	v_mfma_f32_16x16x32_bf16 v[138:141], v[122:125], v[162:165], v[138:141]
	v_mfma_f32_16x16x32_bf16 v[110:113], v[114:117], v[216:219], v[110:113]
	v_mfma_f32_16x16x32_bf16 v[106:109], v[122:125], v[216:219], v[106:109]
	v_mfma_f32_16x16x32_bf16 v[98:101], v[114:117], v[224:227], v[98:101]
	v_mfma_f32_16x16x32_bf16 v[90:93], v[122:125], v[224:227], v[90:93]
	v_mfma_f32_16x16x32_bf16 v[82:85], v[114:117], v[232:235], v[82:85]
	v_mfma_f32_16x16x32_bf16 v[74:77], v[122:125], v[232:235], v[74:77]
	v_mfma_f32_16x16x32_bf16 v[142:145], v[118:121], v[166:169], v[142:145]
	v_mfma_f32_16x16x32_bf16 v[138:141], v[126:129], v[166:169], v[138:141]
	v_mfma_f32_16x16x32_bf16 v[110:113], v[118:121], v[220:223], v[110:113]
	v_mfma_f32_16x16x32_bf16 v[106:109], v[126:129], v[220:223], v[106:109]
	v_mfma_f32_16x16x32_bf16 v[98:101], v[118:121], v[228:231], v[98:101]
	v_mfma_f32_16x16x32_bf16 v[90:93], v[126:129], v[228:231], v[90:93]
	v_mfma_f32_16x16x32_bf16 v[82:85], v[118:121], v[236:239], v[82:85]
	v_mfma_f32_16x16x32_bf16 v[74:77], v[126:129], v[236:239], v[74:77]
	v_mfma_f32_16x16x32_bf16 v[134:137], v[146:149], v[162:165], v[134:137]
	v_mfma_f32_16x16x32_bf16 v[130:133], v[154:157], v[162:165], v[130:133]
	v_mfma_f32_16x16x32_bf16 v[102:105], v[146:149], v[216:219], v[102:105]
	v_mfma_f32_16x16x32_bf16 v[94:97], v[154:157], v[216:219], v[94:97]
	v_mfma_f32_16x16x32_bf16 v[86:89], v[146:149], v[224:227], v[86:89]
	v_mfma_f32_16x16x32_bf16 v[78:81], v[154:157], v[224:227], v[78:81]
	v_mfma_f32_16x16x32_bf16 v[70:73], v[146:149], v[232:235], v[70:73]
	v_mfma_f32_16x16x32_bf16 v[66:69], v[154:157], v[232:235], v[66:69]
	v_mfma_f32_16x16x32_bf16 v[134:137], v[150:153], v[166:169], v[134:137]
	v_mfma_f32_16x16x32_bf16 v[130:133], v[158:161], v[166:169], v[130:133]
	v_mfma_f32_16x16x32_bf16 v[102:105], v[150:153], v[220:223], v[102:105]
	v_mfma_f32_16x16x32_bf16 v[94:97], v[158:161], v[220:223], v[94:97]
	v_mfma_f32_16x16x32_bf16 v[86:89], v[150:153], v[228:231], v[86:89]
	v_mfma_f32_16x16x32_bf16 v[78:81], v[158:161], v[228:231], v[78:81]
	v_mfma_f32_16x16x32_bf16 v[70:73], v[150:153], v[236:239], v[70:73]
	v_mfma_f32_16x16x32_bf16 v[66:69], v[158:161], v[236:239], v[66:69]
	s_setprio 0
	s_barrier
	s_add_i32 s62, s62, s17
	s_mov_b32 m0, s62
	v_lshl_add_u64 v[202:203], v[202:203], 0, s[76:77]
	global_load_lds_dwordx4 v[202:203], off
	ds_read_b128 v[162:165], v214 offset:49152
	ds_read_b128 v[166:169], v214 offset:50176
	ds_read_b128 v[216:219], v214 offset:51200
	ds_read_b128 v[220:223], v214 offset:52224
	ds_read_b128 v[224:227], v214 offset:53248
	ds_read_b128 v[228:231], v214 offset:54272
	ds_read_b128 v[232:235], v214 offset:55296
	ds_read_b128 v[236:239], v214 offset:56320
	s_add_i32 m0, s62, 0x2000
	s_add_u32 s72, s94, 0x40080
	v_lshl_add_u64 v[202:203], v[240:241], 0, s[76:77]
	s_addc_u32 s73, s95, 0
	s_add_i32 s62, s63, s17
	global_load_lds_dwordx4 v[202:203], off
	s_mov_b32 m0, s62
	v_lshl_add_u64 v[202:203], s[72:73], 0, v[174:175]
	global_load_lds_dwordx4 v[202:203], off
	s_add_i32 m0, s62, 0x2000
	v_lshl_add_u64 v[202:203], s[72:73], 0, v[178:179]
	global_load_lds_dwordx4 v[202:203], off
	s_mov_b32 m0, s44
	v_lshl_add_u64 v[202:203], v[242:243], 0, s[76:77]
	global_load_lds_dwordx4 v[202:203], off
	s_mov_b32 m0, s36
	v_lshl_add_u64 v[202:203], v[244:245], 0, s[76:77]
	global_load_lds_dwordx4 v[202:203], off
	s_waitcnt vmcnt(8) lgkmcnt(0)
	s_setprio 1
	s_barrier
	v_mfma_f32_16x16x32_bf16 v[62:65], v[114:117], v[162:165], v[62:65]
	v_mfma_f32_16x16x32_bf16 v[58:61], v[122:125], v[162:165], v[58:61]
	v_mfma_f32_16x16x32_bf16 v[50:53], v[114:117], v[216:219], v[50:53]
	v_mfma_f32_16x16x32_bf16 v[42:45], v[122:125], v[216:219], v[42:45]
	v_mfma_f32_16x16x32_bf16 v[34:37], v[114:117], v[224:227], v[34:37]
	v_mfma_f32_16x16x32_bf16 v[26:29], v[122:125], v[224:227], v[26:29]
	v_mfma_f32_16x16x32_bf16 v[18:21], v[114:117], v[232:235], v[18:21]
	v_mfma_f32_16x16x32_bf16 v[10:13], v[122:125], v[232:235], v[10:13]
	v_mfma_f32_16x16x32_bf16 v[62:65], v[118:121], v[166:169], v[62:65]
	v_mfma_f32_16x16x32_bf16 v[58:61], v[126:129], v[166:169], v[58:61]
	v_mfma_f32_16x16x32_bf16 v[50:53], v[118:121], v[220:223], v[50:53]
	v_mfma_f32_16x16x32_bf16 v[42:45], v[126:129], v[220:223], v[42:45]
	v_mfma_f32_16x16x32_bf16 v[34:37], v[118:121], v[228:231], v[34:37]
	v_mfma_f32_16x16x32_bf16 v[26:29], v[126:129], v[228:231], v[26:29]
	v_mfma_f32_16x16x32_bf16 v[18:21], v[118:121], v[236:239], v[18:21]
	v_mfma_f32_16x16x32_bf16 v[10:13], v[126:129], v[236:239], v[10:13]
	v_mfma_f32_16x16x32_bf16 v[54:57], v[146:149], v[162:165], v[54:57]
	v_mfma_f32_16x16x32_bf16 v[46:49], v[154:157], v[162:165], v[46:49]
	v_mfma_f32_16x16x32_bf16 v[38:41], v[146:149], v[216:219], v[38:41]
	v_mfma_f32_16x16x32_bf16 v[30:33], v[154:157], v[216:219], v[30:33]
	v_mfma_f32_16x16x32_bf16 v[22:25], v[146:149], v[224:227], v[22:25]
	v_mfma_f32_16x16x32_bf16 v[14:17], v[154:157], v[224:227], v[14:17]
	v_mfma_f32_16x16x32_bf16 v[6:9], v[146:149], v[232:235], v[6:9]
	v_mfma_f32_16x16x32_bf16 v[2:5], v[154:157], v[232:235], v[2:5]
	v_mfma_f32_16x16x32_bf16 v[54:57], v[150:153], v[166:169], v[54:57]
	v_mfma_f32_16x16x32_bf16 v[46:49], v[158:161], v[166:169], v[46:49]
	v_mfma_f32_16x16x32_bf16 v[38:41], v[150:153], v[220:223], v[38:41]
	v_mfma_f32_16x16x32_bf16 v[30:33], v[158:161], v[220:223], v[30:33]
	v_mfma_f32_16x16x32_bf16 v[22:25], v[150:153], v[228:231], v[22:25]
	v_mfma_f32_16x16x32_bf16 v[14:17], v[158:161], v[228:231], v[14:17]
	v_mfma_f32_16x16x32_bf16 v[6:9], v[150:153], v[236:239], v[6:9]
	v_mfma_f32_16x16x32_bf16 v[2:5], v[158:161], v[236:239], v[2:5]
	s_setprio 0
	s_barrier
	s_add_u32 s10, s10, 0x100
	s_addc_u32 s11, s11, 0
	s_add_u32 vcc_lo, vcc_lo, 0x100
	s_addc_u32 vcc_hi, vcc_hi, 0
	s_cmp_ge_i32 s66, s18
	s_mov_b32 s94, s66
	s_cbranch_scc0 .LBB0_1428
	s_and_b64 vcc, exec, s[82:83]
	s_cbranch_vccz .LBB0_1431
	s_barrier

.LBB0_1618:
	s_add_u32 s24, s96, s20
	s_addc_u32 s25, s97, s21
	s_and_b64 s[14:15], s[4:5], exec
	s_cselect_b32 s14, s25, s29
	s_cselect_b32 s15, s24, s28
	s_add_u32 s26, s2, s22
	s_addc_u32 s27, s3, s23
	s_and_b64 s[36:37], s[4:5], exec
	s_cselect_b32 s17, s27, s31
	s_cselect_b32 s49, s26, s30
	s_add_u32 s28, s28, 0x40080
	s_addc_u32 s29, s29, 0
	s_add_u32 s50, s30, 0x100
	s_addc_u32 s51, s31, 0
	s_mov_b32 s62, -2
	ds_read_b128 v[154:157], v150
	ds_read_b128 v[158:161], v150 offset:1024
	ds_read_b128 v[162:165], v150 offset:2048
	ds_read_b128 v[166:169], v150 offset:3072
	ds_read_b128 v[170:173], v151
	ds_read_b128 v[174:177], v151 offset:1024
	ds_read_b128 v[178:181], v151 offset:2048
	ds_read_b128 v[182:185], v151 offset:3072
	s_add_u32 s30, s28, 0xfffc0080
	s_addc_u32 s31, s29, -1
	s_cmp_eq_u32 s62, 12
	s_cselect_b32 s37, s14, s31
	s_cselect_b32 s36, s15, s30
	s_cselect_b32 s31, s17, s51
	s_cselect_b32 s30, s49, s50
	v_lshl_add_u64 v[146:147], s[28:29], 0, v[138:139]
	s_add_i32 m0, s19, 0xc000
	ds_read_b128 v[186:189], v152
	ds_read_b128 v[190:193], v152 offset:1024
	ds_read_b128 v[194:197], v152 offset:2048
	ds_read_b128 v[198:201], v152 offset:3072
	ds_read_b128 v[206:209], v152 offset:4096
	ds_read_b128 v[210:213], v152 offset:5120
	ds_read_b128 v[214:217], v152 offset:6144
	ds_read_b128 v[218:221], v152 offset:7168
	global_load_lds_dwordx4 v[146:147], off
	s_add_i32 m0, s19, 0xe000
	v_lshl_add_u64 v[146:147], s[28:29], 0, v[140:141]
	global_load_lds_dwordx4 v[146:147], off
	s_waitcnt vmcnt(8) lgkmcnt(0)
	s_setprio 1
	s_barrier
	v_mfma_f32_16x16x32_bf16 v[126:129], v[154:157], v[186:189], 0
	v_mfma_f32_16x16x32_bf16 v[122:125], v[162:165], v[186:189], 0
	v_mfma_f32_16x16x32_bf16 v[110:113], v[154:157], v[194:197], 0
	v_mfma_f32_16x16x32_bf16 v[106:109], v[162:165], v[194:197], 0
	v_mfma_f32_16x16x32_bf16 v[94:97], v[154:157], v[206:209], 0
	v_mfma_f32_16x16x32_bf16 v[90:93], v[162:165], v[206:209], 0
	v_mfma_f32_16x16x32_bf16 v[78:81], v[154:157], v[214:217], 0
	v_mfma_f32_16x16x32_bf16 v[74:77], v[162:165], v[214:217], 0
	v_mfma_f32_16x16x32_bf16 v[126:129], v[158:161], v[190:193], v[126:129]
	v_mfma_f32_16x16x32_bf16 v[122:125], v[166:169], v[190:193], v[122:125]
	v_mfma_f32_16x16x32_bf16 v[110:113], v[158:161], v[198:201], v[110:113]
	v_mfma_f32_16x16x32_bf16 v[106:109], v[166:169], v[198:201], v[106:109]
	v_mfma_f32_16x16x32_bf16 v[94:97], v[158:161], v[210:213], v[94:97]
	v_mfma_f32_16x16x32_bf16 v[90:93], v[166:169], v[210:213], v[90:93]
	v_mfma_f32_16x16x32_bf16 v[78:81], v[158:161], v[218:221], v[78:81]
	v_mfma_f32_16x16x32_bf16 v[74:77], v[166:169], v[218:221], v[74:77]
	v_mfma_f32_16x16x32_bf16 v[118:121], v[170:173], v[186:189], 0
	v_mfma_f32_16x16x32_bf16 v[114:117], v[178:181], v[186:189], 0
	v_mfma_f32_16x16x32_bf16 v[102:105], v[170:173], v[194:197], 0
	v_mfma_f32_16x16x32_bf16 v[98:101], v[178:181], v[194:197], 0
	v_mfma_f32_16x16x32_bf16 v[86:89], v[170:173], v[206:209], 0
	v_mfma_f32_16x16x32_bf16 v[82:85], v[178:181], v[206:209], 0
	v_mfma_f32_16x16x32_bf16 v[70:73], v[170:173], v[214:217], 0
	v_mfma_f32_16x16x32_bf16 v[66:69], v[178:181], v[214:217], 0
	v_mfma_f32_16x16x32_bf16 v[118:121], v[174:177], v[190:193], v[118:121]
	v_mfma_f32_16x16x32_bf16 v[114:117], v[182:185], v[190:193], v[114:117]
	v_mfma_f32_16x16x32_bf16 v[102:105], v[174:177], v[198:201], v[102:105]
	v_mfma_f32_16x16x32_bf16 v[98:101], v[182:185], v[198:201], v[98:101]
	v_mfma_f32_16x16x32_bf16 v[86:89], v[174:177], v[210:213], v[86:89]
	v_mfma_f32_16x16x32_bf16 v[82:85], v[182:185], v[210:213], v[82:85]
	v_mfma_f32_16x16x32_bf16 v[70:73], v[174:177], v[218:221], v[70:73]
	v_mfma_f32_16x16x32_bf16 v[66:69], v[182:185], v[218:221], v[66:69]
	s_setprio 0
	s_barrier
	s_add_i32 s63, s45, s12
	s_mov_b32 m0, s63
	v_lshl_add_u64 v[146:147], s[30:31], 0, v[134:135]
	global_load_lds_dwordx4 v[146:147], off
	ds_read_b128 v[186:189], v152 offset:16384
	ds_read_b128 v[190:193], v152 offset:17408
	ds_read_b128 v[194:197], v152 offset:18432
	ds_read_b128 v[198:201], v152 offset:19456
	ds_read_b128 v[206:209], v152 offset:20480
	ds_read_b128 v[210:213], v152 offset:21504
	ds_read_b128 v[214:217], v152 offset:22528
	ds_read_b128 v[218:221], v152 offset:23552
	s_add_i32 m0, s63, 0x2000
	s_add_u32 s64, s30, 0x40000
	v_lshl_add_u64 v[202:203], s[30:31], 0, v[130:131]
	s_addc_u32 s65, s31, 0
	s_add_i32 s63, s46, s12
	global_load_lds_dwordx4 v[202:203], off
	v_lshl_add_u64 v[222:223], s[64:65], 0, v[134:135]
	s_mov_b32 m0, s63
	v_lshl_add_u64 v[224:225], s[36:37], 0, v[132:133]
	global_load_lds_dwordx4 v[222:223], off
	s_add_i32 m0, s63, 0x2000
	v_lshl_add_u64 v[222:223], s[64:65], 0, v[130:131]
	global_load_lds_dwordx4 v[222:223], off
	s_mov_b32 m0, s19
	v_lshl_add_u64 v[222:223], s[36:37], 0, v[136:137]
	global_load_lds_dwordx4 v[222:223], off
	s_mov_b32 m0, s33
	s_nop 0
	global_load_lds_dwordx4 v[224:225], off
	s_waitcnt vmcnt(8) lgkmcnt(0)
	s_setprio 1
	s_barrier
	v_mfma_f32_16x16x32_bf16 v[62:65], v[154:157], v[186:189], 0
	v_mfma_f32_16x16x32_bf16 v[58:61], v[162:165], v[186:189], 0
	v_mfma_f32_16x16x32_bf16 v[46:49], v[154:157], v[194:197], 0
	v_mfma_f32_16x16x32_bf16 v[42:45], v[162:165], v[194:197], 0
	v_mfma_f32_16x16x32_bf16 v[30:33], v[154:157], v[206:209], 0
	v_mfma_f32_16x16x32_bf16 v[26:29], v[162:165], v[206:209], 0
	v_mfma_f32_16x16x32_bf16 v[14:17], v[154:157], v[214:217], 0
	v_mfma_f32_16x16x32_bf16 v[10:13], v[162:165], v[214:217], 0
	v_mfma_f32_16x16x32_bf16 v[62:65], v[158:161], v[190:193], v[62:65]
	v_mfma_f32_16x16x32_bf16 v[58:61], v[166:169], v[190:193], v[58:61]
	v_mfma_f32_16x16x32_bf16 v[46:49], v[158:161], v[198:201], v[46:49]
	v_mfma_f32_16x16x32_bf16 v[42:45], v[166:169], v[198:201], v[42:45]
	v_mfma_f32_16x16x32_bf16 v[30:33], v[158:161], v[210:213], v[30:33]
	v_mfma_f32_16x16x32_bf16 v[26:29], v[166:169], v[210:213], v[26:29]
	v_mfma_f32_16x16x32_bf16 v[14:17], v[158:161], v[218:221], v[14:17]
	v_mfma_f32_16x16x32_bf16 v[10:13], v[166:169], v[218:221], v[10:13]
	v_mfma_f32_16x16x32_bf16 v[54:57], v[170:173], v[186:189], 0
	v_mfma_f32_16x16x32_bf16 v[50:53], v[178:181], v[186:189], 0
	v_mfma_f32_16x16x32_bf16 v[38:41], v[170:173], v[194:197], 0
	v_mfma_f32_16x16x32_bf16 v[34:37], v[178:181], v[194:197], 0
	v_mfma_f32_16x16x32_bf16 v[22:25], v[170:173], v[206:209], 0
	v_mfma_f32_16x16x32_bf16 v[18:21], v[178:181], v[206:209], 0
	v_mfma_f32_16x16x32_bf16 v[6:9], v[170:173], v[214:217], 0
	v_mfma_f32_16x16x32_bf16 v[2:5], v[178:181], v[214:217], 0
	v_mfma_f32_16x16x32_bf16 v[54:57], v[174:177], v[190:193], v[54:57]
	v_mfma_f32_16x16x32_bf16 v[50:53], v[182:185], v[190:193], v[50:53]
	v_mfma_f32_16x16x32_bf16 v[38:41], v[174:177], v[198:201], v[38:41]
	v_mfma_f32_16x16x32_bf16 v[34:37], v[182:185], v[198:201], v[34:37]
	v_mfma_f32_16x16x32_bf16 v[22:25], v[174:177], v[210:213], v[22:25]
	v_mfma_f32_16x16x32_bf16 v[18:21], v[182:185], v[210:213], v[18:21]
	v_mfma_f32_16x16x32_bf16 v[6:9], v[174:177], v[218:221], v[6:9]
	v_mfma_f32_16x16x32_bf16 v[2:5], v[182:185], v[218:221], v[2:5]
	s_setprio 0
	s_barrier
	s_add_i32 s63, 0, 0x18000
	v_add_u32_e32 v153, s63, v149
	s_add_i32 s64, 0, 0x1c000
	ds_read_b128 v[154:157], v153
	ds_read_b128 v[158:161], v153 offset:1024
	ds_read_b128 v[162:165], v153 offset:2048
	ds_read_b128 v[166:169], v153 offset:3072
	v_add_u32_e32 v153, s64, v149
	ds_read_b128 v[170:173], v153
	ds_read_b128 v[174:177], v153 offset:1024
	ds_read_b128 v[178:181], v153 offset:2048
	ds_read_b128 v[182:185], v153 offset:3072
	s_add_u32 s36, s36, 0x40000
	s_addc_u32 s37, s37, 0
	s_mov_b32 m0, s35
	v_lshl_add_u64 v[226:227], s[36:37], 0, v[136:137]
	ds_read_b128 v[186:189], v152 offset:32768
	ds_read_b128 v[190:193], v152 offset:33792
	ds_read_b128 v[194:197], v152 offset:34816
	ds_read_b128 v[198:201], v152 offset:35840
	ds_read_b128 v[206:209], v152 offset:36864
	ds_read_b128 v[210:213], v152 offset:37888
	ds_read_b128 v[214:217], v152 offset:38912
	ds_read_b128 v[218:221], v152 offset:39936
	global_load_lds_dwordx4 v[226:227], off
	s_mov_b32 m0, s38
	v_lshl_add_u64 v[226:227], s[36:37], 0, v[132:133]
	global_load_lds_dwordx4 v[226:227], off
	s_waitcnt vmcnt(8) lgkmcnt(0)
	s_setprio 1
	s_barrier
	v_mfma_f32_16x16x32_bf16 v[126:129], v[154:157], v[186:189], v[126:129]
	v_mfma_f32_16x16x32_bf16 v[122:125], v[162:165], v[186:189], v[122:125]
	v_mfma_f32_16x16x32_bf16 v[110:113], v[154:157], v[194:197], v[110:113]
	v_mfma_f32_16x16x32_bf16 v[106:109], v[162:165], v[194:197], v[106:109]
	v_mfma_f32_16x16x32_bf16 v[94:97], v[154:157], v[206:209], v[94:97]
	v_mfma_f32_16x16x32_bf16 v[90:93], v[162:165], v[206:209], v[90:93]
	v_mfma_f32_16x16x32_bf16 v[78:81], v[154:157], v[214:217], v[78:81]
	v_mfma_f32_16x16x32_bf16 v[74:77], v[162:165], v[214:217], v[74:77]
	v_mfma_f32_16x16x32_bf16 v[126:129], v[158:161], v[190:193], v[126:129]
	v_mfma_f32_16x16x32_bf16 v[122:125], v[166:169], v[190:193], v[122:125]
	v_mfma_f32_16x16x32_bf16 v[110:113], v[158:161], v[198:201], v[110:113]
	v_mfma_f32_16x16x32_bf16 v[106:109], v[166:169], v[198:201], v[106:109]
	v_mfma_f32_16x16x32_bf16 v[94:97], v[158:161], v[210:213], v[94:97]
	v_mfma_f32_16x16x32_bf16 v[90:93], v[166:169], v[210:213], v[90:93]
	v_mfma_f32_16x16x32_bf16 v[78:81], v[158:161], v[218:221], v[78:81]
	v_mfma_f32_16x16x32_bf16 v[74:77], v[166:169], v[218:221], v[74:77]
	v_mfma_f32_16x16x32_bf16 v[118:121], v[170:173], v[186:189], v[118:121]
	v_mfma_f32_16x16x32_bf16 v[114:117], v[178:181], v[186:189], v[114:117]
	v_mfma_f32_16x16x32_bf16 v[102:105], v[170:173], v[194:197], v[102:105]
	v_mfma_f32_16x16x32_bf16 v[98:101], v[178:181], v[194:197], v[98:101]
	v_mfma_f32_16x16x32_bf16 v[86:89], v[170:173], v[206:209], v[86:89]
	v_mfma_f32_16x16x32_bf16 v[82:85], v[178:181], v[206:209], v[82:85]
	v_mfma_f32_16x16x32_bf16 v[70:73], v[170:173], v[214:217], v[70:73]
	v_mfma_f32_16x16x32_bf16 v[66:69], v[178:181], v[214:217], v[66:69]
	v_mfma_f32_16x16x32_bf16 v[118:121], v[174:177], v[190:193], v[118:121]
	v_mfma_f32_16x16x32_bf16 v[114:117], v[182:185], v[190:193], v[114:117]
	v_mfma_f32_16x16x32_bf16 v[102:105], v[174:177], v[198:201], v[102:105]
	v_mfma_f32_16x16x32_bf16 v[98:101], v[182:185], v[198:201], v[98:101]
	v_mfma_f32_16x16x32_bf16 v[86:89], v[174:177], v[210:213], v[86:89]
	v_mfma_f32_16x16x32_bf16 v[82:85], v[182:185], v[210:213], v[82:85]
	v_mfma_f32_16x16x32_bf16 v[70:73], v[174:177], v[218:221], v[70:73]
	v_mfma_f32_16x16x32_bf16 v[66:69], v[182:185], v[218:221], v[66:69]
	s_setprio 0
	s_barrier
	s_add_i32 s36, s63, s12
	s_mov_b32 m0, s36
	v_lshl_add_u64 v[146:147], v[146:147], 0, s[8:9]
	global_load_lds_dwordx4 v[146:147], off
	ds_read_b128 v[186:189], v152 offset:49152
	ds_read_b128 v[190:193], v152 offset:50176
	ds_read_b128 v[194:197], v152 offset:51200
	ds_read_b128 v[198:201], v152 offset:52224
	ds_read_b128 v[206:209], v152 offset:53248
	ds_read_b128 v[210:213], v152 offset:54272
	ds_read_b128 v[214:217], v152 offset:55296
	ds_read_b128 v[218:221], v152 offset:56320
	s_add_i32 m0, s36, 0x2000
	s_add_u32 s30, s30, 0x40080
	v_lshl_add_u64 v[146:147], v[202:203], 0, s[8:9]
	s_addc_u32 s31, s31, 0
	s_add_i32 s36, s64, s12
	global_load_lds_dwordx4 v[146:147], off
	s_mov_b32 m0, s36
	v_lshl_add_u64 v[146:147], s[30:31], 0, v[134:135]
	global_load_lds_dwordx4 v[146:147], off
	s_add_i32 m0, s36, 0x2000
	v_lshl_add_u64 v[146:147], s[30:31], 0, v[130:131]
	global_load_lds_dwordx4 v[146:147], off
	s_mov_b32 m0, s42
	v_lshl_add_u64 v[146:147], v[222:223], 0, s[8:9]
	global_load_lds_dwordx4 v[146:147], off
	s_mov_b32 m0, s43
	v_lshl_add_u64 v[146:147], v[224:225], 0, s[8:9]
	global_load_lds_dwordx4 v[146:147], off
	s_waitcnt vmcnt(8) lgkmcnt(0)
	s_setprio 1
	s_barrier
	v_mfma_f32_16x16x32_bf16 v[62:65], v[154:157], v[186:189], v[62:65]
	v_mfma_f32_16x16x32_bf16 v[58:61], v[162:165], v[186:189], v[58:61]
	v_mfma_f32_16x16x32_bf16 v[46:49], v[154:157], v[194:197], v[46:49]
	v_mfma_f32_16x16x32_bf16 v[42:45], v[162:165], v[194:197], v[42:45]
	v_mfma_f32_16x16x32_bf16 v[30:33], v[154:157], v[206:209], v[30:33]
	v_mfma_f32_16x16x32_bf16 v[26:29], v[162:165], v[206:209], v[26:29]
	v_mfma_f32_16x16x32_bf16 v[14:17], v[154:157], v[214:217], v[14:17]
	v_mfma_f32_16x16x32_bf16 v[10:13], v[162:165], v[214:217], v[10:13]
	v_mfma_f32_16x16x32_bf16 v[62:65], v[158:161], v[190:193], v[62:65]
	v_mfma_f32_16x16x32_bf16 v[58:61], v[166:169], v[190:193], v[58:61]
	v_mfma_f32_16x16x32_bf16 v[46:49], v[158:161], v[198:201], v[46:49]
	v_mfma_f32_16x16x32_bf16 v[42:45], v[166:169], v[198:201], v[42:45]
	v_mfma_f32_16x16x32_bf16 v[30:33], v[158:161], v[210:213], v[30:33]
	v_mfma_f32_16x16x32_bf16 v[26:29], v[166:169], v[210:213], v[26:29]
	v_mfma_f32_16x16x32_bf16 v[14:17], v[158:161], v[218:221], v[14:17]
	v_mfma_f32_16x16x32_bf16 v[10:13], v[166:169], v[218:221], v[10:13]
	v_mfma_f32_16x16x32_bf16 v[54:57], v[170:173], v[186:189], v[54:57]
	v_mfma_f32_16x16x32_bf16 v[50:53], v[178:181], v[186:189], v[50:53]
	v_mfma_f32_16x16x32_bf16 v[38:41], v[170:173], v[194:197], v[38:41]
	v_mfma_f32_16x16x32_bf16 v[34:37], v[178:181], v[194:197], v[34:37]
	v_mfma_f32_16x16x32_bf16 v[22:25], v[170:173], v[206:209], v[22:25]
	v_mfma_f32_16x16x32_bf16 v[18:21], v[178:181], v[206:209], v[18:21]
	v_mfma_f32_16x16x32_bf16 v[6:9], v[170:173], v[214:217], v[6:9]
	v_mfma_f32_16x16x32_bf16 v[2:5], v[178:181], v[214:217], v[2:5]
	v_mfma_f32_16x16x32_bf16 v[54:57], v[174:177], v[190:193], v[54:57]
	v_mfma_f32_16x16x32_bf16 v[50:53], v[182:185], v[190:193], v[50:53]
	v_mfma_f32_16x16x32_bf16 v[38:41], v[174:177], v[198:201], v[38:41]
	v_mfma_f32_16x16x32_bf16 v[34:37], v[182:185], v[198:201], v[34:37]
	v_mfma_f32_16x16x32_bf16 v[22:25], v[174:177], v[210:213], v[22:25]
	v_mfma_f32_16x16x32_bf16 v[18:21], v[182:185], v[210:213], v[18:21]
	v_mfma_f32_16x16x32_bf16 v[6:9], v[174:177], v[218:221], v[6:9]
	v_mfma_f32_16x16x32_bf16 v[2:5], v[182:185], v[218:221], v[2:5]
	s_setprio 0
	s_barrier
	s_add_i32 s62, s62, 2
	s_add_u32 s28, s28, 0x100
	s_addc_u32 s29, s29, 0
	s_add_u32 s50, s50, 0x100
	s_addc_u32 s51, s51, 0
	s_cmp_gt_u32 s62, 13
.LBB0_1619:
	ds_read_b128 v[154:157], v150
	ds_read_b128 v[158:161], v150 offset:1024
	ds_read_b128 v[162:165], v150 offset:2048
	ds_read_b128 v[166:169], v150 offset:3072
	ds_read_b128 v[170:173], v151
	ds_read_b128 v[174:177], v151 offset:1024
	ds_read_b128 v[178:181], v151 offset:2048
	ds_read_b128 v[182:185], v151 offset:3072
	s_add_u32 s30, s28, 0xfffc0080
	s_addc_u32 s31, s29, -1
	s_cmp_eq_u32 s62, 12
	s_cselect_b32 s37, s14, s31
	s_cselect_b32 s36, s15, s30
	s_cselect_b32 s31, s17, s51
	s_cselect_b32 s30, s49, s50
	v_lshl_add_u64 v[146:147], s[28:29], 0, v[138:139]
	s_add_i32 m0, s19, 0xc000
	ds_read_b128 v[186:189], v152
	ds_read_b128 v[190:193], v152 offset:1024
	ds_read_b128 v[194:197], v152 offset:2048
	ds_read_b128 v[198:201], v152 offset:3072
	ds_read_b128 v[206:209], v152 offset:4096
	ds_read_b128 v[210:213], v152 offset:5120
	ds_read_b128 v[214:217], v152 offset:6144
	ds_read_b128 v[218:221], v152 offset:7168
	global_load_lds_dwordx4 v[146:147], off
	s_add_i32 m0, s19, 0xe000
	v_lshl_add_u64 v[146:147], s[28:29], 0, v[140:141]
	global_load_lds_dwordx4 v[146:147], off
	s_waitcnt vmcnt(8) lgkmcnt(0)
	s_setprio 1
	s_barrier
	v_mfma_f32_16x16x32_bf16 v[126:129], v[154:157], v[186:189], v[126:129]
	v_mfma_f32_16x16x32_bf16 v[122:125], v[162:165], v[186:189], v[122:125]
	v_mfma_f32_16x16x32_bf16 v[110:113], v[154:157], v[194:197], v[110:113]
	v_mfma_f32_16x16x32_bf16 v[106:109], v[162:165], v[194:197], v[106:109]
	v_mfma_f32_16x16x32_bf16 v[94:97], v[154:157], v[206:209], v[94:97]
	v_mfma_f32_16x16x32_bf16 v[90:93], v[162:165], v[206:209], v[90:93]
	v_mfma_f32_16x16x32_bf16 v[78:81], v[154:157], v[214:217], v[78:81]
	v_mfma_f32_16x16x32_bf16 v[74:77], v[162:165], v[214:217], v[74:77]
	v_mfma_f32_16x16x32_bf16 v[126:129], v[158:161], v[190:193], v[126:129]
	v_mfma_f32_16x16x32_bf16 v[122:125], v[166:169], v[190:193], v[122:125]
	v_mfma_f32_16x16x32_bf16 v[110:113], v[158:161], v[198:201], v[110:113]
	v_mfma_f32_16x16x32_bf16 v[106:109], v[166:169], v[198:201], v[106:109]
	v_mfma_f32_16x16x32_bf16 v[94:97], v[158:161], v[210:213], v[94:97]
	v_mfma_f32_16x16x32_bf16 v[90:93], v[166:169], v[210:213], v[90:93]
	v_mfma_f32_16x16x32_bf16 v[78:81], v[158:161], v[218:221], v[78:81]
	v_mfma_f32_16x16x32_bf16 v[74:77], v[166:169], v[218:221], v[74:77]
	v_mfma_f32_16x16x32_bf16 v[118:121], v[170:173], v[186:189], v[118:121]
	v_mfma_f32_16x16x32_bf16 v[114:117], v[178:181], v[186:189], v[114:117]
	v_mfma_f32_16x16x32_bf16 v[102:105], v[170:173], v[194:197], v[102:105]
	v_mfma_f32_16x16x32_bf16 v[98:101], v[178:181], v[194:197], v[98:101]
	v_mfma_f32_16x16x32_bf16 v[86:89], v[170:173], v[206:209], v[86:89]
	v_mfma_f32_16x16x32_bf16 v[82:85], v[178:181], v[206:209], v[82:85]
	v_mfma_f32_16x16x32_bf16 v[70:73], v[170:173], v[214:217], v[70:73]
	v_mfma_f32_16x16x32_bf16 v[66:69], v[178:181], v[214:217], v[66:69]
	v_mfma_f32_16x16x32_bf16 v[118:121], v[174:177], v[190:193], v[118:121]
	v_mfma_f32_16x16x32_bf16 v[114:117], v[182:185], v[190:193], v[114:117]
	v_mfma_f32_16x16x32_bf16 v[102:105], v[174:177], v[198:201], v[102:105]
	v_mfma_f32_16x16x32_bf16 v[98:101], v[182:185], v[198:201], v[98:101]
	v_mfma_f32_16x16x32_bf16 v[86:89], v[174:177], v[210:213], v[86:89]
	v_mfma_f32_16x16x32_bf16 v[82:85], v[182:185], v[210:213], v[82:85]
	v_mfma_f32_16x16x32_bf16 v[70:73], v[174:177], v[218:221], v[70:73]
	v_mfma_f32_16x16x32_bf16 v[66:69], v[182:185], v[218:221], v[66:69]
	s_setprio 0
	s_barrier
	s_add_i32 s63, s45, s12
	s_mov_b32 m0, s63
	v_lshl_add_u64 v[146:147], s[30:31], 0, v[134:135]
	global_load_lds_dwordx4 v[146:147], off
	ds_read_b128 v[186:189], v152 offset:16384
	ds_read_b128 v[190:193], v152 offset:17408
	ds_read_b128 v[194:197], v152 offset:18432
	ds_read_b128 v[198:201], v152 offset:19456
	ds_read_b128 v[206:209], v152 offset:20480
	ds_read_b128 v[210:213], v152 offset:21504
	ds_read_b128 v[214:217], v152 offset:22528
	ds_read_b128 v[218:221], v152 offset:23552
	s_add_i32 m0, s63, 0x2000
	s_add_u32 s64, s30, 0x40000
	v_lshl_add_u64 v[202:203], s[30:31], 0, v[130:131]
	s_addc_u32 s65, s31, 0
	s_add_i32 s63, s46, s12
	global_load_lds_dwordx4 v[202:203], off
	v_lshl_add_u64 v[222:223], s[64:65], 0, v[134:135]
	s_mov_b32 m0, s63
	v_lshl_add_u64 v[224:225], s[36:37], 0, v[132:133]
	global_load_lds_dwordx4 v[222:223], off
	s_add_i32 m0, s63, 0x2000
	v_lshl_add_u64 v[222:223], s[64:65], 0, v[130:131]
	global_load_lds_dwordx4 v[222:223], off
	s_mov_b32 m0, s19
	v_lshl_add_u64 v[222:223], s[36:37], 0, v[136:137]
	global_load_lds_dwordx4 v[222:223], off
	s_mov_b32 m0, s33
	s_nop 0
	global_load_lds_dwordx4 v[224:225], off
	s_waitcnt vmcnt(8) lgkmcnt(0)
	s_setprio 1
	s_barrier
	v_mfma_f32_16x16x32_bf16 v[62:65], v[154:157], v[186:189], v[62:65]
	v_mfma_f32_16x16x32_bf16 v[58:61], v[162:165], v[186:189], v[58:61]
	v_mfma_f32_16x16x32_bf16 v[46:49], v[154:157], v[194:197], v[46:49]
	v_mfma_f32_16x16x32_bf16 v[42:45], v[162:165], v[194:197], v[42:45]
	v_mfma_f32_16x16x32_bf16 v[30:33], v[154:157], v[206:209], v[30:33]
	v_mfma_f32_16x16x32_bf16 v[26:29], v[162:165], v[206:209], v[26:29]
	v_mfma_f32_16x16x32_bf16 v[14:17], v[154:157], v[214:217], v[14:17]
	v_mfma_f32_16x16x32_bf16 v[10:13], v[162:165], v[214:217], v[10:13]
	v_mfma_f32_16x16x32_bf16 v[62:65], v[158:161], v[190:193], v[62:65]
	v_mfma_f32_16x16x32_bf16 v[58:61], v[166:169], v[190:193], v[58:61]
	v_mfma_f32_16x16x32_bf16 v[46:49], v[158:161], v[198:201], v[46:49]
	v_mfma_f32_16x16x32_bf16 v[42:45], v[166:169], v[198:201], v[42:45]
	v_mfma_f32_16x16x32_bf16 v[30:33], v[158:161], v[210:213], v[30:33]
	v_mfma_f32_16x16x32_bf16 v[26:29], v[166:169], v[210:213], v[26:29]
	v_mfma_f32_16x16x32_bf16 v[14:17], v[158:161], v[218:221], v[14:17]
	v_mfma_f32_16x16x32_bf16 v[10:13], v[166:169], v[218:221], v[10:13]
	v_mfma_f32_16x16x32_bf16 v[54:57], v[170:173], v[186:189], v[54:57]
	v_mfma_f32_16x16x32_bf16 v[50:53], v[178:181], v[186:189], v[50:53]
	v_mfma_f32_16x16x32_bf16 v[38:41], v[170:173], v[194:197], v[38:41]
	v_mfma_f32_16x16x32_bf16 v[34:37], v[178:181], v[194:197], v[34:37]
	v_mfma_f32_16x16x32_bf16 v[22:25], v[170:173], v[206:209], v[22:25]
	v_mfma_f32_16x16x32_bf16 v[18:21], v[178:181], v[206:209], v[18:21]
	v_mfma_f32_16x16x32_bf16 v[6:9], v[170:173], v[214:217], v[6:9]
	v_mfma_f32_16x16x32_bf16 v[2:5], v[178:181], v[214:217], v[2:5]
	v_mfma_f32_16x16x32_bf16 v[54:57], v[174:177], v[190:193], v[54:57]
	v_mfma_f32_16x16x32_bf16 v[50:53], v[182:185], v[190:193], v[50:53]
	v_mfma_f32_16x16x32_bf16 v[38:41], v[174:177], v[198:201], v[38:41]
	v_mfma_f32_16x16x32_bf16 v[34:37], v[182:185], v[198:201], v[34:37]
	v_mfma_f32_16x16x32_bf16 v[22:25], v[174:177], v[210:213], v[22:25]
	v_mfma_f32_16x16x32_bf16 v[18:21], v[182:185], v[210:213], v[18:21]
	v_mfma_f32_16x16x32_bf16 v[6:9], v[174:177], v[218:221], v[6:9]
	v_mfma_f32_16x16x32_bf16 v[2:5], v[182:185], v[218:221], v[2:5]
	s_setprio 0
	s_barrier
	s_add_i32 s63, 0, 0x18000
	v_add_u32_e32 v153, s63, v149
	s_add_i32 s64, 0, 0x1c000
	ds_read_b128 v[154:157], v153
	ds_read_b128 v[158:161], v153 offset:1024
	ds_read_b128 v[162:165], v153 offset:2048
	ds_read_b128 v[166:169], v153 offset:3072
	v_add_u32_e32 v153, s64, v149
	ds_read_b128 v[170:173], v153
	ds_read_b128 v[174:177], v153 offset:1024
	ds_read_b128 v[178:181], v153 offset:2048
	ds_read_b128 v[182:185], v153 offset:3072
	s_add_u32 s36, s36, 0x40000
	s_addc_u32 s37, s37, 0
	s_mov_b32 m0, s35
	v_lshl_add_u64 v[226:227], s[36:37], 0, v[136:137]
	ds_read_b128 v[186:189], v152 offset:32768
	ds_read_b128 v[190:193], v152 offset:33792
	ds_read_b128 v[194:197], v152 offset:34816
	ds_read_b128 v[198:201], v152 offset:35840
	ds_read_b128 v[206:209], v152 offset:36864
	ds_read_b128 v[210:213], v152 offset:37888
	ds_read_b128 v[214:217], v152 offset:38912
	ds_read_b128 v[218:221], v152 offset:39936
	global_load_lds_dwordx4 v[226:227], off
	s_mov_b32 m0, s38
	v_lshl_add_u64 v[226:227], s[36:37], 0, v[132:133]
	global_load_lds_dwordx4 v[226:227], off
	s_waitcnt vmcnt(8) lgkmcnt(0)
	s_setprio 1
	s_barrier
	v_mfma_f32_16x16x32_bf16 v[126:129], v[154:157], v[186:189], v[126:129]
	v_mfma_f32_16x16x32_bf16 v[122:125], v[162:165], v[186:189], v[122:125]
	v_mfma_f32_16x16x32_bf16 v[110:113], v[154:157], v[194:197], v[110:113]
	v_mfma_f32_16x16x32_bf16 v[106:109], v[162:165], v[194:197], v[106:109]
	v_mfma_f32_16x16x32_bf16 v[94:97], v[154:157], v[206:209], v[94:97]
	v_mfma_f32_16x16x32_bf16 v[90:93], v[162:165], v[206:209], v[90:93]
	v_mfma_f32_16x16x32_bf16 v[78:81], v[154:157], v[214:217], v[78:81]
	v_mfma_f32_16x16x32_bf16 v[74:77], v[162:165], v[214:217], v[74:77]
	v_mfma_f32_16x16x32_bf16 v[126:129], v[158:161], v[190:193], v[126:129]
	v_mfma_f32_16x16x32_bf16 v[122:125], v[166:169], v[190:193], v[122:125]
	v_mfma_f32_16x16x32_bf16 v[110:113], v[158:161], v[198:201], v[110:113]
	v_mfma_f32_16x16x32_bf16 v[106:109], v[166:169], v[198:201], v[106:109]
	v_mfma_f32_16x16x32_bf16 v[94:97], v[158:161], v[210:213], v[94:97]
	v_mfma_f32_16x16x32_bf16 v[90:93], v[166:169], v[210:213], v[90:93]
	v_mfma_f32_16x16x32_bf16 v[78:81], v[158:161], v[218:221], v[78:81]
	v_mfma_f32_16x16x32_bf16 v[74:77], v[166:169], v[218:221], v[74:77]
	v_mfma_f32_16x16x32_bf16 v[118:121], v[170:173], v[186:189], v[118:121]
	v_mfma_f32_16x16x32_bf16 v[114:117], v[178:181], v[186:189], v[114:117]
	v_mfma_f32_16x16x32_bf16 v[102:105], v[170:173], v[194:197], v[102:105]
	v_mfma_f32_16x16x32_bf16 v[98:101], v[178:181], v[194:197], v[98:101]
	v_mfma_f32_16x16x32_bf16 v[86:89], v[170:173], v[206:209], v[86:89]
	v_mfma_f32_16x16x32_bf16 v[82:85], v[178:181], v[206:209], v[82:85]
	v_mfma_f32_16x16x32_bf16 v[70:73], v[170:173], v[214:217], v[70:73]
	v_mfma_f32_16x16x32_bf16 v[66:69], v[178:181], v[214:217], v[66:69]
	v_mfma_f32_16x16x32_bf16 v[118:121], v[174:177], v[190:193], v[118:121]
	v_mfma_f32_16x16x32_bf16 v[114:117], v[182:185], v[190:193], v[114:117]
	v_mfma_f32_16x16x32_bf16 v[102:105], v[174:177], v[198:201], v[102:105]
	v_mfma_f32_16x16x32_bf16 v[98:101], v[182:185], v[198:201], v[98:101]
	v_mfma_f32_16x16x32_bf16 v[86:89], v[174:177], v[210:213], v[86:89]
	v_mfma_f32_16x16x32_bf16 v[82:85], v[182:185], v[210:213], v[82:85]
	v_mfma_f32_16x16x32_bf16 v[70:73], v[174:177], v[218:221], v[70:73]
	v_mfma_f32_16x16x32_bf16 v[66:69], v[182:185], v[218:221], v[66:69]
	s_setprio 0
	s_barrier
	s_add_i32 s36, s63, s12
	s_mov_b32 m0, s36
	v_lshl_add_u64 v[146:147], v[146:147], 0, s[8:9]
	global_load_lds_dwordx4 v[146:147], off
	ds_read_b128 v[186:189], v152 offset:49152
	ds_read_b128 v[190:193], v152 offset:50176
	ds_read_b128 v[194:197], v152 offset:51200
	ds_read_b128 v[198:201], v152 offset:52224
	ds_read_b128 v[206:209], v152 offset:53248
	ds_read_b128 v[210:213], v152 offset:54272
	ds_read_b128 v[214:217], v152 offset:55296
	ds_read_b128 v[218:221], v152 offset:56320
	s_add_i32 m0, s36, 0x2000
	s_add_u32 s30, s30, 0x40080
	v_lshl_add_u64 v[146:147], v[202:203], 0, s[8:9]
	s_addc_u32 s31, s31, 0
	s_add_i32 s36, s64, s12
	global_load_lds_dwordx4 v[146:147], off
	s_mov_b32 m0, s36
	v_lshl_add_u64 v[146:147], s[30:31], 0, v[134:135]
	global_load_lds_dwordx4 v[146:147], off
	s_add_i32 m0, s36, 0x2000
	v_lshl_add_u64 v[146:147], s[30:31], 0, v[130:131]
	global_load_lds_dwordx4 v[146:147], off
	s_mov_b32 m0, s42
	v_lshl_add_u64 v[146:147], v[222:223], 0, s[8:9]
	global_load_lds_dwordx4 v[146:147], off
	s_mov_b32 m0, s43
	v_lshl_add_u64 v[146:147], v[224:225], 0, s[8:9]
	global_load_lds_dwordx4 v[146:147], off
	s_waitcnt vmcnt(8) lgkmcnt(0)
	s_setprio 1
	s_barrier
	v_mfma_f32_16x16x32_bf16 v[62:65], v[154:157], v[186:189], v[62:65]
	v_mfma_f32_16x16x32_bf16 v[58:61], v[162:165], v[186:189], v[58:61]
	v_mfma_f32_16x16x32_bf16 v[46:49], v[154:157], v[194:197], v[46:49]
	v_mfma_f32_16x16x32_bf16 v[42:45], v[162:165], v[194:197], v[42:45]
	v_mfma_f32_16x16x32_bf16 v[30:33], v[154:157], v[206:209], v[30:33]
	v_mfma_f32_16x16x32_bf16 v[26:29], v[162:165], v[206:209], v[26:29]
	v_mfma_f32_16x16x32_bf16 v[14:17], v[154:157], v[214:217], v[14:17]
	v_mfma_f32_16x16x32_bf16 v[10:13], v[162:165], v[214:217], v[10:13]
	v_mfma_f32_16x16x32_bf16 v[62:65], v[158:161], v[190:193], v[62:65]
	v_mfma_f32_16x16x32_bf16 v[58:61], v[166:169], v[190:193], v[58:61]
	v_mfma_f32_16x16x32_bf16 v[46:49], v[158:161], v[198:201], v[46:49]
	v_mfma_f32_16x16x32_bf16 v[42:45], v[166:169], v[198:201], v[42:45]
	v_mfma_f32_16x16x32_bf16 v[30:33], v[158:161], v[210:213], v[30:33]
	v_mfma_f32_16x16x32_bf16 v[26:29], v[166:169], v[210:213], v[26:29]
	v_mfma_f32_16x16x32_bf16 v[14:17], v[158:161], v[218:221], v[14:17]
	v_mfma_f32_16x16x32_bf16 v[10:13], v[166:169], v[218:221], v[10:13]
	v_mfma_f32_16x16x32_bf16 v[54:57], v[170:173], v[186:189], v[54:57]
	v_mfma_f32_16x16x32_bf16 v[50:53], v[178:181], v[186:189], v[50:53]
	v_mfma_f32_16x16x32_bf16 v[38:41], v[170:173], v[194:197], v[38:41]
	v_mfma_f32_16x16x32_bf16 v[34:37], v[178:181], v[194:197], v[34:37]
	v_mfma_f32_16x16x32_bf16 v[22:25], v[170:173], v[206:209], v[22:25]
	v_mfma_f32_16x16x32_bf16 v[18:21], v[178:181], v[206:209], v[18:21]
	v_mfma_f32_16x16x32_bf16 v[6:9], v[170:173], v[214:217], v[6:9]
	v_mfma_f32_16x16x32_bf16 v[2:5], v[178:181], v[214:217], v[2:5]
	v_mfma_f32_16x16x32_bf16 v[54:57], v[174:177], v[190:193], v[54:57]
	v_mfma_f32_16x16x32_bf16 v[50:53], v[182:185], v[190:193], v[50:53]
	v_mfma_f32_16x16x32_bf16 v[38:41], v[174:177], v[198:201], v[38:41]
	v_mfma_f32_16x16x32_bf16 v[34:37], v[182:185], v[198:201], v[34:37]
	v_mfma_f32_16x16x32_bf16 v[22:25], v[174:177], v[210:213], v[22:25]
	v_mfma_f32_16x16x32_bf16 v[18:21], v[182:185], v[210:213], v[18:21]
	v_mfma_f32_16x16x32_bf16 v[6:9], v[174:177], v[218:221], v[6:9]
	v_mfma_f32_16x16x32_bf16 v[2:5], v[182:185], v[218:221], v[2:5]
	s_setprio 0
	s_barrier
	s_add_i32 s62, s62, 2
	s_add_u32 s28, s28, 0x100
	s_addc_u32 s29, s29, 0
	s_add_u32 s50, s50, 0x100
	s_addc_u32 s51, s51, 0
	s_cmp_gt_u32 s62, 13
	s_cbranch_scc0 .LBB0_1619
	s_and_b64 vcc, exec, s[10:11]
	s_cbranch_vccz .LBB0_1622
	s_barrier

.LBB0_1707:
	v_readlane_b32 s46, v249, 32
	v_readlane_b32 s47, v249, 33
	s_add_u32 s46, s46, s42
	s_addc_u32 s47, s47, s43
	s_and_b64 s[48:49], s[44:45], exec
	s_cselect_b32 s34, s47, s51
	s_cselect_b32 s66, s46, s50
	s_add_u32 s48, s35, s40
	s_addc_u32 s49, s70, s41
	s_and_b64 s[64:65], s[44:45], exec
	s_cselect_b32 s67, s49, s63
	s_cselect_b32 s68, s48, s62
	s_add_i32 s69, s7, -2
	s_add_u32 s50, s50, 0x100080
	s_addc_u32 s51, s51, 0
	s_add_u32 s91, s62, 0x100
	s_addc_u32 s92, s63, 0
	s_mov_b32 s62, 0
	s_waitcnt vmcnt(0)
	ds_read_b128 v[130:133], v168
	ds_read_b128 v[134:137], v168 offset:1024
	ds_read_b128 v[138:141], v168 offset:2048
	ds_read_b128 v[142:145], v168 offset:3072
	ds_read_b128 v[162:165], v169
	ds_read_b128 v[172:175], v169 offset:1024
	ds_read_b128 v[176:179], v169 offset:2048
	ds_read_b128 v[180:183], v169 offset:3072
	s_add_i32 s93, s62, 2
	s_add_u32 s63, s50, 0xfff00080
	s_addc_u32 s64, s51, -1
	s_cmp_eq_u32 s69, s62
	s_cselect_b32 s62, s68, s91
	s_cselect_b32 s65, s34, s64
	s_cselect_b32 s64, s66, s63
	s_cselect_b32 s63, s67, s92
	v_lshl_add_u64 v[218:219], s[50:51], 0, v[156:157]
	s_add_i32 m0, s12, 0xc000
	ds_read_b128 v[184:187], v170
	ds_read_b128 v[188:191], v170 offset:1024
	ds_read_b128 v[192:195], v170 offset:2048
	ds_read_b128 v[196:199], v170 offset:3072
	ds_read_b128 v[200:203], v170 offset:4096
	ds_read_b128 v[206:209], v170 offset:5120
	ds_read_b128 v[210:213], v170 offset:6144
	ds_read_b128 v[214:217], v170 offset:7168
	global_load_lds_dwordx4 v[218:219], off
	s_add_i32 m0, s12, 0xe000
	v_lshl_add_u64 v[218:219], s[50:51], 0, v[158:159]
	global_load_lds_dwordx4 v[218:219], off
	s_waitcnt vmcnt(8) lgkmcnt(0)
	s_setprio 1
	s_barrier
	v_mfma_f32_16x16x32_bf16 v[126:129], v[130:133], v[184:187], 0
	v_mfma_f32_16x16x32_bf16 v[122:125], v[138:141], v[184:187], 0
	v_mfma_f32_16x16x32_bf16 v[110:113], v[130:133], v[192:195], 0
	v_mfma_f32_16x16x32_bf16 v[106:109], v[138:141], v[192:195], 0
	v_mfma_f32_16x16x32_bf16 v[98:101], v[130:133], v[200:203], 0
	v_mfma_f32_16x16x32_bf16 v[90:93], v[138:141], v[200:203], 0
	v_mfma_f32_16x16x32_bf16 v[82:85], v[130:133], v[210:213], 0
	v_mfma_f32_16x16x32_bf16 v[74:77], v[138:141], v[210:213], 0
	v_mfma_f32_16x16x32_bf16 v[126:129], v[134:137], v[188:191], v[126:129]
	v_mfma_f32_16x16x32_bf16 v[122:125], v[142:145], v[188:191], v[122:125]
	v_mfma_f32_16x16x32_bf16 v[110:113], v[134:137], v[196:199], v[110:113]
	v_mfma_f32_16x16x32_bf16 v[106:109], v[142:145], v[196:199], v[106:109]
	v_mfma_f32_16x16x32_bf16 v[98:101], v[134:137], v[206:209], v[98:101]
	v_mfma_f32_16x16x32_bf16 v[90:93], v[142:145], v[206:209], v[90:93]
	v_mfma_f32_16x16x32_bf16 v[82:85], v[134:137], v[214:217], v[82:85]
	v_mfma_f32_16x16x32_bf16 v[74:77], v[142:145], v[214:217], v[74:77]
	v_mfma_f32_16x16x32_bf16 v[118:121], v[162:165], v[184:187], 0
	v_mfma_f32_16x16x32_bf16 v[114:117], v[176:179], v[184:187], 0
	v_mfma_f32_16x16x32_bf16 v[102:105], v[162:165], v[192:195], 0
	v_mfma_f32_16x16x32_bf16 v[94:97], v[176:179], v[192:195], 0
	v_mfma_f32_16x16x32_bf16 v[86:89], v[162:165], v[200:203], 0
	v_mfma_f32_16x16x32_bf16 v[78:81], v[176:179], v[200:203], 0
	v_mfma_f32_16x16x32_bf16 v[70:73], v[162:165], v[210:213], 0
	v_mfma_f32_16x16x32_bf16 v[66:69], v[176:179], v[210:213], 0
	v_mfma_f32_16x16x32_bf16 v[118:121], v[172:175], v[188:191], v[118:121]
	v_mfma_f32_16x16x32_bf16 v[114:117], v[180:183], v[188:191], v[114:117]
	v_mfma_f32_16x16x32_bf16 v[102:105], v[172:175], v[196:199], v[102:105]
	v_mfma_f32_16x16x32_bf16 v[94:97], v[180:183], v[196:199], v[94:97]
	v_mfma_f32_16x16x32_bf16 v[86:89], v[172:175], v[206:209], v[86:89]
	v_mfma_f32_16x16x32_bf16 v[78:81], v[180:183], v[206:209], v[78:81]
	v_mfma_f32_16x16x32_bf16 v[70:73], v[172:175], v[214:217], v[70:73]
	v_mfma_f32_16x16x32_bf16 v[66:69], v[180:183], v[214:217], v[66:69]
	s_setprio 0
	s_barrier
	s_add_i32 s94, s31, s2
	s_mov_b32 m0, s94
	v_lshl_add_u64 v[218:219], s[62:63], 0, v[148:149]
	global_load_lds_dwordx4 v[218:219], off
	ds_read_b128 v[184:187], v170 offset:16384
	ds_read_b128 v[188:191], v170 offset:17408
	ds_read_b128 v[192:195], v170 offset:18432
	ds_read_b128 v[196:199], v170 offset:19456
	ds_read_b128 v[200:203], v170 offset:20480
	ds_read_b128 v[206:209], v170 offset:21504
	ds_read_b128 v[210:213], v170 offset:22528
	ds_read_b128 v[214:217], v170 offset:23552
	s_add_i32 m0, s94, 0x2000
	s_add_u32 s94, s62, 0x100000
	v_lshl_add_u64 v[220:221], s[62:63], 0, v[152:153]
	s_addc_u32 s95, s63, 0
	s_add_i32 s96, s82, s2
	global_load_lds_dwordx4 v[220:221], off
	v_lshl_add_u64 v[222:223], s[94:95], 0, v[148:149]
	s_mov_b32 m0, s96
	v_lshl_add_u64 v[224:225], s[64:65], 0, v[150:151]
	global_load_lds_dwordx4 v[222:223], off
	s_add_i32 m0, s96, 0x2000
	v_lshl_add_u64 v[222:223], s[94:95], 0, v[152:153]
	global_load_lds_dwordx4 v[222:223], off
	s_mov_b32 m0, s12
	v_lshl_add_u64 v[222:223], s[64:65], 0, v[146:147]
	global_load_lds_dwordx4 v[222:223], off
	s_mov_b32 m0, s13
	s_nop 0
	global_load_lds_dwordx4 v[224:225], off
	s_waitcnt vmcnt(8) lgkmcnt(0)
	s_setprio 1
	s_barrier
	v_mfma_f32_16x16x32_bf16 v[62:65], v[130:133], v[184:187], 0
	v_mfma_f32_16x16x32_bf16 v[58:61], v[138:141], v[184:187], 0
	v_mfma_f32_16x16x32_bf16 v[50:53], v[130:133], v[192:195], 0
	v_mfma_f32_16x16x32_bf16 v[42:45], v[138:141], v[192:195], 0
	v_mfma_f32_16x16x32_bf16 v[34:37], v[130:133], v[200:203], 0
	v_mfma_f32_16x16x32_bf16 v[26:29], v[138:141], v[200:203], 0
	v_mfma_f32_16x16x32_bf16 v[18:21], v[130:133], v[210:213], 0
	v_mfma_f32_16x16x32_bf16 v[10:13], v[138:141], v[210:213], 0
	v_mfma_f32_16x16x32_bf16 v[62:65], v[134:137], v[188:191], v[62:65]
	v_mfma_f32_16x16x32_bf16 v[58:61], v[142:145], v[188:191], v[58:61]
	v_mfma_f32_16x16x32_bf16 v[50:53], v[134:137], v[196:199], v[50:53]
	v_mfma_f32_16x16x32_bf16 v[42:45], v[142:145], v[196:199], v[42:45]
	v_mfma_f32_16x16x32_bf16 v[34:37], v[134:137], v[206:209], v[34:37]
	v_mfma_f32_16x16x32_bf16 v[26:29], v[142:145], v[206:209], v[26:29]
	v_mfma_f32_16x16x32_bf16 v[18:21], v[134:137], v[214:217], v[18:21]
	v_mfma_f32_16x16x32_bf16 v[10:13], v[142:145], v[214:217], v[10:13]
	v_mfma_f32_16x16x32_bf16 v[54:57], v[162:165], v[184:187], 0
	v_mfma_f32_16x16x32_bf16 v[46:49], v[176:179], v[184:187], 0
	v_mfma_f32_16x16x32_bf16 v[38:41], v[162:165], v[192:195], 0
	v_mfma_f32_16x16x32_bf16 v[30:33], v[176:179], v[192:195], 0
	v_mfma_f32_16x16x32_bf16 v[22:25], v[162:165], v[200:203], 0
	v_mfma_f32_16x16x32_bf16 v[14:17], v[176:179], v[200:203], 0
	v_mfma_f32_16x16x32_bf16 v[6:9], v[162:165], v[210:213], 0
	v_mfma_f32_16x16x32_bf16 v[2:5], v[176:179], v[210:213], 0
	v_mfma_f32_16x16x32_bf16 v[54:57], v[172:175], v[188:191], v[54:57]
	v_mfma_f32_16x16x32_bf16 v[46:49], v[180:183], v[188:191], v[46:49]
	v_mfma_f32_16x16x32_bf16 v[38:41], v[172:175], v[196:199], v[38:41]
	v_mfma_f32_16x16x32_bf16 v[30:33], v[180:183], v[196:199], v[30:33]
	v_mfma_f32_16x16x32_bf16 v[22:25], v[172:175], v[206:209], v[22:25]
	v_mfma_f32_16x16x32_bf16 v[14:17], v[180:183], v[206:209], v[14:17]
	v_mfma_f32_16x16x32_bf16 v[6:9], v[172:175], v[214:217], v[6:9]
	v_mfma_f32_16x16x32_bf16 v[2:5], v[180:183], v[214:217], v[2:5]
	s_setprio 0
	s_barrier
	s_add_i32 s94, 0, 0x18000
	s_add_i32 s95, 0, 0x1c000
	v_add_u32_e32 v142, s94, v167
	v_add_u32_e32 v154, s95, v167
	ds_read_b128 v[130:133], v142
	ds_read_b128 v[134:137], v142 offset:1024
	ds_read_b128 v[138:141], v142 offset:2048
	ds_read_b128 v[142:145], v142 offset:3072
	ds_read_b128 v[162:165], v154
	ds_read_b128 v[172:175], v154 offset:1024
	ds_read_b128 v[176:179], v154 offset:2048
	ds_read_b128 v[180:183], v154 offset:3072
	s_add_u32 s64, s64, 0x100000
	s_addc_u32 s65, s65, 0
	s_mov_b32 m0, s18
	v_lshl_add_u64 v[226:227], s[64:65], 0, v[146:147]
	ds_read_b128 v[184:187], v170 offset:32768
	ds_read_b128 v[188:191], v170 offset:33792
	ds_read_b128 v[192:195], v170 offset:34816
	ds_read_b128 v[196:199], v170 offset:35840
	ds_read_b128 v[200:203], v170 offset:36864
	ds_read_b128 v[206:209], v170 offset:37888
	ds_read_b128 v[210:213], v170 offset:38912
	ds_read_b128 v[214:217], v170 offset:39936
	global_load_lds_dwordx4 v[226:227], off
	s_mov_b32 m0, s19
	v_lshl_add_u64 v[226:227], s[64:65], 0, v[150:151]
	global_load_lds_dwordx4 v[226:227], off
	s_waitcnt vmcnt(8) lgkmcnt(0)
	s_setprio 1
	s_barrier
	v_mfma_f32_16x16x32_bf16 v[126:129], v[130:133], v[184:187], v[126:129]
	v_mfma_f32_16x16x32_bf16 v[122:125], v[138:141], v[184:187], v[122:125]
	v_mfma_f32_16x16x32_bf16 v[110:113], v[130:133], v[192:195], v[110:113]
	v_mfma_f32_16x16x32_bf16 v[106:109], v[138:141], v[192:195], v[106:109]
	v_mfma_f32_16x16x32_bf16 v[98:101], v[130:133], v[200:203], v[98:101]
	v_mfma_f32_16x16x32_bf16 v[90:93], v[138:141], v[200:203], v[90:93]
	v_mfma_f32_16x16x32_bf16 v[82:85], v[130:133], v[210:213], v[82:85]
	v_mfma_f32_16x16x32_bf16 v[74:77], v[138:141], v[210:213], v[74:77]
	v_mfma_f32_16x16x32_bf16 v[126:129], v[134:137], v[188:191], v[126:129]
	v_mfma_f32_16x16x32_bf16 v[122:125], v[142:145], v[188:191], v[122:125]
	v_mfma_f32_16x16x32_bf16 v[110:113], v[134:137], v[196:199], v[110:113]
	v_mfma_f32_16x16x32_bf16 v[106:109], v[142:145], v[196:199], v[106:109]
	v_mfma_f32_16x16x32_bf16 v[98:101], v[134:137], v[206:209], v[98:101]
	v_mfma_f32_16x16x32_bf16 v[90:93], v[142:145], v[206:209], v[90:93]
	v_mfma_f32_16x16x32_bf16 v[82:85], v[134:137], v[214:217], v[82:85]
	v_mfma_f32_16x16x32_bf16 v[74:77], v[142:145], v[214:217], v[74:77]
	v_mfma_f32_16x16x32_bf16 v[118:121], v[162:165], v[184:187], v[118:121]
	v_mfma_f32_16x16x32_bf16 v[114:117], v[176:179], v[184:187], v[114:117]
	v_mfma_f32_16x16x32_bf16 v[102:105], v[162:165], v[192:195], v[102:105]
	v_mfma_f32_16x16x32_bf16 v[94:97], v[176:179], v[192:195], v[94:97]
	v_mfma_f32_16x16x32_bf16 v[86:89], v[162:165], v[200:203], v[86:89]
	v_mfma_f32_16x16x32_bf16 v[78:81], v[176:179], v[200:203], v[78:81]
	v_mfma_f32_16x16x32_bf16 v[70:73], v[162:165], v[210:213], v[70:73]
	v_mfma_f32_16x16x32_bf16 v[66:69], v[176:179], v[210:213], v[66:69]
	v_mfma_f32_16x16x32_bf16 v[118:121], v[172:175], v[188:191], v[118:121]
	v_mfma_f32_16x16x32_bf16 v[114:117], v[180:183], v[188:191], v[114:117]
	v_mfma_f32_16x16x32_bf16 v[102:105], v[172:175], v[196:199], v[102:105]
	v_mfma_f32_16x16x32_bf16 v[94:97], v[180:183], v[196:199], v[94:97]
	v_mfma_f32_16x16x32_bf16 v[86:89], v[172:175], v[206:209], v[86:89]
	v_mfma_f32_16x16x32_bf16 v[78:81], v[180:183], v[206:209], v[78:81]
	v_mfma_f32_16x16x32_bf16 v[70:73], v[172:175], v[214:217], v[70:73]
	v_mfma_f32_16x16x32_bf16 v[66:69], v[180:183], v[214:217], v[66:69]
	s_setprio 0
	s_barrier
	s_add_i32 s64, s94, s2
	s_mov_b32 m0, s64
	v_lshl_add_u64 v[218:219], v[218:219], 0, s[16:17]
	global_load_lds_dwordx4 v[218:219], off
	ds_read_b128 v[184:187], v170 offset:49152
	ds_read_b128 v[188:191], v170 offset:50176
	ds_read_b128 v[192:195], v170 offset:51200
	ds_read_b128 v[196:199], v170 offset:52224
	ds_read_b128 v[200:203], v170 offset:53248
	ds_read_b128 v[206:209], v170 offset:54272
	ds_read_b128 v[210:213], v170 offset:55296
	ds_read_b128 v[214:217], v170 offset:56320
	s_add_i32 m0, s64, 0x2000
	s_add_u32 s62, s62, 0x100080
	v_lshl_add_u64 v[218:219], v[220:221], 0, s[16:17]
	s_addc_u32 s63, s63, 0
	s_add_i32 s64, s95, s2
	global_load_lds_dwordx4 v[218:219], off
	s_mov_b32 m0, s64
	v_lshl_add_u64 v[218:219], s[62:63], 0, v[148:149]
	global_load_lds_dwordx4 v[218:219], off
	s_add_i32 m0, s64, 0x2000
	v_lshl_add_u64 v[218:219], s[62:63], 0, v[152:153]
	global_load_lds_dwordx4 v[218:219], off
	s_mov_b32 m0, s74
	v_lshl_add_u64 v[218:219], v[222:223], 0, s[16:17]
	global_load_lds_dwordx4 v[218:219], off
	s_mov_b32 m0, s75
	v_lshl_add_u64 v[218:219], v[224:225], 0, s[16:17]
	global_load_lds_dwordx4 v[218:219], off
	s_waitcnt vmcnt(8) lgkmcnt(0)
	s_setprio 1
	s_barrier
	v_mfma_f32_16x16x32_bf16 v[62:65], v[130:133], v[184:187], v[62:65]
	v_mfma_f32_16x16x32_bf16 v[58:61], v[138:141], v[184:187], v[58:61]
	v_mfma_f32_16x16x32_bf16 v[50:53], v[130:133], v[192:195], v[50:53]
	v_mfma_f32_16x16x32_bf16 v[42:45], v[138:141], v[192:195], v[42:45]
	v_mfma_f32_16x16x32_bf16 v[34:37], v[130:133], v[200:203], v[34:37]
	v_mfma_f32_16x16x32_bf16 v[26:29], v[138:141], v[200:203], v[26:29]
	v_mfma_f32_16x16x32_bf16 v[18:21], v[130:133], v[210:213], v[18:21]
	v_mfma_f32_16x16x32_bf16 v[10:13], v[138:141], v[210:213], v[10:13]
	v_mfma_f32_16x16x32_bf16 v[62:65], v[134:137], v[188:191], v[62:65]
	v_mfma_f32_16x16x32_bf16 v[58:61], v[142:145], v[188:191], v[58:61]
	v_mfma_f32_16x16x32_bf16 v[50:53], v[134:137], v[196:199], v[50:53]
	v_mfma_f32_16x16x32_bf16 v[42:45], v[142:145], v[196:199], v[42:45]
	v_mfma_f32_16x16x32_bf16 v[34:37], v[134:137], v[206:209], v[34:37]
	v_mfma_f32_16x16x32_bf16 v[26:29], v[142:145], v[206:209], v[26:29]
	v_mfma_f32_16x16x32_bf16 v[18:21], v[134:137], v[214:217], v[18:21]
	v_mfma_f32_16x16x32_bf16 v[10:13], v[142:145], v[214:217], v[10:13]
	v_mfma_f32_16x16x32_bf16 v[54:57], v[162:165], v[184:187], v[54:57]
	v_mfma_f32_16x16x32_bf16 v[46:49], v[176:179], v[184:187], v[46:49]
	v_mfma_f32_16x16x32_bf16 v[38:41], v[162:165], v[192:195], v[38:41]
	v_mfma_f32_16x16x32_bf16 v[30:33], v[176:179], v[192:195], v[30:33]
	v_mfma_f32_16x16x32_bf16 v[22:25], v[162:165], v[200:203], v[22:25]
	v_mfma_f32_16x16x32_bf16 v[14:17], v[176:179], v[200:203], v[14:17]
	v_mfma_f32_16x16x32_bf16 v[6:9], v[162:165], v[210:213], v[6:9]
	v_mfma_f32_16x16x32_bf16 v[2:5], v[176:179], v[210:213], v[2:5]
	v_mfma_f32_16x16x32_bf16 v[54:57], v[172:175], v[188:191], v[54:57]
	v_mfma_f32_16x16x32_bf16 v[46:49], v[180:183], v[188:191], v[46:49]
	v_mfma_f32_16x16x32_bf16 v[38:41], v[172:175], v[196:199], v[38:41]
	v_mfma_f32_16x16x32_bf16 v[30:33], v[180:183], v[196:199], v[30:33]
	v_mfma_f32_16x16x32_bf16 v[22:25], v[172:175], v[206:209], v[22:25]
	v_mfma_f32_16x16x32_bf16 v[14:17], v[180:183], v[206:209], v[14:17]
	v_mfma_f32_16x16x32_bf16 v[6:9], v[172:175], v[214:217], v[6:9]
	v_mfma_f32_16x16x32_bf16 v[2:5], v[180:183], v[214:217], v[2:5]
	s_setprio 0
	s_barrier
	s_add_u32 s50, s50, 0x100
	s_addc_u32 s51, s51, 0
	s_add_u32 s91, s91, 0x100
	s_addc_u32 s92, s92, 0
	s_cmp_ge_i32 s93, s7
	s_mov_b32 s62, s93
.LBB0_1708:
	ds_read_b128 v[130:133], v168
	ds_read_b128 v[134:137], v168 offset:1024
	ds_read_b128 v[138:141], v168 offset:2048
	ds_read_b128 v[142:145], v168 offset:3072
	ds_read_b128 v[162:165], v169
	ds_read_b128 v[172:175], v169 offset:1024
	ds_read_b128 v[176:179], v169 offset:2048
	ds_read_b128 v[180:183], v169 offset:3072
	s_add_i32 s93, s62, 2
	s_add_u32 s63, s50, 0xfff00080
	s_addc_u32 s64, s51, -1
	s_cmp_eq_u32 s69, s62
	s_cselect_b32 s62, s68, s91
	s_cselect_b32 s65, s34, s64
	s_cselect_b32 s64, s66, s63
	s_cselect_b32 s63, s67, s92
	v_lshl_add_u64 v[218:219], s[50:51], 0, v[156:157]
	s_add_i32 m0, s12, 0xc000
	ds_read_b128 v[184:187], v170
	ds_read_b128 v[188:191], v170 offset:1024
	ds_read_b128 v[192:195], v170 offset:2048
	ds_read_b128 v[196:199], v170 offset:3072
	ds_read_b128 v[200:203], v170 offset:4096
	ds_read_b128 v[206:209], v170 offset:5120
	ds_read_b128 v[210:213], v170 offset:6144
	ds_read_b128 v[214:217], v170 offset:7168
	global_load_lds_dwordx4 v[218:219], off
	s_add_i32 m0, s12, 0xe000
	v_lshl_add_u64 v[218:219], s[50:51], 0, v[158:159]
	global_load_lds_dwordx4 v[218:219], off
	s_waitcnt vmcnt(8) lgkmcnt(0)
	s_setprio 1
	s_barrier
	v_mfma_f32_16x16x32_bf16 v[126:129], v[130:133], v[184:187], v[126:129]
	v_mfma_f32_16x16x32_bf16 v[122:125], v[138:141], v[184:187], v[122:125]
	v_mfma_f32_16x16x32_bf16 v[110:113], v[130:133], v[192:195], v[110:113]
	v_mfma_f32_16x16x32_bf16 v[106:109], v[138:141], v[192:195], v[106:109]
	v_mfma_f32_16x16x32_bf16 v[98:101], v[130:133], v[200:203], v[98:101]
	v_mfma_f32_16x16x32_bf16 v[90:93], v[138:141], v[200:203], v[90:93]
	v_mfma_f32_16x16x32_bf16 v[82:85], v[130:133], v[210:213], v[82:85]
	v_mfma_f32_16x16x32_bf16 v[74:77], v[138:141], v[210:213], v[74:77]
	v_mfma_f32_16x16x32_bf16 v[126:129], v[134:137], v[188:191], v[126:129]
	v_mfma_f32_16x16x32_bf16 v[122:125], v[142:145], v[188:191], v[122:125]
	v_mfma_f32_16x16x32_bf16 v[110:113], v[134:137], v[196:199], v[110:113]
	v_mfma_f32_16x16x32_bf16 v[106:109], v[142:145], v[196:199], v[106:109]
	v_mfma_f32_16x16x32_bf16 v[98:101], v[134:137], v[206:209], v[98:101]
	v_mfma_f32_16x16x32_bf16 v[90:93], v[142:145], v[206:209], v[90:93]
	v_mfma_f32_16x16x32_bf16 v[82:85], v[134:137], v[214:217], v[82:85]
	v_mfma_f32_16x16x32_bf16 v[74:77], v[142:145], v[214:217], v[74:77]
	v_mfma_f32_16x16x32_bf16 v[118:121], v[162:165], v[184:187], v[118:121]
	v_mfma_f32_16x16x32_bf16 v[114:117], v[176:179], v[184:187], v[114:117]
	v_mfma_f32_16x16x32_bf16 v[102:105], v[162:165], v[192:195], v[102:105]
	v_mfma_f32_16x16x32_bf16 v[94:97], v[176:179], v[192:195], v[94:97]
	v_mfma_f32_16x16x32_bf16 v[86:89], v[162:165], v[200:203], v[86:89]
	v_mfma_f32_16x16x32_bf16 v[78:81], v[176:179], v[200:203], v[78:81]
	v_mfma_f32_16x16x32_bf16 v[70:73], v[162:165], v[210:213], v[70:73]
	v_mfma_f32_16x16x32_bf16 v[66:69], v[176:179], v[210:213], v[66:69]
	v_mfma_f32_16x16x32_bf16 v[118:121], v[172:175], v[188:191], v[118:121]
	v_mfma_f32_16x16x32_bf16 v[114:117], v[180:183], v[188:191], v[114:117]
	v_mfma_f32_16x16x32_bf16 v[102:105], v[172:175], v[196:199], v[102:105]
	v_mfma_f32_16x16x32_bf16 v[94:97], v[180:183], v[196:199], v[94:97]
	v_mfma_f32_16x16x32_bf16 v[86:89], v[172:175], v[206:209], v[86:89]
	v_mfma_f32_16x16x32_bf16 v[78:81], v[180:183], v[206:209], v[78:81]
	v_mfma_f32_16x16x32_bf16 v[70:73], v[172:175], v[214:217], v[70:73]
	v_mfma_f32_16x16x32_bf16 v[66:69], v[180:183], v[214:217], v[66:69]
	s_setprio 0
	s_barrier
	s_add_i32 s94, s31, s2
	s_mov_b32 m0, s94
	v_lshl_add_u64 v[218:219], s[62:63], 0, v[148:149]
	global_load_lds_dwordx4 v[218:219], off
	ds_read_b128 v[184:187], v170 offset:16384
	ds_read_b128 v[188:191], v170 offset:17408
	ds_read_b128 v[192:195], v170 offset:18432
	ds_read_b128 v[196:199], v170 offset:19456
	ds_read_b128 v[200:203], v170 offset:20480
	ds_read_b128 v[206:209], v170 offset:21504
	ds_read_b128 v[210:213], v170 offset:22528
	ds_read_b128 v[214:217], v170 offset:23552
	s_add_i32 m0, s94, 0x2000
	s_add_u32 s94, s62, 0x100000
	v_lshl_add_u64 v[220:221], s[62:63], 0, v[152:153]
	s_addc_u32 s95, s63, 0
	s_add_i32 s96, s82, s2
	global_load_lds_dwordx4 v[220:221], off
	v_lshl_add_u64 v[222:223], s[94:95], 0, v[148:149]
	s_mov_b32 m0, s96
	v_lshl_add_u64 v[224:225], s[64:65], 0, v[150:151]
	global_load_lds_dwordx4 v[222:223], off
	s_add_i32 m0, s96, 0x2000
	v_lshl_add_u64 v[222:223], s[94:95], 0, v[152:153]
	global_load_lds_dwordx4 v[222:223], off
	s_mov_b32 m0, s12
	v_lshl_add_u64 v[222:223], s[64:65], 0, v[146:147]
	global_load_lds_dwordx4 v[222:223], off
	s_mov_b32 m0, s13
	s_nop 0
	global_load_lds_dwordx4 v[224:225], off
	s_waitcnt vmcnt(8) lgkmcnt(0)
	s_setprio 1
	s_barrier
	v_mfma_f32_16x16x32_bf16 v[62:65], v[130:133], v[184:187], v[62:65]
	v_mfma_f32_16x16x32_bf16 v[58:61], v[138:141], v[184:187], v[58:61]
	v_mfma_f32_16x16x32_bf16 v[50:53], v[130:133], v[192:195], v[50:53]
	v_mfma_f32_16x16x32_bf16 v[42:45], v[138:141], v[192:195], v[42:45]
	v_mfma_f32_16x16x32_bf16 v[34:37], v[130:133], v[200:203], v[34:37]
	v_mfma_f32_16x16x32_bf16 v[26:29], v[138:141], v[200:203], v[26:29]
	v_mfma_f32_16x16x32_bf16 v[18:21], v[130:133], v[210:213], v[18:21]
	v_mfma_f32_16x16x32_bf16 v[10:13], v[138:141], v[210:213], v[10:13]
	v_mfma_f32_16x16x32_bf16 v[62:65], v[134:137], v[188:191], v[62:65]
	v_mfma_f32_16x16x32_bf16 v[58:61], v[142:145], v[188:191], v[58:61]
	v_mfma_f32_16x16x32_bf16 v[50:53], v[134:137], v[196:199], v[50:53]
	v_mfma_f32_16x16x32_bf16 v[42:45], v[142:145], v[196:199], v[42:45]
	v_mfma_f32_16x16x32_bf16 v[34:37], v[134:137], v[206:209], v[34:37]
	v_mfma_f32_16x16x32_bf16 v[26:29], v[142:145], v[206:209], v[26:29]
	v_mfma_f32_16x16x32_bf16 v[18:21], v[134:137], v[214:217], v[18:21]
	v_mfma_f32_16x16x32_bf16 v[10:13], v[142:145], v[214:217], v[10:13]
	v_mfma_f32_16x16x32_bf16 v[54:57], v[162:165], v[184:187], v[54:57]
	v_mfma_f32_16x16x32_bf16 v[46:49], v[176:179], v[184:187], v[46:49]
	v_mfma_f32_16x16x32_bf16 v[38:41], v[162:165], v[192:195], v[38:41]
	v_mfma_f32_16x16x32_bf16 v[30:33], v[176:179], v[192:195], v[30:33]
	v_mfma_f32_16x16x32_bf16 v[22:25], v[162:165], v[200:203], v[22:25]
	v_mfma_f32_16x16x32_bf16 v[14:17], v[176:179], v[200:203], v[14:17]
	v_mfma_f32_16x16x32_bf16 v[6:9], v[162:165], v[210:213], v[6:9]
	v_mfma_f32_16x16x32_bf16 v[2:5], v[176:179], v[210:213], v[2:5]
	v_mfma_f32_16x16x32_bf16 v[54:57], v[172:175], v[188:191], v[54:57]
	v_mfma_f32_16x16x32_bf16 v[46:49], v[180:183], v[188:191], v[46:49]
	v_mfma_f32_16x16x32_bf16 v[38:41], v[172:175], v[196:199], v[38:41]
	v_mfma_f32_16x16x32_bf16 v[30:33], v[180:183], v[196:199], v[30:33]
	v_mfma_f32_16x16x32_bf16 v[22:25], v[172:175], v[206:209], v[22:25]
	v_mfma_f32_16x16x32_bf16 v[14:17], v[180:183], v[206:209], v[14:17]
	v_mfma_f32_16x16x32_bf16 v[6:9], v[172:175], v[214:217], v[6:9]
	v_mfma_f32_16x16x32_bf16 v[2:5], v[180:183], v[214:217], v[2:5]
	s_setprio 0
	s_barrier
	s_add_i32 s94, 0, 0x18000
	s_add_i32 s95, 0, 0x1c000
	v_add_u32_e32 v142, s94, v167
	v_add_u32_e32 v154, s95, v167
	ds_read_b128 v[130:133], v142
	ds_read_b128 v[134:137], v142 offset:1024
	ds_read_b128 v[138:141], v142 offset:2048
	ds_read_b128 v[142:145], v142 offset:3072
	ds_read_b128 v[162:165], v154
	ds_read_b128 v[172:175], v154 offset:1024
	ds_read_b128 v[176:179], v154 offset:2048
	ds_read_b128 v[180:183], v154 offset:3072
	s_add_u32 s64, s64, 0x100000
	s_addc_u32 s65, s65, 0
	s_mov_b32 m0, s18
	v_lshl_add_u64 v[226:227], s[64:65], 0, v[146:147]
	ds_read_b128 v[184:187], v170 offset:32768
	ds_read_b128 v[188:191], v170 offset:33792
	ds_read_b128 v[192:195], v170 offset:34816
	ds_read_b128 v[196:199], v170 offset:35840
	ds_read_b128 v[200:203], v170 offset:36864
	ds_read_b128 v[206:209], v170 offset:37888
	ds_read_b128 v[210:213], v170 offset:38912
	ds_read_b128 v[214:217], v170 offset:39936
	global_load_lds_dwordx4 v[226:227], off
	s_mov_b32 m0, s19
	v_lshl_add_u64 v[226:227], s[64:65], 0, v[150:151]
	global_load_lds_dwordx4 v[226:227], off
	s_waitcnt vmcnt(8) lgkmcnt(0)
	s_setprio 1
	s_barrier
	v_mfma_f32_16x16x32_bf16 v[126:129], v[130:133], v[184:187], v[126:129]
	v_mfma_f32_16x16x32_bf16 v[122:125], v[138:141], v[184:187], v[122:125]
	v_mfma_f32_16x16x32_bf16 v[110:113], v[130:133], v[192:195], v[110:113]
	v_mfma_f32_16x16x32_bf16 v[106:109], v[138:141], v[192:195], v[106:109]
	v_mfma_f32_16x16x32_bf16 v[98:101], v[130:133], v[200:203], v[98:101]
	v_mfma_f32_16x16x32_bf16 v[90:93], v[138:141], v[200:203], v[90:93]
	v_mfma_f32_16x16x32_bf16 v[82:85], v[130:133], v[210:213], v[82:85]
	v_mfma_f32_16x16x32_bf16 v[74:77], v[138:141], v[210:213], v[74:77]
	v_mfma_f32_16x16x32_bf16 v[126:129], v[134:137], v[188:191], v[126:129]
	v_mfma_f32_16x16x32_bf16 v[122:125], v[142:145], v[188:191], v[122:125]
	v_mfma_f32_16x16x32_bf16 v[110:113], v[134:137], v[196:199], v[110:113]
	v_mfma_f32_16x16x32_bf16 v[106:109], v[142:145], v[196:199], v[106:109]
	v_mfma_f32_16x16x32_bf16 v[98:101], v[134:137], v[206:209], v[98:101]
	v_mfma_f32_16x16x32_bf16 v[90:93], v[142:145], v[206:209], v[90:93]
	v_mfma_f32_16x16x32_bf16 v[82:85], v[134:137], v[214:217], v[82:85]
	v_mfma_f32_16x16x32_bf16 v[74:77], v[142:145], v[214:217], v[74:77]
	v_mfma_f32_16x16x32_bf16 v[118:121], v[162:165], v[184:187], v[118:121]
	v_mfma_f32_16x16x32_bf16 v[114:117], v[176:179], v[184:187], v[114:117]
	v_mfma_f32_16x16x32_bf16 v[102:105], v[162:165], v[192:195], v[102:105]
	v_mfma_f32_16x16x32_bf16 v[94:97], v[176:179], v[192:195], v[94:97]
	v_mfma_f32_16x16x32_bf16 v[86:89], v[162:165], v[200:203], v[86:89]
	v_mfma_f32_16x16x32_bf16 v[78:81], v[176:179], v[200:203], v[78:81]
	v_mfma_f32_16x16x32_bf16 v[70:73], v[162:165], v[210:213], v[70:73]
	v_mfma_f32_16x16x32_bf16 v[66:69], v[176:179], v[210:213], v[66:69]
	v_mfma_f32_16x16x32_bf16 v[118:121], v[172:175], v[188:191], v[118:121]
	v_mfma_f32_16x16x32_bf16 v[114:117], v[180:183], v[188:191], v[114:117]
	v_mfma_f32_16x16x32_bf16 v[102:105], v[172:175], v[196:199], v[102:105]
	v_mfma_f32_16x16x32_bf16 v[94:97], v[180:183], v[196:199], v[94:97]
	v_mfma_f32_16x16x32_bf16 v[86:89], v[172:175], v[206:209], v[86:89]
	v_mfma_f32_16x16x32_bf16 v[78:81], v[180:183], v[206:209], v[78:81]
	v_mfma_f32_16x16x32_bf16 v[70:73], v[172:175], v[214:217], v[70:73]
	v_mfma_f32_16x16x32_bf16 v[66:69], v[180:183], v[214:217], v[66:69]
	s_setprio 0
	s_barrier
	s_add_i32 s64, s94, s2
	s_mov_b32 m0, s64
	v_lshl_add_u64 v[218:219], v[218:219], 0, s[16:17]
	global_load_lds_dwordx4 v[218:219], off
	ds_read_b128 v[184:187], v170 offset:49152
	ds_read_b128 v[188:191], v170 offset:50176
	ds_read_b128 v[192:195], v170 offset:51200
	ds_read_b128 v[196:199], v170 offset:52224
	ds_read_b128 v[200:203], v170 offset:53248
	ds_read_b128 v[206:209], v170 offset:54272
	ds_read_b128 v[210:213], v170 offset:55296
	ds_read_b128 v[214:217], v170 offset:56320
	s_add_i32 m0, s64, 0x2000
	s_add_u32 s62, s62, 0x100080
	v_lshl_add_u64 v[218:219], v[220:221], 0, s[16:17]
	s_addc_u32 s63, s63, 0
	s_add_i32 s64, s95, s2
	global_load_lds_dwordx4 v[218:219], off
	s_mov_b32 m0, s64
	v_lshl_add_u64 v[218:219], s[62:63], 0, v[148:149]
	global_load_lds_dwordx4 v[218:219], off
	s_add_i32 m0, s64, 0x2000
	v_lshl_add_u64 v[218:219], s[62:63], 0, v[152:153]
	global_load_lds_dwordx4 v[218:219], off
	s_mov_b32 m0, s74
	v_lshl_add_u64 v[218:219], v[222:223], 0, s[16:17]
	global_load_lds_dwordx4 v[218:219], off
	s_mov_b32 m0, s75
	v_lshl_add_u64 v[218:219], v[224:225], 0, s[16:17]
	global_load_lds_dwordx4 v[218:219], off
	s_waitcnt vmcnt(8) lgkmcnt(0)
	s_setprio 1
	s_barrier
	v_mfma_f32_16x16x32_bf16 v[62:65], v[130:133], v[184:187], v[62:65]
	v_mfma_f32_16x16x32_bf16 v[58:61], v[138:141], v[184:187], v[58:61]
	v_mfma_f32_16x16x32_bf16 v[50:53], v[130:133], v[192:195], v[50:53]
	v_mfma_f32_16x16x32_bf16 v[42:45], v[138:141], v[192:195], v[42:45]
	v_mfma_f32_16x16x32_bf16 v[34:37], v[130:133], v[200:203], v[34:37]
	v_mfma_f32_16x16x32_bf16 v[26:29], v[138:141], v[200:203], v[26:29]
	v_mfma_f32_16x16x32_bf16 v[18:21], v[130:133], v[210:213], v[18:21]
	v_mfma_f32_16x16x32_bf16 v[10:13], v[138:141], v[210:213], v[10:13]
	v_mfma_f32_16x16x32_bf16 v[62:65], v[134:137], v[188:191], v[62:65]
	v_mfma_f32_16x16x32_bf16 v[58:61], v[142:145], v[188:191], v[58:61]
	v_mfma_f32_16x16x32_bf16 v[50:53], v[134:137], v[196:199], v[50:53]
	v_mfma_f32_16x16x32_bf16 v[42:45], v[142:145], v[196:199], v[42:45]
	v_mfma_f32_16x16x32_bf16 v[34:37], v[134:137], v[206:209], v[34:37]
	v_mfma_f32_16x16x32_bf16 v[26:29], v[142:145], v[206:209], v[26:29]
	v_mfma_f32_16x16x32_bf16 v[18:21], v[134:137], v[214:217], v[18:21]
	v_mfma_f32_16x16x32_bf16 v[10:13], v[142:145], v[214:217], v[10:13]
	v_mfma_f32_16x16x32_bf16 v[54:57], v[162:165], v[184:187], v[54:57]
	v_mfma_f32_16x16x32_bf16 v[46:49], v[176:179], v[184:187], v[46:49]
	v_mfma_f32_16x16x32_bf16 v[38:41], v[162:165], v[192:195], v[38:41]
	v_mfma_f32_16x16x32_bf16 v[30:33], v[176:179], v[192:195], v[30:33]
	v_mfma_f32_16x16x32_bf16 v[22:25], v[162:165], v[200:203], v[22:25]
	v_mfma_f32_16x16x32_bf16 v[14:17], v[176:179], v[200:203], v[14:17]
	v_mfma_f32_16x16x32_bf16 v[6:9], v[162:165], v[210:213], v[6:9]
	v_mfma_f32_16x16x32_bf16 v[2:5], v[176:179], v[210:213], v[2:5]
	v_mfma_f32_16x16x32_bf16 v[54:57], v[172:175], v[188:191], v[54:57]
	v_mfma_f32_16x16x32_bf16 v[46:49], v[180:183], v[188:191], v[46:49]
	v_mfma_f32_16x16x32_bf16 v[38:41], v[172:175], v[196:199], v[38:41]
	v_mfma_f32_16x16x32_bf16 v[30:33], v[180:183], v[196:199], v[30:33]
	v_mfma_f32_16x16x32_bf16 v[22:25], v[172:175], v[206:209], v[22:25]
	v_mfma_f32_16x16x32_bf16 v[14:17], v[180:183], v[206:209], v[14:17]
	v_mfma_f32_16x16x32_bf16 v[6:9], v[172:175], v[214:217], v[6:9]
	v_mfma_f32_16x16x32_bf16 v[2:5], v[180:183], v[214:217], v[2:5]
	s_setprio 0
	s_barrier
	s_add_u32 s50, s50, 0x100
	s_addc_u32 s51, s51, 0
	s_add_u32 s91, s91, 0x100
	s_addc_u32 s92, s92, 0
	s_cmp_ge_i32 s93, s7
	s_mov_b32 s62, s93
	s_cbranch_scc0 .LBB0_1708
	s_and_b64 vcc, exec, s[20:21]
	s_cbranch_vccz .LBB0_1711
	s_barrier
